# v19 plus nt (streaming) hint on all GEMM epilogue global stores
# baseline (speedup 1.0000x reference)
; __device__ __forceinline__ u32x4 pack8(const f32x4 a, const f32x4 b) { u32x4 w; w.x = cvt_pk_bf16(a[0], a[1]); w.y = cvt_pk_bf16(a[2], a[3]); w.z = cvt_pk_bf16(b[0], b[1]); w.w = cvt_pk_bf16(b[2], b[3]); return w; }
;     __device__ __forceinline__ void operator()(const f32x4 (&acc)[2][2][4][2], const Unit& u, int wr, int wc, int fr, int fq) const {
;         const int pn = u.pn; const bool sample = u.pm >= 256;
;         const int rbase = u.pm * 256 + wr * 64 + fr;
;         if (pn < 2) {
;     ...
;         } else {
;             bf16_t* G = pn < 15 ? GA : GB; const int cb = (pn < 15 ? pn - 11 : pn - 15) * 256 + wc * 32 + fq * 8;
; #pragma unroll
;             for (int ai = 0; ai < 2; ++ai)
; #pragma unroll
;                 for (int m = 0; m < 4; ++m) { const int row = rbase + ai * 128 + m * 16;
; #pragma unroll
;                     for (int bj = 0; bj < 2; ++bj) { f32x4 v0 = acc[ai][bj][m][0], v1 = acc[ai][bj][m][1];
; #pragma unroll
;                         for (int i = 0; i < 4; ++i) { v0[i] = __builtin_amdgcn_rcpf(1.0f + __expf(-v0[i])); v1[i] = __builtin_amdgcn_rcpf(1.0f + __expf(-v1[i])); }
;                         *(u32x4*)(G + (size_t)row * 1024 + cb + bj * 128) = pack8(v0, v1); } }
.LBB0_124:
	s_cmpk_gt_i32 s0, 0xff
	s_cselect_b64 s[38:39], -1, 0
	s_cmpk_lt_i32 s0, 0x100
	s_cselect_b64 s[8:9], -1, 0
	s_lshl_b32 s27, s0, 8
	s_add_i32 s27, s27, s68
	v_or_b32_e32 v184, s27, v153
	s_cmp_gt_i32 s36, 1
	s_mov_b64 s[0:1], -1
	s_cbranch_scc0 .LBB0_390
	s_cmp_gt_u32 s36, 7
	s_cbranch_scc0 .LBB0_195
	s_cmp_gt_u32 s36, 10
	s_cbranch_scc0 .LBB0_128
	v_mul_f32_e32 v133, 0xbfb8aa3b, v120
	v_exp_f32_e32 v133, v133
	v_mul_f32_e32 v134, 0xbfb8aa3b, v125
	v_mul_f32_e32 v135, 0xbfb8aa3b, v121
	v_exp_f32_e32 v134, v134
	v_exp_f32_e32 v135, v135
	s_cmp_lt_u32 s36, 15
	s_cselect_b64 s[0:1], -1, 0
	s_and_b64 s[0:1], s[0:1], exec
	v_add_f32_e32 v133, 1.0, v133
	s_mov_b32 s0, 0x3d200000
	v_mul_f32_e32 v132, 0xbfb8aa3b, v124
	v_rcp_f32_e32 v136, v133
	v_add_f32_e32 v133, 1.0, v134
	v_add_f32_e32 v134, 1.0, v135
	v_mul_f32_e32 v135, 0xbfb8aa3b, v126
	v_mul_f32_e32 v137, 0xbfb8aa3b, v122
	s_cselect_b32 s0, s0, 0x45400000
	v_exp_f32_e32 v132, v132
	v_exp_f32_e32 v135, v135
	v_exp_f32_e32 v137, v137
	v_mul_f32_e32 v138, 0xbfb8aa3b, v127
	v_mul_f32_e32 v139, 0xbfb8aa3b, v123
	s_cselect_b32 s4, -11, -15
	s_add_u32 s0, s86, s0
	v_exp_f32_e32 v138, v138
	v_exp_f32_e32 v139, v139
	s_addc_u32 s1, s87, 0
	s_add_i32 s4, s4, s36
	v_lshl_or_b32 v128, s4, 8, v168
	v_ashrrev_i32_e32 v129, 31, v128
	v_ashrrev_i32_e32 v185, 31, v184
	v_add_f32_e32 v132, 1.0, v132
	v_add_f32_e32 v135, 1.0, v135
	v_add_f32_e32 v137, 1.0, v137
	v_lshl_add_u64 v[130:131], v[128:129], 1, s[0:1]
	v_lshlrev_b64 v[128:129], 11, v[184:185]
	v_rcp_f32_e32 v132, v132
	v_rcp_f32_e32 v133, v133
	v_rcp_f32_e32 v134, v134
	v_rcp_f32_e32 v135, v135
	v_rcp_f32_e32 v137, v137
	v_add_f32_e32 v138, 1.0, v138
	v_add_f32_e32 v139, 1.0, v139
	v_lshl_add_u64 v[128:129], v[130:131], 0, v[128:129]
	v_rcp_f32_e32 v138, v138
	v_rcp_f32_e32 v139, v139
	v_cvt_pk_bf16_f32 v132, v132, v133
	v_cvt_pk_bf16_f32 v133, v135, v138
	v_cvt_pk_bf16_f32 v134, v136, v134
	v_cvt_pk_bf16_f32 v135, v137, v139
	v_mul_f32_e32 v137, 0xbfb8aa3b, v112
	v_mul_f32_e32 v136, 0xbfb8aa3b, v116
	v_exp_f32_e32 v137, v137
	global_store_dwordx4 v[128:129], v[132:135], off nt
	v_exp_f32_e32 v136, v136
	v_mul_f32_e32 v138, 0xbfb8aa3b, v119
	v_mul_f32_e32 v134, 0xbfb8aa3b, v117
	v_mul_f32_e32 v135, 0xbfb8aa3b, v113
	v_exp_f32_e32 v134, v134
	v_exp_f32_e32 v135, v135
	v_add_f32_e32 v133, 1.0, v137
	v_add_f32_e32 v132, 1.0, v136
	v_rcp_f32_e32 v136, v133
	v_add_f32_e32 v133, 1.0, v134
	v_add_f32_e32 v134, 1.0, v135
	v_mul_f32_e32 v135, 0xbfb8aa3b, v118
	v_exp_f32_e32 v135, v135
	v_mul_f32_e32 v137, 0xbfb8aa3b, v114
	v_mul_f32_e32 v139, 0xbfb8aa3b, v115
	v_exp_f32_e32 v137, v137
	v_exp_f32_e32 v138, v138
	v_exp_f32_e32 v139, v139
	v_add_f32_e32 v135, 1.0, v135
	v_rcp_f32_e32 v132, v132
	v_rcp_f32_e32 v133, v133
	v_rcp_f32_e32 v134, v134
	v_rcp_f32_e32 v135, v135
	v_add_f32_e32 v137, 1.0, v137
	v_add_f32_e32 v138, 1.0, v138
	v_add_f32_e32 v139, 1.0, v139
	v_rcp_f32_e32 v137, v137
	v_rcp_f32_e32 v138, v138
	v_rcp_f32_e32 v139, v139
	v_cvt_pk_bf16_f32 v132, v132, v133
	v_cvt_pk_bf16_f32 v133, v135, v138
	v_cvt_pk_bf16_f32 v134, v136, v134
	v_cvt_pk_bf16_f32 v135, v137, v139
	global_store_dwordx4 v[128:129], v[132:135], off offset:256 nt
	v_mul_f32_e32 v139, 0xbfb8aa3b, v106
	v_exp_f32_e32 v139, v139
	v_mul_f32_e32 v134, 0xbfb8aa3b, v108
	v_mul_f32_e32 v135, 0xbfb8aa3b, v104
	v_exp_f32_e32 v134, v134
	v_exp_f32_e32 v135, v135
	v_or_b32_e32 v132, 16, v184
	v_ashrrev_i32_e32 v133, 31, v132
	v_lshlrev_b64 v[132:133], 11, v[132:133]
	v_lshl_add_u64 v[136:137], v[130:131], 0, v[132:133]
	v_add_f32_e32 v132, 1.0, v134
	v_add_f32_e32 v133, 1.0, v135
	v_mul_f32_e32 v134, 0xbfb8aa3b, v109
	v_mul_f32_e32 v135, 0xbfb8aa3b, v105
	v_exp_f32_e32 v134, v134
	v_exp_f32_e32 v135, v135
	v_rcp_f32_e32 v138, v133
	v_mul_f32_e32 v140, 0xbfb8aa3b, v111
	v_add_f32_e32 v133, 1.0, v134
	v_add_f32_e32 v134, 1.0, v135
	v_mul_f32_e32 v135, 0xbfb8aa3b, v110
	v_exp_f32_e32 v135, v135
	v_mul_f32_e32 v141, 0xbfb8aa3b, v107
	v_exp_f32_e32 v140, v140
	v_exp_f32_e32 v141, v141
	v_add_f32_e32 v135, 1.0, v135
	v_add_f32_e32 v139, 1.0, v139
	v_rcp_f32_e32 v132, v132
	v_rcp_f32_e32 v133, v133
	v_rcp_f32_e32 v134, v134
	v_rcp_f32_e32 v135, v135
	v_rcp_f32_e32 v139, v139
	v_add_f32_e32 v140, 1.0, v140
	v_add_f32_e32 v141, 1.0, v141
	v_rcp_f32_e32 v140, v140
	v_rcp_f32_e32 v141, v141
	v_cvt_pk_bf16_f32 v132, v132, v133
	v_cvt_pk_bf16_f32 v133, v135, v140
	v_cvt_pk_bf16_f32 v134, v138, v134
	v_cvt_pk_bf16_f32 v135, v139, v141
	v_mul_f32_e32 v139, 0xbfb8aa3b, v96
	v_mul_f32_e32 v138, 0xbfb8aa3b, v100
	v_exp_f32_e32 v139, v139
	global_store_dwordx4 v[136:137], v[132:135], off nt
	v_exp_f32_e32 v138, v138
	v_mul_f32_e32 v140, 0xbfb8aa3b, v103
	v_mul_f32_e32 v134, 0xbfb8aa3b, v101
	v_mul_f32_e32 v135, 0xbfb8aa3b, v97
	v_exp_f32_e32 v134, v134
	v_exp_f32_e32 v135, v135
	v_add_f32_e32 v133, 1.0, v139
	v_add_f32_e32 v132, 1.0, v138
	v_rcp_f32_e32 v138, v133
	v_add_f32_e32 v133, 1.0, v134
	v_add_f32_e32 v134, 1.0, v135
	v_mul_f32_e32 v135, 0xbfb8aa3b, v102
	v_exp_f32_e32 v135, v135
	v_mul_f32_e32 v139, 0xbfb8aa3b, v98
	v_mul_f32_e32 v141, 0xbfb8aa3b, v99
	v_exp_f32_e32 v139, v139
	v_exp_f32_e32 v140, v140
	v_exp_f32_e32 v141, v141
	v_add_f32_e32 v135, 1.0, v135
	v_rcp_f32_e32 v132, v132
	v_rcp_f32_e32 v133, v133
	v_rcp_f32_e32 v134, v134
	v_rcp_f32_e32 v135, v135
	v_add_f32_e32 v139, 1.0, v139
	v_add_f32_e32 v140, 1.0, v140
	v_add_f32_e32 v141, 1.0, v141
	v_rcp_f32_e32 v139, v139
	v_rcp_f32_e32 v140, v140
	v_rcp_f32_e32 v141, v141
	v_cvt_pk_bf16_f32 v132, v132, v133
	v_cvt_pk_bf16_f32 v133, v135, v140
	v_cvt_pk_bf16_f32 v134, v138, v134
	v_cvt_pk_bf16_f32 v135, v139, v141
; __device__ __forceinline__ u32x4 pack8(const f32x4 a, const f32x4 b) { u32x4 w; w.x = cvt_pk_bf16(a[0], a[1]); w.y = cvt_pk_bf16(a[2], a[3]); w.z = cvt_pk_bf16(b[0], b[1]); w.w = cvt_pk_bf16(b[2], b[3]); return w; }
;     __device__ __forceinline__ void operator()(const f32x4 (&acc)[2][2][4][2], const Unit& u, int wr, int wc, int fr, int fq) const {
;     ...
; #pragma unroll
;             for (int ai = 0; ai < 2; ++ai)
; #pragma unroll
;                 for (int m = 0; m < 4; ++m) { const int row = rbase + ai * 128 + m * 16;
; #pragma unroll
;                     for (int bj = 0; bj < 2; ++bj) { f32x4 v0 = acc[ai][bj][m][0], v1 = acc[ai][bj][m][1];
; #pragma unroll
;                         for (int i = 0; i < 4; ++i) { v0[i] = __builtin_amdgcn_rcpf(1.0f + __expf(-v0[i])); v1[i] = __builtin_amdgcn_rcpf(1.0f + __expf(-v1[i])); }
;                         *(u32x4*)(G + (size_t)row * 1024 + cb + bj * 128) = pack8(v0, v1); } }
	global_store_dwordx4 v[136:137], v[132:135], off offset:256 nt
	v_mul_f32_e32 v139, 0xbfb8aa3b, v90
	v_exp_f32_e32 v139, v139
	v_mul_f32_e32 v134, 0xbfb8aa3b, v92
	v_mul_f32_e32 v135, 0xbfb8aa3b, v88
	v_exp_f32_e32 v134, v134
	v_exp_f32_e32 v135, v135
	v_or_b32_e32 v132, 32, v184
	v_ashrrev_i32_e32 v133, 31, v132
	v_lshlrev_b64 v[132:133], 11, v[132:133]
	v_lshl_add_u64 v[136:137], v[130:131], 0, v[132:133]
	v_add_f32_e32 v132, 1.0, v134
	v_add_f32_e32 v133, 1.0, v135
	v_mul_f32_e32 v134, 0xbfb8aa3b, v93
	v_mul_f32_e32 v135, 0xbfb8aa3b, v89
	v_exp_f32_e32 v134, v134
	v_exp_f32_e32 v135, v135
	v_rcp_f32_e32 v138, v133
	v_mul_f32_e32 v140, 0xbfb8aa3b, v95
	v_add_f32_e32 v133, 1.0, v134
	v_add_f32_e32 v134, 1.0, v135
	v_mul_f32_e32 v135, 0xbfb8aa3b, v94
	v_exp_f32_e32 v135, v135
	v_mul_f32_e32 v141, 0xbfb8aa3b, v91
	v_exp_f32_e32 v140, v140
	v_exp_f32_e32 v141, v141
	v_add_f32_e32 v135, 1.0, v135
	v_add_f32_e32 v139, 1.0, v139
	v_rcp_f32_e32 v132, v132
	v_rcp_f32_e32 v133, v133
	v_rcp_f32_e32 v134, v134
	v_rcp_f32_e32 v135, v135
	v_rcp_f32_e32 v139, v139
	v_add_f32_e32 v140, 1.0, v140
	v_add_f32_e32 v141, 1.0, v141
	v_rcp_f32_e32 v140, v140
	v_rcp_f32_e32 v141, v141
	v_cvt_pk_bf16_f32 v132, v132, v133
	v_cvt_pk_bf16_f32 v133, v135, v140
	v_cvt_pk_bf16_f32 v134, v138, v134
	v_cvt_pk_bf16_f32 v135, v139, v141
	v_mul_f32_e32 v139, 0xbfb8aa3b, v80
	v_mul_f32_e32 v138, 0xbfb8aa3b, v84
	v_exp_f32_e32 v139, v139
	global_store_dwordx4 v[136:137], v[132:135], off nt
	v_exp_f32_e32 v138, v138
	v_mul_f32_e32 v140, 0xbfb8aa3b, v87
	v_mul_f32_e32 v134, 0xbfb8aa3b, v85
	v_mul_f32_e32 v135, 0xbfb8aa3b, v81
	v_exp_f32_e32 v134, v134
	v_exp_f32_e32 v135, v135
	v_add_f32_e32 v133, 1.0, v139
	v_add_f32_e32 v132, 1.0, v138
	v_rcp_f32_e32 v138, v133
	v_add_f32_e32 v133, 1.0, v134
	v_add_f32_e32 v134, 1.0, v135
	v_mul_f32_e32 v135, 0xbfb8aa3b, v86
	v_exp_f32_e32 v135, v135
	v_mul_f32_e32 v139, 0xbfb8aa3b, v82
	v_mul_f32_e32 v141, 0xbfb8aa3b, v83
	v_exp_f32_e32 v139, v139
	v_exp_f32_e32 v140, v140
	v_exp_f32_e32 v141, v141
	v_rcp_f32_e32 v132, v132
	v_add_f32_e32 v135, 1.0, v135
	v_rcp_f32_e32 v133, v133
	v_rcp_f32_e32 v134, v134
	v_rcp_f32_e32 v135, v135
	v_add_f32_e32 v139, 1.0, v139
	v_add_f32_e32 v140, 1.0, v140
	v_add_f32_e32 v141, 1.0, v141
	v_cvt_pk_bf16_f32 v132, v132, v133
	v_rcp_f32_e32 v139, v139
	v_rcp_f32_e32 v140, v140
	v_rcp_f32_e32 v141, v141
	v_cvt_pk_bf16_f32 v133, v135, v140
	v_cvt_pk_bf16_f32 v134, v138, v134
	v_cvt_pk_bf16_f32 v135, v139, v141
	global_store_dwordx4 v[136:137], v[132:135], off offset:256 nt
	v_mul_f32_e32 v138, 0xbfb8aa3b, v79
	v_mul_f32_e32 v139, 0xbfb8aa3b, v75
	v_or_b32_e32 v132, 48, v184
	v_ashrrev_i32_e32 v133, 31, v132
	v_mul_f32_e32 v134, 0xbfb8aa3b, v76
	v_lshlrev_b64 v[132:133], 11, v[132:133]
	v_exp_f32_e32 v136, v134
	v_mul_f32_e32 v134, 0xbfb8aa3b, v72
	v_exp_f32_e32 v137, v134
	v_lshl_add_u64 v[134:135], v[130:131], 0, v[132:133]
	v_mul_f32_e32 v132, 0xbfb8aa3b, v77
	v_mul_f32_e32 v133, 0xbfb8aa3b, v73
	v_exp_f32_e32 v132, v132
	v_exp_f32_e32 v133, v133
	v_add_f32_e32 v131, 1.0, v137
	v_add_f32_e32 v130, 1.0, v136
	v_rcp_f32_e32 v136, v131
	v_add_f32_e32 v131, 1.0, v132
	v_add_f32_e32 v132, 1.0, v133
	v_mul_f32_e32 v133, 0xbfb8aa3b, v78
	v_mul_f32_e32 v137, 0xbfb8aa3b, v74
	v_exp_f32_e32 v133, v133
	v_exp_f32_e32 v137, v137
	v_exp_f32_e32 v138, v138
	v_exp_f32_e32 v139, v139
	v_add_f32_e32 v133, 1.0, v133
	v_add_f32_e32 v137, 1.0, v137
	v_rcp_f32_e32 v130, v130
	v_rcp_f32_e32 v131, v131
	v_rcp_f32_e32 v132, v132
	v_rcp_f32_e32 v133, v133
	v_rcp_f32_e32 v137, v137
	v_add_f32_e32 v138, 1.0, v138
	v_add_f32_e32 v139, 1.0, v139
	v_rcp_f32_e32 v138, v138
	v_rcp_f32_e32 v139, v139
	v_cvt_pk_bf16_f32 v130, v130, v131
	v_cvt_pk_bf16_f32 v131, v133, v138
	v_cvt_pk_bf16_f32 v132, v136, v132
	v_cvt_pk_bf16_f32 v133, v137, v139
	v_mul_f32_e32 v137, 0xbfb8aa3b, v64
	v_mul_f32_e32 v136, 0xbfb8aa3b, v68
	v_exp_f32_e32 v137, v137
	global_store_dwordx4 v[134:135], v[130:133], off nt
	v_exp_f32_e32 v136, v136
	v_mul_f32_e32 v138, 0xbfb8aa3b, v71
	v_mul_f32_e32 v132, 0xbfb8aa3b, v69
	v_mul_f32_e32 v133, 0xbfb8aa3b, v65
	v_exp_f32_e32 v132, v132
	v_exp_f32_e32 v133, v133
	v_add_f32_e32 v131, 1.0, v137
	v_add_f32_e32 v130, 1.0, v136
	v_rcp_f32_e32 v136, v131
	v_add_f32_e32 v131, 1.0, v132
	v_add_f32_e32 v132, 1.0, v133
	v_mul_f32_e32 v133, 0xbfb8aa3b, v70
	v_exp_f32_e32 v133, v133
	v_mul_f32_e32 v137, 0xbfb8aa3b, v66
	v_exp_f32_e32 v138, v138
	v_mul_f32_e32 v139, 0xbfb8aa3b, v67
	v_exp_f32_e32 v137, v137
	v_exp_f32_e32 v139, v139
	v_rcp_f32_e32 v130, v130
	v_rcp_f32_e32 v131, v131
	v_add_f32_e32 v133, 1.0, v133
	v_add_f32_e32 v138, 1.0, v138
	v_rcp_f32_e32 v132, v132
	v_rcp_f32_e32 v133, v133
	v_add_f32_e32 v137, 1.0, v137
	v_rcp_f32_e32 v138, v138
	v_add_f32_e32 v139, 1.0, v139
	v_cvt_pk_bf16_f32 v130, v130, v131
	v_cvt_pk_bf16_f32 v131, v133, v138
	v_rcp_f32_e32 v137, v137
	v_rcp_f32_e32 v139, v139
	v_cvt_pk_bf16_f32 v132, v136, v132
	v_cvt_pk_bf16_f32 v133, v137, v139
	global_store_dwordx4 v[134:135], v[130:133], off offset:256 nt
	v_mul_f32_e32 v137, 0xbfb8aa3b, v58
	v_mul_f32_e32 v138, 0xbfb8aa3b, v63
	v_mul_f32_e32 v131, 0xbfb8aa3b, v56
	v_exp_f32_e32 v131, v131
	v_mul_f32_e32 v132, 0xbfb8aa3b, v61
	v_mul_f32_e32 v133, 0xbfb8aa3b, v57
	v_exp_f32_e32 v132, v132
	v_exp_f32_e32 v133, v133
	v_mul_f32_e32 v130, 0xbfb8aa3b, v60
	v_add_f32_e32 v131, 1.0, v131
	v_exp_f32_e32 v130, v130
	v_rcp_f32_e32 v136, v131
	v_add_f32_e32 v131, 1.0, v132
	v_add_f32_e32 v132, 1.0, v133
	v_mul_f32_e32 v133, 0xbfb8aa3b, v62
	v_mul_f32_e32 v139, 0xbfb8aa3b, v59
	v_exp_f32_e32 v133, v133
	v_exp_f32_e32 v137, v137
	v_exp_f32_e32 v138, v138
; __device__ __forceinline__ u32x4 pack8(const f32x4 a, const f32x4 b) { u32x4 w; w.x = cvt_pk_bf16(a[0], a[1]); w.y = cvt_pk_bf16(a[2], a[3]); w.z = cvt_pk_bf16(b[0], b[1]); w.w = cvt_pk_bf16(b[2], b[3]); return w; }
;     __device__ __forceinline__ void operator()(const f32x4 (&acc)[2][2][4][2], const Unit& u, int wr, int wc, int fr, int fq) const {
;     ...
; #pragma unroll
;             for (int ai = 0; ai < 2; ++ai)
; #pragma unroll
;                 for (int m = 0; m < 4; ++m) { const int row = rbase + ai * 128 + m * 16;
; #pragma unroll
;                     for (int bj = 0; bj < 2; ++bj) { f32x4 v0 = acc[ai][bj][m][0], v1 = acc[ai][bj][m][1];
; #pragma unroll
;                         for (int i = 0; i < 4; ++i) { v0[i] = __builtin_amdgcn_rcpf(1.0f + __expf(-v0[i])); v1[i] = __builtin_amdgcn_rcpf(1.0f + __expf(-v1[i])); }
;                         *(u32x4*)(G + (size_t)row * 1024 + cb + bj * 128) = pack8(v0, v1); } }
	v_exp_f32_e32 v139, v139
	s_mov_b64 s[0:1], 0x40000
	v_add_f32_e32 v130, 1.0, v130
	v_lshl_add_u64 v[134:135], v[128:129], 0, s[0:1]
	v_rcp_f32_e32 v130, v130
	v_rcp_f32_e32 v131, v131
	v_rcp_f32_e32 v132, v132
	v_add_f32_e32 v133, 1.0, v133
	v_add_f32_e32 v137, 1.0, v137
	v_add_f32_e32 v138, 1.0, v138
	v_add_f32_e32 v139, 1.0, v139
	s_mov_b32 s0, 0x40000
	v_rcp_f32_e32 v133, v133
	v_rcp_f32_e32 v137, v137
	v_rcp_f32_e32 v138, v138
	v_rcp_f32_e32 v139, v139
	v_cvt_pk_bf16_f32 v130, v130, v131
	v_cvt_pk_bf16_f32 v131, v133, v138
	v_cvt_pk_bf16_f32 v132, v136, v132
	v_add_co_u32_e32 v136, vcc, s0, v128
	v_cvt_pk_bf16_f32 v133, v137, v139
	v_mul_f32_e32 v139, 0xbfb8aa3b, v48
	s_nop 0
	v_addc_co_u32_e32 v137, vcc, 0, v129, vcc
	v_mul_f32_e32 v138, 0xbfb8aa3b, v52
	v_exp_f32_e32 v139, v139
	global_store_dwordx4 v[136:137], v[130:133], off nt
	v_exp_f32_e32 v138, v138
	v_mul_f32_e32 v137, 0xbfb8aa3b, v50
	v_mul_f32_e32 v132, 0xbfb8aa3b, v53
	v_mul_f32_e32 v133, 0xbfb8aa3b, v49
	v_exp_f32_e32 v132, v132
	v_exp_f32_e32 v133, v133
	v_add_f32_e32 v131, 1.0, v139
	v_add_f32_e32 v130, 1.0, v138
	v_rcp_f32_e32 v136, v131
	v_add_f32_e32 v131, 1.0, v132
	v_add_f32_e32 v132, 1.0, v133
	v_mul_f32_e32 v133, 0xbfb8aa3b, v54
	v_mul_f32_e32 v138, 0xbfb8aa3b, v55
	v_exp_f32_e32 v133, v133
	v_exp_f32_e32 v138, v138
	v_mul_f32_e32 v139, 0xbfb8aa3b, v51
	v_exp_f32_e32 v137, v137
	v_exp_f32_e32 v139, v139
	v_rcp_f32_e32 v130, v130
	v_rcp_f32_e32 v131, v131
	v_add_f32_e32 v133, 1.0, v133
	v_add_f32_e32 v138, 1.0, v138
	v_rcp_f32_e32 v132, v132
	v_rcp_f32_e32 v133, v133
	v_add_f32_e32 v137, 1.0, v137
	v_rcp_f32_e32 v138, v138
	v_add_f32_e32 v139, 1.0, v139
	v_cvt_pk_bf16_f32 v130, v130, v131
	v_cvt_pk_bf16_f32 v131, v133, v138
	v_rcp_f32_e32 v137, v137
	v_rcp_f32_e32 v139, v139
	v_cvt_pk_bf16_f32 v132, v136, v132
	v_cvt_pk_bf16_f32 v133, v137, v139
	global_store_dwordx4 v[134:135], v[130:133], off offset:256 nt
	v_mul_f32_e32 v137, 0xbfb8aa3b, v42
	v_mul_f32_e32 v138, 0xbfb8aa3b, v47
	v_mul_f32_e32 v131, 0xbfb8aa3b, v40
	v_exp_f32_e32 v131, v131
	v_mul_f32_e32 v132, 0xbfb8aa3b, v45
	v_mul_f32_e32 v133, 0xbfb8aa3b, v41
	v_exp_f32_e32 v132, v132
	v_exp_f32_e32 v133, v133
	v_mul_f32_e32 v130, 0xbfb8aa3b, v44
	v_add_f32_e32 v131, 1.0, v131
	v_exp_f32_e32 v130, v130
	v_rcp_f32_e32 v136, v131
	v_add_f32_e32 v131, 1.0, v132
	v_add_f32_e32 v132, 1.0, v133
	v_mul_f32_e32 v133, 0xbfb8aa3b, v46
	v_mul_f32_e32 v139, 0xbfb8aa3b, v43
	v_exp_f32_e32 v133, v133
	v_exp_f32_e32 v137, v137
	v_exp_f32_e32 v138, v138
	v_exp_f32_e32 v139, v139
	s_mov_b64 s[0:1], 0x48000
	v_add_f32_e32 v130, 1.0, v130
	v_lshl_add_u64 v[134:135], v[128:129], 0, s[0:1]
	v_rcp_f32_e32 v130, v130
	v_rcp_f32_e32 v131, v131
	v_rcp_f32_e32 v132, v132
	v_add_f32_e32 v133, 1.0, v133
	v_add_f32_e32 v137, 1.0, v137
	v_add_f32_e32 v138, 1.0, v138
	v_add_f32_e32 v139, 1.0, v139
	s_mov_b32 s0, 0x48000
	v_rcp_f32_e32 v133, v133
	v_rcp_f32_e32 v137, v137
	v_rcp_f32_e32 v138, v138
	v_rcp_f32_e32 v139, v139
	v_cvt_pk_bf16_f32 v130, v130, v131
	v_cvt_pk_bf16_f32 v131, v133, v138
	v_cvt_pk_bf16_f32 v132, v136, v132
	v_add_co_u32_e32 v136, vcc, s0, v128
	v_cvt_pk_bf16_f32 v133, v137, v139
	v_mul_f32_e32 v139, 0xbfb8aa3b, v32
	s_nop 0
	v_addc_co_u32_e32 v137, vcc, 0, v129, vcc
	v_mul_f32_e32 v138, 0xbfb8aa3b, v36
	v_exp_f32_e32 v139, v139
	global_store_dwordx4 v[136:137], v[130:133], off nt
	v_exp_f32_e32 v138, v138
	v_mul_f32_e32 v137, 0xbfb8aa3b, v34
	v_mul_f32_e32 v132, 0xbfb8aa3b, v37
	v_mul_f32_e32 v133, 0xbfb8aa3b, v33
	v_exp_f32_e32 v132, v132
	v_exp_f32_e32 v133, v133
	v_add_f32_e32 v131, 1.0, v139
	v_add_f32_e32 v130, 1.0, v138
	v_rcp_f32_e32 v136, v131
	v_add_f32_e32 v131, 1.0, v132
	v_add_f32_e32 v132, 1.0, v133
	v_mul_f32_e32 v133, 0xbfb8aa3b, v38
	v_mul_f32_e32 v138, 0xbfb8aa3b, v39
	v_exp_f32_e32 v133, v133
	v_exp_f32_e32 v138, v138
	v_mul_f32_e32 v139, 0xbfb8aa3b, v35
	v_exp_f32_e32 v137, v137
	v_exp_f32_e32 v139, v139
	v_rcp_f32_e32 v130, v130
	v_rcp_f32_e32 v131, v131
	v_add_f32_e32 v133, 1.0, v133
	v_add_f32_e32 v138, 1.0, v138
	v_rcp_f32_e32 v132, v132
	v_rcp_f32_e32 v133, v133
	v_add_f32_e32 v137, 1.0, v137
	v_rcp_f32_e32 v138, v138
	v_add_f32_e32 v139, 1.0, v139
	v_cvt_pk_bf16_f32 v130, v130, v131
	v_cvt_pk_bf16_f32 v131, v133, v138
	v_rcp_f32_e32 v137, v137
	v_rcp_f32_e32 v139, v139
	v_cvt_pk_bf16_f32 v132, v136, v132
	v_cvt_pk_bf16_f32 v133, v137, v139
	global_store_dwordx4 v[134:135], v[130:133], off offset:256 nt
	v_mul_f32_e32 v137, 0xbfb8aa3b, v26
	v_mul_f32_e32 v138, 0xbfb8aa3b, v31
	v_mul_f32_e32 v131, 0xbfb8aa3b, v24
	v_exp_f32_e32 v131, v131
	v_mul_f32_e32 v132, 0xbfb8aa3b, v29
	v_mul_f32_e32 v133, 0xbfb8aa3b, v25
	v_exp_f32_e32 v132, v132
	v_exp_f32_e32 v133, v133
	v_mul_f32_e32 v130, 0xbfb8aa3b, v28
	v_add_f32_e32 v131, 1.0, v131
	v_exp_f32_e32 v130, v130
	v_rcp_f32_e32 v136, v131
	v_add_f32_e32 v131, 1.0, v132
	v_add_f32_e32 v132, 1.0, v133
	v_mul_f32_e32 v133, 0xbfb8aa3b, v30
	v_mul_f32_e32 v139, 0xbfb8aa3b, v27
	v_exp_f32_e32 v133, v133
	v_exp_f32_e32 v137, v137
	v_exp_f32_e32 v138, v138
	v_exp_f32_e32 v139, v139
	s_mov_b64 s[0:1], 0x50000
	v_add_f32_e32 v130, 1.0, v130
	v_lshl_add_u64 v[134:135], v[128:129], 0, s[0:1]
	v_rcp_f32_e32 v130, v130
	v_rcp_f32_e32 v131, v131
	v_rcp_f32_e32 v132, v132
	v_add_f32_e32 v133, 1.0, v133
	v_add_f32_e32 v137, 1.0, v137
	v_add_f32_e32 v138, 1.0, v138
	v_add_f32_e32 v139, 1.0, v139
	s_mov_b32 s0, 0x50000
	v_rcp_f32_e32 v133, v133
	v_rcp_f32_e32 v137, v137
	v_rcp_f32_e32 v138, v138
	v_rcp_f32_e32 v139, v139
	v_cvt_pk_bf16_f32 v130, v130, v131
	v_cvt_pk_bf16_f32 v131, v133, v138
	v_cvt_pk_bf16_f32 v132, v136, v132
	v_add_co_u32_e32 v136, vcc, s0, v128
; __device__ __forceinline__ u32x4 pack8(const f32x4 a, const f32x4 b) { u32x4 w; w.x = cvt_pk_bf16(a[0], a[1]); w.y = cvt_pk_bf16(a[2], a[3]); w.z = cvt_pk_bf16(b[0], b[1]); w.w = cvt_pk_bf16(b[2], b[3]); return w; }
;     __device__ __forceinline__ void operator()(const f32x4 (&acc)[2][2][4][2], const Unit& u, int wr, int wc, int fr, int fq) const {
;     ...
;         } else if (pn < 11) {
;             const int g = pn - 8; const int sh = 2 * g, dil = 1 << sh, L = 2048 >> sh, keep = 128 << sh;
;             const size_t okp = g == 0 ? O_KVP0 : (g == 1 ? O_KVP1 : O_KVP2), oks = g == 0 ? O_KVS0 : (g == 1 ? O_KVS1 : O_KVS2);
; #pragma unroll
;             for (int ai = 0; ai < 2; ++ai)
; #pragma unroll
;                 for (int m = 0; m < 4; ++m) { const int row = rbase + ai * 128 + m * 16;
;                     int b, t;
;                     if (!sample) { b = row >> 11; t = row & 2047; } else { const int sr = row - MP; b = sr >> 3; t = sr & 7; }
; #pragma unroll
;                     for (int bj = 0; bj < 2; ++bj) { const int hc = bj * 128 + wc * 32 + fq * 8; const f32x4 v0 = acc[ai][bj][m][0], v1 = acc[ai][bj][m][1];
;                         if (!sample) {
;                             *(u32x4*)(VT + (size_t)g * MP * 256 + (size_t)b * 524288 + (t & (dil - 1)) * (L * 256) + (hc >> 6) * (L * 64) + (t >> sh) * 64 + (hc & 63)) = pack8(v0, v1);
;                             if (t >= 2048 - keep) { float* p = out + okp + ((size_t)(b * keep + t - (2048 - keep)) * 2 + 1) * 256 + hc; *(f32x4*)p = v0; *(f32x4*)(p + 4) = v1; } }
;                         else { float* p = out + oks + ((size_t)(b * keep + keep - 8 + t) * 2 + 1) * 256 + hc; *(f32x4*)p = v0; *(f32x4*)(p + 4) = v1; } } }
;     ...
; #pragma unroll
;             for (int ai = 0; ai < 2; ++ai)
; #pragma unroll
;                 for (int m = 0; m < 4; ++m) { const int row = rbase + ai * 128 + m * 16;
; #pragma unroll
;                     for (int bj = 0; bj < 2; ++bj) { f32x4 v0 = acc[ai][bj][m][0], v1 = acc[ai][bj][m][1];
; #pragma unroll
;                         for (int i = 0; i < 4; ++i) { v0[i] = __builtin_amdgcn_rcpf(1.0f + __expf(-v0[i])); v1[i] = __builtin_amdgcn_rcpf(1.0f + __expf(-v1[i])); }
;                         *(u32x4*)(G + (size_t)row * 1024 + cb + bj * 128) = pack8(v0, v1); } }
	v_cvt_pk_bf16_f32 v133, v137, v139
	v_mul_f32_e32 v139, 0xbfb8aa3b, v16
	s_nop 0
	v_addc_co_u32_e32 v137, vcc, 0, v129, vcc
	v_mul_f32_e32 v138, 0xbfb8aa3b, v20
	v_exp_f32_e32 v139, v139
	global_store_dwordx4 v[136:137], v[130:133], off nt
	v_exp_f32_e32 v138, v138
	v_mul_f32_e32 v137, 0xbfb8aa3b, v18
	v_mul_f32_e32 v132, 0xbfb8aa3b, v21
	v_mul_f32_e32 v133, 0xbfb8aa3b, v17
	v_exp_f32_e32 v132, v132
	v_exp_f32_e32 v133, v133
	v_add_f32_e32 v131, 1.0, v139
	v_add_f32_e32 v130, 1.0, v138
	v_rcp_f32_e32 v136, v131
	v_add_f32_e32 v131, 1.0, v132
	v_add_f32_e32 v132, 1.0, v133
	v_mul_f32_e32 v133, 0xbfb8aa3b, v22
	v_mul_f32_e32 v138, 0xbfb8aa3b, v23
	v_exp_f32_e32 v133, v133
	v_exp_f32_e32 v138, v138
	v_mul_f32_e32 v139, 0xbfb8aa3b, v19
	v_exp_f32_e32 v137, v137
	v_exp_f32_e32 v139, v139
	v_rcp_f32_e32 v130, v130
	v_rcp_f32_e32 v131, v131
	v_add_f32_e32 v133, 1.0, v133
	v_add_f32_e32 v138, 1.0, v138
	v_rcp_f32_e32 v132, v132
	v_rcp_f32_e32 v133, v133
	v_add_f32_e32 v137, 1.0, v137
	v_rcp_f32_e32 v138, v138
	v_add_f32_e32 v139, 1.0, v139
	v_cvt_pk_bf16_f32 v130, v130, v131
	v_cvt_pk_bf16_f32 v131, v133, v138
	v_rcp_f32_e32 v137, v137
	v_rcp_f32_e32 v139, v139
	v_cvt_pk_bf16_f32 v132, v136, v132
	v_cvt_pk_bf16_f32 v133, v137, v139
	global_store_dwordx4 v[134:135], v[130:133], off offset:256 nt
	v_mul_f32_e32 v137, 0xbfb8aa3b, v10
	v_exp_f32_e32 v137, v137
	v_mul_f32_e32 v131, 0xbfb8aa3b, v8
	v_exp_f32_e32 v131, v131
	v_mul_f32_e32 v132, 0xbfb8aa3b, v13
	v_mul_f32_e32 v133, 0xbfb8aa3b, v9
	v_exp_f32_e32 v132, v132
	v_exp_f32_e32 v133, v133
	v_add_f32_e32 v131, 1.0, v131
	v_mul_f32_e32 v130, 0xbfb8aa3b, v12
	v_rcp_f32_e32 v136, v131
	v_add_f32_e32 v131, 1.0, v132
	v_add_f32_e32 v132, 1.0, v133
	v_mul_f32_e32 v133, 0xbfb8aa3b, v14
	v_exp_f32_e32 v130, v130
	v_exp_f32_e32 v133, v133
	v_mul_f32_e32 v138, 0xbfb8aa3b, v15
	v_mul_f32_e32 v139, 0xbfb8aa3b, v11
	v_exp_f32_e32 v138, v138
	v_exp_f32_e32 v139, v139
	s_mov_b64 s[0:1], 0x58000
	v_lshl_add_u64 v[134:135], v[128:129], 0, s[0:1]
	v_add_f32_e32 v130, 1.0, v130
	v_add_f32_e32 v133, 1.0, v133
	v_add_f32_e32 v137, 1.0, v137
	s_mov_b32 s0, 0x58000
	v_rcp_f32_e32 v130, v130
	v_rcp_f32_e32 v131, v131
	v_rcp_f32_e32 v132, v132
	v_rcp_f32_e32 v133, v133
	v_rcp_f32_e32 v137, v137
	v_add_f32_e32 v138, 1.0, v138
	v_add_f32_e32 v139, 1.0, v139
	v_add_co_u32_e32 v128, vcc, s0, v128
	v_rcp_f32_e32 v138, v138
	v_rcp_f32_e32 v139, v139
	v_cvt_pk_bf16_f32 v130, v130, v131
	v_cvt_pk_bf16_f32 v131, v133, v138
	v_cvt_pk_bf16_f32 v132, v136, v132
	v_cvt_pk_bf16_f32 v133, v137, v139
	v_addc_co_u32_e32 v129, vcc, 0, v129, vcc
	v_mul_f32_e32 v137, 0xbfb8aa3b, v0
	v_exp_f32_e32 v137, v137
	global_store_dwordx4 v[128:129], v[130:133], off nt
	v_mul_f32_e32 v136, 0xbfb8aa3b, v4
	v_exp_f32_e32 v136, v136
	v_mul_f32_e32 v130, 0xbfb8aa3b, v5
	v_mul_f32_e32 v131, 0xbfb8aa3b, v1
	v_exp_f32_e32 v130, v130
	v_exp_f32_e32 v131, v131
	v_add_f32_e32 v129, 1.0, v137
	v_rcp_f32_e32 v132, v129
	v_add_f32_e32 v129, 1.0, v130
	v_add_f32_e32 v130, 1.0, v131
	v_mul_f32_e32 v131, 0xbfb8aa3b, v6
	v_add_f32_e32 v128, 1.0, v136
	v_exp_f32_e32 v131, v131
	v_mul_f32_e32 v133, 0xbfb8aa3b, v2
	v_mul_f32_e32 v136, 0xbfb8aa3b, v7
	v_mul_f32_e32 v137, 0xbfb8aa3b, v3
	v_exp_f32_e32 v133, v133
	v_exp_f32_e32 v136, v136
	v_exp_f32_e32 v137, v137
	v_add_f32_e32 v131, 1.0, v131
	v_rcp_f32_e32 v128, v128
	v_rcp_f32_e32 v129, v129
	v_rcp_f32_e32 v130, v130
	v_rcp_f32_e32 v131, v131
	v_add_f32_e32 v133, 1.0, v133
	v_add_f32_e32 v136, 1.0, v136
	v_add_f32_e32 v137, 1.0, v137
	v_rcp_f32_e32 v133, v133
	v_rcp_f32_e32 v136, v136
	v_rcp_f32_e32 v137, v137
	v_cvt_pk_bf16_f32 v128, v128, v129
	v_cvt_pk_bf16_f32 v129, v131, v136
	v_cvt_pk_bf16_f32 v130, v132, v130
	v_cvt_pk_bf16_f32 v131, v133, v137
	global_store_dwordx4 v[134:135], v[128:131], off offset:256 nt
	s_mov_b64 s[0:1], 0
.LBB0_128:
	s_andn2_b64 vcc, exec, s[0:1]
	s_cbranch_vccnz .LBB0_194
	s_add_i32 s16, s36, -8
	s_lshl_b32 s29, s16, 1
	s_lshr_b32 s0, 0x800, s29
	s_lshl_b32 s43, 0x80, s29
	s_cmp_eq_u32 s16, 1
	s_mov_b32 s1, 0x433c000
	s_mov_b32 s4, 0x742c000
	s_cselect_b32 s1, s1, 0x4b3c000
	s_cselect_b32 s4, s4, 0x942c000
	s_cmp_eq_u32 s16, 0
	s_cselect_b32 s6, 0x413c000, s1
	s_cselect_b32 s42, 0x6c2c000, s4
	s_ashr_i32 s46, s27, 11
	v_add_u32_e32 v128, 0xffff0000, v184
	v_ashrrev_i32_e32 v128, 3, v128
	v_mov_b32_e32 v129, s46
	v_and_b32_e32 v136, 0x7cf, v184
	v_cndmask_b32_e64 v128, v129, v128, s[38:39]
	s_lshl_b32 s94, -1, s29
	v_cndmask_b32_e64 v132, v136, v171, s[38:39]
	v_ashrrev_i32_e32 v129, 31, v128
	s_lshl_b32 s25, s0, 8
	s_sub_i32 s92, 0x800, s43
	s_add_i32 s93, s29, 7
	v_lshlrev_b64 v[130:131], 20, v[128:129]
	v_bitop3_b32 v129, v132, s94, v132 bitop3:0x30
	s_lshl_b32 s7, s0, 6
	s_add_i32 s24, s43, 0xfffff800
	s_add_i32 s43, s43, -8
	v_mul_u32_u24_e32 v138, s25, v129
	v_lshrrev_b32_e32 v129, s29, v132
	v_cmp_le_u32_e64 s[0:1], s92, v132
	v_lshl_add_u32 v132, v128, s93, v132
	v_add_u32_e32 v128, s24, v132
	v_add_u32_e32 v132, s43, v132
	v_ashrrev_i32_e32 v133, 31, v132
	v_lshlrev_b32_e32 v137, 6, v129
	v_ashrrev_i32_e32 v129, 31, v128
	v_lshlrev_b64 v[132:133], 11, v[132:133]
	v_cndmask_b32_e64 v134, 0, 1, s[8:9]
	s_mov_b64 s[10:11], s[38:39]
	s_lshl_b64 s[40:41], s[16:17], 25
	v_lshlrev_b64 v[128:129], 11, v[128:129]
	v_cmp_ne_u32_e64 s[4:5], 1, v134
	s_andn2_b64 vcc, exec, s[8:9]
	s_mov_b64 s[70:71], s[38:39]
	v_mov_b64_e32 v[134:135], v[132:133]
	s_mov_b64 s[72:73], s[42:43]
	s_cbranch_vccnz .LBB0_131
	v_readlane_b32 s16, v254, 14
	s_add_u32 s68, s16, s40
	v_readlane_b32 s16, v254, 16
	s_addc_u32 s69, s16, s41
	v_readlane_b32 s16, v254, 18
	v_lshl_add_u64 v[134:135], s[68:69], 0, v[130:131]
	v_lshlrev_b32_e32 v164, 1, v138
	s_mul_i32 s16, s7, s16
	v_lshl_add_u64 v[134:135], v[134:135], 0, v[164:165]
	s_lshl_b32 s16, s16, 1
	v_lshl_add_u64 v[134:135], v[134:135], 0, s[16:17]
	v_lshlrev_b32_e32 v164, 1, v137
	v_lshl_add_u64 v[134:135], v[134:135], 0, v[164:165]
	v_lshlrev_b32_e32 v164, 1, v170
	v_lshl_add_u64 v[134:135], v[134:135], 0, v[164:165]
	s_andn2_b64 s[68:69], s[38:39], exec
	s_and_b64 s[70:71], s[0:1], exec
	v_cvt_pk_bf16_f32 v140, v124, v125
	v_cvt_pk_bf16_f32 v141, v126, v127
	v_cvt_pk_bf16_f32 v142, v120, v121
	v_cvt_pk_bf16_f32 v143, v122, v123
	global_store_dwordx4 v[134:135], v[140:143], off nt
	s_or_b64 s[70:71], s[68:69], s[70:71]
	v_mov_b64_e32 v[134:135], v[128:129]
	s_mov_b64 s[72:73], s[6:7]
; __device__ __forceinline__ u32x4 pack8(const f32x4 a, const f32x4 b) { u32x4 w; w.x = cvt_pk_bf16(a[0], a[1]); w.y = cvt_pk_bf16(a[2], a[3]); w.z = cvt_pk_bf16(b[0], b[1]); w.w = cvt_pk_bf16(b[2], b[3]); return w; }
;     __device__ __forceinline__ void operator()(const f32x4 (&acc)[2][2][4][2], const Unit& u, int wr, int wc, int fr, int fq) const {
;     ...
; #pragma unroll
;             for (int ai = 0; ai < 2; ++ai)
; #pragma unroll
;                 for (int m = 0; m < 4; ++m) { const int row = rbase + ai * 128 + m * 16;
;                     int b, t;
;                     if (!sample) { b = row >> 11; t = row & 2047; } else { const int sr = row - MP; b = sr >> 3; t = sr & 7; }
; #pragma unroll
;                     for (int bj = 0; bj < 2; ++bj) { const int hc = bj * 128 + wc * 32 + fq * 8; const f32x4 v0 = acc[ai][bj][m][0], v1 = acc[ai][bj][m][1];
;                         if (!sample) {
;                             *(u32x4*)(VT + (size_t)g * MP * 256 + (size_t)b * 524288 + (t & (dil - 1)) * (L * 256) + (hc >> 6) * (L * 64) + (t >> sh) * 64 + (hc & 63)) = pack8(v0, v1);
;                             if (t >= 2048 - keep) { float* p = out + okp + ((size_t)(b * keep + t - (2048 - keep)) * 2 + 1) * 256 + hc; *(f32x4*)p = v0; *(f32x4*)(p + 4) = v1; } }
;                         else { float* p = out + oks + ((size_t)(b * keep + keep - 8 + t) * 2 + 1) * 256 + hc; *(f32x4*)p = v0; *(f32x4*)(p + 4) = v1; } } }
.LBB0_131:
	s_and_saveexec_b64 s[68:69], s[70:71]
	s_cbranch_execz .LBB0_133
	s_lshl_b32 s16, s72, 2
	s_add_u32 s70, s84, s16
	s_addc_u32 s71, s85, 0
	v_lshl_add_u64 v[134:135], s[70:71], 0, v[134:135]
	v_lshlrev_b32_e32 v164, 2, v168
	v_lshl_add_u64 v[134:135], v[134:135], 0, v[164:165]
	global_store_dwordx4 v[134:135], v[124:127], off offset:1024 nt
	global_store_dwordx4 v[134:135], v[120:123], off offset:1040 nt
.LBB0_133:
	s_or_b64 exec, exec, s[68:69]
	s_and_b64 vcc, exec, s[4:5]
	s_mov_b64 s[68:69], s[10:11]
	s_mov_b64 s[70:71], s[42:43]
	s_cbranch_vccnz .LBB0_135
	v_readlane_b32 s16, v254, 14
	s_add_u32 s68, s16, s40
	v_readlane_b32 s16, v254, 16
	s_addc_u32 s69, s16, s41
	v_readlane_b32 s16, v254, 20
	v_lshl_add_u64 v[130:131], s[68:69], 0, v[130:131]
	v_lshlrev_b32_e32 v164, 1, v138
	s_mul_i32 s16, s7, s16
	v_lshl_add_u64 v[130:131], v[130:131], 0, v[164:165]
	s_lshl_b32 s16, s16, 1
	v_lshl_add_u64 v[130:131], v[130:131], 0, s[16:17]
	v_lshlrev_b32_e32 v164, 1, v137
	v_lshl_add_u64 v[130:131], v[130:131], 0, v[164:165]
	v_lshlrev_b32_e32 v164, 1, v170
	v_cvt_pk_bf16_f32 v132, v116, v117
	v_cvt_pk_bf16_f32 v133, v118, v119
	v_lshl_add_u64 v[130:131], v[130:131], 0, v[164:165]
	s_andn2_b64 s[68:69], s[38:39], exec
	s_and_b64 s[0:1], s[0:1], exec
	v_cvt_pk_bf16_f32 v134, v112, v113
	v_cvt_pk_bf16_f32 v135, v114, v115
	global_store_dwordx4 v[130:131], v[132:135], off nt
	s_or_b64 s[68:69], s[68:69], s[0:1]
	s_mov_b64 s[70:71], s[6:7]
	v_mov_b64_e32 v[132:133], v[128:129]
.LBB0_135:
	s_and_saveexec_b64 s[0:1], s[68:69]
	s_cbranch_execz .LBB0_137
	s_lshl_b32 s16, s70, 2
	s_add_u32 s68, s84, s16
	s_addc_u32 s69, s85, 0
	v_lshl_add_u64 v[128:129], s[68:69], 0, v[132:133]
	v_lshlrev_b32_e32 v164, 2, v168
	v_lshl_add_u64 v[128:129], v[128:129], 0, v[164:165]
	global_store_dwordx4 v[128:129], v[116:119], off offset:1536 nt
	global_store_dwordx4 v[128:129], v[112:115], off offset:1552 nt
.LBB0_137:
	s_or_b64 exec, exec, s[0:1]
	v_add_u32_e32 v128, 0xffff0010, v184
	v_ashrrev_i32_e32 v128, 3, v128
	v_mov_b32_e32 v130, s46
	v_or_b32_e32 v129, 16, v136
	v_cndmask_b32_e64 v128, v130, v128, s[38:39]
	s_not_b32 s94, s94
	v_cndmask_b32_e64 v132, v129, v171, s[38:39]
	v_ashrrev_i32_e32 v129, 31, v128
	v_lshlrev_b64 v[130:131], 20, v[128:129]
	v_and_b32_e32 v129, s94, v132
	v_mul_u32_u24_e32 v138, s25, v129
	v_lshrrev_b32_e32 v129, s29, v132
	v_cmp_le_u32_e64 s[0:1], s92, v132
	v_lshl_add_u32 v132, v128, s93, v132
	v_add_u32_e32 v128, s24, v132
	v_add_u32_e32 v132, s43, v132
	v_ashrrev_i32_e32 v133, 31, v132
	v_lshlrev_b32_e32 v137, 6, v129
	v_ashrrev_i32_e32 v129, 31, v128
	v_lshlrev_b64 v[132:133], 11, v[132:133]
	v_lshlrev_b64 v[128:129], 11, v[128:129]
	s_and_b64 vcc, exec, s[4:5]
	s_mov_b64 s[70:71], s[10:11]
	v_mov_b64_e32 v[134:135], v[132:133]
	s_mov_b64 s[72:73], s[42:43]
	s_cbranch_vccnz .LBB0_139
	v_readlane_b32 s16, v254, 14
	s_add_u32 s68, s16, s40
	v_readlane_b32 s16, v254, 16
	s_addc_u32 s69, s16, s41
	v_readlane_b32 s16, v254, 18
	v_lshl_add_u64 v[134:135], s[68:69], 0, v[130:131]
	v_lshlrev_b32_e32 v164, 1, v138
	s_mul_i32 s16, s7, s16
	v_lshl_add_u64 v[134:135], v[134:135], 0, v[164:165]
	s_lshl_b32 s16, s16, 1
	v_lshl_add_u64 v[134:135], v[134:135], 0, s[16:17]
	v_lshlrev_b32_e32 v164, 1, v137
	v_lshl_add_u64 v[134:135], v[134:135], 0, v[164:165]
	v_lshlrev_b32_e32 v164, 1, v170
	v_lshl_add_u64 v[134:135], v[134:135], 0, v[164:165]
	s_andn2_b64 s[68:69], s[38:39], exec
	s_and_b64 s[70:71], s[0:1], exec
	v_cvt_pk_bf16_f32 v140, v108, v109
	v_cvt_pk_bf16_f32 v141, v110, v111
	v_cvt_pk_bf16_f32 v142, v104, v105
	v_cvt_pk_bf16_f32 v143, v106, v107
	global_store_dwordx4 v[134:135], v[140:143], off nt
	s_or_b64 s[70:71], s[68:69], s[70:71]
	v_mov_b64_e32 v[134:135], v[128:129]
	s_mov_b64 s[72:73], s[6:7]
.LBB0_139:
	s_and_saveexec_b64 s[68:69], s[70:71]
	s_cbranch_execz .LBB0_141
	s_lshl_b32 s16, s72, 2
	s_add_u32 s70, s84, s16
	s_addc_u32 s71, s85, 0
	v_lshl_add_u64 v[134:135], s[70:71], 0, v[134:135]
	v_lshlrev_b32_e32 v164, 2, v168
	v_lshl_add_u64 v[134:135], v[134:135], 0, v[164:165]
	global_store_dwordx4 v[134:135], v[108:111], off offset:1024 nt
	global_store_dwordx4 v[134:135], v[104:107], off offset:1040 nt
.LBB0_141:
	s_or_b64 exec, exec, s[68:69]
	s_and_b64 vcc, exec, s[4:5]
	s_mov_b64 s[68:69], s[10:11]
	s_mov_b64 s[70:71], s[42:43]
	s_cbranch_vccnz .LBB0_143
	v_readlane_b32 s16, v254, 14
	s_add_u32 s68, s16, s40
	v_readlane_b32 s16, v254, 16
	s_addc_u32 s69, s16, s41
	v_readlane_b32 s16, v254, 20
	v_lshl_add_u64 v[130:131], s[68:69], 0, v[130:131]
	v_lshlrev_b32_e32 v164, 1, v138
	s_mul_i32 s16, s7, s16
	v_lshl_add_u64 v[130:131], v[130:131], 0, v[164:165]
	s_lshl_b32 s16, s16, 1
	v_lshl_add_u64 v[130:131], v[130:131], 0, s[16:17]
	v_lshlrev_b32_e32 v164, 1, v137
	v_lshl_add_u64 v[130:131], v[130:131], 0, v[164:165]
	v_lshlrev_b32_e32 v164, 1, v170
	v_cvt_pk_bf16_f32 v132, v100, v101
	v_cvt_pk_bf16_f32 v133, v102, v103
	v_lshl_add_u64 v[130:131], v[130:131], 0, v[164:165]
	s_andn2_b64 s[68:69], s[38:39], exec
	s_and_b64 s[0:1], s[0:1], exec
	v_cvt_pk_bf16_f32 v134, v96, v97
	v_cvt_pk_bf16_f32 v135, v98, v99
	global_store_dwordx4 v[130:131], v[132:135], off nt
	s_or_b64 s[68:69], s[68:69], s[0:1]
	s_mov_b64 s[70:71], s[6:7]
	v_mov_b64_e32 v[132:133], v[128:129]
.LBB0_143:
	s_and_saveexec_b64 s[0:1], s[68:69]
	s_cbranch_execz .LBB0_145
	s_lshl_b32 s16, s70, 2
	s_add_u32 s68, s84, s16
	s_addc_u32 s69, s85, 0
	v_lshl_add_u64 v[128:129], s[68:69], 0, v[132:133]
	v_lshlrev_b32_e32 v164, 2, v168
	v_lshl_add_u64 v[128:129], v[128:129], 0, v[164:165]
	global_store_dwordx4 v[128:129], v[100:103], off offset:1536 nt
	global_store_dwordx4 v[128:129], v[96:99], off offset:1552 nt
; __device__ __forceinline__ u32x4 pack8(const f32x4 a, const f32x4 b) { u32x4 w; w.x = cvt_pk_bf16(a[0], a[1]); w.y = cvt_pk_bf16(a[2], a[3]); w.z = cvt_pk_bf16(b[0], b[1]); w.w = cvt_pk_bf16(b[2], b[3]); return w; }
;     __device__ __forceinline__ void operator()(const f32x4 (&acc)[2][2][4][2], const Unit& u, int wr, int wc, int fr, int fq) const {
;     ...
; #pragma unroll
;             for (int ai = 0; ai < 2; ++ai)
; #pragma unroll
;                 for (int m = 0; m < 4; ++m) { const int row = rbase + ai * 128 + m * 16;
;                     int b, t;
;                     if (!sample) { b = row >> 11; t = row & 2047; } else { const int sr = row - MP; b = sr >> 3; t = sr & 7; }
; #pragma unroll
;                     for (int bj = 0; bj < 2; ++bj) { const int hc = bj * 128 + wc * 32 + fq * 8; const f32x4 v0 = acc[ai][bj][m][0], v1 = acc[ai][bj][m][1];
;                         if (!sample) {
;                             *(u32x4*)(VT + (size_t)g * MP * 256 + (size_t)b * 524288 + (t & (dil - 1)) * (L * 256) + (hc >> 6) * (L * 64) + (t >> sh) * 64 + (hc & 63)) = pack8(v0, v1);
;                             if (t >= 2048 - keep) { float* p = out + okp + ((size_t)(b * keep + t - (2048 - keep)) * 2 + 1) * 256 + hc; *(f32x4*)p = v0; *(f32x4*)(p + 4) = v1; } }
;                         else { float* p = out + oks + ((size_t)(b * keep + keep - 8 + t) * 2 + 1) * 256 + hc; *(f32x4*)p = v0; *(f32x4*)(p + 4) = v1; } } }
.LBB0_145:
	s_or_b64 exec, exec, s[0:1]
	v_add_u32_e32 v128, 0xffff0020, v184
	v_ashrrev_i32_e32 v128, 3, v128
	v_mov_b32_e32 v130, s46
	v_or_b32_e32 v129, 32, v136
	v_cndmask_b32_e64 v128, v130, v128, s[38:39]
	v_cndmask_b32_e64 v132, v129, v171, s[38:39]
	v_ashrrev_i32_e32 v129, 31, v128
	v_lshlrev_b64 v[130:131], 20, v[128:129]
	v_and_b32_e32 v129, s94, v132
	v_mul_u32_u24_e32 v138, s25, v129
	v_lshrrev_b32_e32 v129, s29, v132
	v_cmp_le_u32_e64 s[0:1], s92, v132
	v_lshl_add_u32 v132, v128, s93, v132
	v_add_u32_e32 v128, s24, v132
	v_add_u32_e32 v132, s43, v132
	v_ashrrev_i32_e32 v133, 31, v132
	v_lshlrev_b32_e32 v137, 6, v129
	v_ashrrev_i32_e32 v129, 31, v128
	v_lshlrev_b64 v[132:133], 11, v[132:133]
	v_lshlrev_b64 v[128:129], 11, v[128:129]
	s_and_b64 vcc, exec, s[4:5]
	s_mov_b64 s[70:71], s[10:11]
	v_mov_b64_e32 v[134:135], v[132:133]
	s_mov_b64 s[72:73], s[42:43]
	s_cbranch_vccnz .LBB0_147
	v_readlane_b32 s16, v254, 14
	s_add_u32 s68, s16, s40
	v_readlane_b32 s16, v254, 16
	s_addc_u32 s69, s16, s41
	v_readlane_b32 s16, v254, 18
	v_lshl_add_u64 v[134:135], s[68:69], 0, v[130:131]
	v_lshlrev_b32_e32 v164, 1, v138
	s_mul_i32 s16, s7, s16
	v_lshl_add_u64 v[134:135], v[134:135], 0, v[164:165]
	s_lshl_b32 s16, s16, 1
	v_lshl_add_u64 v[134:135], v[134:135], 0, s[16:17]
	v_lshlrev_b32_e32 v164, 1, v137
	v_lshl_add_u64 v[134:135], v[134:135], 0, v[164:165]
	v_lshlrev_b32_e32 v164, 1, v170
	v_lshl_add_u64 v[134:135], v[134:135], 0, v[164:165]
	s_andn2_b64 s[68:69], s[38:39], exec
	s_and_b64 s[70:71], s[0:1], exec
	v_cvt_pk_bf16_f32 v140, v92, v93
	v_cvt_pk_bf16_f32 v141, v94, v95
	v_cvt_pk_bf16_f32 v142, v88, v89
	v_cvt_pk_bf16_f32 v143, v90, v91
	global_store_dwordx4 v[134:135], v[140:143], off nt
	s_or_b64 s[70:71], s[68:69], s[70:71]
	v_mov_b64_e32 v[134:135], v[128:129]
	s_mov_b64 s[72:73], s[6:7]
.LBB0_147:
	s_and_saveexec_b64 s[68:69], s[70:71]
	s_cbranch_execz .LBB0_149
	s_lshl_b32 s16, s72, 2
	s_add_u32 s70, s84, s16
	s_addc_u32 s71, s85, 0
	v_lshl_add_u64 v[134:135], s[70:71], 0, v[134:135]
	v_lshlrev_b32_e32 v164, 2, v168
	v_lshl_add_u64 v[134:135], v[134:135], 0, v[164:165]
	global_store_dwordx4 v[134:135], v[92:95], off offset:1024 nt
	global_store_dwordx4 v[134:135], v[88:91], off offset:1040 nt
.LBB0_149:
	s_or_b64 exec, exec, s[68:69]
	s_and_b64 vcc, exec, s[4:5]
	s_mov_b64 s[68:69], s[10:11]
	s_mov_b64 s[70:71], s[42:43]
	s_cbranch_vccnz .LBB0_151
	v_readlane_b32 s16, v254, 14
	s_add_u32 s68, s16, s40
	v_readlane_b32 s16, v254, 16
	s_addc_u32 s69, s16, s41
	v_readlane_b32 s16, v254, 20
	v_lshl_add_u64 v[130:131], s[68:69], 0, v[130:131]
	v_lshlrev_b32_e32 v164, 1, v138
	s_mul_i32 s16, s7, s16
	v_lshl_add_u64 v[130:131], v[130:131], 0, v[164:165]
	s_lshl_b32 s16, s16, 1
	v_lshl_add_u64 v[130:131], v[130:131], 0, s[16:17]
	v_lshlrev_b32_e32 v164, 1, v137
	v_lshl_add_u64 v[130:131], v[130:131], 0, v[164:165]
	v_lshlrev_b32_e32 v164, 1, v170
	v_cvt_pk_bf16_f32 v132, v84, v85
	v_cvt_pk_bf16_f32 v133, v86, v87
	v_lshl_add_u64 v[130:131], v[130:131], 0, v[164:165]
	s_andn2_b64 s[68:69], s[38:39], exec
	s_and_b64 s[0:1], s[0:1], exec
	v_cvt_pk_bf16_f32 v134, v80, v81
	v_cvt_pk_bf16_f32 v135, v82, v83
	global_store_dwordx4 v[130:131], v[132:135], off nt
	s_or_b64 s[68:69], s[68:69], s[0:1]
	s_mov_b64 s[70:71], s[6:7]
	v_mov_b64_e32 v[132:133], v[128:129]
.LBB0_151:
	s_and_saveexec_b64 s[0:1], s[68:69]
	s_cbranch_execz .LBB0_153
	s_lshl_b32 s16, s70, 2
	s_add_u32 s68, s84, s16
	s_addc_u32 s69, s85, 0
	v_lshl_add_u64 v[128:129], s[68:69], 0, v[132:133]
	v_lshlrev_b32_e32 v164, 2, v168
	v_lshl_add_u64 v[128:129], v[128:129], 0, v[164:165]
	global_store_dwordx4 v[128:129], v[84:87], off offset:1536 nt
	global_store_dwordx4 v[128:129], v[80:83], off offset:1552 nt
.LBB0_153:
	s_or_b64 exec, exec, s[0:1]
	v_add_u32_e32 v128, 0xffff0030, v184
	v_ashrrev_i32_e32 v128, 3, v128
	v_mov_b32_e32 v130, s46
	v_or_b32_e32 v129, 48, v136
	v_cndmask_b32_e64 v128, v130, v128, s[38:39]
	v_cndmask_b32_e64 v132, v129, v171, s[38:39]
	v_ashrrev_i32_e32 v129, 31, v128
	v_lshlrev_b64 v[130:131], 20, v[128:129]
	v_and_b32_e32 v129, s94, v132
	v_mul_u32_u24_e32 v137, s25, v129
	v_lshrrev_b32_e32 v129, s29, v132
	v_cmp_le_u32_e64 s[0:1], s92, v132
	v_lshl_add_u32 v132, v128, s93, v132
	v_add_u32_e32 v128, s24, v132
	v_add_u32_e32 v132, s43, v132
	v_ashrrev_i32_e32 v133, 31, v132
	v_lshlrev_b32_e32 v136, 6, v129
	v_ashrrev_i32_e32 v129, 31, v128
	v_lshlrev_b64 v[132:133], 11, v[132:133]
	v_lshlrev_b64 v[128:129], 11, v[128:129]
	s_and_b64 vcc, exec, s[4:5]
	s_mov_b64 s[70:71], s[10:11]
	v_mov_b64_e32 v[134:135], v[132:133]
	s_mov_b64 s[72:73], s[42:43]
	s_cbranch_vccnz .LBB0_155
	v_readlane_b32 s16, v254, 14
	s_add_u32 s68, s16, s40
	v_readlane_b32 s16, v254, 16
	s_addc_u32 s69, s16, s41
	v_readlane_b32 s16, v254, 18
	v_lshl_add_u64 v[134:135], s[68:69], 0, v[130:131]
	v_lshlrev_b32_e32 v164, 1, v137
	s_mul_i32 s16, s7, s16
	v_lshl_add_u64 v[134:135], v[134:135], 0, v[164:165]
	s_lshl_b32 s16, s16, 1
	v_lshl_add_u64 v[134:135], v[134:135], 0, s[16:17]
	v_lshlrev_b32_e32 v164, 1, v136
	v_lshl_add_u64 v[134:135], v[134:135], 0, v[164:165]
	v_lshlrev_b32_e32 v164, 1, v170
	v_lshl_add_u64 v[134:135], v[134:135], 0, v[164:165]
	s_andn2_b64 s[68:69], s[38:39], exec
	s_and_b64 s[70:71], s[0:1], exec
	v_cvt_pk_bf16_f32 v138, v76, v77
	v_cvt_pk_bf16_f32 v139, v78, v79
	v_cvt_pk_bf16_f32 v140, v72, v73
	v_cvt_pk_bf16_f32 v141, v74, v75
	global_store_dwordx4 v[134:135], v[138:141], off nt
	s_or_b64 s[70:71], s[68:69], s[70:71]
	v_mov_b64_e32 v[134:135], v[128:129]
	s_mov_b64 s[72:73], s[6:7]
; __device__ __forceinline__ u32x4 pack8(const f32x4 a, const f32x4 b) { u32x4 w; w.x = cvt_pk_bf16(a[0], a[1]); w.y = cvt_pk_bf16(a[2], a[3]); w.z = cvt_pk_bf16(b[0], b[1]); w.w = cvt_pk_bf16(b[2], b[3]); return w; }
;     __device__ __forceinline__ void operator()(const f32x4 (&acc)[2][2][4][2], const Unit& u, int wr, int wc, int fr, int fq) const {
;     ...
; #pragma unroll
;             for (int ai = 0; ai < 2; ++ai)
; #pragma unroll
;                 for (int m = 0; m < 4; ++m) { const int row = rbase + ai * 128 + m * 16;
;                     int b, t;
;                     if (!sample) { b = row >> 11; t = row & 2047; } else { const int sr = row - MP; b = sr >> 3; t = sr & 7; }
; #pragma unroll
;                     for (int bj = 0; bj < 2; ++bj) { const int hc = bj * 128 + wc * 32 + fq * 8; const f32x4 v0 = acc[ai][bj][m][0], v1 = acc[ai][bj][m][1];
;                         if (!sample) {
;                             *(u32x4*)(VT + (size_t)g * MP * 256 + (size_t)b * 524288 + (t & (dil - 1)) * (L * 256) + (hc >> 6) * (L * 64) + (t >> sh) * 64 + (hc & 63)) = pack8(v0, v1);
;                             if (t >= 2048 - keep) { float* p = out + okp + ((size_t)(b * keep + t - (2048 - keep)) * 2 + 1) * 256 + hc; *(f32x4*)p = v0; *(f32x4*)(p + 4) = v1; } }
;                         else { float* p = out + oks + ((size_t)(b * keep + keep - 8 + t) * 2 + 1) * 256 + hc; *(f32x4*)p = v0; *(f32x4*)(p + 4) = v1; } } }
.LBB0_155:
	s_and_saveexec_b64 s[68:69], s[70:71]
	s_cbranch_execz .LBB0_157
	s_lshl_b32 s16, s72, 2
	s_add_u32 s70, s84, s16
	s_addc_u32 s71, s85, 0
	v_lshl_add_u64 v[134:135], s[70:71], 0, v[134:135]
	v_lshlrev_b32_e32 v164, 2, v168
	v_lshl_add_u64 v[134:135], v[134:135], 0, v[164:165]
	global_store_dwordx4 v[134:135], v[76:79], off offset:1024 nt
	global_store_dwordx4 v[134:135], v[72:75], off offset:1040 nt
.LBB0_157:
	s_or_b64 exec, exec, s[68:69]
	s_and_b64 vcc, exec, s[4:5]
	s_mov_b64 s[68:69], s[10:11]
	s_mov_b64 s[70:71], s[42:43]
	s_cbranch_vccnz .LBB0_159
	v_readlane_b32 s16, v254, 14
	s_add_u32 s68, s16, s40
	v_readlane_b32 s16, v254, 16
	s_addc_u32 s69, s16, s41
	v_readlane_b32 s16, v254, 20
	v_lshl_add_u64 v[130:131], s[68:69], 0, v[130:131]
	v_lshlrev_b32_e32 v164, 1, v137
	s_mul_i32 s16, s7, s16
	v_lshl_add_u64 v[130:131], v[130:131], 0, v[164:165]
	s_lshl_b32 s16, s16, 1
	v_lshl_add_u64 v[130:131], v[130:131], 0, s[16:17]
	v_lshlrev_b32_e32 v164, 1, v136
	v_lshl_add_u64 v[130:131], v[130:131], 0, v[164:165]
	v_lshlrev_b32_e32 v164, 1, v170
	v_cvt_pk_bf16_f32 v132, v68, v69
	v_cvt_pk_bf16_f32 v133, v70, v71
	v_lshl_add_u64 v[130:131], v[130:131], 0, v[164:165]
	s_andn2_b64 s[68:69], s[38:39], exec
	s_and_b64 s[0:1], s[0:1], exec
	v_cvt_pk_bf16_f32 v134, v64, v65
	v_cvt_pk_bf16_f32 v135, v66, v67
	global_store_dwordx4 v[130:131], v[132:135], off nt
	s_or_b64 s[68:69], s[68:69], s[0:1]
	s_mov_b64 s[70:71], s[6:7]
	v_mov_b64_e32 v[132:133], v[128:129]
.LBB0_159:
	s_and_saveexec_b64 s[0:1], s[68:69]
	s_cbranch_execz .LBB0_161
	s_lshl_b32 s16, s70, 2
	s_add_u32 s68, s84, s16
	s_addc_u32 s69, s85, 0
	v_lshl_add_u64 v[128:129], s[68:69], 0, v[132:133]
	v_lshlrev_b32_e32 v164, 2, v168
	v_lshl_add_u64 v[128:129], v[128:129], 0, v[164:165]
	global_store_dwordx4 v[128:129], v[68:71], off offset:1536 nt
	global_store_dwordx4 v[128:129], v[64:67], off offset:1552 nt
.LBB0_161:
	s_or_b64 exec, exec, s[0:1]
	v_add_u32_e32 v128, 0x80, v184
	v_add_u32_e32 v129, 0xffff0080, v184
	v_ashrrev_i32_e32 v136, 11, v128
	v_ashrrev_i32_e32 v129, 3, v129
	v_and_b32_e32 v130, 0x7cf, v128
	v_cndmask_b32_e64 v128, v136, v129, s[38:39]
	v_cndmask_b32_e64 v132, v130, v171, s[38:39]
	v_ashrrev_i32_e32 v129, 31, v128
	v_lshlrev_b64 v[130:131], 20, v[128:129]
	v_and_b32_e32 v129, s94, v132
	v_mul_u32_u24_e32 v138, s25, v129
	v_lshrrev_b32_e32 v129, s29, v132
	v_cmp_le_u32_e64 s[0:1], s92, v132
	v_lshl_add_u32 v132, v128, s93, v132
	v_add_u32_e32 v128, s24, v132
	v_add_u32_e32 v132, s43, v132
	v_ashrrev_i32_e32 v133, 31, v132
	v_lshlrev_b32_e32 v137, 6, v129
	v_ashrrev_i32_e32 v129, 31, v128
	v_lshlrev_b64 v[132:133], 11, v[132:133]
	v_lshlrev_b64 v[128:129], 11, v[128:129]
	s_and_b64 vcc, exec, s[4:5]
	s_mov_b64 s[70:71], s[10:11]
	v_mov_b64_e32 v[134:135], v[132:133]
	s_mov_b64 s[72:73], s[42:43]
	s_cbranch_vccnz .LBB0_163
	v_readlane_b32 s16, v254, 14
	s_add_u32 s68, s16, s40
	v_readlane_b32 s16, v254, 16
	s_addc_u32 s69, s16, s41
	v_readlane_b32 s16, v254, 18
	v_lshl_add_u64 v[134:135], s[68:69], 0, v[130:131]
	v_lshlrev_b32_e32 v164, 1, v138
	s_mul_i32 s16, s7, s16
	v_lshl_add_u64 v[134:135], v[134:135], 0, v[164:165]
	s_lshl_b32 s16, s16, 1
	v_lshl_add_u64 v[134:135], v[134:135], 0, s[16:17]
	v_lshlrev_b32_e32 v164, 1, v137
	v_lshl_add_u64 v[134:135], v[134:135], 0, v[164:165]
	v_lshlrev_b32_e32 v164, 1, v170
	v_lshl_add_u64 v[134:135], v[134:135], 0, v[164:165]
	s_andn2_b64 s[68:69], s[38:39], exec
	s_and_b64 s[70:71], s[0:1], exec
	v_cvt_pk_bf16_f32 v140, v60, v61
	v_cvt_pk_bf16_f32 v141, v62, v63
	v_cvt_pk_bf16_f32 v142, v56, v57
	v_cvt_pk_bf16_f32 v143, v58, v59
	global_store_dwordx4 v[134:135], v[140:143], off nt
	s_or_b64 s[70:71], s[68:69], s[70:71]
	v_mov_b64_e32 v[134:135], v[128:129]
	s_mov_b64 s[72:73], s[6:7]
.LBB0_163:
	s_and_saveexec_b64 s[68:69], s[70:71]
	s_cbranch_execz .LBB0_165
	s_lshl_b32 s16, s72, 2
	s_add_u32 s70, s84, s16
	s_addc_u32 s71, s85, 0
	v_lshl_add_u64 v[134:135], s[70:71], 0, v[134:135]
	v_lshlrev_b32_e32 v164, 2, v168
	v_lshl_add_u64 v[134:135], v[134:135], 0, v[164:165]
	global_store_dwordx4 v[134:135], v[60:63], off offset:1024 nt
	global_store_dwordx4 v[134:135], v[56:59], off offset:1040 nt
.LBB0_165:
	s_or_b64 exec, exec, s[68:69]
	s_and_b64 vcc, exec, s[4:5]
	s_mov_b64 s[68:69], s[10:11]
	s_mov_b64 s[70:71], s[42:43]
	s_cbranch_vccnz .LBB0_167
	v_readlane_b32 s16, v254, 14
	s_add_u32 s68, s16, s40
	v_readlane_b32 s16, v254, 16
	s_addc_u32 s69, s16, s41
	v_readlane_b32 s16, v254, 20
	v_lshl_add_u64 v[130:131], s[68:69], 0, v[130:131]
	v_lshlrev_b32_e32 v164, 1, v138
	s_mul_i32 s16, s7, s16
	v_lshl_add_u64 v[130:131], v[130:131], 0, v[164:165]
	s_lshl_b32 s16, s16, 1
	v_lshl_add_u64 v[130:131], v[130:131], 0, s[16:17]
	v_lshlrev_b32_e32 v164, 1, v137
	v_lshl_add_u64 v[130:131], v[130:131], 0, v[164:165]
	v_lshlrev_b32_e32 v164, 1, v170
	v_cvt_pk_bf16_f32 v132, v52, v53
	v_cvt_pk_bf16_f32 v133, v54, v55
	v_lshl_add_u64 v[130:131], v[130:131], 0, v[164:165]
	s_andn2_b64 s[68:69], s[38:39], exec
	s_and_b64 s[0:1], s[0:1], exec
	v_cvt_pk_bf16_f32 v134, v48, v49
	v_cvt_pk_bf16_f32 v135, v50, v51
	global_store_dwordx4 v[130:131], v[132:135], off nt
	s_or_b64 s[68:69], s[68:69], s[0:1]
	s_mov_b64 s[70:71], s[6:7]
	v_mov_b64_e32 v[132:133], v[128:129]
.LBB0_167:
	s_and_saveexec_b64 s[0:1], s[68:69]
	s_cbranch_execz .LBB0_169
	s_lshl_b32 s16, s70, 2
	s_add_u32 s68, s84, s16
	s_addc_u32 s69, s85, 0
	v_lshl_add_u64 v[128:129], s[68:69], 0, v[132:133]
	v_lshlrev_b32_e32 v164, 2, v168
	v_lshl_add_u64 v[128:129], v[128:129], 0, v[164:165]
	global_store_dwordx4 v[128:129], v[52:55], off offset:1536 nt
	global_store_dwordx4 v[128:129], v[48:51], off offset:1552 nt
; __device__ __forceinline__ u32x4 pack8(const f32x4 a, const f32x4 b) { u32x4 w; w.x = cvt_pk_bf16(a[0], a[1]); w.y = cvt_pk_bf16(a[2], a[3]); w.z = cvt_pk_bf16(b[0], b[1]); w.w = cvt_pk_bf16(b[2], b[3]); return w; }
;     __device__ __forceinline__ void operator()(const f32x4 (&acc)[2][2][4][2], const Unit& u, int wr, int wc, int fr, int fq) const {
;     ...
; #pragma unroll
;             for (int ai = 0; ai < 2; ++ai)
; #pragma unroll
;                 for (int m = 0; m < 4; ++m) { const int row = rbase + ai * 128 + m * 16;
;                     int b, t;
;                     if (!sample) { b = row >> 11; t = row & 2047; } else { const int sr = row - MP; b = sr >> 3; t = sr & 7; }
; #pragma unroll
;                     for (int bj = 0; bj < 2; ++bj) { const int hc = bj * 128 + wc * 32 + fq * 8; const f32x4 v0 = acc[ai][bj][m][0], v1 = acc[ai][bj][m][1];
;                         if (!sample) {
;                             *(u32x4*)(VT + (size_t)g * MP * 256 + (size_t)b * 524288 + (t & (dil - 1)) * (L * 256) + (hc >> 6) * (L * 64) + (t >> sh) * 64 + (hc & 63)) = pack8(v0, v1);
;                             if (t >= 2048 - keep) { float* p = out + okp + ((size_t)(b * keep + t - (2048 - keep)) * 2 + 1) * 256 + hc; *(f32x4*)p = v0; *(f32x4*)(p + 4) = v1; } }
;                         else { float* p = out + oks + ((size_t)(b * keep + keep - 8 + t) * 2 + 1) * 256 + hc; *(f32x4*)p = v0; *(f32x4*)(p + 4) = v1; } } }
.LBB0_169:
	s_or_b64 exec, exec, s[0:1]
	v_add_u32_e32 v129, 0xffff0090, v184
	v_add_u32_e32 v128, 0x90, v184
	v_ashrrev_i32_e32 v129, 3, v129
	v_and_b32_e32 v130, 0x7df, v128
	v_cndmask_b32_e64 v128, v136, v129, s[38:39]
	v_cndmask_b32_e64 v132, v130, v171, s[38:39]
	v_ashrrev_i32_e32 v129, 31, v128
	v_lshlrev_b64 v[130:131], 20, v[128:129]
	v_and_b32_e32 v129, s94, v132
	v_mul_u32_u24_e32 v138, s25, v129
	v_lshrrev_b32_e32 v129, s29, v132
	v_cmp_le_u32_e64 s[0:1], s92, v132
	v_lshl_add_u32 v132, v128, s93, v132
	v_add_u32_e32 v128, s24, v132
	v_add_u32_e32 v132, s43, v132
	v_ashrrev_i32_e32 v133, 31, v132
	v_lshlrev_b32_e32 v137, 6, v129
	v_ashrrev_i32_e32 v129, 31, v128
	v_lshlrev_b64 v[132:133], 11, v[132:133]
	v_lshlrev_b64 v[128:129], 11, v[128:129]
	s_and_b64 vcc, exec, s[4:5]
	s_mov_b64 s[70:71], s[10:11]
	v_mov_b64_e32 v[134:135], v[132:133]
	s_mov_b64 s[72:73], s[42:43]
	s_cbranch_vccnz .LBB0_171
	v_readlane_b32 s16, v254, 14
	s_add_u32 s68, s16, s40
	v_readlane_b32 s16, v254, 16
	s_addc_u32 s69, s16, s41
	v_readlane_b32 s16, v254, 18
	v_lshl_add_u64 v[134:135], s[68:69], 0, v[130:131]
	v_lshlrev_b32_e32 v164, 1, v138
	s_mul_i32 s16, s7, s16
	v_lshl_add_u64 v[134:135], v[134:135], 0, v[164:165]
	s_lshl_b32 s16, s16, 1
	v_lshl_add_u64 v[134:135], v[134:135], 0, s[16:17]
	v_lshlrev_b32_e32 v164, 1, v137
	v_lshl_add_u64 v[134:135], v[134:135], 0, v[164:165]
	v_lshlrev_b32_e32 v164, 1, v170
	v_lshl_add_u64 v[134:135], v[134:135], 0, v[164:165]
	s_andn2_b64 s[68:69], s[38:39], exec
	s_and_b64 s[70:71], s[0:1], exec
	v_cvt_pk_bf16_f32 v140, v44, v45
	v_cvt_pk_bf16_f32 v141, v46, v47
	v_cvt_pk_bf16_f32 v142, v40, v41
	v_cvt_pk_bf16_f32 v143, v42, v43
	global_store_dwordx4 v[134:135], v[140:143], off nt
	s_or_b64 s[70:71], s[68:69], s[70:71]
	v_mov_b64_e32 v[134:135], v[128:129]
	s_mov_b64 s[72:73], s[6:7]
.LBB0_171:
	s_and_saveexec_b64 s[68:69], s[70:71]
	s_cbranch_execz .LBB0_173
	s_lshl_b32 s16, s72, 2
	s_add_u32 s70, s84, s16
	s_addc_u32 s71, s85, 0
	v_lshl_add_u64 v[134:135], s[70:71], 0, v[134:135]
	v_lshlrev_b32_e32 v164, 2, v168
	v_lshl_add_u64 v[134:135], v[134:135], 0, v[164:165]
	global_store_dwordx4 v[134:135], v[44:47], off offset:1024 nt
	global_store_dwordx4 v[134:135], v[40:43], off offset:1040 nt
.LBB0_173:
	s_or_b64 exec, exec, s[68:69]
	s_and_b64 vcc, exec, s[4:5]
	s_mov_b64 s[68:69], s[10:11]
	s_mov_b64 s[70:71], s[42:43]
	s_cbranch_vccnz .LBB0_175
	v_readlane_b32 s16, v254, 14
	s_add_u32 s68, s16, s40
	v_readlane_b32 s16, v254, 16
	s_addc_u32 s69, s16, s41
	v_readlane_b32 s16, v254, 20
	v_lshl_add_u64 v[130:131], s[68:69], 0, v[130:131]
	v_lshlrev_b32_e32 v164, 1, v138
	s_mul_i32 s16, s7, s16
	v_lshl_add_u64 v[130:131], v[130:131], 0, v[164:165]
	s_lshl_b32 s16, s16, 1
	v_lshl_add_u64 v[130:131], v[130:131], 0, s[16:17]
	v_lshlrev_b32_e32 v164, 1, v137
	v_lshl_add_u64 v[130:131], v[130:131], 0, v[164:165]
	v_lshlrev_b32_e32 v164, 1, v170
	v_cvt_pk_bf16_f32 v132, v36, v37
	v_cvt_pk_bf16_f32 v133, v38, v39
	v_lshl_add_u64 v[130:131], v[130:131], 0, v[164:165]
	s_andn2_b64 s[68:69], s[38:39], exec
	s_and_b64 s[0:1], s[0:1], exec
	v_cvt_pk_bf16_f32 v134, v32, v33
	v_cvt_pk_bf16_f32 v135, v34, v35
	global_store_dwordx4 v[130:131], v[132:135], off nt
	s_or_b64 s[68:69], s[68:69], s[0:1]
	s_mov_b64 s[70:71], s[6:7]
	v_mov_b64_e32 v[132:133], v[128:129]
.LBB0_175:
	s_and_saveexec_b64 s[0:1], s[68:69]
	s_cbranch_execz .LBB0_177
	s_lshl_b32 s16, s70, 2
	s_add_u32 s68, s84, s16
	s_addc_u32 s69, s85, 0
	v_lshl_add_u64 v[128:129], s[68:69], 0, v[132:133]
	v_lshlrev_b32_e32 v164, 2, v168
	v_lshl_add_u64 v[128:129], v[128:129], 0, v[164:165]
	global_store_dwordx4 v[128:129], v[36:39], off offset:1536 nt
	global_store_dwordx4 v[128:129], v[32:35], off offset:1552 nt
.LBB0_177:
	s_or_b64 exec, exec, s[0:1]
	v_add_u32_e32 v129, 0xffff00a0, v184
	v_add_u32_e32 v128, 0xa0, v184
	v_ashrrev_i32_e32 v129, 3, v129
	v_and_b32_e32 v130, 0x7ef, v128
	v_cndmask_b32_e64 v128, v136, v129, s[38:39]
	v_cndmask_b32_e64 v132, v130, v171, s[38:39]
	v_ashrrev_i32_e32 v129, 31, v128
	v_lshlrev_b64 v[130:131], 20, v[128:129]
	v_and_b32_e32 v129, s94, v132
	v_mul_u32_u24_e32 v138, s25, v129
	v_lshrrev_b32_e32 v129, s29, v132
	v_cmp_le_u32_e64 s[0:1], s92, v132
	v_lshl_add_u32 v132, v128, s93, v132
	v_add_u32_e32 v128, s24, v132
	v_add_u32_e32 v132, s43, v132
	v_ashrrev_i32_e32 v133, 31, v132
	v_lshlrev_b32_e32 v137, 6, v129
	v_ashrrev_i32_e32 v129, 31, v128
	v_lshlrev_b64 v[132:133], 11, v[132:133]
	v_lshlrev_b64 v[128:129], 11, v[128:129]
	s_and_b64 vcc, exec, s[4:5]
	s_mov_b64 s[70:71], s[10:11]
	v_mov_b64_e32 v[134:135], v[132:133]
	s_mov_b64 s[72:73], s[42:43]
	s_cbranch_vccnz .LBB0_179
	v_readlane_b32 s16, v254, 14
	s_add_u32 s68, s16, s40
	v_readlane_b32 s16, v254, 16
	s_addc_u32 s69, s16, s41
	v_readlane_b32 s16, v254, 18
	v_lshl_add_u64 v[134:135], s[68:69], 0, v[130:131]
	v_lshlrev_b32_e32 v164, 1, v138
	s_mul_i32 s16, s7, s16
	v_lshl_add_u64 v[134:135], v[134:135], 0, v[164:165]
	s_lshl_b32 s16, s16, 1
	v_lshl_add_u64 v[134:135], v[134:135], 0, s[16:17]
	v_lshlrev_b32_e32 v164, 1, v137
	v_lshl_add_u64 v[134:135], v[134:135], 0, v[164:165]
	v_lshlrev_b32_e32 v164, 1, v170
	v_lshl_add_u64 v[134:135], v[134:135], 0, v[164:165]
	s_andn2_b64 s[68:69], s[38:39], exec
	s_and_b64 s[70:71], s[0:1], exec
	v_cvt_pk_bf16_f32 v140, v28, v29
	v_cvt_pk_bf16_f32 v141, v30, v31
	v_cvt_pk_bf16_f32 v142, v24, v25
	v_cvt_pk_bf16_f32 v143, v26, v27
	global_store_dwordx4 v[134:135], v[140:143], off nt
	s_or_b64 s[70:71], s[68:69], s[70:71]
	v_mov_b64_e32 v[134:135], v[128:129]
	s_mov_b64 s[72:73], s[6:7]
; __device__ __forceinline__ u32x4 pack8(const f32x4 a, const f32x4 b) { u32x4 w; w.x = cvt_pk_bf16(a[0], a[1]); w.y = cvt_pk_bf16(a[2], a[3]); w.z = cvt_pk_bf16(b[0], b[1]); w.w = cvt_pk_bf16(b[2], b[3]); return w; }
;     __device__ __forceinline__ void operator()(const f32x4 (&acc)[2][2][4][2], const Unit& u, int wr, int wc, int fr, int fq) const {
;     ...
; #pragma unroll
;             for (int ai = 0; ai < 2; ++ai)
; #pragma unroll
;                 for (int m = 0; m < 4; ++m) { const int row = rbase + ai * 128 + m * 16;
;                     int b, t;
;                     if (!sample) { b = row >> 11; t = row & 2047; } else { const int sr = row - MP; b = sr >> 3; t = sr & 7; }
; #pragma unroll
;                     for (int bj = 0; bj < 2; ++bj) { const int hc = bj * 128 + wc * 32 + fq * 8; const f32x4 v0 = acc[ai][bj][m][0], v1 = acc[ai][bj][m][1];
;                         if (!sample) {
;                             *(u32x4*)(VT + (size_t)g * MP * 256 + (size_t)b * 524288 + (t & (dil - 1)) * (L * 256) + (hc >> 6) * (L * 64) + (t >> sh) * 64 + (hc & 63)) = pack8(v0, v1);
;                             if (t >= 2048 - keep) { float* p = out + okp + ((size_t)(b * keep + t - (2048 - keep)) * 2 + 1) * 256 + hc; *(f32x4*)p = v0; *(f32x4*)(p + 4) = v1; } }
;                         else { float* p = out + oks + ((size_t)(b * keep + keep - 8 + t) * 2 + 1) * 256 + hc; *(f32x4*)p = v0; *(f32x4*)(p + 4) = v1; } } }
.LBB0_179:
	s_and_saveexec_b64 s[68:69], s[70:71]
	s_cbranch_execz .LBB0_181
	s_lshl_b32 s16, s72, 2
	s_add_u32 s70, s84, s16
	s_addc_u32 s71, s85, 0
	v_lshl_add_u64 v[134:135], s[70:71], 0, v[134:135]
	v_lshlrev_b32_e32 v164, 2, v168
	v_lshl_add_u64 v[134:135], v[134:135], 0, v[164:165]
	global_store_dwordx4 v[134:135], v[28:31], off offset:1024 nt
	global_store_dwordx4 v[134:135], v[24:27], off offset:1040 nt
.LBB0_181:
	s_or_b64 exec, exec, s[68:69]
	s_and_b64 vcc, exec, s[4:5]
	s_mov_b64 s[68:69], s[10:11]
	s_mov_b64 s[70:71], s[42:43]
	s_cbranch_vccnz .LBB0_183
	v_readlane_b32 s16, v254, 14
	s_add_u32 s68, s16, s40
	v_readlane_b32 s16, v254, 16
	s_addc_u32 s69, s16, s41
	v_readlane_b32 s16, v254, 20
	v_lshl_add_u64 v[130:131], s[68:69], 0, v[130:131]
	v_lshlrev_b32_e32 v164, 1, v138
	s_mul_i32 s16, s7, s16
	v_lshl_add_u64 v[130:131], v[130:131], 0, v[164:165]
	s_lshl_b32 s16, s16, 1
	v_lshl_add_u64 v[130:131], v[130:131], 0, s[16:17]
	v_lshlrev_b32_e32 v164, 1, v137
	v_lshl_add_u64 v[130:131], v[130:131], 0, v[164:165]
	v_lshlrev_b32_e32 v164, 1, v170
	v_cvt_pk_bf16_f32 v132, v20, v21
	v_cvt_pk_bf16_f32 v133, v22, v23
	v_lshl_add_u64 v[130:131], v[130:131], 0, v[164:165]
	s_andn2_b64 s[68:69], s[38:39], exec
	s_and_b64 s[0:1], s[0:1], exec
	v_cvt_pk_bf16_f32 v134, v16, v17
	v_cvt_pk_bf16_f32 v135, v18, v19
	global_store_dwordx4 v[130:131], v[132:135], off nt
	s_or_b64 s[68:69], s[68:69], s[0:1]
	s_mov_b64 s[70:71], s[6:7]
	v_mov_b64_e32 v[132:133], v[128:129]
.LBB0_183:
	s_and_saveexec_b64 s[0:1], s[68:69]
	s_cbranch_execz .LBB0_185
	s_lshl_b32 s16, s70, 2
	s_add_u32 s68, s84, s16
	s_addc_u32 s69, s85, 0
	v_lshl_add_u64 v[128:129], s[68:69], 0, v[132:133]
	v_lshlrev_b32_e32 v164, 2, v168
	v_lshl_add_u64 v[128:129], v[128:129], 0, v[164:165]
	global_store_dwordx4 v[128:129], v[20:23], off offset:1536 nt
	global_store_dwordx4 v[128:129], v[16:19], off offset:1552 nt
.LBB0_185:
	s_or_b64 exec, exec, s[0:1]
	v_add_u32_e32 v129, 0xffff00b0, v184
	v_add_u32_e32 v128, 0xb0, v184
	v_ashrrev_i32_e32 v129, 3, v129
	v_and_b32_e32 v130, 0x7ff, v128
	v_cndmask_b32_e64 v128, v136, v129, s[38:39]
	v_cndmask_b32_e64 v132, v130, v171, s[38:39]
	v_ashrrev_i32_e32 v129, 31, v128
	v_lshlrev_b64 v[130:131], 20, v[128:129]
	v_and_b32_e32 v129, s94, v132
	v_mul_u32_u24_e32 v137, s25, v129
	v_lshrrev_b32_e32 v129, s29, v132
	v_cmp_le_u32_e64 s[0:1], s92, v132
	v_lshl_add_u32 v132, v128, s93, v132
	v_add_u32_e32 v128, s24, v132
	v_add_u32_e32 v132, s43, v132
	v_ashrrev_i32_e32 v133, 31, v132
	v_lshlrev_b32_e32 v136, 6, v129
	v_ashrrev_i32_e32 v129, 31, v128
	v_lshlrev_b64 v[132:133], 11, v[132:133]
	v_lshlrev_b64 v[128:129], 11, v[128:129]
	s_and_b64 vcc, exec, s[4:5]
	s_mov_b64 s[70:71], s[10:11]
	v_mov_b64_e32 v[134:135], v[132:133]
	s_mov_b64 s[72:73], s[42:43]
	s_cbranch_vccnz .LBB0_187
	v_readlane_b32 s16, v254, 14
	s_add_u32 s24, s16, s40
	v_readlane_b32 s16, v254, 16
	s_addc_u32 s25, s16, s41
	v_readlane_b32 s16, v254, 18
	v_lshl_add_u64 v[134:135], s[24:25], 0, v[130:131]
	v_lshlrev_b32_e32 v164, 1, v137
	s_mul_i32 s16, s7, s16
	v_lshl_add_u64 v[134:135], v[134:135], 0, v[164:165]
	s_lshl_b32 s16, s16, 1
	v_lshl_add_u64 v[134:135], v[134:135], 0, s[16:17]
	v_lshlrev_b32_e32 v164, 1, v136
	v_lshl_add_u64 v[134:135], v[134:135], 0, v[164:165]
	v_lshlrev_b32_e32 v164, 1, v170
	v_lshl_add_u64 v[134:135], v[134:135], 0, v[164:165]
	s_andn2_b64 s[24:25], s[38:39], exec
	s_and_b64 s[68:69], s[0:1], exec
	v_cvt_pk_bf16_f32 v138, v12, v13
	v_cvt_pk_bf16_f32 v139, v14, v15
	v_cvt_pk_bf16_f32 v140, v8, v9
	v_cvt_pk_bf16_f32 v141, v10, v11
	global_store_dwordx4 v[134:135], v[138:141], off nt
	s_or_b64 s[70:71], s[24:25], s[68:69]
	v_mov_b64_e32 v[134:135], v[128:129]
	s_mov_b64 s[72:73], s[6:7]
.LBB0_187:
	s_and_saveexec_b64 s[68:69], s[70:71]
	s_cbranch_execz .LBB0_189
	s_lshl_b32 s16, s72, 2
	s_add_u32 s24, s84, s16
	s_addc_u32 s25, s85, 0
	v_lshl_add_u64 v[134:135], s[24:25], 0, v[134:135]
	v_lshlrev_b32_e32 v164, 2, v168
	v_lshl_add_u64 v[134:135], v[134:135], 0, v[164:165]
	global_store_dwordx4 v[134:135], v[12:15], off offset:1024 nt
	global_store_dwordx4 v[134:135], v[8:11], off offset:1040 nt
.LBB0_189:
	s_or_b64 exec, exec, s[68:69]
	v_readlane_b32 s70, v254, 23
	s_and_b64 vcc, exec, s[4:5]
	v_readlane_b32 s46, v254, 21
	v_readlane_b32 s68, v254, 22
	v_readlane_b32 s71, v254, 24
	s_cbranch_vccnz .LBB0_191
	v_readlane_b32 s4, v254, 14
	s_add_u32 s4, s4, s40
	v_readlane_b32 s5, v254, 16
	s_addc_u32 s5, s5, s41
	v_lshlrev_b32_e32 v164, 1, v137
	v_lshl_add_u64 v[130:131], s[4:5], 0, v[130:131]
	v_readlane_b32 s4, v254, 20
	s_mul_i32 s7, s7, s4
	v_lshl_add_u64 v[130:131], v[130:131], 0, v[164:165]
	s_lshl_b32 s16, s7, 1
	v_lshl_add_u64 v[130:131], v[130:131], 0, s[16:17]
	v_lshlrev_b32_e32 v164, 1, v136
	v_lshl_add_u64 v[130:131], v[130:131], 0, v[164:165]
	v_lshlrev_b32_e32 v164, 1, v170
	v_cvt_pk_bf16_f32 v132, v4, v5
	v_cvt_pk_bf16_f32 v133, v6, v7
	v_lshl_add_u64 v[130:131], v[130:131], 0, v[164:165]
	s_andn2_b64 s[4:5], s[38:39], exec
	s_and_b64 s[0:1], s[0:1], exec
	v_cvt_pk_bf16_f32 v134, v0, v1
	v_cvt_pk_bf16_f32 v135, v2, v3
	global_store_dwordx4 v[130:131], v[132:135], off nt
	s_or_b64 s[10:11], s[4:5], s[0:1]
	s_mov_b64 s[42:43], s[6:7]
	v_mov_b64_e32 v[132:133], v[128:129]
.LBB0_191:
	s_and_saveexec_b64 s[0:1], s[10:11]
	s_movk_i32 s40, 0x7f0
	s_cbranch_execz .LBB0_193
	s_lshl_b32 s4, s42, 2
	s_add_u32 s4, s84, s4
	s_addc_u32 s5, s85, 0
	v_lshl_add_u64 v[128:129], s[4:5], 0, v[132:133]
	v_lshlrev_b32_e32 v164, 2, v168
	v_lshl_add_u64 v[128:129], v[128:129], 0, v[164:165]
	global_store_dwordx4 v[128:129], v[4:7], off offset:1536 nt
	global_store_dwordx4 v[128:129], v[0:3], off offset:1552 nt

; __device__ __forceinline__ u32x4 pack8(const f32x4 a, const f32x4 b) { u32x4 w; w.x = cvt_pk_bf16(a[0], a[1]); w.y = cvt_pk_bf16(a[2], a[3]); w.z = cvt_pk_bf16(b[0], b[1]); w.w = cvt_pk_bf16(b[2], b[3]); return w; }
; __device__ __forceinline__ float dot4(const f32x4 a, const f32x4 b) { return (a[0] * b[0] + a[1] * b[1]) + (a[2] * b[2] + a[3] * b[3]); }
;     __device__ __forceinline__ void operator()(const f32x4 (&acc)[2][2][4][2], const Unit& u, int wr, int wc, int fr, int fq) const {
;     ...
;                 for (int m = 0; m < 4; ++m) { const int row = rbase + ai * 128 + m * 16;
;                     float ss = 0.f;
; #pragma unroll
;                     for (int bj = 0; bj < 2; ++bj)
; #pragma unroll
;                         for (int n = 0; n < 2; ++n) ss += dot4(acc[ai][bj][m][n], acc[ai][bj][m][n]);
;                     ss += __shfl_xor(ss, 16); ss += __shfl_xor(ss, 32);
;                     float rs = __builtin_amdgcn_rsqf(ss * (1.0f / 64.0f) + EPS); if (isq) rs *= QSCALE;
;                     int b, t, Rg;
;                     if (!sample) { b = row >> 11; t = row & 2047; Rg = b * 524288 + (t & (dil - 1)) * (L * 256) + (t >> sh) * 64 + wc * (L * 64); } else { const int sr = row - MP; b = sr >> 3; t = sr & 7; Rg = row * 256 + wc * 64; }
; #pragma unroll
;                     for (int bj = 0; bj < 2; ++bj) { const int hc = wc * 64 + bj * 32 + fq * 8, dd = bj * 32 + fq * 8;
;                         const f32x4 v0 = acc[ai][bj][m][0] * rs * w[bj][0], v1 = acc[ai][bj][m][1] * rs * w[bj][1];
;                         if (isq) { *(u32x4*)(QG + (size_t)g * M * 256 + (size_t)Rg + dd) = pack8(v0, v1); }
;                         else {
;                             if (!sample) { *(u32x4*)(KG + (size_t)g * MP * 256 + (size_t)Rg + dd) = pack8(v0, v1);
;                                 if (t >= 2048 - keep) { float* p = out + okp + ((size_t)(b * keep + t - (2048 - keep)) * 2) * 256 + hc; *(f32x4*)p = v0; *(f32x4*)(p + 4) = v1; } }
;                             else { float* p = out + oks + ((size_t)(b * keep + keep - 8 + t) * 2) * 256 + hc; *(f32x4*)p = v0; *(f32x4*)(p + 4) = v1; } } } }
.LBB0_200:
	s_waitcnt lgkmcnt(0)
	v_add_f32_e32 v144, v144, v146
	v_fmamk_f32 v144, v144, 0x3c800000, v195
	v_rsq_f32_e32 v144, v144
	s_lshl_b32 s73, 0x80, s92
	s_cmp_eq_u32 s42, 1
	s_mov_b32 s0, 0x433c000
	s_mov_b32 s1, 0x742c000
	s_cselect_b32 s0, s0, 0x4b3c000
	s_cselect_b32 s1, s1, 0x942c000
	s_cmp_eq_u32 s42, 0
	s_cselect_b32 s29, 0x413c000, s0
	s_cselect_b32 s16, 0x6c2c000, s1
	s_add_i32 s68, s92, 7
	v_mul_f32_e32 v146, 0x3e38aa3b, v144
	s_add_i32 s72, s73, 0xfffff800
	v_cndmask_b32_e64 v192, v144, v146, s[6:7]
	v_lshl_add_u32 v146, v147, s68, v145
	s_sub_i32 s93, 0x800, s73
	v_add_u32_e32 v144, s72, v146
	s_add_i32 s73, s73, -8
	v_cmp_le_i32_e64 s[10:11], s93, v145
	v_ashrrev_i32_e32 v145, 31, v144
	v_lshlrev_b64 v[190:191], 11, v[144:145]
	v_add_u32_e32 v144, s73, v146
	v_ashrrev_i32_e32 v145, 31, v144
	s_ashr_i32 s43, s42, 31
	v_lshlrev_b64 v[188:189], 11, v[144:145]
	v_pk_mul_f32 v[144:145], v[124:125], v[192:193] op_sel_hi:[1,0]
	v_pk_mul_f32 v[146:147], v[126:127], v[192:193] op_sel_hi:[1,0]
	v_pk_mul_f32 v[148:149], v[120:121], v[192:193] op_sel_hi:[1,0]
	v_pk_mul_f32 v[150:151], v[122:123], v[192:193] op_sel_hi:[1,0]
	s_lshl_b64 s[0:1], s[42:43], 25
	v_ashrrev_i32_e32 v187, 31, v186
	s_waitcnt vmcnt(0)
	v_pk_mul_f32 v[146:147], v[142:143], v[146:147]
	v_pk_mul_f32 v[144:145], v[140:141], v[144:145]
	v_pk_mul_f32 v[150:151], v[138:139], v[150:151]
	v_pk_mul_f32 v[148:149], v[136:137], v[148:149]
	s_mov_b64 s[8:9], -1
	s_and_b64 vcc, exec, s[40:41]
	s_cbranch_vccz .LBB0_208
	s_and_b64 vcc, exec, s[4:5]
	s_cbranch_vccnz .LBB0_205
	s_add_u32 s8, s46, s0
	v_readlane_b32 s9, v254, 12
	s_addc_u32 s9, s9, s1
	v_lshlrev_b32_e32 v164, 1, v166
	v_lshl_add_u64 v[206:207], v[186:187], 1, s[8:9]
	v_lshl_add_u64 v[206:207], v[206:207], 0, v[164:165]
	v_cvt_pk_bf16_f32 v202, v144, v145
	v_cvt_pk_bf16_f32 v203, v146, v147
	v_cvt_pk_bf16_f32 v204, v148, v149
	v_cvt_pk_bf16_f32 v205, v150, v151
	global_store_dwordx4 v[206:207], v[202:205], off nt
	s_and_saveexec_b64 s[8:9], s[10:11]
	s_cbranch_execz .LBB0_204
	s_lshl_b32 s25, s29, 2
	s_add_u32 vcc_lo, s84, s25
	s_addc_u32 vcc_hi, s85, 0
	v_lshl_add_u64 v[202:203], vcc, 0, v[190:191]
	v_lshlrev_b32_e32 v164, 2, v172
	v_lshl_add_u64 v[202:203], v[202:203], 0, v[164:165]
	global_store_dwordx4 v[202:203], v[144:147], off nt
	global_store_dwordx4 v[202:203], v[148:151], off offset:16 nt

; __device__ __forceinline__ u32x4 pack8(const f32x4 a, const f32x4 b) { u32x4 w; w.x = cvt_pk_bf16(a[0], a[1]); w.y = cvt_pk_bf16(a[2], a[3]); w.z = cvt_pk_bf16(b[0], b[1]); w.w = cvt_pk_bf16(b[2], b[3]); return w; }
;     __device__ __forceinline__ void operator()(const f32x4 (&acc)[2][2][4][2], const Unit& u, int wr, int wc, int fr, int fq) const {
;     ...
;                         else {
;                             if (!sample) { *(u32x4*)(KG + (size_t)g * MP * 256 + (size_t)Rg + dd) = pack8(v0, v1);
;                                 if (t >= 2048 - keep) { float* p = out + okp + ((size_t)(b * keep + t - (2048 - keep)) * 2) * 256 + hc; *(f32x4*)p = v0; *(f32x4*)(p + 4) = v1; } }
;                             else { float* p = out + oks + ((size_t)(b * keep + keep - 8 + t) * 2) * 256 + hc; *(f32x4*)p = v0; *(f32x4*)(p + 4) = v1; } } } }
.LBB0_205:
	s_andn2_b64 vcc, exec, s[8:9]
	s_cbranch_vccnz .LBB0_207
	s_lshl_b32 s8, s16, 2
	s_add_u32 s8, s84, s8
	s_addc_u32 s9, s85, 0
	v_lshl_add_u64 v[202:203], s[8:9], 0, v[188:189]
	v_lshlrev_b32_e32 v164, 2, v172
	v_lshl_add_u64 v[202:203], v[202:203], 0, v[164:165]
	global_store_dwordx4 v[202:203], v[144:147], off nt
	global_store_dwordx4 v[202:203], v[148:151], off offset:16 nt

; __device__ __forceinline__ u32x4 pack8(const f32x4 a, const f32x4 b) { u32x4 w; w.x = cvt_pk_bf16(a[0], a[1]); w.y = cvt_pk_bf16(a[2], a[3]); w.z = cvt_pk_bf16(b[0], b[1]); w.w = cvt_pk_bf16(b[2], b[3]); return w; }
;     __device__ __forceinline__ void operator()(const f32x4 (&acc)[2][2][4][2], const Unit& u, int wr, int wc, int fr, int fq) const {
;     ...
;                     for (int bj = 0; bj < 2; ++bj) { const int hc = wc * 64 + bj * 32 + fq * 8, dd = bj * 32 + fq * 8;
;                         const f32x4 v0 = acc[ai][bj][m][0] * rs * w[bj][0], v1 = acc[ai][bj][m][1] * rs * w[bj][1];
;                         if (isq) { *(u32x4*)(QG + (size_t)g * M * 256 + (size_t)Rg + dd) = pack8(v0, v1); }
;                         else {
;                             if (!sample) { *(u32x4*)(KG + (size_t)g * MP * 256 + (size_t)Rg + dd) = pack8(v0, v1);
;                                 if (t >= 2048 - keep) { float* p = out + okp + ((size_t)(b * keep + t - (2048 - keep)) * 2) * 256 + hc; *(f32x4*)p = v0; *(f32x4*)(p + 4) = v1; } }
;                             else { float* p = out + oks + ((size_t)(b * keep + keep - 8 + t) * 2) * 256 + hc; *(f32x4*)p = v0; *(f32x4*)(p + 4) = v1; } } } }
.LBB0_208:
	s_mul_i32 s42, s42, 0x2080000
	s_andn2_b64 vcc, exec, s[8:9]
	s_ashr_i32 s43, s42, 31
	s_cbranch_vccnz .LBB0_210
	s_add_u32 s8, s81, s42
	s_addc_u32 s9, s82, s43
	v_cvt_pk_bf16_f32 v144, v144, v145
	v_cvt_pk_bf16_f32 v145, v146, v147
	v_cvt_pk_bf16_f32 v146, v148, v149
	v_lshl_add_u64 v[148:149], v[186:187], 1, s[8:9]
	v_lshlrev_b32_e32 v164, 1, v166
	v_lshl_add_u64 v[148:149], v[148:149], 0, v[164:165]
	v_cvt_pk_bf16_f32 v147, v150, v151
	global_store_dwordx4 v[148:149], v[144:147], off nt
.LBB0_210:
	v_mov_b32_e32 v193, v192
	v_mov_b32_e32 v148, v192
	v_mov_b32_e32 v149, v192
	v_pk_mul_f32 v[144:145], v[118:119], v[148:149]
	v_pk_mul_f32 v[150:151], v[116:117], v[192:193]
	v_pk_mul_f32 v[146:147], v[134:135], v[144:145]
	v_pk_mul_f32 v[144:145], v[132:133], v[150:151]
	v_pk_mul_f32 v[150:151], v[114:115], v[148:149]
	v_pk_mul_f32 v[148:149], v[112:113], v[192:193]
	v_cndmask_b32_e64 v164, 0, 1, s[40:41]
	v_pk_mul_f32 v[148:149], v[128:129], v[148:149]
	v_pk_mul_f32 v[150:151], v[130:131], v[150:151]
	v_cmp_ne_u32_e64 s[8:9], 1, v164
	s_andn2_b64 vcc, exec, s[40:41]
	s_mov_b64 s[40:41], -1
	s_cbranch_vccnz .LBB0_218
	s_and_b64 vcc, exec, s[4:5]
	s_cbranch_vccnz .LBB0_215
	s_add_u32 s40, s46, s0
	v_readlane_b32 s25, v254, 12
	s_addc_u32 s41, s25, s1
	v_lshl_add_u64 v[192:193], v[186:187], 1, s[40:41]
	v_lshlrev_b32_e32 v164, 1, v166
	v_lshl_add_u64 v[192:193], v[192:193], 0, v[164:165]
	v_cvt_pk_bf16_f32 v202, v144, v145
	v_cvt_pk_bf16_f32 v203, v146, v147
	v_cvt_pk_bf16_f32 v204, v148, v149
	v_cvt_pk_bf16_f32 v205, v150, v151
	global_store_dwordx4 v[192:193], v[202:205], off offset:64 nt
	s_and_saveexec_b64 s[40:41], s[10:11]
	s_cbranch_execz .LBB0_214
	s_lshl_b32 s10, s29, 2
	s_add_u32 s10, s84, s10
	s_addc_u32 s11, s85, 0
	v_lshl_add_u64 v[190:191], s[10:11], 0, v[190:191]
	v_lshlrev_b32_e32 v164, 2, v172
	v_lshl_add_u64 v[190:191], v[190:191], 0, v[164:165]
	global_store_dwordx4 v[190:191], v[144:147], off offset:128 nt
	global_store_dwordx4 v[190:191], v[148:151], off offset:144 nt

; __device__ __forceinline__ u32x4 pack8(const f32x4 a, const f32x4 b) { u32x4 w; w.x = cvt_pk_bf16(a[0], a[1]); w.y = cvt_pk_bf16(a[2], a[3]); w.z = cvt_pk_bf16(b[0], b[1]); w.w = cvt_pk_bf16(b[2], b[3]); return w; }
;     __device__ __forceinline__ void operator()(const f32x4 (&acc)[2][2][4][2], const Unit& u, int wr, int wc, int fr, int fq) const {
;     ...
;                         else {
;                             if (!sample) { *(u32x4*)(KG + (size_t)g * MP * 256 + (size_t)Rg + dd) = pack8(v0, v1);
;                                 if (t >= 2048 - keep) { float* p = out + okp + ((size_t)(b * keep + t - (2048 - keep)) * 2) * 256 + hc; *(f32x4*)p = v0; *(f32x4*)(p + 4) = v1; } }
;                             else { float* p = out + oks + ((size_t)(b * keep + keep - 8 + t) * 2) * 256 + hc; *(f32x4*)p = v0; *(f32x4*)(p + 4) = v1; } } } }
.LBB0_215:
	s_andn2_b64 vcc, exec, s[40:41]
	s_cbranch_vccnz .LBB0_217
	s_lshl_b32 s10, s16, 2
	s_add_u32 s10, s84, s10
	s_addc_u32 s11, s85, 0
	v_lshl_add_u64 v[188:189], s[10:11], 0, v[188:189]
	v_lshlrev_b32_e32 v164, 2, v172
	v_lshl_add_u64 v[188:189], v[188:189], 0, v[164:165]
	global_store_dwordx4 v[188:189], v[144:147], off offset:128 nt
	global_store_dwordx4 v[188:189], v[148:151], off offset:144 nt

; __device__ __forceinline__ u32x4 pack8(const f32x4 a, const f32x4 b) { u32x4 w; w.x = cvt_pk_bf16(a[0], a[1]); w.y = cvt_pk_bf16(a[2], a[3]); w.z = cvt_pk_bf16(b[0], b[1]); w.w = cvt_pk_bf16(b[2], b[3]); return w; }
;     __device__ __forceinline__ void operator()(const f32x4 (&acc)[2][2][4][2], const Unit& u, int wr, int wc, int fr, int fq) const {
;     ...
;                     for (int bj = 0; bj < 2; ++bj) { const int hc = wc * 64 + bj * 32 + fq * 8, dd = bj * 32 + fq * 8;
;                         const f32x4 v0 = acc[ai][bj][m][0] * rs * w[bj][0], v1 = acc[ai][bj][m][1] * rs * w[bj][1];
;                         if (isq) { *(u32x4*)(QG + (size_t)g * M * 256 + (size_t)Rg + dd) = pack8(v0, v1); }
.LBB0_218:
	s_andn2_b64 vcc, exec, s[40:41]
	s_cbranch_vccnz .LBB0_220
	s_add_u32 s10, s81, s42
	s_addc_u32 s11, s82, s43
	v_cvt_pk_bf16_f32 v144, v144, v145
	v_cvt_pk_bf16_f32 v145, v146, v147
	v_cvt_pk_bf16_f32 v146, v148, v149
	v_lshl_add_u64 v[148:149], v[186:187], 1, s[10:11]
	v_lshlrev_b32_e32 v164, 1, v166
	v_lshl_add_u64 v[148:149], v[148:149], 0, v[164:165]
	v_cvt_pk_bf16_f32 v147, v150, v151
	global_store_dwordx4 v[148:149], v[144:147], off offset:64 nt

; __device__ __forceinline__ u32x4 pack8(const f32x4 a, const f32x4 b) { u32x4 w; w.x = cvt_pk_bf16(a[0], a[1]); w.y = cvt_pk_bf16(a[2], a[3]); w.z = cvt_pk_bf16(b[0], b[1]); w.w = cvt_pk_bf16(b[2], b[3]); return w; }
; __device__ __forceinline__ float dot4(const f32x4 a, const f32x4 b) { return (a[0] * b[0] + a[1] * b[1]) + (a[2] * b[2] + a[3] * b[3]); }
;     __device__ __forceinline__ void operator()(const f32x4 (&acc)[2][2][4][2], const Unit& u, int wr, int wc, int fr, int fq) const {
;     ...
;                 for (int m = 0; m < 4; ++m) { const int row = rbase + ai * 128 + m * 16;
;                     float ss = 0.f;
; #pragma unroll
;                     for (int bj = 0; bj < 2; ++bj)
; #pragma unroll
;                         for (int n = 0; n < 2; ++n) ss += dot4(acc[ai][bj][m][n], acc[ai][bj][m][n]);
;                     ss += __shfl_xor(ss, 16); ss += __shfl_xor(ss, 32);
;                     float rs = __builtin_amdgcn_rsqf(ss * (1.0f / 64.0f) + EPS); if (isq) rs *= QSCALE;
;                     int b, t, Rg;
;                     if (!sample) { b = row >> 11; t = row & 2047; Rg = b * 524288 + (t & (dil - 1)) * (L * 256) + (t >> sh) * 64 + wc * (L * 64); } else { const int sr = row - MP; b = sr >> 3; t = sr & 7; Rg = row * 256 + wc * 64; }
; #pragma unroll
;                     for (int bj = 0; bj < 2; ++bj) { const int hc = wc * 64 + bj * 32 + fq * 8, dd = bj * 32 + fq * 8;
;                         const f32x4 v0 = acc[ai][bj][m][0] * rs * w[bj][0], v1 = acc[ai][bj][m][1] * rs * w[bj][1];
;                         if (isq) { *(u32x4*)(QG + (size_t)g * M * 256 + (size_t)Rg + dd) = pack8(v0, v1); }
;                         else {
;                             if (!sample) { *(u32x4*)(KG + (size_t)g * MP * 256 + (size_t)Rg + dd) = pack8(v0, v1);
;                                 if (t >= 2048 - keep) { float* p = out + okp + ((size_t)(b * keep + t - (2048 - keep)) * 2) * 256 + hc; *(f32x4*)p = v0; *(f32x4*)(p + 4) = v1; } }
;                             else { float* p = out + oks + ((size_t)(b * keep + keep - 8 + t) * 2) * 256 + hc; *(f32x4*)p = v0; *(f32x4*)(p + 4) = v1; } } } }
.LBB0_224:
	s_waitcnt lgkmcnt(0)
	v_add_f32_e32 v144, v144, v145
	v_fmamk_f32 v144, v144, 0x3c800000, v195
	v_rsq_f32_e32 v144, v144
	v_cmp_le_i32_e64 s[10:11], s93, v146
	v_lshl_add_u32 v146, v148, s68, v146
	v_ashrrev_i32_e32 v187, 31, v186
	v_mul_f32_e32 v145, 0x3e38aa3b, v144
	v_cndmask_b32_e64 v192, v144, v145, s[6:7]
	v_add_u32_e32 v144, s72, v146
	v_ashrrev_i32_e32 v145, 31, v144
	v_lshlrev_b64 v[190:191], 11, v[144:145]
	v_add_u32_e32 v144, s73, v146
	v_ashrrev_i32_e32 v145, 31, v144
	v_lshlrev_b64 v[188:189], 11, v[144:145]
	v_pk_mul_f32 v[144:145], v[108:109], v[192:193] op_sel_hi:[1,0]
	v_pk_mul_f32 v[146:147], v[110:111], v[192:193] op_sel_hi:[1,0]
	v_pk_mul_f32 v[148:149], v[104:105], v[192:193] op_sel_hi:[1,0]
	v_pk_mul_f32 v[150:151], v[106:107], v[192:193] op_sel_hi:[1,0]
	v_pk_mul_f32 v[146:147], v[142:143], v[146:147]
	v_pk_mul_f32 v[144:145], v[140:141], v[144:145]
	v_pk_mul_f32 v[150:151], v[138:139], v[150:151]
	v_pk_mul_f32 v[148:149], v[136:137], v[148:149]
	s_and_b64 vcc, exec, s[8:9]
	s_mov_b64 s[40:41], -1
	s_cbranch_vccnz .LBB0_232
	s_and_b64 vcc, exec, s[4:5]
	s_cbranch_vccnz .LBB0_229
	s_add_u32 s40, s46, s0
	v_readlane_b32 s25, v254, 12
	s_addc_u32 s41, s25, s1
	v_lshl_add_u64 v[206:207], v[186:187], 1, s[40:41]
	v_lshlrev_b32_e32 v164, 1, v166
	v_lshl_add_u64 v[206:207], v[206:207], 0, v[164:165]
	v_cvt_pk_bf16_f32 v202, v144, v145
	v_cvt_pk_bf16_f32 v203, v146, v147
	v_cvt_pk_bf16_f32 v204, v148, v149
	v_cvt_pk_bf16_f32 v205, v150, v151
	global_store_dwordx4 v[206:207], v[202:205], off nt
	s_and_saveexec_b64 s[40:41], s[10:11]
	s_cbranch_execz .LBB0_228
	s_lshl_b32 s25, s29, 2
	s_add_u32 vcc_lo, s84, s25
	s_addc_u32 vcc_hi, s85, 0
	v_lshl_add_u64 v[202:203], vcc, 0, v[190:191]
	v_lshlrev_b32_e32 v164, 2, v172
	v_lshl_add_u64 v[202:203], v[202:203], 0, v[164:165]
	global_store_dwordx4 v[202:203], v[144:147], off nt
	global_store_dwordx4 v[202:203], v[148:151], off offset:16 nt

; __device__ __forceinline__ u32x4 pack8(const f32x4 a, const f32x4 b) { u32x4 w; w.x = cvt_pk_bf16(a[0], a[1]); w.y = cvt_pk_bf16(a[2], a[3]); w.z = cvt_pk_bf16(b[0], b[1]); w.w = cvt_pk_bf16(b[2], b[3]); return w; }
;     __device__ __forceinline__ void operator()(const f32x4 (&acc)[2][2][4][2], const Unit& u, int wr, int wc, int fr, int fq) const {
;     ...
;                         else {
;                             if (!sample) { *(u32x4*)(KG + (size_t)g * MP * 256 + (size_t)Rg + dd) = pack8(v0, v1);
;                                 if (t >= 2048 - keep) { float* p = out + okp + ((size_t)(b * keep + t - (2048 - keep)) * 2) * 256 + hc; *(f32x4*)p = v0; *(f32x4*)(p + 4) = v1; } }
;                             else { float* p = out + oks + ((size_t)(b * keep + keep - 8 + t) * 2) * 256 + hc; *(f32x4*)p = v0; *(f32x4*)(p + 4) = v1; } } } }
.LBB0_229:
	s_andn2_b64 vcc, exec, s[40:41]
	s_cbranch_vccnz .LBB0_231
	s_lshl_b32 s25, s16, 2
	s_add_u32 s40, s84, s25
	s_addc_u32 s41, s85, 0
	v_lshl_add_u64 v[202:203], s[40:41], 0, v[188:189]
	v_lshlrev_b32_e32 v164, 2, v172
	v_lshl_add_u64 v[202:203], v[202:203], 0, v[164:165]
	global_store_dwordx4 v[202:203], v[144:147], off nt
	global_store_dwordx4 v[202:203], v[148:151], off offset:16 nt

; __device__ __forceinline__ u32x4 pack8(const f32x4 a, const f32x4 b) { u32x4 w; w.x = cvt_pk_bf16(a[0], a[1]); w.y = cvt_pk_bf16(a[2], a[3]); w.z = cvt_pk_bf16(b[0], b[1]); w.w = cvt_pk_bf16(b[2], b[3]); return w; }
;     __device__ __forceinline__ void operator()(const f32x4 (&acc)[2][2][4][2], const Unit& u, int wr, int wc, int fr, int fq) const {
;     ...
;                     for (int bj = 0; bj < 2; ++bj) { const int hc = wc * 64 + bj * 32 + fq * 8, dd = bj * 32 + fq * 8;
;                         const f32x4 v0 = acc[ai][bj][m][0] * rs * w[bj][0], v1 = acc[ai][bj][m][1] * rs * w[bj][1];
;                         if (isq) { *(u32x4*)(QG + (size_t)g * M * 256 + (size_t)Rg + dd) = pack8(v0, v1); }
;                         else {
;                             if (!sample) { *(u32x4*)(KG + (size_t)g * MP * 256 + (size_t)Rg + dd) = pack8(v0, v1);
;                                 if (t >= 2048 - keep) { float* p = out + okp + ((size_t)(b * keep + t - (2048 - keep)) * 2) * 256 + hc; *(f32x4*)p = v0; *(f32x4*)(p + 4) = v1; } }
;                             else { float* p = out + oks + ((size_t)(b * keep + keep - 8 + t) * 2) * 256 + hc; *(f32x4*)p = v0; *(f32x4*)(p + 4) = v1; } } } }
.LBB0_232:
	s_andn2_b64 vcc, exec, s[40:41]
	s_cbranch_vccnz .LBB0_234
	s_add_u32 s40, s81, s42
	s_addc_u32 s41, s82, s43
	v_cvt_pk_bf16_f32 v144, v144, v145
	v_cvt_pk_bf16_f32 v145, v146, v147
	v_cvt_pk_bf16_f32 v146, v148, v149
	v_lshl_add_u64 v[148:149], v[186:187], 1, s[40:41]
	v_lshlrev_b32_e32 v164, 1, v166
	v_lshl_add_u64 v[148:149], v[148:149], 0, v[164:165]
	v_cvt_pk_bf16_f32 v147, v150, v151
	global_store_dwordx4 v[148:149], v[144:147], off nt
.LBB0_234:
	v_mov_b32_e32 v193, v192
	v_mov_b32_e32 v148, v192
	v_mov_b32_e32 v149, v192
	v_pk_mul_f32 v[144:145], v[102:103], v[148:149]
	v_pk_mul_f32 v[150:151], v[100:101], v[192:193]
	v_pk_mul_f32 v[148:149], v[98:99], v[148:149]
	v_pk_mul_f32 v[192:193], v[96:97], v[192:193]
	v_pk_mul_f32 v[146:147], v[134:135], v[144:145]
	v_pk_mul_f32 v[144:145], v[132:133], v[150:151]
	v_pk_mul_f32 v[150:151], v[130:131], v[148:149]
	v_pk_mul_f32 v[148:149], v[128:129], v[192:193]
	s_and_b64 vcc, exec, s[8:9]
	s_mov_b64 s[40:41], -1
	s_cbranch_vccnz .LBB0_242
	s_and_b64 vcc, exec, s[4:5]
	s_cbranch_vccnz .LBB0_239
	s_add_u32 s40, s46, s0
	v_readlane_b32 s25, v254, 12
	s_addc_u32 s41, s25, s1
	v_lshl_add_u64 v[192:193], v[186:187], 1, s[40:41]
	v_lshlrev_b32_e32 v164, 1, v166
	v_lshl_add_u64 v[192:193], v[192:193], 0, v[164:165]
	v_cvt_pk_bf16_f32 v202, v144, v145
	v_cvt_pk_bf16_f32 v203, v146, v147
	v_cvt_pk_bf16_f32 v204, v148, v149
	v_cvt_pk_bf16_f32 v205, v150, v151
	global_store_dwordx4 v[192:193], v[202:205], off offset:64 nt
	s_and_saveexec_b64 s[40:41], s[10:11]
	s_cbranch_execz .LBB0_238
	s_lshl_b32 s10, s29, 2
	s_add_u32 s10, s84, s10
	s_addc_u32 s11, s85, 0
	v_lshl_add_u64 v[190:191], s[10:11], 0, v[190:191]
	v_lshlrev_b32_e32 v164, 2, v172
	v_lshl_add_u64 v[190:191], v[190:191], 0, v[164:165]
	global_store_dwordx4 v[190:191], v[144:147], off offset:128 nt
	global_store_dwordx4 v[190:191], v[148:151], off offset:144 nt

; __device__ __forceinline__ u32x4 pack8(const f32x4 a, const f32x4 b) { u32x4 w; w.x = cvt_pk_bf16(a[0], a[1]); w.y = cvt_pk_bf16(a[2], a[3]); w.z = cvt_pk_bf16(b[0], b[1]); w.w = cvt_pk_bf16(b[2], b[3]); return w; }
; __device__ __forceinline__ float dot4(const f32x4 a, const f32x4 b) { return (a[0] * b[0] + a[1] * b[1]) + (a[2] * b[2] + a[3] * b[3]); }
;     __device__ __forceinline__ void operator()(const f32x4 (&acc)[2][2][4][2], const Unit& u, int wr, int wc, int fr, int fq) const {
;     ...
;                 for (int m = 0; m < 4; ++m) { const int row = rbase + ai * 128 + m * 16;
;                     float ss = 0.f;
; #pragma unroll
;                     for (int bj = 0; bj < 2; ++bj)
; #pragma unroll
;                         for (int n = 0; n < 2; ++n) ss += dot4(acc[ai][bj][m][n], acc[ai][bj][m][n]);
;                     ss += __shfl_xor(ss, 16); ss += __shfl_xor(ss, 32);
;                     float rs = __builtin_amdgcn_rsqf(ss * (1.0f / 64.0f) + EPS); if (isq) rs *= QSCALE;
;                     int b, t, Rg;
;                     if (!sample) { b = row >> 11; t = row & 2047; Rg = b * 524288 + (t & (dil - 1)) * (L * 256) + (t >> sh) * 64 + wc * (L * 64); } else { const int sr = row - MP; b = sr >> 3; t = sr & 7; Rg = row * 256 + wc * 64; }
; #pragma unroll
;                     for (int bj = 0; bj < 2; ++bj) { const int hc = wc * 64 + bj * 32 + fq * 8, dd = bj * 32 + fq * 8;
;                         const f32x4 v0 = acc[ai][bj][m][0] * rs * w[bj][0], v1 = acc[ai][bj][m][1] * rs * w[bj][1];
;                         if (isq) { *(u32x4*)(QG + (size_t)g * M * 256 + (size_t)Rg + dd) = pack8(v0, v1); }
;                         else {
;                             if (!sample) { *(u32x4*)(KG + (size_t)g * MP * 256 + (size_t)Rg + dd) = pack8(v0, v1);
;                                 if (t >= 2048 - keep) { float* p = out + okp + ((size_t)(b * keep + t - (2048 - keep)) * 2) * 256 + hc; *(f32x4*)p = v0; *(f32x4*)(p + 4) = v1; } }
;                             else { float* p = out + oks + ((size_t)(b * keep + keep - 8 + t) * 2) * 256 + hc; *(f32x4*)p = v0; *(f32x4*)(p + 4) = v1; } } } }
.LBB0_248:
	s_waitcnt lgkmcnt(0)
	v_add_f32_e32 v144, v144, v145
	v_fmamk_f32 v144, v144, 0x3c800000, v195
	v_rsq_f32_e32 v144, v144
	v_cmp_le_i32_e64 s[10:11], s93, v146
	v_lshl_add_u32 v146, v148, s68, v146
	v_ashrrev_i32_e32 v187, 31, v186
	v_mul_f32_e32 v145, 0x3e38aa3b, v144
	v_cndmask_b32_e64 v192, v144, v145, s[6:7]
	v_add_u32_e32 v144, s72, v146
	v_ashrrev_i32_e32 v145, 31, v144
	v_lshlrev_b64 v[190:191], 11, v[144:145]
	v_add_u32_e32 v144, s73, v146
	v_ashrrev_i32_e32 v145, 31, v144
	v_lshlrev_b64 v[188:189], 11, v[144:145]
	v_pk_mul_f32 v[144:145], v[92:93], v[192:193] op_sel_hi:[1,0]
	v_pk_mul_f32 v[146:147], v[94:95], v[192:193] op_sel_hi:[1,0]
	v_pk_mul_f32 v[148:149], v[88:89], v[192:193] op_sel_hi:[1,0]
	v_pk_mul_f32 v[150:151], v[90:91], v[192:193] op_sel_hi:[1,0]
	v_pk_mul_f32 v[146:147], v[142:143], v[146:147]
	v_pk_mul_f32 v[144:145], v[140:141], v[144:145]
	v_pk_mul_f32 v[150:151], v[138:139], v[150:151]
	v_pk_mul_f32 v[148:149], v[136:137], v[148:149]
	s_and_b64 vcc, exec, s[8:9]
	s_mov_b64 s[40:41], -1
	s_cbranch_vccnz .LBB0_256
	s_and_b64 vcc, exec, s[4:5]
	s_cbranch_vccnz .LBB0_253
	s_add_u32 s40, s46, s0
	v_readlane_b32 s25, v254, 12
	s_addc_u32 s41, s25, s1
	v_lshl_add_u64 v[206:207], v[186:187], 1, s[40:41]
	v_lshlrev_b32_e32 v164, 1, v166
	v_lshl_add_u64 v[206:207], v[206:207], 0, v[164:165]
	v_cvt_pk_bf16_f32 v202, v144, v145
	v_cvt_pk_bf16_f32 v203, v146, v147
	v_cvt_pk_bf16_f32 v204, v148, v149
	v_cvt_pk_bf16_f32 v205, v150, v151
	global_store_dwordx4 v[206:207], v[202:205], off nt
	s_and_saveexec_b64 s[40:41], s[10:11]
	s_cbranch_execz .LBB0_252
	s_lshl_b32 s25, s29, 2
	s_add_u32 vcc_lo, s84, s25
	s_addc_u32 vcc_hi, s85, 0
	v_lshl_add_u64 v[202:203], vcc, 0, v[190:191]
	v_lshlrev_b32_e32 v164, 2, v172
	v_lshl_add_u64 v[202:203], v[202:203], 0, v[164:165]
	global_store_dwordx4 v[202:203], v[144:147], off nt
	global_store_dwordx4 v[202:203], v[148:151], off offset:16 nt

; __device__ __forceinline__ u32x4 pack8(const f32x4 a, const f32x4 b) { u32x4 w; w.x = cvt_pk_bf16(a[0], a[1]); w.y = cvt_pk_bf16(a[2], a[3]); w.z = cvt_pk_bf16(b[0], b[1]); w.w = cvt_pk_bf16(b[2], b[3]); return w; }
;     __device__ __forceinline__ void operator()(const f32x4 (&acc)[2][2][4][2], const Unit& u, int wr, int wc, int fr, int fq) const {
;     ...
;                     for (int bj = 0; bj < 2; ++bj) { const int hc = wc * 64 + bj * 32 + fq * 8, dd = bj * 32 + fq * 8;
;                         const f32x4 v0 = acc[ai][bj][m][0] * rs * w[bj][0], v1 = acc[ai][bj][m][1] * rs * w[bj][1];
;                         if (isq) { *(u32x4*)(QG + (size_t)g * M * 256 + (size_t)Rg + dd) = pack8(v0, v1); }
;                         else {
;                             if (!sample) { *(u32x4*)(KG + (size_t)g * MP * 256 + (size_t)Rg + dd) = pack8(v0, v1);
;                                 if (t >= 2048 - keep) { float* p = out + okp + ((size_t)(b * keep + t - (2048 - keep)) * 2) * 256 + hc; *(f32x4*)p = v0; *(f32x4*)(p + 4) = v1; } }
;                             else { float* p = out + oks + ((size_t)(b * keep + keep - 8 + t) * 2) * 256 + hc; *(f32x4*)p = v0; *(f32x4*)(p + 4) = v1; } } } }
.LBB0_258:
	v_mov_b32_e32 v193, v192
	v_mov_b32_e32 v148, v192
	v_mov_b32_e32 v149, v192
	v_pk_mul_f32 v[144:145], v[86:87], v[148:149]
	v_pk_mul_f32 v[150:151], v[84:85], v[192:193]
	v_pk_mul_f32 v[148:149], v[82:83], v[148:149]
	v_pk_mul_f32 v[192:193], v[80:81], v[192:193]
	v_pk_mul_f32 v[146:147], v[134:135], v[144:145]
	v_pk_mul_f32 v[144:145], v[132:133], v[150:151]
	v_pk_mul_f32 v[150:151], v[130:131], v[148:149]
	v_pk_mul_f32 v[148:149], v[128:129], v[192:193]
	s_and_b64 vcc, exec, s[8:9]
	s_mov_b64 s[40:41], -1
	s_cbranch_vccnz .LBB0_266
	s_and_b64 vcc, exec, s[4:5]
	s_cbranch_vccnz .LBB0_263
	s_add_u32 s40, s46, s0
	v_readlane_b32 s25, v254, 12
	s_addc_u32 s41, s25, s1
	v_lshl_add_u64 v[192:193], v[186:187], 1, s[40:41]
	v_lshlrev_b32_e32 v164, 1, v166
	v_lshl_add_u64 v[192:193], v[192:193], 0, v[164:165]
	v_cvt_pk_bf16_f32 v202, v144, v145
	v_cvt_pk_bf16_f32 v203, v146, v147
	v_cvt_pk_bf16_f32 v204, v148, v149
	v_cvt_pk_bf16_f32 v205, v150, v151
	global_store_dwordx4 v[192:193], v[202:205], off offset:64 nt
	s_and_saveexec_b64 s[40:41], s[10:11]
	s_cbranch_execz .LBB0_262
	s_lshl_b32 s10, s29, 2
	s_add_u32 s10, s84, s10
	s_addc_u32 s11, s85, 0
	v_lshl_add_u64 v[190:191], s[10:11], 0, v[190:191]
	v_lshlrev_b32_e32 v164, 2, v172
	v_lshl_add_u64 v[190:191], v[190:191], 0, v[164:165]
	global_store_dwordx4 v[190:191], v[144:147], off offset:128 nt
	global_store_dwordx4 v[190:191], v[148:151], off offset:144 nt

; __device__ __forceinline__ u32x4 pack8(const f32x4 a, const f32x4 b) { u32x4 w; w.x = cvt_pk_bf16(a[0], a[1]); w.y = cvt_pk_bf16(a[2], a[3]); w.z = cvt_pk_bf16(b[0], b[1]); w.w = cvt_pk_bf16(b[2], b[3]); return w; }
; __device__ __forceinline__ float dot4(const f32x4 a, const f32x4 b) { return (a[0] * b[0] + a[1] * b[1]) + (a[2] * b[2] + a[3] * b[3]); }
;     __device__ __forceinline__ void operator()(const f32x4 (&acc)[2][2][4][2], const Unit& u, int wr, int wc, int fr, int fq) const {
;     ...
;                 for (int m = 0; m < 4; ++m) { const int row = rbase + ai * 128 + m * 16;
;                     float ss = 0.f;
; #pragma unroll
;                     for (int bj = 0; bj < 2; ++bj)
; #pragma unroll
;                         for (int n = 0; n < 2; ++n) ss += dot4(acc[ai][bj][m][n], acc[ai][bj][m][n]);
;                     ss += __shfl_xor(ss, 16); ss += __shfl_xor(ss, 32);
;                     float rs = __builtin_amdgcn_rsqf(ss * (1.0f / 64.0f) + EPS); if (isq) rs *= QSCALE;
;                     int b, t, Rg;
;                     if (!sample) { b = row >> 11; t = row & 2047; Rg = b * 524288 + (t & (dil - 1)) * (L * 256) + (t >> sh) * 64 + wc * (L * 64); } else { const int sr = row - MP; b = sr >> 3; t = sr & 7; Rg = row * 256 + wc * 64; }
; #pragma unroll
;                     for (int bj = 0; bj < 2; ++bj) { const int hc = wc * 64 + bj * 32 + fq * 8, dd = bj * 32 + fq * 8;
;                         const f32x4 v0 = acc[ai][bj][m][0] * rs * w[bj][0], v1 = acc[ai][bj][m][1] * rs * w[bj][1];
;                         if (isq) { *(u32x4*)(QG + (size_t)g * M * 256 + (size_t)Rg + dd) = pack8(v0, v1); }
;                         else {
;                             if (!sample) { *(u32x4*)(KG + (size_t)g * MP * 256 + (size_t)Rg + dd) = pack8(v0, v1);
;                                 if (t >= 2048 - keep) { float* p = out + okp + ((size_t)(b * keep + t - (2048 - keep)) * 2) * 256 + hc; *(f32x4*)p = v0; *(f32x4*)(p + 4) = v1; } }
;                             else { float* p = out + oks + ((size_t)(b * keep + keep - 8 + t) * 2) * 256 + hc; *(f32x4*)p = v0; *(f32x4*)(p + 4) = v1; } } } }
.LBB0_272:
	s_waitcnt lgkmcnt(0)
	v_add_f32_e32 v144, v144, v145
	v_fmamk_f32 v144, v144, 0x3c800000, v195
	v_rsq_f32_e32 v144, v144
	v_cmp_le_i32_e64 s[10:11], s93, v146
	v_lshl_add_u32 v146, v148, s68, v146
	v_ashrrev_i32_e32 v187, 31, v186
	v_mul_f32_e32 v145, 0x3e38aa3b, v144
	v_cndmask_b32_e64 v192, v144, v145, s[6:7]
	v_add_u32_e32 v144, s72, v146
	v_ashrrev_i32_e32 v145, 31, v144
	v_lshlrev_b64 v[190:191], 11, v[144:145]
	v_add_u32_e32 v144, s73, v146
	v_ashrrev_i32_e32 v145, 31, v144
	v_lshlrev_b64 v[188:189], 11, v[144:145]
	v_pk_mul_f32 v[144:145], v[76:77], v[192:193] op_sel_hi:[1,0]
	v_pk_mul_f32 v[146:147], v[78:79], v[192:193] op_sel_hi:[1,0]
	v_pk_mul_f32 v[148:149], v[72:73], v[192:193] op_sel_hi:[1,0]
	v_pk_mul_f32 v[150:151], v[74:75], v[192:193] op_sel_hi:[1,0]
	v_pk_mul_f32 v[146:147], v[142:143], v[146:147]
	v_pk_mul_f32 v[144:145], v[140:141], v[144:145]
	v_pk_mul_f32 v[150:151], v[138:139], v[150:151]
	v_pk_mul_f32 v[148:149], v[136:137], v[148:149]
	s_and_b64 vcc, exec, s[8:9]
	s_mov_b64 s[40:41], -1
	s_cbranch_vccnz .LBB0_280
	s_and_b64 vcc, exec, s[4:5]
	s_cbranch_vccnz .LBB0_277
	s_add_u32 s24, s46, s0
	v_readlane_b32 s25, v254, 12
	s_addc_u32 s25, s25, s1
	v_lshlrev_b32_e32 v164, 1, v166
	v_lshl_add_u64 v[206:207], v[186:187], 1, s[24:25]
	v_lshl_add_u64 v[206:207], v[206:207], 0, v[164:165]
	v_cvt_pk_bf16_f32 v202, v144, v145
	v_cvt_pk_bf16_f32 v203, v146, v147
	v_cvt_pk_bf16_f32 v204, v148, v149
	v_cvt_pk_bf16_f32 v205, v150, v151
	global_store_dwordx4 v[206:207], v[202:205], off nt
	s_and_saveexec_b64 s[40:41], s[10:11]
	s_cbranch_execz .LBB0_276
	s_lshl_b32 s24, s29, 2
	s_add_u32 s24, s84, s24
	s_addc_u32 s25, s85, 0
	v_lshl_add_u64 v[202:203], s[24:25], 0, v[190:191]
	v_lshlrev_b32_e32 v164, 2, v172
	v_lshl_add_u64 v[202:203], v[202:203], 0, v[164:165]
	global_store_dwordx4 v[202:203], v[144:147], off nt
	global_store_dwordx4 v[202:203], v[148:151], off offset:16 nt

; __device__ __forceinline__ u32x4 pack8(const f32x4 a, const f32x4 b) { u32x4 w; w.x = cvt_pk_bf16(a[0], a[1]); w.y = cvt_pk_bf16(a[2], a[3]); w.z = cvt_pk_bf16(b[0], b[1]); w.w = cvt_pk_bf16(b[2], b[3]); return w; }
;     __device__ __forceinline__ void operator()(const f32x4 (&acc)[2][2][4][2], const Unit& u, int wr, int wc, int fr, int fq) const {
;     ...
;                         else {
;                             if (!sample) { *(u32x4*)(KG + (size_t)g * MP * 256 + (size_t)Rg + dd) = pack8(v0, v1);
;                                 if (t >= 2048 - keep) { float* p = out + okp + ((size_t)(b * keep + t - (2048 - keep)) * 2) * 256 + hc; *(f32x4*)p = v0; *(f32x4*)(p + 4) = v1; } }
;                             else { float* p = out + oks + ((size_t)(b * keep + keep - 8 + t) * 2) * 256 + hc; *(f32x4*)p = v0; *(f32x4*)(p + 4) = v1; } } } }
.LBB0_277:
	s_andn2_b64 vcc, exec, s[40:41]
	s_cbranch_vccnz .LBB0_279
	s_lshl_b32 s24, s16, 2
	s_add_u32 s24, s84, s24
	s_addc_u32 s25, s85, 0
	v_lshl_add_u64 v[202:203], s[24:25], 0, v[188:189]
	v_lshlrev_b32_e32 v164, 2, v172
	v_lshl_add_u64 v[202:203], v[202:203], 0, v[164:165]
	global_store_dwordx4 v[202:203], v[144:147], off nt
	global_store_dwordx4 v[202:203], v[148:151], off offset:16 nt

; __device__ __forceinline__ u32x4 pack8(const f32x4 a, const f32x4 b) { u32x4 w; w.x = cvt_pk_bf16(a[0], a[1]); w.y = cvt_pk_bf16(a[2], a[3]); w.z = cvt_pk_bf16(b[0], b[1]); w.w = cvt_pk_bf16(b[2], b[3]); return w; }
;     __device__ __forceinline__ void operator()(const f32x4 (&acc)[2][2][4][2], const Unit& u, int wr, int wc, int fr, int fq) const {
;     ...
;                     for (int bj = 0; bj < 2; ++bj) { const int hc = wc * 64 + bj * 32 + fq * 8, dd = bj * 32 + fq * 8;
;                         const f32x4 v0 = acc[ai][bj][m][0] * rs * w[bj][0], v1 = acc[ai][bj][m][1] * rs * w[bj][1];
;                         if (isq) { *(u32x4*)(QG + (size_t)g * M * 256 + (size_t)Rg + dd) = pack8(v0, v1); }
;                         else {
;                             if (!sample) { *(u32x4*)(KG + (size_t)g * MP * 256 + (size_t)Rg + dd) = pack8(v0, v1);
;                                 if (t >= 2048 - keep) { float* p = out + okp + ((size_t)(b * keep + t - (2048 - keep)) * 2) * 256 + hc; *(f32x4*)p = v0; *(f32x4*)(p + 4) = v1; } }
;                             else { float* p = out + oks + ((size_t)(b * keep + keep - 8 + t) * 2) * 256 + hc; *(f32x4*)p = v0; *(f32x4*)(p + 4) = v1; } } } }
.LBB0_280:
	s_andn2_b64 vcc, exec, s[40:41]
	s_cbranch_vccnz .LBB0_282
	s_add_u32 s24, s81, s42
	s_addc_u32 s25, s82, s43
	v_cvt_pk_bf16_f32 v144, v144, v145
	v_cvt_pk_bf16_f32 v145, v146, v147
	v_cvt_pk_bf16_f32 v146, v148, v149
	v_lshl_add_u64 v[148:149], v[186:187], 1, s[24:25]
	v_lshlrev_b32_e32 v164, 1, v166
	v_lshl_add_u64 v[148:149], v[148:149], 0, v[164:165]
	v_cvt_pk_bf16_f32 v147, v150, v151
	global_store_dwordx4 v[148:149], v[144:147], off nt
.LBB0_282:
	v_mov_b32_e32 v193, v192
	v_mov_b32_e32 v148, v192
	v_mov_b32_e32 v149, v192
	v_pk_mul_f32 v[144:145], v[70:71], v[148:149]
	v_pk_mul_f32 v[150:151], v[68:69], v[192:193]
	v_pk_mul_f32 v[148:149], v[66:67], v[148:149]
	v_pk_mul_f32 v[192:193], v[64:65], v[192:193]
	v_pk_mul_f32 v[146:147], v[134:135], v[144:145]
	v_pk_mul_f32 v[144:145], v[132:133], v[150:151]
	v_pk_mul_f32 v[150:151], v[130:131], v[148:149]
	v_pk_mul_f32 v[148:149], v[128:129], v[192:193]
	s_and_b64 vcc, exec, s[8:9]
	s_mov_b64 s[40:41], -1
	s_cbranch_vccnz .LBB0_290
	s_and_b64 vcc, exec, s[4:5]
	s_cbranch_vccnz .LBB0_287
	s_add_u32 s24, s46, s0
	v_readlane_b32 s25, v254, 12
	s_addc_u32 s25, s25, s1
	v_lshlrev_b32_e32 v164, 1, v166
	v_lshl_add_u64 v[192:193], v[186:187], 1, s[24:25]
	v_lshl_add_u64 v[192:193], v[192:193], 0, v[164:165]
	v_cvt_pk_bf16_f32 v202, v144, v145
	v_cvt_pk_bf16_f32 v203, v146, v147
	v_cvt_pk_bf16_f32 v204, v148, v149
	v_cvt_pk_bf16_f32 v205, v150, v151
	global_store_dwordx4 v[192:193], v[202:205], off offset:64 nt
	s_and_saveexec_b64 s[40:41], s[10:11]
	s_cbranch_execz .LBB0_286
	s_lshl_b32 s10, s29, 2
	s_add_u32 s10, s84, s10
	s_addc_u32 s11, s85, 0
	v_lshl_add_u64 v[190:191], s[10:11], 0, v[190:191]
	v_lshlrev_b32_e32 v164, 2, v172
	v_lshl_add_u64 v[190:191], v[190:191], 0, v[164:165]
	global_store_dwordx4 v[190:191], v[144:147], off offset:128 nt
	global_store_dwordx4 v[190:191], v[148:151], off offset:144 nt

; __device__ __forceinline__ u32x4 pack8(const f32x4 a, const f32x4 b) { u32x4 w; w.x = cvt_pk_bf16(a[0], a[1]); w.y = cvt_pk_bf16(a[2], a[3]); w.z = cvt_pk_bf16(b[0], b[1]); w.w = cvt_pk_bf16(b[2], b[3]); return w; }
; __device__ __forceinline__ float dot4(const f32x4 a, const f32x4 b) { return (a[0] * b[0] + a[1] * b[1]) + (a[2] * b[2] + a[3] * b[3]); }
;     __device__ __forceinline__ void operator()(const f32x4 (&acc)[2][2][4][2], const Unit& u, int wr, int wc, int fr, int fq) const {
;     ...
;                 for (int m = 0; m < 4; ++m) { const int row = rbase + ai * 128 + m * 16;
;                     float ss = 0.f;
; #pragma unroll
;                     for (int bj = 0; bj < 2; ++bj)
; #pragma unroll
;                         for (int n = 0; n < 2; ++n) ss += dot4(acc[ai][bj][m][n], acc[ai][bj][m][n]);
;                     ss += __shfl_xor(ss, 16); ss += __shfl_xor(ss, 32);
;                     float rs = __builtin_amdgcn_rsqf(ss * (1.0f / 64.0f) + EPS); if (isq) rs *= QSCALE;
;                     int b, t, Rg;
;                     if (!sample) { b = row >> 11; t = row & 2047; Rg = b * 524288 + (t & (dil - 1)) * (L * 256) + (t >> sh) * 64 + wc * (L * 64); } else { const int sr = row - MP; b = sr >> 3; t = sr & 7; Rg = row * 256 + wc * 64; }
; #pragma unroll
;                     for (int bj = 0; bj < 2; ++bj) { const int hc = wc * 64 + bj * 32 + fq * 8, dd = bj * 32 + fq * 8;
;                         const f32x4 v0 = acc[ai][bj][m][0] * rs * w[bj][0], v1 = acc[ai][bj][m][1] * rs * w[bj][1];
;                         if (isq) { *(u32x4*)(QG + (size_t)g * M * 256 + (size_t)Rg + dd) = pack8(v0, v1); }
;                         else {
;                             if (!sample) { *(u32x4*)(KG + (size_t)g * MP * 256 + (size_t)Rg + dd) = pack8(v0, v1);
;                                 if (t >= 2048 - keep) { float* p = out + okp + ((size_t)(b * keep + t - (2048 - keep)) * 2) * 256 + hc; *(f32x4*)p = v0; *(f32x4*)(p + 4) = v1; } }
;                             else { float* p = out + oks + ((size_t)(b * keep + keep - 8 + t) * 2) * 256 + hc; *(f32x4*)p = v0; *(f32x4*)(p + 4) = v1; } } } }
.LBB0_296:
	s_waitcnt lgkmcnt(0)
	v_add_f32_e32 v144, v144, v145
	v_fmamk_f32 v144, v144, 0x3c800000, v195
	v_rsq_f32_e32 v144, v144
	v_cmp_le_i32_e64 s[10:11], s93, v146
	v_lshl_add_u32 v146, v148, s68, v146
	v_ashrrev_i32_e32 v187, 31, v186
	v_mul_f32_e32 v145, 0x3e38aa3b, v144
	v_cndmask_b32_e64 v192, v144, v145, s[6:7]
	v_add_u32_e32 v144, s72, v146
	v_ashrrev_i32_e32 v145, 31, v144
	v_lshlrev_b64 v[190:191], 11, v[144:145]
	v_add_u32_e32 v144, s73, v146
	v_ashrrev_i32_e32 v145, 31, v144
	v_lshlrev_b64 v[188:189], 11, v[144:145]
	v_pk_mul_f32 v[144:145], v[60:61], v[192:193] op_sel_hi:[1,0]
	v_pk_mul_f32 v[146:147], v[62:63], v[192:193] op_sel_hi:[1,0]
	v_pk_mul_f32 v[148:149], v[56:57], v[192:193] op_sel_hi:[1,0]
	v_pk_mul_f32 v[150:151], v[58:59], v[192:193] op_sel_hi:[1,0]
	v_pk_mul_f32 v[146:147], v[142:143], v[146:147]
	v_pk_mul_f32 v[144:145], v[140:141], v[144:145]
	v_pk_mul_f32 v[150:151], v[138:139], v[150:151]
	v_pk_mul_f32 v[148:149], v[136:137], v[148:149]
	s_and_b64 vcc, exec, s[8:9]
	s_mov_b64 s[40:41], -1
	s_cbranch_vccnz .LBB0_304
	s_and_b64 vcc, exec, s[4:5]
	s_cbranch_vccnz .LBB0_301
	s_add_u32 s24, s46, s0
	v_readlane_b32 s25, v254, 12
	s_addc_u32 s25, s25, s1
	v_lshlrev_b32_e32 v164, 1, v166
	v_lshl_add_u64 v[208:209], v[186:187], 1, s[24:25]
	v_lshl_add_u64 v[208:209], v[208:209], 0, v[164:165]
	v_cvt_pk_bf16_f32 v204, v144, v145
	v_cvt_pk_bf16_f32 v205, v146, v147
	v_cvt_pk_bf16_f32 v206, v148, v149
	v_cvt_pk_bf16_f32 v207, v150, v151
	global_store_dwordx4 v[208:209], v[204:207], off nt
	s_and_saveexec_b64 s[40:41], s[10:11]
	s_cbranch_execz .LBB0_300
	s_lshl_b32 s24, s29, 2
	s_add_u32 s24, s84, s24
	s_addc_u32 s25, s85, 0
	v_lshl_add_u64 v[204:205], s[24:25], 0, v[190:191]
	v_lshlrev_b32_e32 v164, 2, v172
	v_lshl_add_u64 v[204:205], v[204:205], 0, v[164:165]
	global_store_dwordx4 v[204:205], v[144:147], off nt
	global_store_dwordx4 v[204:205], v[148:151], off offset:16 nt

; __device__ __forceinline__ u32x4 pack8(const f32x4 a, const f32x4 b) { u32x4 w; w.x = cvt_pk_bf16(a[0], a[1]); w.y = cvt_pk_bf16(a[2], a[3]); w.z = cvt_pk_bf16(b[0], b[1]); w.w = cvt_pk_bf16(b[2], b[3]); return w; }
;     __device__ __forceinline__ void operator()(const f32x4 (&acc)[2][2][4][2], const Unit& u, int wr, int wc, int fr, int fq) const {
;     ...
;                         else {
;                             if (!sample) { *(u32x4*)(KG + (size_t)g * MP * 256 + (size_t)Rg + dd) = pack8(v0, v1);
;                                 if (t >= 2048 - keep) { float* p = out + okp + ((size_t)(b * keep + t - (2048 - keep)) * 2) * 256 + hc; *(f32x4*)p = v0; *(f32x4*)(p + 4) = v1; } }
;                             else { float* p = out + oks + ((size_t)(b * keep + keep - 8 + t) * 2) * 256 + hc; *(f32x4*)p = v0; *(f32x4*)(p + 4) = v1; } } } }
.LBB0_301:
	s_andn2_b64 vcc, exec, s[40:41]
	s_cbranch_vccnz .LBB0_303
	s_lshl_b32 s24, s16, 2
	s_add_u32 s24, s84, s24
	s_addc_u32 s25, s85, 0
	v_lshl_add_u64 v[204:205], s[24:25], 0, v[188:189]
	v_lshlrev_b32_e32 v164, 2, v172
	v_lshl_add_u64 v[204:205], v[204:205], 0, v[164:165]
	global_store_dwordx4 v[204:205], v[144:147], off nt
	global_store_dwordx4 v[204:205], v[148:151], off offset:16 nt

; __device__ __forceinline__ u32x4 pack8(const f32x4 a, const f32x4 b) { u32x4 w; w.x = cvt_pk_bf16(a[0], a[1]); w.y = cvt_pk_bf16(a[2], a[3]); w.z = cvt_pk_bf16(b[0], b[1]); w.w = cvt_pk_bf16(b[2], b[3]); return w; }
;     __device__ __forceinline__ void operator()(const f32x4 (&acc)[2][2][4][2], const Unit& u, int wr, int wc, int fr, int fq) const {
;     ...
;                     for (int bj = 0; bj < 2; ++bj) { const int hc = wc * 64 + bj * 32 + fq * 8, dd = bj * 32 + fq * 8;
;                         const f32x4 v0 = acc[ai][bj][m][0] * rs * w[bj][0], v1 = acc[ai][bj][m][1] * rs * w[bj][1];
;                         if (isq) { *(u32x4*)(QG + (size_t)g * M * 256 + (size_t)Rg + dd) = pack8(v0, v1); }
;                         else {
;                             if (!sample) { *(u32x4*)(KG + (size_t)g * MP * 256 + (size_t)Rg + dd) = pack8(v0, v1);
;                                 if (t >= 2048 - keep) { float* p = out + okp + ((size_t)(b * keep + t - (2048 - keep)) * 2) * 256 + hc; *(f32x4*)p = v0; *(f32x4*)(p + 4) = v1; } }
;                             else { float* p = out + oks + ((size_t)(b * keep + keep - 8 + t) * 2) * 256 + hc; *(f32x4*)p = v0; *(f32x4*)(p + 4) = v1; } } } }
.LBB0_306:
	v_mov_b32_e32 v193, v192
	v_mov_b32_e32 v148, v192
	v_mov_b32_e32 v149, v192
	v_pk_mul_f32 v[144:145], v[54:55], v[148:149]
	v_pk_mul_f32 v[150:151], v[52:53], v[192:193]
	v_pk_mul_f32 v[148:149], v[50:51], v[148:149]
	v_pk_mul_f32 v[192:193], v[48:49], v[192:193]
	v_pk_mul_f32 v[146:147], v[134:135], v[144:145]
	v_pk_mul_f32 v[144:145], v[132:133], v[150:151]
	v_pk_mul_f32 v[150:151], v[130:131], v[148:149]
	v_pk_mul_f32 v[148:149], v[128:129], v[192:193]
	s_and_b64 vcc, exec, s[8:9]
	s_mov_b64 s[40:41], -1
	s_cbranch_vccnz .LBB0_314
	s_and_b64 vcc, exec, s[4:5]
	s_cbranch_vccnz .LBB0_311
	s_add_u32 s24, s46, s0
	v_readlane_b32 s25, v254, 12
	s_addc_u32 s25, s25, s1
	v_lshlrev_b32_e32 v164, 1, v166
	v_lshl_add_u64 v[192:193], v[186:187], 1, s[24:25]
	v_lshl_add_u64 v[192:193], v[192:193], 0, v[164:165]
	v_cvt_pk_bf16_f32 v204, v144, v145
	v_cvt_pk_bf16_f32 v205, v146, v147
	v_cvt_pk_bf16_f32 v206, v148, v149
	v_cvt_pk_bf16_f32 v207, v150, v151
	global_store_dwordx4 v[192:193], v[204:207], off offset:64 nt
	s_and_saveexec_b64 s[40:41], s[10:11]
	s_cbranch_execz .LBB0_310
	s_lshl_b32 s10, s29, 2
	s_add_u32 s10, s84, s10
	s_addc_u32 s11, s85, 0
	v_lshl_add_u64 v[190:191], s[10:11], 0, v[190:191]
	v_lshlrev_b32_e32 v164, 2, v172
	v_lshl_add_u64 v[190:191], v[190:191], 0, v[164:165]
	global_store_dwordx4 v[190:191], v[144:147], off offset:128 nt
	global_store_dwordx4 v[190:191], v[148:151], off offset:144 nt

; __device__ __forceinline__ u32x4 pack8(const f32x4 a, const f32x4 b) { u32x4 w; w.x = cvt_pk_bf16(a[0], a[1]); w.y = cvt_pk_bf16(a[2], a[3]); w.z = cvt_pk_bf16(b[0], b[1]); w.w = cvt_pk_bf16(b[2], b[3]); return w; }
; __device__ __forceinline__ float dot4(const f32x4 a, const f32x4 b) { return (a[0] * b[0] + a[1] * b[1]) + (a[2] * b[2] + a[3] * b[3]); }
;     __device__ __forceinline__ void operator()(const f32x4 (&acc)[2][2][4][2], const Unit& u, int wr, int wc, int fr, int fq) const {
;     ...
;                 for (int m = 0; m < 4; ++m) { const int row = rbase + ai * 128 + m * 16;
;                     float ss = 0.f;
; #pragma unroll
;                     for (int bj = 0; bj < 2; ++bj)
; #pragma unroll
;                         for (int n = 0; n < 2; ++n) ss += dot4(acc[ai][bj][m][n], acc[ai][bj][m][n]);
;                     ss += __shfl_xor(ss, 16); ss += __shfl_xor(ss, 32);
;                     float rs = __builtin_amdgcn_rsqf(ss * (1.0f / 64.0f) + EPS); if (isq) rs *= QSCALE;
;                     int b, t, Rg;
;                     if (!sample) { b = row >> 11; t = row & 2047; Rg = b * 524288 + (t & (dil - 1)) * (L * 256) + (t >> sh) * 64 + wc * (L * 64); } else { const int sr = row - MP; b = sr >> 3; t = sr & 7; Rg = row * 256 + wc * 64; }
; #pragma unroll
;                     for (int bj = 0; bj < 2; ++bj) { const int hc = wc * 64 + bj * 32 + fq * 8, dd = bj * 32 + fq * 8;
;                         const f32x4 v0 = acc[ai][bj][m][0] * rs * w[bj][0], v1 = acc[ai][bj][m][1] * rs * w[bj][1];
;                         if (isq) { *(u32x4*)(QG + (size_t)g * M * 256 + (size_t)Rg + dd) = pack8(v0, v1); }
;                         else {
;                             if (!sample) { *(u32x4*)(KG + (size_t)g * MP * 256 + (size_t)Rg + dd) = pack8(v0, v1);
;                                 if (t >= 2048 - keep) { float* p = out + okp + ((size_t)(b * keep + t - (2048 - keep)) * 2) * 256 + hc; *(f32x4*)p = v0; *(f32x4*)(p + 4) = v1; } }
;                             else { float* p = out + oks + ((size_t)(b * keep + keep - 8 + t) * 2) * 256 + hc; *(f32x4*)p = v0; *(f32x4*)(p + 4) = v1; } } } }
.LBB0_320:
	s_waitcnt lgkmcnt(0)
	v_add_f32_e32 v144, v144, v145
	v_fmamk_f32 v144, v144, 0x3c800000, v195
	v_rsq_f32_e32 v144, v144
	v_cmp_le_i32_e64 s[10:11], s93, v146
	v_lshl_add_u32 v146, v148, s68, v146
	v_ashrrev_i32_e32 v187, 31, v186
	v_mul_f32_e32 v145, 0x3e38aa3b, v144
	v_cndmask_b32_e64 v192, v144, v145, s[6:7]
	v_add_u32_e32 v144, s72, v146
	v_ashrrev_i32_e32 v145, 31, v144
	v_lshlrev_b64 v[190:191], 11, v[144:145]
	v_add_u32_e32 v144, s73, v146
	v_ashrrev_i32_e32 v145, 31, v144
	v_lshlrev_b64 v[188:189], 11, v[144:145]
	v_pk_mul_f32 v[144:145], v[44:45], v[192:193] op_sel_hi:[1,0]
	v_pk_mul_f32 v[146:147], v[46:47], v[192:193] op_sel_hi:[1,0]
	v_pk_mul_f32 v[148:149], v[40:41], v[192:193] op_sel_hi:[1,0]
	v_pk_mul_f32 v[150:151], v[42:43], v[192:193] op_sel_hi:[1,0]
	v_pk_mul_f32 v[146:147], v[142:143], v[146:147]
	v_pk_mul_f32 v[144:145], v[140:141], v[144:145]
	v_pk_mul_f32 v[150:151], v[138:139], v[150:151]
	v_pk_mul_f32 v[148:149], v[136:137], v[148:149]
	s_and_b64 vcc, exec, s[8:9]
	s_mov_b64 s[40:41], -1
	s_cbranch_vccnz .LBB0_328
	s_and_b64 vcc, exec, s[4:5]
	s_cbranch_vccnz .LBB0_325
	s_add_u32 s24, s46, s0
	v_readlane_b32 s25, v254, 12
	s_addc_u32 s25, s25, s1
	v_lshlrev_b32_e32 v164, 1, v166
	v_lshl_add_u64 v[208:209], v[186:187], 1, s[24:25]
	v_lshl_add_u64 v[208:209], v[208:209], 0, v[164:165]
	v_cvt_pk_bf16_f32 v204, v144, v145
	v_cvt_pk_bf16_f32 v205, v146, v147
	v_cvt_pk_bf16_f32 v206, v148, v149
	v_cvt_pk_bf16_f32 v207, v150, v151
	global_store_dwordx4 v[208:209], v[204:207], off nt
	s_and_saveexec_b64 s[40:41], s[10:11]
	s_cbranch_execz .LBB0_324
	s_lshl_b32 s24, s29, 2
	s_add_u32 s24, s84, s24
	s_addc_u32 s25, s85, 0
	v_lshl_add_u64 v[204:205], s[24:25], 0, v[190:191]
	v_lshlrev_b32_e32 v164, 2, v172
	v_lshl_add_u64 v[204:205], v[204:205], 0, v[164:165]
	global_store_dwordx4 v[204:205], v[144:147], off nt
	global_store_dwordx4 v[204:205], v[148:151], off offset:16 nt

; __device__ __forceinline__ u32x4 pack8(const f32x4 a, const f32x4 b) { u32x4 w; w.x = cvt_pk_bf16(a[0], a[1]); w.y = cvt_pk_bf16(a[2], a[3]); w.z = cvt_pk_bf16(b[0], b[1]); w.w = cvt_pk_bf16(b[2], b[3]); return w; }
;     __device__ __forceinline__ void operator()(const f32x4 (&acc)[2][2][4][2], const Unit& u, int wr, int wc, int fr, int fq) const {
;     ...
;                     for (int bj = 0; bj < 2; ++bj) { const int hc = wc * 64 + bj * 32 + fq * 8, dd = bj * 32 + fq * 8;
;                         const f32x4 v0 = acc[ai][bj][m][0] * rs * w[bj][0], v1 = acc[ai][bj][m][1] * rs * w[bj][1];
;                         if (isq) { *(u32x4*)(QG + (size_t)g * M * 256 + (size_t)Rg + dd) = pack8(v0, v1); }
;                         else {
;                             if (!sample) { *(u32x4*)(KG + (size_t)g * MP * 256 + (size_t)Rg + dd) = pack8(v0, v1);
;                                 if (t >= 2048 - keep) { float* p = out + okp + ((size_t)(b * keep + t - (2048 - keep)) * 2) * 256 + hc; *(f32x4*)p = v0; *(f32x4*)(p + 4) = v1; } }
;                             else { float* p = out + oks + ((size_t)(b * keep + keep - 8 + t) * 2) * 256 + hc; *(f32x4*)p = v0; *(f32x4*)(p + 4) = v1; } } } }
.LBB0_330:
	v_mov_b32_e32 v193, v192
	v_mov_b32_e32 v148, v192
	v_mov_b32_e32 v149, v192
	v_pk_mul_f32 v[144:145], v[38:39], v[148:149]
	v_pk_mul_f32 v[150:151], v[36:37], v[192:193]
	v_pk_mul_f32 v[148:149], v[34:35], v[148:149]
	v_pk_mul_f32 v[192:193], v[32:33], v[192:193]
	v_pk_mul_f32 v[146:147], v[134:135], v[144:145]
	v_pk_mul_f32 v[144:145], v[132:133], v[150:151]
	v_pk_mul_f32 v[150:151], v[130:131], v[148:149]
	v_pk_mul_f32 v[148:149], v[128:129], v[192:193]
	s_and_b64 vcc, exec, s[8:9]
	s_mov_b64 s[40:41], -1
	s_cbranch_vccnz .LBB0_338
	s_and_b64 vcc, exec, s[4:5]
	s_cbranch_vccnz .LBB0_335
	s_add_u32 s24, s46, s0
	v_readlane_b32 s25, v254, 12
	s_addc_u32 s25, s25, s1
	v_lshlrev_b32_e32 v164, 1, v166
	v_lshl_add_u64 v[192:193], v[186:187], 1, s[24:25]
	v_lshl_add_u64 v[192:193], v[192:193], 0, v[164:165]
	v_cvt_pk_bf16_f32 v204, v144, v145
	v_cvt_pk_bf16_f32 v205, v146, v147
	v_cvt_pk_bf16_f32 v206, v148, v149
	v_cvt_pk_bf16_f32 v207, v150, v151
	global_store_dwordx4 v[192:193], v[204:207], off offset:64 nt
	s_and_saveexec_b64 s[40:41], s[10:11]
	s_cbranch_execz .LBB0_334
	s_lshl_b32 s10, s29, 2
	s_add_u32 s10, s84, s10
	s_addc_u32 s11, s85, 0
	v_lshl_add_u64 v[190:191], s[10:11], 0, v[190:191]
	v_lshlrev_b32_e32 v164, 2, v172
	v_lshl_add_u64 v[190:191], v[190:191], 0, v[164:165]
	global_store_dwordx4 v[190:191], v[144:147], off offset:128 nt
	global_store_dwordx4 v[190:191], v[148:151], off offset:144 nt

; __device__ __forceinline__ u32x4 pack8(const f32x4 a, const f32x4 b) { u32x4 w; w.x = cvt_pk_bf16(a[0], a[1]); w.y = cvt_pk_bf16(a[2], a[3]); w.z = cvt_pk_bf16(b[0], b[1]); w.w = cvt_pk_bf16(b[2], b[3]); return w; }
; __device__ __forceinline__ float dot4(const f32x4 a, const f32x4 b) { return (a[0] * b[0] + a[1] * b[1]) + (a[2] * b[2] + a[3] * b[3]); }
;     __device__ __forceinline__ void operator()(const f32x4 (&acc)[2][2][4][2], const Unit& u, int wr, int wc, int fr, int fq) const {
;     ...
;                 for (int m = 0; m < 4; ++m) { const int row = rbase + ai * 128 + m * 16;
;                     float ss = 0.f;
; #pragma unroll
;                     for (int bj = 0; bj < 2; ++bj)
; #pragma unroll
;                         for (int n = 0; n < 2; ++n) ss += dot4(acc[ai][bj][m][n], acc[ai][bj][m][n]);
;                     ss += __shfl_xor(ss, 16); ss += __shfl_xor(ss, 32);
;                     float rs = __builtin_amdgcn_rsqf(ss * (1.0f / 64.0f) + EPS); if (isq) rs *= QSCALE;
;                     int b, t, Rg;
;                     if (!sample) { b = row >> 11; t = row & 2047; Rg = b * 524288 + (t & (dil - 1)) * (L * 256) + (t >> sh) * 64 + wc * (L * 64); } else { const int sr = row - MP; b = sr >> 3; t = sr & 7; Rg = row * 256 + wc * 64; }
; #pragma unroll
;                     for (int bj = 0; bj < 2; ++bj) { const int hc = wc * 64 + bj * 32 + fq * 8, dd = bj * 32 + fq * 8;
;                         const f32x4 v0 = acc[ai][bj][m][0] * rs * w[bj][0], v1 = acc[ai][bj][m][1] * rs * w[bj][1];
;                         if (isq) { *(u32x4*)(QG + (size_t)g * M * 256 + (size_t)Rg + dd) = pack8(v0, v1); }
;                         else {
;                             if (!sample) { *(u32x4*)(KG + (size_t)g * MP * 256 + (size_t)Rg + dd) = pack8(v0, v1);
;                                 if (t >= 2048 - keep) { float* p = out + okp + ((size_t)(b * keep + t - (2048 - keep)) * 2) * 256 + hc; *(f32x4*)p = v0; *(f32x4*)(p + 4) = v1; } }
;                             else { float* p = out + oks + ((size_t)(b * keep + keep - 8 + t) * 2) * 256 + hc; *(f32x4*)p = v0; *(f32x4*)(p + 4) = v1; } } } }
.LBB0_344:
	s_waitcnt lgkmcnt(0)
	v_add_f32_e32 v144, v144, v145
	v_fmamk_f32 v144, v144, 0x3c800000, v195
	v_rsq_f32_e32 v144, v144
	v_cmp_le_i32_e64 s[10:11], s93, v146
	v_lshl_add_u32 v146, v148, s68, v146
	v_ashrrev_i32_e32 v187, 31, v186
	v_mul_f32_e32 v145, 0x3e38aa3b, v144
	v_cndmask_b32_e64 v192, v144, v145, s[6:7]
	v_add_u32_e32 v144, s72, v146
	v_ashrrev_i32_e32 v145, 31, v144
	v_lshlrev_b64 v[190:191], 11, v[144:145]
	v_add_u32_e32 v144, s73, v146
	v_ashrrev_i32_e32 v145, 31, v144
	v_lshlrev_b64 v[188:189], 11, v[144:145]
	v_pk_mul_f32 v[144:145], v[28:29], v[192:193] op_sel_hi:[1,0]
	v_pk_mul_f32 v[146:147], v[30:31], v[192:193] op_sel_hi:[1,0]
	v_pk_mul_f32 v[148:149], v[24:25], v[192:193] op_sel_hi:[1,0]
	v_pk_mul_f32 v[150:151], v[26:27], v[192:193] op_sel_hi:[1,0]
	v_pk_mul_f32 v[146:147], v[142:143], v[146:147]
	v_pk_mul_f32 v[144:145], v[140:141], v[144:145]
	v_pk_mul_f32 v[150:151], v[138:139], v[150:151]
	v_pk_mul_f32 v[148:149], v[136:137], v[148:149]
	s_and_b64 vcc, exec, s[8:9]
	s_mov_b64 s[40:41], -1
	s_cbranch_vccnz .LBB0_352
	s_and_b64 vcc, exec, s[4:5]
	s_cbranch_vccnz .LBB0_349
	s_add_u32 s24, s46, s0
	v_readlane_b32 s25, v254, 12
	s_addc_u32 s25, s25, s1
	v_lshlrev_b32_e32 v164, 1, v166
	v_lshl_add_u64 v[208:209], v[186:187], 1, s[24:25]
	v_lshl_add_u64 v[208:209], v[208:209], 0, v[164:165]
	v_cvt_pk_bf16_f32 v204, v144, v145
	v_cvt_pk_bf16_f32 v205, v146, v147
	v_cvt_pk_bf16_f32 v206, v148, v149
	v_cvt_pk_bf16_f32 v207, v150, v151
	global_store_dwordx4 v[208:209], v[204:207], off nt
	s_and_saveexec_b64 s[40:41], s[10:11]
	s_cbranch_execz .LBB0_348
	s_lshl_b32 s24, s29, 2
	s_add_u32 s24, s84, s24
	s_addc_u32 s25, s85, 0
	v_lshl_add_u64 v[204:205], s[24:25], 0, v[190:191]
	v_lshlrev_b32_e32 v164, 2, v172
	v_lshl_add_u64 v[204:205], v[204:205], 0, v[164:165]
	global_store_dwordx4 v[204:205], v[144:147], off nt
	global_store_dwordx4 v[204:205], v[148:151], off offset:16 nt

; __device__ __forceinline__ u32x4 pack8(const f32x4 a, const f32x4 b) { u32x4 w; w.x = cvt_pk_bf16(a[0], a[1]); w.y = cvt_pk_bf16(a[2], a[3]); w.z = cvt_pk_bf16(b[0], b[1]); w.w = cvt_pk_bf16(b[2], b[3]); return w; }
;     __device__ __forceinline__ void operator()(const f32x4 (&acc)[2][2][4][2], const Unit& u, int wr, int wc, int fr, int fq) const {
;     ...
;                     for (int bj = 0; bj < 2; ++bj) { const int hc = wc * 64 + bj * 32 + fq * 8, dd = bj * 32 + fq * 8;
;                         const f32x4 v0 = acc[ai][bj][m][0] * rs * w[bj][0], v1 = acc[ai][bj][m][1] * rs * w[bj][1];
;                         if (isq) { *(u32x4*)(QG + (size_t)g * M * 256 + (size_t)Rg + dd) = pack8(v0, v1); }
;                         else {
;                             if (!sample) { *(u32x4*)(KG + (size_t)g * MP * 256 + (size_t)Rg + dd) = pack8(v0, v1);
;                                 if (t >= 2048 - keep) { float* p = out + okp + ((size_t)(b * keep + t - (2048 - keep)) * 2) * 256 + hc; *(f32x4*)p = v0; *(f32x4*)(p + 4) = v1; } }
;                             else { float* p = out + oks + ((size_t)(b * keep + keep - 8 + t) * 2) * 256 + hc; *(f32x4*)p = v0; *(f32x4*)(p + 4) = v1; } } } }
.LBB0_354:
	v_mov_b32_e32 v193, v192
	v_mov_b32_e32 v148, v192
	v_mov_b32_e32 v149, v192
	v_pk_mul_f32 v[144:145], v[22:23], v[148:149]
	v_pk_mul_f32 v[150:151], v[20:21], v[192:193]
	v_pk_mul_f32 v[148:149], v[18:19], v[148:149]
	v_pk_mul_f32 v[192:193], v[16:17], v[192:193]
	v_pk_mul_f32 v[146:147], v[134:135], v[144:145]
	v_pk_mul_f32 v[144:145], v[132:133], v[150:151]
	v_pk_mul_f32 v[150:151], v[130:131], v[148:149]
	v_pk_mul_f32 v[148:149], v[128:129], v[192:193]
	s_and_b64 vcc, exec, s[8:9]
	s_mov_b64 s[40:41], -1
	s_cbranch_vccnz .LBB0_362
	s_and_b64 vcc, exec, s[4:5]
	s_cbranch_vccnz .LBB0_359
	s_add_u32 s24, s46, s0
	v_readlane_b32 s25, v254, 12
	s_addc_u32 s25, s25, s1
	v_lshlrev_b32_e32 v164, 1, v166
	v_lshl_add_u64 v[192:193], v[186:187], 1, s[24:25]
	v_lshl_add_u64 v[192:193], v[192:193], 0, v[164:165]
	v_cvt_pk_bf16_f32 v204, v144, v145
	v_cvt_pk_bf16_f32 v205, v146, v147
	v_cvt_pk_bf16_f32 v206, v148, v149
	v_cvt_pk_bf16_f32 v207, v150, v151
	global_store_dwordx4 v[192:193], v[204:207], off offset:64 nt
	s_and_saveexec_b64 s[40:41], s[10:11]
	s_cbranch_execz .LBB0_358
	s_lshl_b32 s10, s29, 2
	s_add_u32 s10, s84, s10
	s_addc_u32 s11, s85, 0
	v_lshl_add_u64 v[190:191], s[10:11], 0, v[190:191]
	v_lshlrev_b32_e32 v164, 2, v172
	v_lshl_add_u64 v[190:191], v[190:191], 0, v[164:165]
	global_store_dwordx4 v[190:191], v[144:147], off offset:128 nt
	global_store_dwordx4 v[190:191], v[148:151], off offset:144 nt

; __device__ __forceinline__ u32x4 pack8(const f32x4 a, const f32x4 b) { u32x4 w; w.x = cvt_pk_bf16(a[0], a[1]); w.y = cvt_pk_bf16(a[2], a[3]); w.z = cvt_pk_bf16(b[0], b[1]); w.w = cvt_pk_bf16(b[2], b[3]); return w; }
; __device__ __forceinline__ float dot4(const f32x4 a, const f32x4 b) { return (a[0] * b[0] + a[1] * b[1]) + (a[2] * b[2] + a[3] * b[3]); }
;     __device__ __forceinline__ void operator()(const f32x4 (&acc)[2][2][4][2], const Unit& u, int wr, int wc, int fr, int fq) const {
;     ...
;                 for (int m = 0; m < 4; ++m) { const int row = rbase + ai * 128 + m * 16;
;                     float ss = 0.f;
; #pragma unroll
;                     for (int bj = 0; bj < 2; ++bj)
; #pragma unroll
;                         for (int n = 0; n < 2; ++n) ss += dot4(acc[ai][bj][m][n], acc[ai][bj][m][n]);
;                     ss += __shfl_xor(ss, 16); ss += __shfl_xor(ss, 32);
;                     float rs = __builtin_amdgcn_rsqf(ss * (1.0f / 64.0f) + EPS); if (isq) rs *= QSCALE;
;                     int b, t, Rg;
;                     if (!sample) { b = row >> 11; t = row & 2047; Rg = b * 524288 + (t & (dil - 1)) * (L * 256) + (t >> sh) * 64 + wc * (L * 64); } else { const int sr = row - MP; b = sr >> 3; t = sr & 7; Rg = row * 256 + wc * 64; }
; #pragma unroll
;                     for (int bj = 0; bj < 2; ++bj) { const int hc = wc * 64 + bj * 32 + fq * 8, dd = bj * 32 + fq * 8;
;                         const f32x4 v0 = acc[ai][bj][m][0] * rs * w[bj][0], v1 = acc[ai][bj][m][1] * rs * w[bj][1];
;                         if (isq) { *(u32x4*)(QG + (size_t)g * M * 256 + (size_t)Rg + dd) = pack8(v0, v1); }
;                         else {
;                             if (!sample) { *(u32x4*)(KG + (size_t)g * MP * 256 + (size_t)Rg + dd) = pack8(v0, v1);
;                                 if (t >= 2048 - keep) { float* p = out + okp + ((size_t)(b * keep + t - (2048 - keep)) * 2) * 256 + hc; *(f32x4*)p = v0; *(f32x4*)(p + 4) = v1; } }
;                             else { float* p = out + oks + ((size_t)(b * keep + keep - 8 + t) * 2) * 256 + hc; *(f32x4*)p = v0; *(f32x4*)(p + 4) = v1; } } } }
.LBB0_368:
	s_waitcnt lgkmcnt(0)
	v_add_f32_e32 v145, v145, v147
	v_fmamk_f32 v145, v145, 0x3c800000, v195
	v_rsq_f32_e32 v145, v145
	v_lshl_add_u32 v151, v202, s68, v146
	v_readlane_b32 s70, v254, 23
	s_mov_b64 s[10:11], -1
	v_mul_f32_e32 v147, 0x3e38aa3b, v145
	v_cndmask_b32_e64 v150, v145, v147, s[6:7]
	v_cmp_le_i32_e64 s[6:7], s93, v146
	v_add_u32_e32 v146, s72, v151
	v_ashrrev_i32_e32 v147, 31, v146
	v_lshlrev_b64 v[148:149], 11, v[146:147]
	v_add_u32_e32 v146, s73, v151
	v_pk_mul_f32 v[186:187], v[12:13], v[150:151] op_sel_hi:[1,0]
	v_pk_mul_f32 v[188:189], v[14:15], v[150:151] op_sel_hi:[1,0]
	v_ashrrev_i32_e32 v147, 31, v146
	v_pk_mul_f32 v[142:143], v[142:143], v[188:189]
	v_pk_mul_f32 v[140:141], v[140:141], v[186:187]
	v_pk_mul_f32 v[186:187], v[8:9], v[150:151] op_sel_hi:[1,0]
	v_pk_mul_f32 v[188:189], v[10:11], v[150:151] op_sel_hi:[1,0]
	v_ashrrev_i32_e32 v145, 31, v144
	v_lshlrev_b64 v[146:147], 11, v[146:147]
	v_pk_mul_f32 v[138:139], v[138:139], v[188:189]
	v_pk_mul_f32 v[136:137], v[136:137], v[186:187]
	s_and_b64 vcc, exec, s[8:9]
	v_readlane_b32 s46, v254, 21
	v_readlane_b32 s68, v254, 22
	v_readlane_b32 s71, v254, 24
	s_movk_i32 s40, 0x7f0
	s_cbranch_vccnz .LBB0_376
	s_and_b64 vcc, exec, s[4:5]
	s_cbranch_vccnz .LBB0_373
	v_readlane_b32 s10, v254, 11
	s_add_u32 s10, s10, s0
	v_readlane_b32 s11, v254, 12
	s_addc_u32 s11, s11, s1
	v_lshlrev_b32_e32 v164, 1, v166
	v_lshl_add_u64 v[190:191], v[144:145], 1, s[10:11]
	v_lshl_add_u64 v[190:191], v[190:191], 0, v[164:165]
	v_cvt_pk_bf16_f32 v186, v140, v141
	v_cvt_pk_bf16_f32 v187, v142, v143
	v_cvt_pk_bf16_f32 v188, v136, v137
	v_cvt_pk_bf16_f32 v189, v138, v139
	global_store_dwordx4 v[190:191], v[186:189], off nt
	s_and_saveexec_b64 s[10:11], s[6:7]
	s_cbranch_execz .LBB0_372
	s_lshl_b32 s24, s29, 2
	s_add_u32 s24, s84, s24
	s_addc_u32 s25, s85, 0
	v_lshl_add_u64 v[186:187], s[24:25], 0, v[148:149]
	v_lshlrev_b32_e32 v164, 2, v172
	v_lshl_add_u64 v[186:187], v[186:187], 0, v[164:165]
	global_store_dwordx4 v[186:187], v[140:143], off nt
	global_store_dwordx4 v[186:187], v[136:139], off offset:16 nt

; __device__ __forceinline__ u32x4 pack8(const f32x4 a, const f32x4 b) { u32x4 w; w.x = cvt_pk_bf16(a[0], a[1]); w.y = cvt_pk_bf16(a[2], a[3]); w.z = cvt_pk_bf16(b[0], b[1]); w.w = cvt_pk_bf16(b[2], b[3]); return w; }
;     __device__ __forceinline__ void operator()(const f32x4 (&acc)[2][2][4][2], const Unit& u, int wr, int wc, int fr, int fq) const {
;     ...
;                         else {
;                             if (!sample) { *(u32x4*)(KG + (size_t)g * MP * 256 + (size_t)Rg + dd) = pack8(v0, v1);
;                                 if (t >= 2048 - keep) { float* p = out + okp + ((size_t)(b * keep + t - (2048 - keep)) * 2) * 256 + hc; *(f32x4*)p = v0; *(f32x4*)(p + 4) = v1; } }
;                             else { float* p = out + oks + ((size_t)(b * keep + keep - 8 + t) * 2) * 256 + hc; *(f32x4*)p = v0; *(f32x4*)(p + 4) = v1; } } } }
.LBB0_373:
	s_andn2_b64 vcc, exec, s[10:11]
	s_cbranch_vccnz .LBB0_375
	s_lshl_b32 s10, s16, 2
	s_add_u32 s10, s84, s10
	s_addc_u32 s11, s85, 0
	v_lshl_add_u64 v[186:187], s[10:11], 0, v[146:147]
	v_lshlrev_b32_e32 v164, 2, v172
	v_lshl_add_u64 v[186:187], v[186:187], 0, v[164:165]
	global_store_dwordx4 v[186:187], v[140:143], off nt
	global_store_dwordx4 v[186:187], v[136:139], off offset:16 nt

; __device__ __forceinline__ u32x4 pack8(const f32x4 a, const f32x4 b) { u32x4 w; w.x = cvt_pk_bf16(a[0], a[1]); w.y = cvt_pk_bf16(a[2], a[3]); w.z = cvt_pk_bf16(b[0], b[1]); w.w = cvt_pk_bf16(b[2], b[3]); return w; }
;     __device__ __forceinline__ void operator()(const f32x4 (&acc)[2][2][4][2], const Unit& u, int wr, int wc, int fr, int fq) const {
;     ...
;                     for (int bj = 0; bj < 2; ++bj) { const int hc = wc * 64 + bj * 32 + fq * 8, dd = bj * 32 + fq * 8;
;                         const f32x4 v0 = acc[ai][bj][m][0] * rs * w[bj][0], v1 = acc[ai][bj][m][1] * rs * w[bj][1];
;                         if (isq) { *(u32x4*)(QG + (size_t)g * M * 256 + (size_t)Rg + dd) = pack8(v0, v1); }
;                         else {
;                             if (!sample) { *(u32x4*)(KG + (size_t)g * MP * 256 + (size_t)Rg + dd) = pack8(v0, v1);
;                                 if (t >= 2048 - keep) { float* p = out + okp + ((size_t)(b * keep + t - (2048 - keep)) * 2) * 256 + hc; *(f32x4*)p = v0; *(f32x4*)(p + 4) = v1; } }
;                             else { float* p = out + oks + ((size_t)(b * keep + keep - 8 + t) * 2) * 256 + hc; *(f32x4*)p = v0; *(f32x4*)(p + 4) = v1; } } } }
.LBB0_376:
	s_andn2_b64 vcc, exec, s[10:11]
	s_cbranch_vccnz .LBB0_378
	s_add_u32 s10, s81, s42
	s_addc_u32 s11, s82, s43
	v_cvt_pk_bf16_f32 v140, v140, v141
	v_cvt_pk_bf16_f32 v141, v142, v143
	v_cvt_pk_bf16_f32 v142, v136, v137
	v_lshl_add_u64 v[136:137], v[144:145], 1, s[10:11]
	v_lshlrev_b32_e32 v164, 1, v166
	v_lshl_add_u64 v[136:137], v[136:137], 0, v[164:165]
	v_cvt_pk_bf16_f32 v143, v138, v139
	global_store_dwordx4 v[136:137], v[140:143], off nt
.LBB0_378:
	v_mov_b32_e32 v136, v150
	v_mov_b32_e32 v137, v150
	v_mov_b32_e32 v151, v150
	v_pk_mul_f32 v[138:139], v[6:7], v[136:137]
	v_pk_mul_f32 v[140:141], v[4:5], v[150:151]
	v_pk_mul_f32 v[134:135], v[134:135], v[138:139]
	v_pk_mul_f32 v[136:137], v[2:3], v[136:137]
	v_pk_mul_f32 v[138:139], v[0:1], v[150:151]
	v_pk_mul_f32 v[132:133], v[132:133], v[140:141]
	v_pk_mul_f32 v[130:131], v[130:131], v[136:137]
	v_pk_mul_f32 v[128:129], v[128:129], v[138:139]
	s_and_b64 vcc, exec, s[8:9]
	s_mov_b64 s[8:9], -1
	s_cbranch_vccnz .LBB0_386
	s_and_b64 vcc, exec, s[4:5]
	s_mov_b64 s[4:5], -1
	s_cbranch_vccnz .LBB0_383
	v_readlane_b32 s4, v254, 11
	s_add_u32 s0, s4, s0
	v_readlane_b32 s4, v254, 12
	s_addc_u32 s1, s4, s1
	v_lshl_add_u64 v[140:141], v[144:145], 1, s[0:1]
	v_lshlrev_b32_e32 v164, 1, v166
	v_lshl_add_u64 v[140:141], v[140:141], 0, v[164:165]
	v_cvt_pk_bf16_f32 v136, v132, v133
	v_cvt_pk_bf16_f32 v137, v134, v135
	v_cvt_pk_bf16_f32 v138, v128, v129
	v_cvt_pk_bf16_f32 v139, v130, v131
	global_store_dwordx4 v[140:141], v[136:139], off offset:64 nt
	s_and_saveexec_b64 s[0:1], s[6:7]
	s_cbranch_execz .LBB0_382
	s_lshl_b32 s4, s29, 2
	s_add_u32 s4, s84, s4
	s_addc_u32 s5, s85, 0
	v_lshl_add_u64 v[136:137], s[4:5], 0, v[148:149]
	v_lshlrev_b32_e32 v164, 2, v172
	v_lshl_add_u64 v[136:137], v[136:137], 0, v[164:165]
	global_store_dwordx4 v[136:137], v[132:135], off offset:128 nt
	global_store_dwordx4 v[136:137], v[128:131], off offset:144 nt

; __device__ __forceinline__ u32x4 pack8(const f32x4 a, const f32x4 b) { u32x4 w; w.x = cvt_pk_bf16(a[0], a[1]); w.y = cvt_pk_bf16(a[2], a[3]); w.z = cvt_pk_bf16(b[0], b[1]); w.w = cvt_pk_bf16(b[2], b[3]); return w; }
;     __device__ __forceinline__ void operator()(const f32x4 (&acc)[2][2][4][2], const Unit& u, int wr, int wc, int fr, int fq) const {
;     ...
;                         else {
;                             if (!sample) { *(u32x4*)(KG + (size_t)g * MP * 256 + (size_t)Rg + dd) = pack8(v0, v1);
;                                 if (t >= 2048 - keep) { float* p = out + okp + ((size_t)(b * keep + t - (2048 - keep)) * 2) * 256 + hc; *(f32x4*)p = v0; *(f32x4*)(p + 4) = v1; } }
;                             else { float* p = out + oks + ((size_t)(b * keep + keep - 8 + t) * 2) * 256 + hc; *(f32x4*)p = v0; *(f32x4*)(p + 4) = v1; } } } }
.LBB0_383:
	s_andn2_b64 vcc, exec, s[4:5]
	s_cbranch_vccnz .LBB0_385
	s_lshl_b32 s0, s16, 2
	s_add_u32 s0, s84, s0
	s_addc_u32 s1, s85, 0
	v_lshl_add_u64 v[136:137], s[0:1], 0, v[146:147]
	v_lshlrev_b32_e32 v164, 2, v172
	v_lshl_add_u64 v[136:137], v[136:137], 0, v[164:165]
	global_store_dwordx4 v[136:137], v[132:135], off offset:128 nt
	global_store_dwordx4 v[136:137], v[128:131], off offset:144 nt

; __device__ __forceinline__ u32x4 pack8(const f32x4 a, const f32x4 b) { u32x4 w; w.x = cvt_pk_bf16(a[0], a[1]); w.y = cvt_pk_bf16(a[2], a[3]); w.z = cvt_pk_bf16(b[0], b[1]); w.w = cvt_pk_bf16(b[2], b[3]); return w; }
;     __device__ __forceinline__ void operator()(const f32x4 (&acc)[2][2][4][2], const Unit& u, int wr, int wc, int fr, int fq) const {
;     ...
;                     for (int bj = 0; bj < 2; ++bj) { const int hc = wc * 64 + bj * 32 + fq * 8, dd = bj * 32 + fq * 8;
;                         const f32x4 v0 = acc[ai][bj][m][0] * rs * w[bj][0], v1 = acc[ai][bj][m][1] * rs * w[bj][1];
;                         if (isq) { *(u32x4*)(QG + (size_t)g * M * 256 + (size_t)Rg + dd) = pack8(v0, v1); }
.LBB0_386:
	s_andn2_b64 vcc, exec, s[8:9]
	s_cbranch_vccnz .LBB0_388
	s_add_u32 s0, s81, s42
	s_addc_u32 s1, s82, s43
	v_cvt_pk_bf16_f32 v132, v132, v133
	v_cvt_pk_bf16_f32 v133, v134, v135
	v_cvt_pk_bf16_f32 v134, v128, v129
	v_lshl_add_u64 v[128:129], v[144:145], 1, s[0:1]
	v_lshlrev_b32_e32 v164, 1, v166
	v_lshl_add_u64 v[128:129], v[128:129], 0, v[164:165]
	v_cvt_pk_bf16_f32 v135, v130, v131
	global_store_dwordx4 v[128:129], v[132:135], off offset:64 nt

; __device__ __forceinline__ u32x4 pack8(const f32x4 a, const f32x4 b) { u32x4 w; w.x = cvt_pk_bf16(a[0], a[1]); w.y = cvt_pk_bf16(a[2], a[3]); w.z = cvt_pk_bf16(b[0], b[1]); w.w = cvt_pk_bf16(b[2], b[3]); return w; }
;     __device__ __forceinline__ void operator()(const f32x4 (&acc)[2][2][4][2], const Unit& u, int wr, int wc, int fr, int fq) const {
;         const int pn = u.pn; const bool sample = u.pm >= 256;
;         const int rbase = u.pm * 256 + wr * 64 + fr;
;         if (pn < 2) {
; #pragma unroll
;             for (int ai = 0; ai < 2; ++ai)
; #pragma unroll
;                 for (int m = 0; m < 4; ++m) { const int row = rbase + ai * 128 + m * 16;
; #pragma unroll
;                     for (int bj = 0; bj < 2; ++bj) { const int col = pn * 256 + bj * 128 + wc * 32 + fq * 8; const f32x4 v0 = acc[ai][bj][m][0], v1 = acc[ai][bj][m][1];
;                         *(u32x4*)(A + (size_t)row * 512 + col) = pack8(v0, v1);
;                         if (!sample) { const int b = row >> 11, t = row & 2047; if (t >= 2033) { float* p = out + O_POOLP + (size_t)(b * 15 + t - 2033) * 512 + col; *(f32x4*)p = v0; *(f32x4*)(p + 4) = v1; } }
;                         else { const int sr = row - MP, b = sr >> 3, t = sr & 7; float* p = out + O_POOLS + (size_t)(b * 15 + 7 + t) * 512 + col; *(f32x4*)p = v0; *(f32x4*)(p + 4) = v1; } } }
.LBB0_391:
	v_add_u32_e32 v129, 0xffff0000, v184
	v_ashrrev_i32_e32 v185, 31, v184
	v_ashrrev_i32_e32 v129, 3, v129
	v_lshl_or_b32 v128, s36, 8, v168
	v_lshlrev_b64 v[130:131], 10, v[184:185]
	v_mad_u64_u32 v[132:133], s[0:1], v129, 15, v[174:175]
	v_ashrrev_i32_e32 v133, 31, v132
	v_lshl_add_u64 v[130:131], s[20:21], 0, v[130:131]
	v_ashrrev_i32_e32 v129, 31, v128
	v_lshlrev_b64 v[136:137], 11, v[132:133]
	v_cvt_pk_bf16_f32 v132, v124, v125
	v_lshl_add_u64 v[130:131], v[128:129], 1, v[130:131]
	v_cvt_pk_bf16_f32 v133, v126, v127
	v_cvt_pk_bf16_f32 v134, v120, v121
	v_cvt_pk_bf16_f32 v135, v122, v123
	global_store_dwordx4 v[130:131], v[132:135], off nt
	s_andn2_b64 vcc, exec, s[38:39]
	s_nop 0
	v_cndmask_b32_e64 v132, 0, 1, s[38:39]
	v_cmp_ne_u32_e64 s[4:5], 1, v132
	v_lshl_add_u64 v[132:133], s[14:15], 0, v[136:137]
	v_lshl_add_u64 v[132:133], v[128:129], 2, v[132:133]
	s_cbranch_vccnz .LBB0_393
	global_store_dwordx4 v[132:133], v[124:127], off nt
	global_store_dwordx4 v[132:133], v[120:123], off offset:16 nt
.LBB0_393:
	s_and_b64 vcc, exec, s[4:5]
	s_nop 0
	v_cvt_pk_bf16_f32 v120, v116, v117
	v_cvt_pk_bf16_f32 v121, v118, v119
	v_cvt_pk_bf16_f32 v122, v112, v113
	v_cvt_pk_bf16_f32 v123, v114, v115
	global_store_dwordx4 v[130:131], v[120:123], off offset:256 nt
	s_cbranch_vccnz .LBB0_395
	global_store_dwordx4 v[132:133], v[116:119], off offset:512 nt
	global_store_dwordx4 v[132:133], v[112:115], off offset:528 nt
.LBB0_395:
	s_nop 1
	v_add_u32_e32 v114, 0xffff0010, v184
	v_or_b32_e32 v112, 16, v184
	v_ashrrev_i32_e32 v114, 3, v114
	v_ashrrev_i32_e32 v113, 31, v112
	v_mad_u64_u32 v[114:115], s[0:1], v114, 15, v[174:175]
	v_lshlrev_b64 v[112:113], 10, v[112:113]
	v_ashrrev_i32_e32 v115, 31, v114
	v_lshlrev_b64 v[120:121], 11, v[114:115]
	v_lshl_add_u64 v[112:113], s[20:21], 0, v[112:113]
	v_lshl_add_u64 v[114:115], v[128:129], 1, v[112:113]
	v_lshl_add_u64 v[112:113], s[14:15], 0, v[120:121]
	s_and_b64 vcc, exec, s[4:5]
	v_lshl_add_u64 v[112:113], v[128:129], 2, v[112:113]
	v_cvt_pk_bf16_f32 v116, v108, v109
	v_cvt_pk_bf16_f32 v117, v110, v111
	v_cvt_pk_bf16_f32 v118, v104, v105
	v_cvt_pk_bf16_f32 v119, v106, v107
	global_store_dwordx4 v[114:115], v[116:119], off nt
	s_cbranch_vccnz .LBB0_397
	global_store_dwordx4 v[112:113], v[108:111], off nt
	global_store_dwordx4 v[112:113], v[104:107], off offset:16 nt
.LBB0_397:
	s_and_b64 vcc, exec, s[4:5]
	s_nop 0
	v_cvt_pk_bf16_f32 v104, v100, v101
	v_cvt_pk_bf16_f32 v105, v102, v103
	v_cvt_pk_bf16_f32 v106, v96, v97
	v_cvt_pk_bf16_f32 v107, v98, v99
	global_store_dwordx4 v[114:115], v[104:107], off offset:256 nt
	s_cbranch_vccnz .LBB0_399
	global_store_dwordx4 v[112:113], v[100:103], off offset:512 nt
	global_store_dwordx4 v[112:113], v[96:99], off offset:528 nt
.LBB0_399:
	s_nop 1
	v_add_u32_e32 v98, 0xffff0020, v184
	v_or_b32_e32 v96, 32, v184
	v_ashrrev_i32_e32 v98, 3, v98
	v_ashrrev_i32_e32 v97, 31, v96
	v_mad_u64_u32 v[98:99], s[0:1], v98, 15, v[174:175]
	v_lshlrev_b64 v[96:97], 10, v[96:97]
	v_ashrrev_i32_e32 v99, 31, v98
	v_lshlrev_b64 v[104:105], 11, v[98:99]
	v_lshl_add_u64 v[96:97], s[20:21], 0, v[96:97]
	v_lshl_add_u64 v[98:99], v[128:129], 1, v[96:97]
	v_lshl_add_u64 v[96:97], s[14:15], 0, v[104:105]
	s_and_b64 vcc, exec, s[4:5]
	v_lshl_add_u64 v[96:97], v[128:129], 2, v[96:97]
	v_cvt_pk_bf16_f32 v100, v92, v93
	v_cvt_pk_bf16_f32 v101, v94, v95
	v_cvt_pk_bf16_f32 v102, v88, v89
	v_cvt_pk_bf16_f32 v103, v90, v91
	global_store_dwordx4 v[98:99], v[100:103], off nt
	s_cbranch_vccnz .LBB0_401
	global_store_dwordx4 v[96:97], v[92:95], off nt
	global_store_dwordx4 v[96:97], v[88:91], off offset:16 nt
.LBB0_401:
	s_and_b64 vcc, exec, s[4:5]
	s_mov_b64 s[0:1], 0x10400000
	v_cvt_pk_bf16_f32 v88, v84, v85
	v_cvt_pk_bf16_f32 v89, v86, v87
	v_cvt_pk_bf16_f32 v90, v80, v81
	v_cvt_pk_bf16_f32 v91, v82, v83
	global_store_dwordx4 v[98:99], v[88:91], off offset:256 nt
	s_cbranch_vccnz .LBB0_403
	s_mov_b64 s[0:1], 0x1acf0000
	global_store_dwordx4 v[96:97], v[84:87], off offset:512 nt
	global_store_dwordx4 v[96:97], v[80:83], off offset:528 nt
.LBB0_403:
	s_ashr_i32 s6, s27, 11
	s_mul_i32 s6, s6, 15
	s_movk_i32 s7, 0x7ff
	s_addk_i32 s6, 0xf80f
	v_bitop3_b32 v82, v184, s7, 48 bitop3:0xc8
	v_cmp_lt_u32_e32 vcc, s40, v82
	v_add_u32_e32 v82, s6, v82
	v_ashrrev_i32_e32 v83, 31, v82
	v_lshlrev_b64 v[88:89], 11, v[82:83]
	v_add_u32_e32 v82, 0xffff0030, v184
	v_or_b32_e32 v80, 48, v184
	v_ashrrev_i32_e32 v82, 3, v82
	v_ashrrev_i32_e32 v81, 31, v80
	v_mad_u64_u32 v[82:83], s[6:7], v82, 15, v[174:175]
	v_lshlrev_b64 v[80:81], 10, v[80:81]
	v_ashrrev_i32_e32 v83, 31, v82
	v_lshlrev_b64 v[90:91], 11, v[82:83]
	v_lshl_add_u64 v[80:81], s[20:21], 0, v[80:81]
	v_lshl_add_u64 v[82:83], v[128:129], 1, v[80:81]
	s_or_b64 s[6:7], s[38:39], vcc
	v_cndmask_b32_e64 v81, v89, v91, s[38:39]
	v_cndmask_b32_e64 v80, v88, v90, s[38:39]
	v_cvt_pk_bf16_f32 v84, v76, v77
	v_cvt_pk_bf16_f32 v85, v78, v79
	v_cvt_pk_bf16_f32 v86, v72, v73
	v_cvt_pk_bf16_f32 v87, v74, v75
	global_store_dwordx4 v[82:83], v[84:87], off nt
	s_and_saveexec_b64 s[8:9], s[6:7]
	s_cbranch_execz .LBB0_405
	s_add_u32 s0, s84, s0
	s_addc_u32 s1, s85, s1
	v_lshl_add_u64 v[84:85], s[0:1], 0, v[80:81]
	v_lshl_add_u64 v[84:85], v[128:129], 2, v[84:85]
	global_store_dwordx4 v[84:85], v[76:79], off nt
	global_store_dwordx4 v[84:85], v[72:75], off offset:16 nt
; __device__ __forceinline__ u32x4 pack8(const f32x4 a, const f32x4 b) { u32x4 w; w.x = cvt_pk_bf16(a[0], a[1]); w.y = cvt_pk_bf16(a[2], a[3]); w.z = cvt_pk_bf16(b[0], b[1]); w.w = cvt_pk_bf16(b[2], b[3]); return w; }
;     __device__ __forceinline__ void operator()(const f32x4 (&acc)[2][2][4][2], const Unit& u, int wr, int wc, int fr, int fq) const {
;     ...
; #pragma unroll
;             for (int ai = 0; ai < 2; ++ai)
; #pragma unroll
;                 for (int m = 0; m < 4; ++m) { const int row = rbase + ai * 128 + m * 16;
; #pragma unroll
;                     for (int bj = 0; bj < 2; ++bj) { const int col = pn * 256 + bj * 128 + wc * 32 + fq * 8; const f32x4 v0 = acc[ai][bj][m][0], v1 = acc[ai][bj][m][1];
;                         *(u32x4*)(A + (size_t)row * 512 + col) = pack8(v0, v1);
;                         if (!sample) { const int b = row >> 11, t = row & 2047; if (t >= 2033) { float* p = out + O_POOLP + (size_t)(b * 15 + t - 2033) * 512 + col; *(f32x4*)p = v0; *(f32x4*)(p + 4) = v1; } }
;                         else { const int sr = row - MP, b = sr >> 3, t = sr & 7; float* p = out + O_POOLS + (size_t)(b * 15 + 7 + t) * 512 + col; *(f32x4*)p = v0; *(f32x4*)(p + 4) = v1; } } }
.LBB0_405:
	s_or_b64 exec, exec, s[8:9]
	s_nop 0
	v_cvt_pk_bf16_f32 v72, v68, v69
	v_cvt_pk_bf16_f32 v73, v70, v71
	v_cvt_pk_bf16_f32 v74, v64, v65
	v_cvt_pk_bf16_f32 v75, v66, v67
	global_store_dwordx4 v[82:83], v[72:75], off offset:256 nt
	s_and_saveexec_b64 s[0:1], s[6:7]
	s_cbranch_execz .LBB0_407
	s_and_b64 s[6:7], s[38:39], exec
	s_mov_b32 s6, 0x1acf0000
	s_cselect_b32 s6, s6, 0x10400000
	s_add_u32 s6, s84, s6
	s_addc_u32 s7, s85, 0
	v_lshl_add_u64 v[72:73], s[6:7], 0, v[80:81]
	v_lshl_add_u64 v[72:73], v[128:129], 2, v[72:73]
	global_store_dwordx4 v[72:73], v[68:71], off offset:512 nt
	global_store_dwordx4 v[72:73], v[64:67], off offset:528 nt
.LBB0_407:
	s_or_b64 exec, exec, s[0:1]
	s_nop 0
	v_add_u32_e32 v64, 0x80, v184
	v_ashrrev_i32_e32 v65, 31, v64
	v_lshlrev_b64 v[66:67], 10, v[64:65]
	v_add_u32_e32 v65, 0xffff0080, v184
	v_ashrrev_i32_e32 v65, 3, v65
	v_mad_u64_u32 v[68:69], s[0:1], v65, 15, v[174:175]
	v_ashrrev_i32_e32 v69, 31, v68
	v_lshlrev_b64 v[74:75], 11, v[68:69]
	v_lshl_add_u64 v[66:67], s[20:21], 0, v[66:67]
	v_lshl_add_u64 v[68:69], v[128:129], 1, v[66:67]
	v_lshl_add_u64 v[66:67], s[14:15], 0, v[74:75]
	s_and_b64 vcc, exec, s[4:5]
	v_lshl_add_u64 v[66:67], v[128:129], 2, v[66:67]
	v_cvt_pk_bf16_f32 v70, v60, v61
	v_cvt_pk_bf16_f32 v71, v62, v63
	v_cvt_pk_bf16_f32 v72, v56, v57
	v_cvt_pk_bf16_f32 v73, v58, v59
	global_store_dwordx4 v[68:69], v[70:73], off nt
	s_cbranch_vccnz .LBB0_409
	global_store_dwordx4 v[66:67], v[60:63], off nt
	global_store_dwordx4 v[66:67], v[56:59], off offset:16 nt
.LBB0_409:
	s_and_b64 vcc, exec, s[4:5]
	s_nop 0
	v_cvt_pk_bf16_f32 v56, v52, v53
	v_cvt_pk_bf16_f32 v57, v54, v55
	v_cvt_pk_bf16_f32 v58, v48, v49
	v_cvt_pk_bf16_f32 v59, v50, v51
	global_store_dwordx4 v[68:69], v[56:59], off offset:256 nt
	s_cbranch_vccnz .LBB0_411
	global_store_dwordx4 v[66:67], v[52:55], off offset:512 nt
	global_store_dwordx4 v[66:67], v[48:51], off offset:528 nt
.LBB0_411:
	s_nop 1
	v_add_u32_e32 v50, 0xffff0090, v184
	v_ashrrev_i32_e32 v50, 3, v50
	v_lshlrev_b64 v[48:49], 10, v[184:185]
	v_mad_u64_u32 v[50:51], s[0:1], v50, 15, v[174:175]
	v_ashrrev_i32_e32 v51, 31, v50
	v_lshl_add_u64 v[48:49], s[20:21], 0, v[48:49]
	v_lshlrev_b64 v[56:57], 11, v[50:51]
	v_lshl_add_u64 v[50:51], v[128:129], 1, v[48:49]
	v_add_co_u32_e32 v48, vcc, 0x24000, v50
	v_cvt_pk_bf16_f32 v52, v44, v45
	v_cvt_pk_bf16_f32 v53, v46, v47
	v_cvt_pk_bf16_f32 v54, v40, v41
	v_cvt_pk_bf16_f32 v55, v42, v43
	s_nop 1
	v_addc_co_u32_e32 v49, vcc, 0, v51, vcc
	global_store_dwordx4 v[48:49], v[52:55], off nt
	v_lshl_add_u64 v[48:49], s[14:15], 0, v[56:57]
	s_and_b64 vcc, exec, s[4:5]
	v_lshl_add_u64 v[48:49], v[128:129], 2, v[48:49]
	s_cbranch_vccnz .LBB0_413
	global_store_dwordx4 v[48:49], v[44:47], off nt
	global_store_dwordx4 v[48:49], v[40:43], off offset:16 nt
.LBB0_413:
	s_mov_b64 s[0:1], 0x24000
	v_lshl_add_u64 v[44:45], v[50:51], 0, s[0:1]
	s_and_b64 vcc, exec, s[4:5]
	v_cvt_pk_bf16_f32 v40, v36, v37
	v_cvt_pk_bf16_f32 v41, v38, v39
	v_cvt_pk_bf16_f32 v42, v32, v33
	v_cvt_pk_bf16_f32 v43, v34, v35
	global_store_dwordx4 v[44:45], v[40:43], off offset:256 nt
	s_cbranch_vccnz .LBB0_415
	global_store_dwordx4 v[48:49], v[36:39], off offset:512 nt
	global_store_dwordx4 v[48:49], v[32:35], off offset:528 nt
.LBB0_415:
	s_nop 1
	v_add_u32_e32 v34, 0xffff00a0, v184
	v_ashrrev_i32_e32 v34, 3, v34
	v_lshlrev_b64 v[32:33], 10, v[184:185]
	v_mad_u64_u32 v[34:35], s[0:1], v34, 15, v[174:175]
	v_ashrrev_i32_e32 v35, 31, v34
	v_lshl_add_u64 v[32:33], s[20:21], 0, v[32:33]
	v_lshlrev_b64 v[40:41], 11, v[34:35]
	v_lshl_add_u64 v[34:35], v[128:129], 1, v[32:33]
	v_add_co_u32_e32 v32, vcc, 0x28000, v34
	v_cvt_pk_bf16_f32 v36, v28, v29
	v_cvt_pk_bf16_f32 v37, v30, v31
	v_cvt_pk_bf16_f32 v38, v24, v25
	v_cvt_pk_bf16_f32 v39, v26, v27
	s_nop 1
	v_addc_co_u32_e32 v33, vcc, 0, v35, vcc
	global_store_dwordx4 v[32:33], v[36:39], off nt
	v_lshl_add_u64 v[32:33], s[14:15], 0, v[40:41]
	s_and_b64 vcc, exec, s[4:5]
	v_lshl_add_u64 v[32:33], v[128:129], 2, v[32:33]
	s_cbranch_vccnz .LBB0_417
	global_store_dwordx4 v[32:33], v[28:31], off nt
	global_store_dwordx4 v[32:33], v[24:27], off offset:16 nt
.LBB0_417:
	s_mov_b64 s[0:1], 0x28000
	v_lshl_add_u64 v[28:29], v[34:35], 0, s[0:1]
	s_and_b64 vcc, exec, s[4:5]
	s_mov_b64 s[0:1], 0x10400000
	v_cvt_pk_bf16_f32 v24, v20, v21
	v_cvt_pk_bf16_f32 v25, v22, v23
	v_cvt_pk_bf16_f32 v26, v16, v17
	v_cvt_pk_bf16_f32 v27, v18, v19
	global_store_dwordx4 v[28:29], v[24:27], off offset:256 nt
	s_cbranch_vccnz .LBB0_419
	s_mov_b64 s[0:1], 0x1acf0000
	global_store_dwordx4 v[32:33], v[20:23], off offset:512 nt
	global_store_dwordx4 v[32:33], v[16:19], off offset:528 nt
.LBB0_419:
	s_nop 1
	v_ashrrev_i32_e32 v16, 11, v64
	v_mul_i32_i24_e32 v20, 15, v16
	v_add_u32_e32 v16, 0xb0, v184
	v_ashrrev_i32_e32 v17, 31, v16
	v_lshlrev_b64 v[18:19], 10, v[16:17]
	v_and_b32_e32 v16, 0x7ff, v16
	s_movk_i32 s4, 0xf80f
	v_cmp_lt_u32_e32 vcc, s40, v16
	v_add3_u32 v16, v16, v20, s4
	v_add_u32_e32 v20, 0xffff00b0, v184
	v_ashrrev_i32_e32 v20, 3, v20
	v_mad_u64_u32 v[20:21], s[4:5], v20, 15, v[174:175]
	v_ashrrev_i32_e32 v17, 31, v16
	v_ashrrev_i32_e32 v21, 31, v20
	v_lshlrev_b64 v[16:17], 11, v[16:17]
	v_lshlrev_b64 v[24:25], 11, v[20:21]
	v_lshl_add_u64 v[18:19], s[20:21], 0, v[18:19]
	v_lshl_add_u64 v[18:19], v[128:129], 1, v[18:19]
	s_or_b64 s[4:5], s[38:39], vcc
	v_cndmask_b32_e64 v17, v17, v25, s[38:39]
	v_cndmask_b32_e64 v16, v16, v24, s[38:39]
	v_cvt_pk_bf16_f32 v20, v12, v13
	v_cvt_pk_bf16_f32 v21, v14, v15
	v_cvt_pk_bf16_f32 v22, v8, v9
	v_cvt_pk_bf16_f32 v23, v10, v11
	global_store_dwordx4 v[18:19], v[20:23], off nt
	s_and_saveexec_b64 s[6:7], s[4:5]
	s_cbranch_execz .LBB0_421
	s_add_u32 s0, s84, s0
	s_addc_u32 s1, s85, s1
	v_lshl_add_u64 v[20:21], s[0:1], 0, v[16:17]
	v_lshl_add_u64 v[20:21], v[128:129], 2, v[20:21]
	global_store_dwordx4 v[20:21], v[12:15], off nt
	global_store_dwordx4 v[20:21], v[8:11], off offset:16 nt
.LBB0_421:
	s_or_b64 exec, exec, s[6:7]
	s_nop 0
	v_cvt_pk_bf16_f32 v8, v4, v5
	v_cvt_pk_bf16_f32 v9, v6, v7
	v_cvt_pk_bf16_f32 v10, v0, v1
	v_cvt_pk_bf16_f32 v11, v2, v3
	global_store_dwordx4 v[18:19], v[8:11], off offset:256 nt
	s_and_saveexec_b64 s[0:1], s[4:5]
	s_cbranch_execz .LBB0_423
	s_and_b64 s[4:5], s[38:39], exec
	s_mov_b32 s4, 0x1acf0000
	s_cselect_b32 s4, s4, 0x10400000
	s_add_u32 s4, s84, s4
	s_addc_u32 s5, s85, 0
	v_lshl_add_u64 v[8:9], s[4:5], 0, v[16:17]
	v_lshl_add_u64 v[8:9], v[128:129], 2, v[8:9]
	global_store_dwordx4 v[8:9], v[4:7], off offset:512 nt
	global_store_dwordx4 v[8:9], v[0:3], off offset:528 nt

; __device__ __forceinline__ u32x4 pack8(const f32x4 a, const f32x4 b) { u32x4 w; w.x = cvt_pk_bf16(a[0], a[1]); w.y = cvt_pk_bf16(a[2], a[3]); w.z = cvt_pk_bf16(b[0], b[1]); w.w = cvt_pk_bf16(b[2], b[3]); return w; }
; __device__ __forceinline__ void unpack8(const u32x4 w, f32x4& a, f32x4& b) { a = (f32x4){bflo(w.x), bfhi(w.x), bflo(w.y), bfhi(w.y)}; b = (f32x4){bflo(w.z), bfhi(w.z), bflo(w.w), bfhi(w.w)}; }
;     __device__ __forceinline__ void operator()(const f32x4 (&acc)[2][2][4][2], const Unit& u, int wr, int wc, int fr, int fq) const {
;         const int rbase = u.pm * 256 + wr * 64 + fr, cb = u.pn * 256 + wc * 32 + fq * 8;
; #pragma unroll
;         for (int ai = 0; ai < 2; ++ai)
; #pragma unroll
;             for (int m = 0; m < 4; ++m) { const size_t ro = (size_t)(rbase + ai * 128 + m * 16) * 1024 + cb;
; #pragma unroll
;                 for (int bj = 0; bj < 2; ++bj) { f32x4 g0, g1; unpack8(*(const u32x4*)(G + ro + bj * 128), g0, g1);
;                     f32x4 v0 = acc[ai][bj][m][0] * g0, v1 = acc[ai][bj][m][1] * g1;
;                     if (!FIRST) { f32x4 o0, o1; unpack8(*(const u32x4*)(O + ro + bj * 128), o0, o1); v0 += o0; v1 += o1; }
;                     *(u32x4*)(O + ro + bj * 128) = pack8(v0, v1); }
;                 asm volatile("" ::: "memory"); }
;     }
.LBB0_1287:
	v_lshl_add_u32 v148, s34, 8, v150
	v_lshl_or_b32 v146, s69, 8, v152
	v_ashrrev_i32_e32 v149, 31, v148
	v_ashrrev_i32_e32 v147, 31, v146
	v_lshlrev_b64 v[144:145], 10, v[148:149]
	v_lshl_add_u64 v[144:145], v[144:145], 0, v[146:147]
	v_lshlrev_b64 v[144:145], 1, v[144:145]
	v_lshl_add_u64 v[160:161], s[10:11], 0, v[144:145]
	global_load_dwordx4 v[156:159], v[160:161], off
	s_andn2_b64 vcc, exec, s[0:1]
	s_mov_b64 s[0:1], -1
	s_waitcnt vmcnt(0)
	v_lshlrev_b32_e32 v162, 16, v156
	v_and_b32_e32 v163, 0xffff0000, v156
	v_lshlrev_b32_e32 v156, 16, v157
	v_and_b32_e32 v157, 0xffff0000, v157
	v_lshlrev_b32_e32 v164, 16, v158
	v_and_b32_e32 v165, 0xffff0000, v158
	v_lshlrev_b32_e32 v158, 16, v159
	v_and_b32_e32 v159, 0xffff0000, v159
	v_pk_mul_f32 v[126:127], v[126:127], v[156:157]
	v_pk_mul_f32 v[124:125], v[124:125], v[162:163]
	v_pk_mul_f32 v[156:157], v[122:123], v[158:159]
	v_pk_mul_f32 v[122:123], v[120:121], v[164:165]
	v_cvt_pk_bf16_f32 v120, v124, v125
	v_cvt_pk_bf16_f32 v121, v126, v127
	v_lshl_add_u64 v[158:159], s[8:9], 0, v[144:145]
	v_cvt_pk_bf16_f32 v122, v122, v123
	v_cvt_pk_bf16_f32 v123, v156, v157
	global_load_dwordx4 v[124:127], v[160:161], off offset:256
	v_or_b32_e32 v156, 16, v148
	v_ashrrev_i32_e32 v157, 31, v156
	v_lshlrev_b64 v[156:157], 10, v[156:157]
	global_store_dwordx4 v[158:159], v[120:123], off nt
	v_lshl_add_u64 v[156:157], v[156:157], 0, v[146:147]
	v_lshlrev_b64 v[156:157], 1, v[156:157]
	v_lshl_add_u64 v[160:161], s[10:11], 0, v[156:157]
	s_waitcnt vmcnt(1)
	v_lshlrev_b32_e32 v120, 16, v124
	v_and_b32_e32 v121, 0xffff0000, v124
	v_lshlrev_b32_e32 v122, 16, v125
	v_and_b32_e32 v123, 0xffff0000, v125
	v_lshlrev_b32_e32 v124, 16, v126
	v_and_b32_e32 v125, 0xffff0000, v126
	v_lshlrev_b32_e32 v126, 16, v127
	v_and_b32_e32 v127, 0xffff0000, v127
	v_pk_mul_f32 v[116:117], v[116:117], v[120:121]
	v_pk_mul_f32 v[120:121], v[110:111], v[126:127]
	v_pk_mul_f32 v[110:111], v[108:109], v[124:125]
	v_pk_mul_f32 v[118:119], v[118:119], v[122:123]
	v_cvt_pk_bf16_f32 v108, v116, v117
	s_nop 0
	v_cvt_pk_bf16_f32 v109, v118, v119
	v_cvt_pk_bf16_f32 v110, v110, v111
	v_cvt_pk_bf16_f32 v111, v120, v121
	global_store_dwordx4 v[158:159], v[108:111], off offset:256 nt
	global_load_dwordx4 v[108:111], v[160:161], off
	s_waitcnt vmcnt(0)
	v_lshlrev_b32_e32 v116, 16, v108
	v_and_b32_e32 v117, 0xffff0000, v108
	v_lshlrev_b32_e32 v108, 16, v109
	v_and_b32_e32 v109, 0xffff0000, v109
	v_lshlrev_b32_e32 v118, 16, v110
	v_and_b32_e32 v119, 0xffff0000, v110
	v_lshlrev_b32_e32 v110, 16, v111
	v_and_b32_e32 v111, 0xffff0000, v111
	v_pk_mul_f32 v[108:109], v[114:115], v[108:109]
	v_pk_mul_f32 v[110:111], v[106:107], v[110:111]
	v_pk_mul_f32 v[106:107], v[104:105], v[118:119]
	v_pk_mul_f32 v[112:113], v[112:113], v[116:117]
	v_lshl_add_u64 v[114:115], s[8:9], 0, v[156:157]
	v_cvt_pk_bf16_f32 v104, v112, v113
	v_cvt_pk_bf16_f32 v105, v108, v109
	v_cvt_pk_bf16_f32 v106, v106, v107
	v_cvt_pk_bf16_f32 v107, v110, v111
	global_load_dwordx4 v[108:111], v[160:161], off offset:256
	v_or_b32_e32 v112, 32, v148
	v_ashrrev_i32_e32 v113, 31, v112
	v_lshlrev_b64 v[112:113], 10, v[112:113]
	global_store_dwordx4 v[114:115], v[104:107], off nt
	v_lshl_add_u64 v[112:113], v[112:113], 0, v[146:147]
	v_lshlrev_b64 v[112:113], 1, v[112:113]
	v_lshl_add_u64 v[116:117], s[10:11], 0, v[112:113]
	s_waitcnt vmcnt(1)
	v_lshlrev_b32_e32 v104, 16, v108
	v_and_b32_e32 v105, 0xffff0000, v108
	v_lshlrev_b32_e32 v106, 16, v109
	v_and_b32_e32 v107, 0xffff0000, v109
	v_lshlrev_b32_e32 v108, 16, v110
	v_and_b32_e32 v109, 0xffff0000, v110
	v_lshlrev_b32_e32 v110, 16, v111
	v_and_b32_e32 v111, 0xffff0000, v111
	v_pk_mul_f32 v[100:101], v[100:101], v[104:105]
	v_pk_mul_f32 v[104:105], v[94:95], v[110:111]
	v_pk_mul_f32 v[94:95], v[92:93], v[108:109]
	v_pk_mul_f32 v[102:103], v[102:103], v[106:107]
	v_cvt_pk_bf16_f32 v92, v100, v101
	s_nop 0
	v_cvt_pk_bf16_f32 v93, v102, v103
	v_cvt_pk_bf16_f32 v94, v94, v95
	v_cvt_pk_bf16_f32 v95, v104, v105
	global_store_dwordx4 v[114:115], v[92:95], off offset:256 nt
	global_load_dwordx4 v[92:95], v[116:117], off
	s_waitcnt vmcnt(0)
	v_lshlrev_b32_e32 v100, 16, v92
	v_and_b32_e32 v101, 0xffff0000, v92
	v_lshlrev_b32_e32 v92, 16, v93
	v_and_b32_e32 v93, 0xffff0000, v93
	v_lshlrev_b32_e32 v102, 16, v94
	v_and_b32_e32 v103, 0xffff0000, v94
	v_lshlrev_b32_e32 v94, 16, v95
	v_and_b32_e32 v95, 0xffff0000, v95
	v_pk_mul_f32 v[92:93], v[98:99], v[92:93]
	v_pk_mul_f32 v[94:95], v[90:91], v[94:95]
	v_pk_mul_f32 v[90:91], v[88:89], v[102:103]
	v_pk_mul_f32 v[96:97], v[96:97], v[100:101]
	v_lshl_add_u64 v[98:99], s[8:9], 0, v[112:113]
	v_cvt_pk_bf16_f32 v88, v96, v97
	v_cvt_pk_bf16_f32 v89, v92, v93
	v_cvt_pk_bf16_f32 v90, v90, v91
	v_cvt_pk_bf16_f32 v91, v94, v95
	global_load_dwordx4 v[92:95], v[116:117], off offset:256
	v_or_b32_e32 v96, 48, v148
	v_ashrrev_i32_e32 v97, 31, v96
	v_lshlrev_b64 v[96:97], 10, v[96:97]
	global_store_dwordx4 v[98:99], v[88:91], off nt
	v_lshl_add_u64 v[96:97], v[96:97], 0, v[146:147]
	v_lshlrev_b64 v[96:97], 1, v[96:97]
	v_lshl_add_u64 v[100:101], s[10:11], 0, v[96:97]
	s_waitcnt vmcnt(1)
	v_lshlrev_b32_e32 v88, 16, v92
	v_and_b32_e32 v89, 0xffff0000, v92
	v_lshlrev_b32_e32 v90, 16, v93
	v_and_b32_e32 v91, 0xffff0000, v93
	v_lshlrev_b32_e32 v92, 16, v94
	v_and_b32_e32 v93, 0xffff0000, v94
	v_lshlrev_b32_e32 v94, 16, v95
	v_and_b32_e32 v95, 0xffff0000, v95
	v_pk_mul_f32 v[84:85], v[84:85], v[88:89]
	v_pk_mul_f32 v[88:89], v[78:79], v[94:95]
	v_pk_mul_f32 v[78:79], v[76:77], v[92:93]
	v_pk_mul_f32 v[86:87], v[86:87], v[90:91]
	v_cvt_pk_bf16_f32 v76, v84, v85
	s_nop 0
	v_cvt_pk_bf16_f32 v77, v86, v87
	v_cvt_pk_bf16_f32 v78, v78, v79
	v_cvt_pk_bf16_f32 v79, v88, v89
	global_store_dwordx4 v[98:99], v[76:79], off offset:256 nt
	global_load_dwordx4 v[76:79], v[100:101], off
	s_waitcnt vmcnt(0)
; __device__ __forceinline__ u32x4 pack8(const f32x4 a, const f32x4 b) { u32x4 w; w.x = cvt_pk_bf16(a[0], a[1]); w.y = cvt_pk_bf16(a[2], a[3]); w.z = cvt_pk_bf16(b[0], b[1]); w.w = cvt_pk_bf16(b[2], b[3]); return w; }
; __device__ __forceinline__ void unpack8(const u32x4 w, f32x4& a, f32x4& b) { a = (f32x4){bflo(w.x), bfhi(w.x), bflo(w.y), bfhi(w.y)}; b = (f32x4){bflo(w.z), bfhi(w.z), bflo(w.w), bfhi(w.w)}; }
;     __device__ __forceinline__ void operator()(const f32x4 (&acc)[2][2][4][2], const Unit& u, int wr, int wc, int fr, int fq) const {
;         const int rbase = u.pm * 256 + wr * 64 + fr, cb = u.pn * 256 + wc * 32 + fq * 8;
; #pragma unroll
;         for (int ai = 0; ai < 2; ++ai)
; #pragma unroll
;             for (int m = 0; m < 4; ++m) { const size_t ro = (size_t)(rbase + ai * 128 + m * 16) * 1024 + cb;
; #pragma unroll
;                 for (int bj = 0; bj < 2; ++bj) { f32x4 g0, g1; unpack8(*(const u32x4*)(G + ro + bj * 128), g0, g1);
;                     f32x4 v0 = acc[ai][bj][m][0] * g0, v1 = acc[ai][bj][m][1] * g1;
;                     if (!FIRST) { f32x4 o0, o1; unpack8(*(const u32x4*)(O + ro + bj * 128), o0, o1); v0 += o0; v1 += o1; }
;                     *(u32x4*)(O + ro + bj * 128) = pack8(v0, v1); }
;                 asm volatile("" ::: "memory"); }
;     }
	v_lshlrev_b32_e32 v84, 16, v76
	v_and_b32_e32 v85, 0xffff0000, v76
	v_lshlrev_b32_e32 v76, 16, v77
	v_and_b32_e32 v77, 0xffff0000, v77
	v_lshlrev_b32_e32 v86, 16, v78
	v_and_b32_e32 v87, 0xffff0000, v78
	v_lshlrev_b32_e32 v78, 16, v79
	v_and_b32_e32 v79, 0xffff0000, v79
	v_pk_mul_f32 v[76:77], v[82:83], v[76:77]
	v_pk_mul_f32 v[78:79], v[74:75], v[78:79]
	v_pk_mul_f32 v[74:75], v[72:73], v[86:87]
	v_pk_mul_f32 v[80:81], v[80:81], v[84:85]
	v_lshl_add_u64 v[82:83], s[8:9], 0, v[96:97]
	v_cvt_pk_bf16_f32 v72, v80, v81
	v_cvt_pk_bf16_f32 v73, v76, v77
	v_cvt_pk_bf16_f32 v74, v74, v75
	v_cvt_pk_bf16_f32 v75, v78, v79
	global_load_dwordx4 v[76:79], v[100:101], off offset:256
	v_lshl_add_u64 v[80:81], v[144:145], 0, s[16:17]
	global_store_dwordx4 v[82:83], v[72:75], off nt
	v_lshl_add_u64 v[84:85], s[10:11], 0, v[80:81]
	s_waitcnt vmcnt(1)
	v_lshlrev_b32_e32 v72, 16, v76
	v_and_b32_e32 v73, 0xffff0000, v76
	v_lshlrev_b32_e32 v74, 16, v77
	v_and_b32_e32 v75, 0xffff0000, v77
	v_lshlrev_b32_e32 v76, 16, v78
	v_and_b32_e32 v77, 0xffff0000, v78
	v_lshlrev_b32_e32 v78, 16, v79
	v_and_b32_e32 v79, 0xffff0000, v79
	v_pk_mul_f32 v[68:69], v[68:69], v[72:73]
	v_pk_mul_f32 v[72:73], v[66:67], v[78:79]
	v_pk_mul_f32 v[66:67], v[64:65], v[76:77]
	v_pk_mul_f32 v[70:71], v[70:71], v[74:75]
	v_cvt_pk_bf16_f32 v64, v68, v69
	s_nop 0
	v_cvt_pk_bf16_f32 v65, v70, v71
	v_cvt_pk_bf16_f32 v66, v66, v67
	v_cvt_pk_bf16_f32 v67, v72, v73
	global_store_dwordx4 v[82:83], v[64:67], off offset:256 nt
	global_load_dwordx4 v[64:67], v[84:85], off
	s_waitcnt vmcnt(0)
	v_lshlrev_b32_e32 v68, 16, v64
	v_and_b32_e32 v69, 0xffff0000, v64
	v_lshlrev_b32_e32 v64, 16, v65
	v_and_b32_e32 v65, 0xffff0000, v65
	v_lshlrev_b32_e32 v70, 16, v66
	v_and_b32_e32 v71, 0xffff0000, v66
	v_lshlrev_b32_e32 v66, 16, v67
	v_and_b32_e32 v67, 0xffff0000, v67
	v_pk_mul_f32 v[62:63], v[62:63], v[64:65]
	v_pk_mul_f32 v[60:61], v[60:61], v[68:69]
	v_pk_mul_f32 v[64:65], v[58:59], v[66:67]
	v_pk_mul_f32 v[58:59], v[56:57], v[70:71]
	v_cvt_pk_bf16_f32 v56, v60, v61
	v_cvt_pk_bf16_f32 v57, v62, v63
	v_lshl_add_u64 v[66:67], s[8:9], 0, v[80:81]
	v_cvt_pk_bf16_f32 v58, v58, v59
	v_cvt_pk_bf16_f32 v59, v64, v65
	global_load_dwordx4 v[60:63], v[84:85], off offset:256
	v_lshl_add_u64 v[64:65], v[144:145], 0, s[18:19]
	global_store_dwordx4 v[66:67], v[56:59], off nt
	v_lshl_add_u64 v[68:69], s[10:11], 0, v[64:65]
	s_waitcnt vmcnt(1)
	v_lshlrev_b32_e32 v56, 16, v60
	v_and_b32_e32 v57, 0xffff0000, v60
	v_lshlrev_b32_e32 v58, 16, v61
	v_and_b32_e32 v59, 0xffff0000, v61
	v_lshlrev_b32_e32 v60, 16, v62
	v_and_b32_e32 v61, 0xffff0000, v62
	v_lshlrev_b32_e32 v62, 16, v63
	v_and_b32_e32 v63, 0xffff0000, v63
	v_pk_mul_f32 v[52:53], v[52:53], v[56:57]
	v_pk_mul_f32 v[56:57], v[46:47], v[62:63]
	v_pk_mul_f32 v[46:47], v[44:45], v[60:61]
	v_pk_mul_f32 v[54:55], v[54:55], v[58:59]
	v_cvt_pk_bf16_f32 v44, v52, v53
	s_nop 0
	v_cvt_pk_bf16_f32 v45, v54, v55
	v_cvt_pk_bf16_f32 v46, v46, v47
	v_cvt_pk_bf16_f32 v47, v56, v57
	global_store_dwordx4 v[66:67], v[44:47], off offset:256 nt
	global_load_dwordx4 v[44:47], v[68:69], off
	s_waitcnt vmcnt(0)
	v_lshlrev_b32_e32 v52, 16, v44
	v_and_b32_e32 v53, 0xffff0000, v44
	v_lshlrev_b32_e32 v44, 16, v45
	v_and_b32_e32 v45, 0xffff0000, v45
	v_lshlrev_b32_e32 v54, 16, v46
	v_and_b32_e32 v55, 0xffff0000, v46
	v_lshlrev_b32_e32 v46, 16, v47
	v_and_b32_e32 v47, 0xffff0000, v47
	v_pk_mul_f32 v[44:45], v[50:51], v[44:45]
	v_pk_mul_f32 v[46:47], v[42:43], v[46:47]
	v_pk_mul_f32 v[42:43], v[40:41], v[54:55]
	v_pk_mul_f32 v[48:49], v[48:49], v[52:53]
	v_lshl_add_u64 v[50:51], s[8:9], 0, v[64:65]
	v_cvt_pk_bf16_f32 v40, v48, v49
	v_cvt_pk_bf16_f32 v41, v44, v45
	v_cvt_pk_bf16_f32 v42, v42, v43
	v_cvt_pk_bf16_f32 v43, v46, v47
	global_load_dwordx4 v[44:47], v[68:69], off offset:256
	v_lshl_add_u64 v[48:49], v[144:145], 0, s[20:21]
	global_store_dwordx4 v[50:51], v[40:43], off nt
	v_lshl_add_u64 v[52:53], s[10:11], 0, v[48:49]
	s_waitcnt vmcnt(1)
; __device__ __forceinline__ u32x4 pack8(const f32x4 a, const f32x4 b) { u32x4 w; w.x = cvt_pk_bf16(a[0], a[1]); w.y = cvt_pk_bf16(a[2], a[3]); w.z = cvt_pk_bf16(b[0], b[1]); w.w = cvt_pk_bf16(b[2], b[3]); return w; }
; __device__ __forceinline__ void unpack8(const u32x4 w, f32x4& a, f32x4& b) { a = (f32x4){bflo(w.x), bfhi(w.x), bflo(w.y), bfhi(w.y)}; b = (f32x4){bflo(w.z), bfhi(w.z), bflo(w.w), bfhi(w.w)}; }
;     __device__ __forceinline__ void operator()(const f32x4 (&acc)[2][2][4][2], const Unit& u, int wr, int wc, int fr, int fq) const {
;         const int rbase = u.pm * 256 + wr * 64 + fr, cb = u.pn * 256 + wc * 32 + fq * 8;
; #pragma unroll
;         for (int ai = 0; ai < 2; ++ai)
; #pragma unroll
;             for (int m = 0; m < 4; ++m) { const size_t ro = (size_t)(rbase + ai * 128 + m * 16) * 1024 + cb;
; #pragma unroll
;                 for (int bj = 0; bj < 2; ++bj) { f32x4 g0, g1; unpack8(*(const u32x4*)(G + ro + bj * 128), g0, g1);
;                     f32x4 v0 = acc[ai][bj][m][0] * g0, v1 = acc[ai][bj][m][1] * g1;
;                     if (!FIRST) { f32x4 o0, o1; unpack8(*(const u32x4*)(O + ro + bj * 128), o0, o1); v0 += o0; v1 += o1; }
;                     *(u32x4*)(O + ro + bj * 128) = pack8(v0, v1); }
;                 asm volatile("" ::: "memory"); }
;     }
	v_lshlrev_b32_e32 v40, 16, v44
	v_and_b32_e32 v41, 0xffff0000, v44
	v_lshlrev_b32_e32 v42, 16, v45
	v_and_b32_e32 v43, 0xffff0000, v45
	v_lshlrev_b32_e32 v44, 16, v46
	v_and_b32_e32 v45, 0xffff0000, v46
	v_lshlrev_b32_e32 v46, 16, v47
	v_and_b32_e32 v47, 0xffff0000, v47
	v_pk_mul_f32 v[36:37], v[36:37], v[40:41]
	v_pk_mul_f32 v[40:41], v[30:31], v[46:47]
	v_pk_mul_f32 v[30:31], v[28:29], v[44:45]
	v_pk_mul_f32 v[38:39], v[38:39], v[42:43]
	v_cvt_pk_bf16_f32 v28, v36, v37
	s_nop 0
	v_cvt_pk_bf16_f32 v29, v38, v39
	v_cvt_pk_bf16_f32 v30, v30, v31
	v_cvt_pk_bf16_f32 v31, v40, v41
	global_store_dwordx4 v[50:51], v[28:31], off offset:256 nt
	global_load_dwordx4 v[28:31], v[52:53], off
	s_waitcnt vmcnt(0)
	v_lshlrev_b32_e32 v36, 16, v28
	v_and_b32_e32 v37, 0xffff0000, v28
	v_lshlrev_b32_e32 v28, 16, v29
	v_and_b32_e32 v29, 0xffff0000, v29
	v_lshlrev_b32_e32 v38, 16, v30
	v_and_b32_e32 v39, 0xffff0000, v30
	v_lshlrev_b32_e32 v30, 16, v31
	v_and_b32_e32 v31, 0xffff0000, v31
	v_pk_mul_f32 v[28:29], v[34:35], v[28:29]
	v_pk_mul_f32 v[30:31], v[26:27], v[30:31]
	v_pk_mul_f32 v[26:27], v[24:25], v[38:39]
	v_pk_mul_f32 v[32:33], v[32:33], v[36:37]
	v_lshl_add_u64 v[34:35], s[8:9], 0, v[48:49]
	v_cvt_pk_bf16_f32 v24, v32, v33
	v_cvt_pk_bf16_f32 v25, v28, v29
	v_cvt_pk_bf16_f32 v26, v26, v27
	v_cvt_pk_bf16_f32 v27, v30, v31
	global_load_dwordx4 v[28:31], v[52:53], off offset:256
	v_lshl_add_u64 v[32:33], v[144:145], 0, s[22:23]
	global_store_dwordx4 v[34:35], v[24:27], off nt
	v_lshl_add_u64 v[36:37], s[10:11], 0, v[32:33]
	s_waitcnt vmcnt(1)
	v_lshlrev_b32_e32 v24, 16, v28
	v_and_b32_e32 v25, 0xffff0000, v28
	v_lshlrev_b32_e32 v26, 16, v29
	v_and_b32_e32 v27, 0xffff0000, v29
	v_lshlrev_b32_e32 v28, 16, v30
	v_and_b32_e32 v29, 0xffff0000, v30
	v_lshlrev_b32_e32 v30, 16, v31
	v_and_b32_e32 v31, 0xffff0000, v31
	v_pk_mul_f32 v[20:21], v[20:21], v[24:25]
	v_pk_mul_f32 v[24:25], v[14:15], v[30:31]
	v_pk_mul_f32 v[14:15], v[12:13], v[28:29]
	v_pk_mul_f32 v[22:23], v[22:23], v[26:27]
	v_cvt_pk_bf16_f32 v12, v20, v21
	s_nop 0
	v_cvt_pk_bf16_f32 v13, v22, v23
	v_cvt_pk_bf16_f32 v14, v14, v15
	v_cvt_pk_bf16_f32 v15, v24, v25
	global_store_dwordx4 v[34:35], v[12:15], off offset:256 nt
	global_load_dwordx4 v[12:15], v[36:37], off
	s_waitcnt vmcnt(0)
	v_lshlrev_b32_e32 v20, 16, v12
	v_and_b32_e32 v21, 0xffff0000, v12
	v_lshlrev_b32_e32 v12, 16, v13
	v_and_b32_e32 v13, 0xffff0000, v13
	v_lshlrev_b32_e32 v22, 16, v14
	v_and_b32_e32 v23, 0xffff0000, v14
	v_lshlrev_b32_e32 v14, 16, v15
	v_and_b32_e32 v15, 0xffff0000, v15
	v_pk_mul_f32 v[12:13], v[18:19], v[12:13]
	v_pk_mul_f32 v[14:15], v[10:11], v[14:15]
	v_pk_mul_f32 v[10:11], v[8:9], v[22:23]
	v_pk_mul_f32 v[16:17], v[16:17], v[20:21]
	s_nop 0
	v_cvt_pk_bf16_f32 v8, v16, v17
	v_cvt_pk_bf16_f32 v9, v12, v13
	v_cvt_pk_bf16_f32 v10, v10, v11
	v_cvt_pk_bf16_f32 v11, v14, v15
	global_load_dwordx4 v[12:15], v[36:37], off offset:256
	v_lshl_add_u64 v[16:17], s[8:9], 0, v[32:33]
	global_store_dwordx4 v[16:17], v[8:11], off nt
	s_waitcnt vmcnt(1)
	s_nop 0
	v_lshlrev_b32_e32 v8, 16, v12
	v_and_b32_e32 v9, 0xffff0000, v12
	v_lshlrev_b32_e32 v10, 16, v13
	v_and_b32_e32 v11, 0xffff0000, v13
	v_lshlrev_b32_e32 v12, 16, v14
	v_and_b32_e32 v13, 0xffff0000, v14
	v_lshlrev_b32_e32 v14, 16, v15
	v_and_b32_e32 v15, 0xffff0000, v15
	v_pk_mul_f32 v[4:5], v[4:5], v[8:9]
	v_pk_mul_f32 v[8:9], v[2:3], v[14:15]
	v_pk_mul_f32 v[2:3], v[0:1], v[12:13]
	v_pk_mul_f32 v[6:7], v[6:7], v[10:11]
	v_cvt_pk_bf16_f32 v0, v4, v5
	s_nop 0
	v_cvt_pk_bf16_f32 v1, v6, v7
	v_cvt_pk_bf16_f32 v2, v2, v3
	v_cvt_pk_bf16_f32 v3, v8, v9
	global_store_dwordx4 v[16:17], v[0:3], off offset:256 nt
	s_cbranch_vccnz .LBB0_1280
	s_andn2_b64 vcc, exec, s[6:7]
	s_cbranch_vccnz .LBB0_1279
	s_barrier
	s_branch .LBB0_1279

; __device__ __forceinline__ u32x4 pack8(const f32x4 a, const f32x4 b) { u32x4 w; w.x = cvt_pk_bf16(a[0], a[1]); w.y = cvt_pk_bf16(a[2], a[3]); w.z = cvt_pk_bf16(b[0], b[1]); w.w = cvt_pk_bf16(b[2], b[3]); return w; }
; __device__ __forceinline__ void unpack8(const u32x4 w, f32x4& a, f32x4& b) { a = (f32x4){bflo(w.x), bfhi(w.x), bflo(w.y), bfhi(w.y)}; b = (f32x4){bflo(w.z), bfhi(w.z), bflo(w.w), bfhi(w.w)}; }
;     __device__ __forceinline__ void operator()(const f32x4 (&acc)[2][2][4][2], const Unit& u, int wr, int wc, int fr, int fq) const {
;         const int rbase = u.pm * 256 + wr * 64 + fr, cb = u.pn * 256 + wc * 32 + fq * 8;
; #pragma unroll
;         for (int ai = 0; ai < 2; ++ai)
; #pragma unroll
;             for (int m = 0; m < 4; ++m) { const size_t ro = (size_t)(rbase + ai * 128 + m * 16) * 1024 + cb;
; #pragma unroll
;                 for (int bj = 0; bj < 2; ++bj) { f32x4 g0, g1; unpack8(*(const u32x4*)(G + ro + bj * 128), g0, g1);
;                     f32x4 v0 = acc[ai][bj][m][0] * g0, v1 = acc[ai][bj][m][1] * g1;
;                     if (!FIRST) { f32x4 o0, o1; unpack8(*(const u32x4*)(O + ro + bj * 128), o0, o1); v0 += o0; v1 += o1; }
;                     *(u32x4*)(O + ro + bj * 128) = pack8(v0, v1); }
;                 asm volatile("" ::: "memory"); }
.LBB0_1356:
	v_lshl_add_u32 v144, s42, 8, v146
	v_lshl_or_b32 v142, s82, 8, v148
	v_ashrrev_i32_e32 v145, 31, v144
	v_ashrrev_i32_e32 v143, 31, v142
	v_lshlrev_b64 v[140:141], 10, v[144:145]
	v_lshl_add_u64 v[140:141], v[140:141], 0, v[142:143]
	v_lshlrev_b64 v[140:141], 1, v[140:141]
	v_lshl_add_u64 v[162:163], s[12:13], 0, v[140:141]
	v_lshl_add_u64 v[164:165], s[8:9], 0, v[140:141]
	global_load_dwordx4 v[154:157], v[162:163], off
	global_load_dwordx4 v[158:161], v[164:165], off
	s_andn2_b64 vcc, exec, s[4:5]
	s_mov_b64 s[4:5], -1
	s_waitcnt vmcnt(0)
	v_lshlrev_b32_e32 v166, 16, v154
	v_and_b32_e32 v167, 0xffff0000, v154
	v_lshlrev_b32_e32 v154, 16, v155
	v_and_b32_e32 v155, 0xffff0000, v155
	v_lshlrev_b32_e32 v168, 16, v156
	v_and_b32_e32 v169, 0xffff0000, v156
	v_lshlrev_b32_e32 v156, 16, v157
	v_and_b32_e32 v157, 0xffff0000, v157
	v_lshlrev_b32_e32 v170, 16, v158
	v_and_b32_e32 v171, 0xffff0000, v158
	v_lshlrev_b32_e32 v158, 16, v159
	v_and_b32_e32 v159, 0xffff0000, v159
	v_lshlrev_b32_e32 v172, 16, v160
	v_and_b32_e32 v173, 0xffff0000, v160
	v_lshlrev_b32_e32 v160, 16, v161
	v_and_b32_e32 v161, 0xffff0000, v161
	v_pk_fma_f32 v[126:127], v[126:127], v[154:155], v[158:159]
	v_pk_fma_f32 v[124:125], v[124:125], v[166:167], v[170:171]
	v_pk_fma_f32 v[154:155], v[122:123], v[156:157], v[160:161]
	v_pk_fma_f32 v[122:123], v[120:121], v[168:169], v[172:173]
	v_cvt_pk_bf16_f32 v120, v124, v125
	v_cvt_pk_bf16_f32 v121, v126, v127
	v_or_b32_e32 v158, 16, v144
	v_cvt_pk_bf16_f32 v122, v122, v123
	v_cvt_pk_bf16_f32 v123, v154, v155
	global_load_dwordx4 v[124:127], v[162:163], off offset:256
	global_load_dwordx4 v[154:157], v[164:165], off offset:256
	v_ashrrev_i32_e32 v159, 31, v158
	v_lshlrev_b64 v[158:159], 10, v[158:159]
	global_store_dwordx4 v[164:165], v[120:123], off nt
	v_lshl_add_u64 v[158:159], v[158:159], 0, v[142:143]
	v_lshlrev_b64 v[158:159], 1, v[158:159]
	v_lshl_add_u64 v[160:161], s[12:13], 0, v[158:159]
	s_waitcnt vmcnt(2)
	v_lshlrev_b32_e32 v120, 16, v124
	v_and_b32_e32 v121, 0xffff0000, v124
	v_lshlrev_b32_e32 v122, 16, v125
	v_and_b32_e32 v123, 0xffff0000, v125
	s_waitcnt vmcnt(1)
	v_lshlrev_b32_e32 v162, 16, v154
	v_and_b32_e32 v163, 0xffff0000, v154
	v_lshlrev_b32_e32 v154, 16, v155
	v_and_b32_e32 v155, 0xffff0000, v155
	v_lshlrev_b32_e32 v124, 16, v126
	v_and_b32_e32 v125, 0xffff0000, v126
	v_lshlrev_b32_e32 v126, 16, v127
	v_and_b32_e32 v127, 0xffff0000, v127
	v_lshlrev_b32_e32 v166, 16, v156
	v_and_b32_e32 v167, 0xffff0000, v156
	v_lshlrev_b32_e32 v156, 16, v157
	v_and_b32_e32 v157, 0xffff0000, v157
	v_pk_fma_f32 v[114:115], v[114:115], v[122:123], v[154:155]
	v_pk_fma_f32 v[112:113], v[112:113], v[120:121], v[162:163]
	v_pk_fma_f32 v[118:119], v[118:119], v[126:127], v[156:157]
	v_pk_fma_f32 v[116:117], v[116:117], v[124:125], v[166:167]
	v_cvt_pk_bf16_f32 v112, v112, v113
	v_cvt_pk_bf16_f32 v113, v114, v115
	v_lshl_add_u64 v[120:121], s[8:9], 0, v[158:159]
	v_cvt_pk_bf16_f32 v114, v116, v117
	v_cvt_pk_bf16_f32 v115, v118, v119
	global_store_dwordx4 v[164:165], v[112:115], off offset:256 nt
	global_load_dwordx4 v[112:115], v[160:161], off
	global_load_dwordx4 v[116:119], v[120:121], off
	s_waitcnt vmcnt(1)
	v_lshlrev_b32_e32 v122, 16, v112
	v_and_b32_e32 v123, 0xffff0000, v112
	v_lshlrev_b32_e32 v112, 16, v113
	v_and_b32_e32 v113, 0xffff0000, v113
	v_lshlrev_b32_e32 v124, 16, v114
	v_and_b32_e32 v125, 0xffff0000, v114
	v_lshlrev_b32_e32 v114, 16, v115
	v_and_b32_e32 v115, 0xffff0000, v115
	s_waitcnt vmcnt(0)
	v_lshlrev_b32_e32 v126, 16, v116
	v_and_b32_e32 v127, 0xffff0000, v116
	v_lshlrev_b32_e32 v116, 16, v117
	v_and_b32_e32 v117, 0xffff0000, v117
	v_lshlrev_b32_e32 v154, 16, v118
	v_and_b32_e32 v155, 0xffff0000, v118
	v_lshlrev_b32_e32 v118, 16, v119
	v_and_b32_e32 v119, 0xffff0000, v119
	v_pk_fma_f32 v[110:111], v[110:111], v[112:113], v[116:117]
	v_pk_fma_f32 v[108:109], v[108:109], v[122:123], v[126:127]
	v_pk_fma_f32 v[112:113], v[106:107], v[114:115], v[118:119]
	v_pk_fma_f32 v[106:107], v[104:105], v[124:125], v[154:155]
	v_cvt_pk_bf16_f32 v104, v108, v109
	v_cvt_pk_bf16_f32 v105, v110, v111
	v_or_b32_e32 v116, 32, v144
	v_cvt_pk_bf16_f32 v106, v106, v107
	v_cvt_pk_bf16_f32 v107, v112, v113
	global_load_dwordx4 v[108:111], v[160:161], off offset:256
	global_load_dwordx4 v[112:115], v[120:121], off offset:256
	v_ashrrev_i32_e32 v117, 31, v116
	v_lshlrev_b64 v[116:117], 10, v[116:117]
	global_store_dwordx4 v[120:121], v[104:107], off nt
	v_lshl_add_u64 v[116:117], v[116:117], 0, v[142:143]
	v_lshlrev_b64 v[116:117], 1, v[116:117]
	v_lshl_add_u64 v[118:119], s[12:13], 0, v[116:117]
	s_waitcnt vmcnt(2)
	v_lshlrev_b32_e32 v104, 16, v108
	v_and_b32_e32 v105, 0xffff0000, v108
	v_lshlrev_b32_e32 v106, 16, v109
	v_and_b32_e32 v107, 0xffff0000, v109
	s_waitcnt vmcnt(1)
	v_lshlrev_b32_e32 v122, 16, v112
	v_and_b32_e32 v123, 0xffff0000, v112
	v_lshlrev_b32_e32 v112, 16, v113
	v_and_b32_e32 v113, 0xffff0000, v113
	v_lshlrev_b32_e32 v108, 16, v110
	v_and_b32_e32 v109, 0xffff0000, v110
	v_lshlrev_b32_e32 v110, 16, v111
	v_and_b32_e32 v111, 0xffff0000, v111
	v_lshlrev_b32_e32 v124, 16, v114
	v_and_b32_e32 v125, 0xffff0000, v114
	v_lshlrev_b32_e32 v114, 16, v115
	v_and_b32_e32 v115, 0xffff0000, v115
	v_pk_fma_f32 v[98:99], v[98:99], v[106:107], v[112:113]
	v_pk_fma_f32 v[96:97], v[96:97], v[104:105], v[122:123]
	v_pk_fma_f32 v[102:103], v[102:103], v[110:111], v[114:115]
	v_pk_fma_f32 v[100:101], v[100:101], v[108:109], v[124:125]
	v_cvt_pk_bf16_f32 v96, v96, v97
	v_cvt_pk_bf16_f32 v97, v98, v99
	v_lshl_add_u64 v[104:105], s[8:9], 0, v[116:117]
	v_cvt_pk_bf16_f32 v98, v100, v101
	v_cvt_pk_bf16_f32 v99, v102, v103
	global_store_dwordx4 v[120:121], v[96:99], off offset:256 nt
	global_load_dwordx4 v[96:99], v[118:119], off
	global_load_dwordx4 v[100:103], v[104:105], off
	s_waitcnt vmcnt(1)
; __device__ __forceinline__ u32x4 pack8(const f32x4 a, const f32x4 b) { u32x4 w; w.x = cvt_pk_bf16(a[0], a[1]); w.y = cvt_pk_bf16(a[2], a[3]); w.z = cvt_pk_bf16(b[0], b[1]); w.w = cvt_pk_bf16(b[2], b[3]); return w; }
; __device__ __forceinline__ void unpack8(const u32x4 w, f32x4& a, f32x4& b) { a = (f32x4){bflo(w.x), bfhi(w.x), bflo(w.y), bfhi(w.y)}; b = (f32x4){bflo(w.z), bfhi(w.z), bflo(w.w), bfhi(w.w)}; }
;     __device__ __forceinline__ void operator()(const f32x4 (&acc)[2][2][4][2], const Unit& u, int wr, int wc, int fr, int fq) const {
;         const int rbase = u.pm * 256 + wr * 64 + fr, cb = u.pn * 256 + wc * 32 + fq * 8;
; #pragma unroll
;         for (int ai = 0; ai < 2; ++ai)
; #pragma unroll
;             for (int m = 0; m < 4; ++m) { const size_t ro = (size_t)(rbase + ai * 128 + m * 16) * 1024 + cb;
; #pragma unroll
;                 for (int bj = 0; bj < 2; ++bj) { f32x4 g0, g1; unpack8(*(const u32x4*)(G + ro + bj * 128), g0, g1);
;                     f32x4 v0 = acc[ai][bj][m][0] * g0, v1 = acc[ai][bj][m][1] * g1;
;                     if (!FIRST) { f32x4 o0, o1; unpack8(*(const u32x4*)(O + ro + bj * 128), o0, o1); v0 += o0; v1 += o1; }
;                     *(u32x4*)(O + ro + bj * 128) = pack8(v0, v1); }
;                 asm volatile("" ::: "memory"); }
	v_lshlrev_b32_e32 v106, 16, v96
	v_and_b32_e32 v107, 0xffff0000, v96
	v_lshlrev_b32_e32 v96, 16, v97
	v_and_b32_e32 v97, 0xffff0000, v97
	v_lshlrev_b32_e32 v108, 16, v98
	v_and_b32_e32 v109, 0xffff0000, v98
	v_lshlrev_b32_e32 v98, 16, v99
	v_and_b32_e32 v99, 0xffff0000, v99
	s_waitcnt vmcnt(0)
	v_lshlrev_b32_e32 v110, 16, v100
	v_and_b32_e32 v111, 0xffff0000, v100
	v_lshlrev_b32_e32 v100, 16, v101
	v_and_b32_e32 v101, 0xffff0000, v101
	v_lshlrev_b32_e32 v112, 16, v102
	v_and_b32_e32 v113, 0xffff0000, v102
	v_lshlrev_b32_e32 v102, 16, v103
	v_and_b32_e32 v103, 0xffff0000, v103
	v_pk_fma_f32 v[94:95], v[94:95], v[96:97], v[100:101]
	v_pk_fma_f32 v[92:93], v[92:93], v[106:107], v[110:111]
	v_pk_fma_f32 v[96:97], v[90:91], v[98:99], v[102:103]
	v_pk_fma_f32 v[90:91], v[88:89], v[108:109], v[112:113]
	v_cvt_pk_bf16_f32 v88, v92, v93
	v_cvt_pk_bf16_f32 v89, v94, v95
	v_or_b32_e32 v100, 48, v144
	v_cvt_pk_bf16_f32 v90, v90, v91
	v_cvt_pk_bf16_f32 v91, v96, v97
	global_load_dwordx4 v[92:95], v[118:119], off offset:256
	global_load_dwordx4 v[96:99], v[104:105], off offset:256
	v_ashrrev_i32_e32 v101, 31, v100
	v_lshlrev_b64 v[100:101], 10, v[100:101]
	global_store_dwordx4 v[104:105], v[88:91], off nt
	v_lshl_add_u64 v[100:101], v[100:101], 0, v[142:143]
	v_lshlrev_b64 v[100:101], 1, v[100:101]
	v_lshl_add_u64 v[102:103], s[12:13], 0, v[100:101]
	s_waitcnt vmcnt(2)
	v_lshlrev_b32_e32 v88, 16, v92
	v_and_b32_e32 v89, 0xffff0000, v92
	v_lshlrev_b32_e32 v90, 16, v93
	v_and_b32_e32 v91, 0xffff0000, v93
	s_waitcnt vmcnt(1)
	v_lshlrev_b32_e32 v106, 16, v96
	v_and_b32_e32 v107, 0xffff0000, v96
	v_lshlrev_b32_e32 v96, 16, v97
	v_and_b32_e32 v97, 0xffff0000, v97
	v_lshlrev_b32_e32 v92, 16, v94
	v_and_b32_e32 v93, 0xffff0000, v94
	v_lshlrev_b32_e32 v94, 16, v95
	v_and_b32_e32 v95, 0xffff0000, v95
	v_lshlrev_b32_e32 v108, 16, v98
	v_and_b32_e32 v109, 0xffff0000, v98
	v_lshlrev_b32_e32 v98, 16, v99
	v_and_b32_e32 v99, 0xffff0000, v99
	v_pk_fma_f32 v[82:83], v[82:83], v[90:91], v[96:97]
	v_pk_fma_f32 v[80:81], v[80:81], v[88:89], v[106:107]
	v_pk_fma_f32 v[86:87], v[86:87], v[94:95], v[98:99]
	v_pk_fma_f32 v[84:85], v[84:85], v[92:93], v[108:109]
	v_cvt_pk_bf16_f32 v80, v80, v81
	v_cvt_pk_bf16_f32 v81, v82, v83
	v_lshl_add_u64 v[88:89], s[8:9], 0, v[100:101]
	v_cvt_pk_bf16_f32 v82, v84, v85
	v_cvt_pk_bf16_f32 v83, v86, v87
	global_store_dwordx4 v[104:105], v[80:83], off offset:256 nt
	global_load_dwordx4 v[80:83], v[102:103], off
	global_load_dwordx4 v[84:87], v[88:89], off
	s_waitcnt vmcnt(1)
	v_lshlrev_b32_e32 v90, 16, v80
	v_and_b32_e32 v91, 0xffff0000, v80
	v_lshlrev_b32_e32 v80, 16, v81
	v_and_b32_e32 v81, 0xffff0000, v81
	v_lshlrev_b32_e32 v92, 16, v82
	v_and_b32_e32 v93, 0xffff0000, v82
	v_lshlrev_b32_e32 v82, 16, v83
	v_and_b32_e32 v83, 0xffff0000, v83
	s_waitcnt vmcnt(0)
	v_lshlrev_b32_e32 v94, 16, v84
	v_and_b32_e32 v95, 0xffff0000, v84
	v_lshlrev_b32_e32 v84, 16, v85
	v_and_b32_e32 v85, 0xffff0000, v85
	v_lshlrev_b32_e32 v96, 16, v86
	v_and_b32_e32 v97, 0xffff0000, v86
	v_lshlrev_b32_e32 v86, 16, v87
	v_and_b32_e32 v87, 0xffff0000, v87
	v_pk_fma_f32 v[78:79], v[78:79], v[80:81], v[84:85]
	v_pk_fma_f32 v[76:77], v[76:77], v[90:91], v[94:95]
	v_pk_fma_f32 v[80:81], v[74:75], v[82:83], v[86:87]
	v_pk_fma_f32 v[74:75], v[72:73], v[92:93], v[96:97]
	v_cvt_pk_bf16_f32 v72, v76, v77
	v_cvt_pk_bf16_f32 v73, v78, v79
	v_lshl_add_u64 v[84:85], v[140:141], 0, s[24:25]
	v_cvt_pk_bf16_f32 v74, v74, v75
	v_cvt_pk_bf16_f32 v75, v80, v81
	global_load_dwordx4 v[76:79], v[102:103], off offset:256
	global_load_dwordx4 v[80:83], v[88:89], off offset:256
	v_lshl_add_u64 v[86:87], s[12:13], 0, v[84:85]
	global_store_dwordx4 v[88:89], v[72:75], off nt
	s_waitcnt vmcnt(1)
	v_lshlrev_b32_e32 v90, 16, v80
	v_lshlrev_b32_e32 v72, 16, v76
	v_and_b32_e32 v73, 0xffff0000, v76
	v_lshlrev_b32_e32 v74, 16, v77
	v_and_b32_e32 v75, 0xffff0000, v77
	v_and_b32_e32 v91, 0xffff0000, v80
	v_lshlrev_b32_e32 v80, 16, v81
	v_and_b32_e32 v81, 0xffff0000, v81
	v_lshlrev_b32_e32 v76, 16, v78
	v_and_b32_e32 v77, 0xffff0000, v78
	v_lshlrev_b32_e32 v78, 16, v79
	v_and_b32_e32 v79, 0xffff0000, v79
	v_lshlrev_b32_e32 v92, 16, v82
	v_and_b32_e32 v93, 0xffff0000, v82
	v_lshlrev_b32_e32 v82, 16, v83
	v_and_b32_e32 v83, 0xffff0000, v83
	v_pk_fma_f32 v[66:67], v[66:67], v[74:75], v[80:81]
	v_pk_fma_f32 v[64:65], v[64:65], v[72:73], v[90:91]
	v_pk_fma_f32 v[70:71], v[70:71], v[78:79], v[82:83]
	v_pk_fma_f32 v[68:69], v[68:69], v[76:77], v[92:93]
	v_cvt_pk_bf16_f32 v64, v64, v65
	v_cvt_pk_bf16_f32 v65, v66, v67
	v_lshl_add_u64 v[72:73], s[8:9], 0, v[84:85]
	v_cvt_pk_bf16_f32 v66, v68, v69
	v_cvt_pk_bf16_f32 v67, v70, v71
	global_store_dwordx4 v[88:89], v[64:67], off offset:256 nt
	global_load_dwordx4 v[64:67], v[86:87], off
	global_load_dwordx4 v[68:71], v[72:73], off
	s_waitcnt vmcnt(1)
	v_lshlrev_b32_e32 v74, 16, v64
	v_and_b32_e32 v75, 0xffff0000, v64
	v_lshlrev_b32_e32 v64, 16, v65
	v_and_b32_e32 v65, 0xffff0000, v65
	v_lshlrev_b32_e32 v76, 16, v66
	v_and_b32_e32 v77, 0xffff0000, v66
	v_lshlrev_b32_e32 v66, 16, v67
	v_and_b32_e32 v67, 0xffff0000, v67
	s_waitcnt vmcnt(0)
	v_lshlrev_b32_e32 v78, 16, v68
	v_and_b32_e32 v79, 0xffff0000, v68
	v_lshlrev_b32_e32 v68, 16, v69
	v_and_b32_e32 v69, 0xffff0000, v69
	v_lshlrev_b32_e32 v80, 16, v70
	v_and_b32_e32 v81, 0xffff0000, v70
	v_lshlrev_b32_e32 v70, 16, v71
	v_and_b32_e32 v71, 0xffff0000, v71
	v_pk_fma_f32 v[62:63], v[62:63], v[64:65], v[68:69]
	v_pk_fma_f32 v[60:61], v[60:61], v[74:75], v[78:79]
	v_pk_fma_f32 v[64:65], v[58:59], v[66:67], v[70:71]
	v_pk_fma_f32 v[58:59], v[56:57], v[76:77], v[80:81]
	v_cvt_pk_bf16_f32 v56, v60, v61
	v_cvt_pk_bf16_f32 v57, v62, v63
	v_lshl_add_u64 v[68:69], v[140:141], 0, s[26:27]
	v_cvt_pk_bf16_f32 v58, v58, v59
	v_cvt_pk_bf16_f32 v59, v64, v65
	global_load_dwordx4 v[60:63], v[86:87], off offset:256
	global_load_dwordx4 v[64:67], v[72:73], off offset:256
	v_lshl_add_u64 v[70:71], s[12:13], 0, v[68:69]
	global_store_dwordx4 v[72:73], v[56:59], off nt
	s_waitcnt vmcnt(1)
; __device__ __forceinline__ u32x4 pack8(const f32x4 a, const f32x4 b) { u32x4 w; w.x = cvt_pk_bf16(a[0], a[1]); w.y = cvt_pk_bf16(a[2], a[3]); w.z = cvt_pk_bf16(b[0], b[1]); w.w = cvt_pk_bf16(b[2], b[3]); return w; }
; __device__ __forceinline__ void unpack8(const u32x4 w, f32x4& a, f32x4& b) { a = (f32x4){bflo(w.x), bfhi(w.x), bflo(w.y), bfhi(w.y)}; b = (f32x4){bflo(w.z), bfhi(w.z), bflo(w.w), bfhi(w.w)}; }
;     __device__ __forceinline__ void operator()(const f32x4 (&acc)[2][2][4][2], const Unit& u, int wr, int wc, int fr, int fq) const {
;         const int rbase = u.pm * 256 + wr * 64 + fr, cb = u.pn * 256 + wc * 32 + fq * 8;
; #pragma unroll
;         for (int ai = 0; ai < 2; ++ai)
; #pragma unroll
;             for (int m = 0; m < 4; ++m) { const size_t ro = (size_t)(rbase + ai * 128 + m * 16) * 1024 + cb;
; #pragma unroll
;                 for (int bj = 0; bj < 2; ++bj) { f32x4 g0, g1; unpack8(*(const u32x4*)(G + ro + bj * 128), g0, g1);
;                     f32x4 v0 = acc[ai][bj][m][0] * g0, v1 = acc[ai][bj][m][1] * g1;
;                     if (!FIRST) { f32x4 o0, o1; unpack8(*(const u32x4*)(O + ro + bj * 128), o0, o1); v0 += o0; v1 += o1; }
;                     *(u32x4*)(O + ro + bj * 128) = pack8(v0, v1); }
;                 asm volatile("" ::: "memory"); }
	v_lshlrev_b32_e32 v74, 16, v64
	v_lshlrev_b32_e32 v56, 16, v60
	v_and_b32_e32 v57, 0xffff0000, v60
	v_lshlrev_b32_e32 v58, 16, v61
	v_and_b32_e32 v59, 0xffff0000, v61
	v_and_b32_e32 v75, 0xffff0000, v64
	v_lshlrev_b32_e32 v64, 16, v65
	v_and_b32_e32 v65, 0xffff0000, v65
	v_lshlrev_b32_e32 v60, 16, v62
	v_and_b32_e32 v61, 0xffff0000, v62
	v_lshlrev_b32_e32 v62, 16, v63
	v_and_b32_e32 v63, 0xffff0000, v63
	v_lshlrev_b32_e32 v76, 16, v66
	v_and_b32_e32 v77, 0xffff0000, v66
	v_lshlrev_b32_e32 v66, 16, v67
	v_and_b32_e32 v67, 0xffff0000, v67
	v_pk_fma_f32 v[50:51], v[50:51], v[58:59], v[64:65]
	v_pk_fma_f32 v[48:49], v[48:49], v[56:57], v[74:75]
	v_pk_fma_f32 v[54:55], v[54:55], v[62:63], v[66:67]
	v_pk_fma_f32 v[52:53], v[52:53], v[60:61], v[76:77]
	v_cvt_pk_bf16_f32 v48, v48, v49
	v_cvt_pk_bf16_f32 v49, v50, v51
	v_lshl_add_u64 v[56:57], s[8:9], 0, v[68:69]
	v_cvt_pk_bf16_f32 v50, v52, v53
	v_cvt_pk_bf16_f32 v51, v54, v55
	global_store_dwordx4 v[72:73], v[48:51], off offset:256 nt
	global_load_dwordx4 v[48:51], v[70:71], off
	global_load_dwordx4 v[52:55], v[56:57], off
	s_waitcnt vmcnt(1)
	v_lshlrev_b32_e32 v58, 16, v48
	v_and_b32_e32 v59, 0xffff0000, v48
	v_lshlrev_b32_e32 v48, 16, v49
	v_and_b32_e32 v49, 0xffff0000, v49
	v_lshlrev_b32_e32 v60, 16, v50
	v_and_b32_e32 v61, 0xffff0000, v50
	v_lshlrev_b32_e32 v50, 16, v51
	v_and_b32_e32 v51, 0xffff0000, v51
	s_waitcnt vmcnt(0)
	v_lshlrev_b32_e32 v62, 16, v52
	v_and_b32_e32 v63, 0xffff0000, v52
	v_lshlrev_b32_e32 v52, 16, v53
	v_and_b32_e32 v53, 0xffff0000, v53
	v_lshlrev_b32_e32 v64, 16, v54
	v_and_b32_e32 v65, 0xffff0000, v54
	v_lshlrev_b32_e32 v54, 16, v55
	v_and_b32_e32 v55, 0xffff0000, v55
	v_pk_fma_f32 v[46:47], v[46:47], v[48:49], v[52:53]
	v_pk_fma_f32 v[44:45], v[44:45], v[58:59], v[62:63]
	v_pk_fma_f32 v[48:49], v[42:43], v[50:51], v[54:55]
	v_pk_fma_f32 v[42:43], v[40:41], v[60:61], v[64:65]
	v_cvt_pk_bf16_f32 v40, v44, v45
	v_cvt_pk_bf16_f32 v41, v46, v47
	v_lshl_add_u64 v[52:53], v[140:141], 0, s[28:29]
	v_cvt_pk_bf16_f32 v42, v42, v43
	v_cvt_pk_bf16_f32 v43, v48, v49
	global_load_dwordx4 v[44:47], v[70:71], off offset:256
	global_load_dwordx4 v[48:51], v[56:57], off offset:256
	v_lshl_add_u64 v[54:55], s[12:13], 0, v[52:53]
	global_store_dwordx4 v[56:57], v[40:43], off nt
	s_waitcnt vmcnt(1)
	v_lshlrev_b32_e32 v58, 16, v48
	v_lshlrev_b32_e32 v40, 16, v44
	v_and_b32_e32 v41, 0xffff0000, v44
	v_lshlrev_b32_e32 v42, 16, v45
	v_and_b32_e32 v43, 0xffff0000, v45
	v_and_b32_e32 v59, 0xffff0000, v48
	v_lshlrev_b32_e32 v48, 16, v49
	v_and_b32_e32 v49, 0xffff0000, v49
	v_lshlrev_b32_e32 v44, 16, v46
	v_and_b32_e32 v45, 0xffff0000, v46
	v_lshlrev_b32_e32 v46, 16, v47
	v_and_b32_e32 v47, 0xffff0000, v47
	v_lshlrev_b32_e32 v60, 16, v50
	v_and_b32_e32 v61, 0xffff0000, v50
	v_lshlrev_b32_e32 v50, 16, v51
	v_and_b32_e32 v51, 0xffff0000, v51
	v_pk_fma_f32 v[34:35], v[34:35], v[42:43], v[48:49]
	v_pk_fma_f32 v[32:33], v[32:33], v[40:41], v[58:59]
	v_pk_fma_f32 v[38:39], v[38:39], v[46:47], v[50:51]
	v_pk_fma_f32 v[36:37], v[36:37], v[44:45], v[60:61]
	v_cvt_pk_bf16_f32 v32, v32, v33
	v_cvt_pk_bf16_f32 v33, v34, v35
	v_lshl_add_u64 v[40:41], s[8:9], 0, v[52:53]
	v_cvt_pk_bf16_f32 v34, v36, v37
	v_cvt_pk_bf16_f32 v35, v38, v39
	global_store_dwordx4 v[56:57], v[32:35], off offset:256 nt
	global_load_dwordx4 v[32:35], v[54:55], off
	global_load_dwordx4 v[36:39], v[40:41], off
	s_waitcnt vmcnt(1)
	v_lshlrev_b32_e32 v42, 16, v32
	v_and_b32_e32 v43, 0xffff0000, v32
	v_lshlrev_b32_e32 v32, 16, v33
	v_and_b32_e32 v33, 0xffff0000, v33
	v_lshlrev_b32_e32 v44, 16, v34
	v_and_b32_e32 v45, 0xffff0000, v34
	v_lshlrev_b32_e32 v34, 16, v35
	v_and_b32_e32 v35, 0xffff0000, v35
	s_waitcnt vmcnt(0)
; #define PG8_BAR __builtin_amdgcn_s_barrier()
; __device__ __forceinline__ u32x4 pack8(const f32x4 a, const f32x4 b) { u32x4 w; w.x = cvt_pk_bf16(a[0], a[1]); w.y = cvt_pk_bf16(a[2], a[3]); w.z = cvt_pk_bf16(b[0], b[1]); w.w = cvt_pk_bf16(b[2], b[3]); return w; }
; __device__ __forceinline__ void unpack8(const u32x4 w, f32x4& a, f32x4& b) { a = (f32x4){bflo(w.x), bfhi(w.x), bflo(w.y), bfhi(w.y)}; b = (f32x4){bflo(w.z), bfhi(w.z), bflo(w.w), bfhi(w.w)}; }
; template <class Epi, class Sched, bool ALIGN_EPI = false, bool SP2 = false>
; __device__ __forceinline__ void gemm_phase(PG8_LAS unsigned char* lds, const Gemm g, const Sched& S, const Epi& E) {
;     ...
;         if constexpr (ALIGN_EPI) { if (wr == 0) PG8_BAR; }
;         if constexpr (!Epi::AFTER_DRAIN) { E(acc, cur, wr, wc, fr, fq); S.done(cur); }
;         if (!has_next) break;
; #pragma unroll
;         for (int a = 0; a < 2; ++a)
; #pragma unroll
;             for (int b = 0; b < 2; ++b)
; #pragma unroll
;                 for (int m = 0; m < 4; ++m)
; #pragma unroll
;                     for (int n = 0; n < 2; ++n) acc[a][b][m][n] = (f32x4){0.f, 0.f, 0.f, 0.f};
;         cur = nxt; cA = nA; cB = nB; ++ui;
;         if constexpr (ALIGN_EPI) { if (wr == 1) PG8_BAR; }
;     }
;     __device__ __forceinline__ void operator()(const f32x4 (&acc)[2][2][4][2], const Unit& u, int wr, int wc, int fr, int fq) const {
;         const int rbase = u.pm * 256 + wr * 64 + fr, cb = u.pn * 256 + wc * 32 + fq * 8;
; #pragma unroll
;         for (int ai = 0; ai < 2; ++ai)
; #pragma unroll
;             for (int m = 0; m < 4; ++m) { const size_t ro = (size_t)(rbase + ai * 128 + m * 16) * 1024 + cb;
; #pragma unroll
;                 for (int bj = 0; bj < 2; ++bj) { f32x4 g0, g1; unpack8(*(const u32x4*)(G + ro + bj * 128), g0, g1);
;                     f32x4 v0 = acc[ai][bj][m][0] * g0, v1 = acc[ai][bj][m][1] * g1;
;                     if (!FIRST) { f32x4 o0, o1; unpack8(*(const u32x4*)(O + ro + bj * 128), o0, o1); v0 += o0; v1 += o1; }
;                     *(u32x4*)(O + ro + bj * 128) = pack8(v0, v1); }
;                 asm volatile("" ::: "memory"); }
	v_lshlrev_b32_e32 v46, 16, v36
	v_and_b32_e32 v47, 0xffff0000, v36
	v_lshlrev_b32_e32 v36, 16, v37
	v_and_b32_e32 v37, 0xffff0000, v37
	v_lshlrev_b32_e32 v48, 16, v38
	v_and_b32_e32 v49, 0xffff0000, v38
	v_lshlrev_b32_e32 v38, 16, v39
	v_and_b32_e32 v39, 0xffff0000, v39
	v_pk_fma_f32 v[30:31], v[30:31], v[32:33], v[36:37]
	v_pk_fma_f32 v[28:29], v[28:29], v[42:43], v[46:47]
	v_pk_fma_f32 v[32:33], v[26:27], v[34:35], v[38:39]
	v_pk_fma_f32 v[26:27], v[24:25], v[44:45], v[48:49]
	v_cvt_pk_bf16_f32 v24, v28, v29
	v_cvt_pk_bf16_f32 v25, v30, v31
	v_lshl_add_u64 v[36:37], v[140:141], 0, s[30:31]
	v_cvt_pk_bf16_f32 v26, v26, v27
	v_cvt_pk_bf16_f32 v27, v32, v33
	global_load_dwordx4 v[28:31], v[54:55], off offset:256
	global_load_dwordx4 v[32:35], v[40:41], off offset:256
	v_lshl_add_u64 v[38:39], s[12:13], 0, v[36:37]
	global_store_dwordx4 v[40:41], v[24:27], off nt
	s_waitcnt vmcnt(1)
	v_lshlrev_b32_e32 v42, 16, v32
	v_lshlrev_b32_e32 v24, 16, v28
	v_and_b32_e32 v25, 0xffff0000, v28
	v_lshlrev_b32_e32 v26, 16, v29
	v_and_b32_e32 v27, 0xffff0000, v29
	v_and_b32_e32 v43, 0xffff0000, v32
	v_lshlrev_b32_e32 v32, 16, v33
	v_and_b32_e32 v33, 0xffff0000, v33
	v_lshlrev_b32_e32 v28, 16, v30
	v_and_b32_e32 v29, 0xffff0000, v30
	v_lshlrev_b32_e32 v30, 16, v31
	v_and_b32_e32 v31, 0xffff0000, v31
	v_lshlrev_b32_e32 v44, 16, v34
	v_and_b32_e32 v45, 0xffff0000, v34
	v_lshlrev_b32_e32 v34, 16, v35
	v_and_b32_e32 v35, 0xffff0000, v35
	v_pk_fma_f32 v[18:19], v[18:19], v[26:27], v[32:33]
	v_pk_fma_f32 v[16:17], v[16:17], v[24:25], v[42:43]
	v_pk_fma_f32 v[22:23], v[22:23], v[30:31], v[34:35]
	v_pk_fma_f32 v[20:21], v[20:21], v[28:29], v[44:45]
	v_cvt_pk_bf16_f32 v16, v16, v17
	v_cvt_pk_bf16_f32 v17, v18, v19
	v_lshl_add_u64 v[24:25], s[8:9], 0, v[36:37]
	v_cvt_pk_bf16_f32 v18, v20, v21
	v_cvt_pk_bf16_f32 v19, v22, v23
	global_store_dwordx4 v[40:41], v[16:19], off offset:256 nt
	global_load_dwordx4 v[16:19], v[38:39], off
	global_load_dwordx4 v[20:23], v[24:25], off
	s_waitcnt vmcnt(1)
	v_lshlrev_b32_e32 v26, 16, v16
	v_and_b32_e32 v27, 0xffff0000, v16
	v_lshlrev_b32_e32 v16, 16, v17
	v_and_b32_e32 v17, 0xffff0000, v17
	v_lshlrev_b32_e32 v28, 16, v18
	v_and_b32_e32 v29, 0xffff0000, v18
	v_lshlrev_b32_e32 v18, 16, v19
	v_and_b32_e32 v19, 0xffff0000, v19
	s_waitcnt vmcnt(0)
	v_lshlrev_b32_e32 v30, 16, v20
	v_and_b32_e32 v31, 0xffff0000, v20
	v_lshlrev_b32_e32 v20, 16, v21
	v_and_b32_e32 v21, 0xffff0000, v21
	v_lshlrev_b32_e32 v32, 16, v22
	v_and_b32_e32 v33, 0xffff0000, v22
	v_lshlrev_b32_e32 v22, 16, v23
	v_and_b32_e32 v23, 0xffff0000, v23
	v_pk_fma_f32 v[14:15], v[14:15], v[16:17], v[20:21]
	v_pk_fma_f32 v[12:13], v[12:13], v[26:27], v[30:31]
	v_pk_fma_f32 v[16:17], v[10:11], v[18:19], v[22:23]
	v_pk_fma_f32 v[10:11], v[8:9], v[28:29], v[32:33]
	v_cvt_pk_bf16_f32 v8, v12, v13
	v_cvt_pk_bf16_f32 v9, v14, v15
	s_nop 0
	v_cvt_pk_bf16_f32 v10, v10, v11
	v_cvt_pk_bf16_f32 v11, v16, v17
	global_load_dwordx4 v[12:15], v[38:39], off offset:256
	global_load_dwordx4 v[16:19], v[24:25], off offset:256
	s_waitcnt vmcnt(0)
	v_lshlrev_b32_e32 v20, 16, v16
	global_store_dwordx4 v[24:25], v[8:11], off nt
	v_and_b32_e32 v21, 0xffff0000, v16
	v_lshlrev_b32_e32 v22, 16, v18
	v_lshlrev_b32_e32 v8, 16, v12
	v_and_b32_e32 v9, 0xffff0000, v12
	v_lshlrev_b32_e32 v10, 16, v13
	v_and_b32_e32 v11, 0xffff0000, v13
	v_lshlrev_b32_e32 v12, 16, v14
	v_and_b32_e32 v13, 0xffff0000, v14
	v_lshlrev_b32_e32 v14, 16, v15
	v_and_b32_e32 v15, 0xffff0000, v15
	v_and_b32_e32 v23, 0xffff0000, v18
	v_lshlrev_b32_e32 v18, 16, v19
	v_and_b32_e32 v19, 0xffff0000, v19
	v_lshlrev_b32_e32 v16, 16, v17
	v_and_b32_e32 v17, 0xffff0000, v17
	v_pk_fma_f32 v[4:5], v[4:5], v[8:9], v[20:21]
	v_pk_fma_f32 v[8:9], v[2:3], v[14:15], v[18:19]
	v_pk_fma_f32 v[2:3], v[0:1], v[12:13], v[22:23]
	v_pk_fma_f32 v[6:7], v[6:7], v[10:11], v[16:17]
	v_cvt_pk_bf16_f32 v0, v4, v5
	s_nop 0
	v_cvt_pk_bf16_f32 v1, v6, v7
	v_cvt_pk_bf16_f32 v2, v2, v3
	v_cvt_pk_bf16_f32 v3, v8, v9
	global_store_dwordx4 v[24:25], v[0:3], off offset:256 nt
	s_cbranch_vccnz .LBB0_1351
	s_andn2_b64 vcc, exec, s[10:11]
	s_cbranch_vccnz .LBB0_1350
	s_barrier
	s_branch .LBB0_1350

; __device__ __forceinline__ u32x4 pack8(const f32x4 a, const f32x4 b) { u32x4 w; w.x = cvt_pk_bf16(a[0], a[1]); w.y = cvt_pk_bf16(a[2], a[3]); w.z = cvt_pk_bf16(b[0], b[1]); w.w = cvt_pk_bf16(b[2], b[3]); return w; }
; __device__ __forceinline__ float dot4(const f32x4 a, const f32x4 b) { return (a[0] * b[0] + a[1] * b[1]) + (a[2] * b[2] + a[3] * b[3]); }
;     __device__ __forceinline__ void operator()(const f32x4 (&acc)[2][2][4][2], const Unit& u, int wr, int wc, int fr, int fq) const {
;         const int rbase = u.pm * 256 + wr * 64 + fr, cb = u.pn * 256 + wc * 32 + fq * 8;
;         f32x4 w[2][2];
; #pragma unroll
;         for (int bj = 0; bj < 2; ++bj) { w[bj][0] = *(const f32x4*)(ln2 + cb + bj * 128); w[bj][1] = *(const f32x4*)(ln2 + cb + bj * 128 + 4); }
; #pragma unroll
;         for (int ai = 0; ai < 2; ++ai)
; #pragma unroll
;             for (int m = 0; m < 4; ++m) { const int row = rbase + ai * 128 + m * 16; const float* xr = (row < MP ? xp + (size_t)row * 1024 : xs + (size_t)(row - MP) * 1024) + cb;
;                 float ss = 0.f;
; #pragma unroll
;                 for (int bj = 0; bj < 2; ++bj) { const f32x4 h0 = *(const f32x4*)(xr + bj * 128) + acc[ai][bj][m][0], h1 = *(const f32x4*)(xr + bj * 128 + 4) + acc[ai][bj][m][1];
;                     float* yp = y + (size_t)row * 1024 + cb + bj * 128; *(f32x4*)yp = h0; *(f32x4*)(yp + 4) = h1;
;                     ss += dot4(h0, h0) + dot4(h1, h1);
;                     *(u32x4*)(HN + (size_t)row * 1024 + cb + bj * 128) = pack8(h0 * w[bj][0], h1 * w[bj][1]); }
;                 ss += __shfl_xor(ss, 16); ss += __shfl_xor(ss, 32);
;                 if (fq == 0) SSP[(size_t)row * 16 + u.pn * 4 + wc] = ss;
;                 asm volatile("" ::: "memory"); }
.LBB0_1426:
	v_lshl_or_b32 v162, s14, 8, v172
	v_ashrrev_i32_e32 v163, 31, v162
	v_lshl_add_u64 v[60:61], v[162:163], 2, s[78:79]
	global_load_dwordx4 v[72:75], v[60:61], off offset:16
	global_load_dwordx4 v[76:79], v[60:61], off
	global_load_dwordx4 v[56:59], v[60:61], off offset:528
	s_nop 0
	global_load_dwordx4 v[60:63], v[60:61], off offset:512
	v_lshl_add_u32 v166, s30, 8, v170
	v_cmp_lt_i32_e32 vcc, s66, v166
	s_and_saveexec_b64 s[30:31], vcc
	s_xor_b64 s[30:31], exec, s[30:31]
	v_add_u32_e32 v152, 0xffff0000, v166
	v_lshlrev_b64 v[164:165], 12, v[152:153]
	v_lshl_add_u64 v[168:169], s[50:51], 0, v[164:165]
	v_mov_b32_e32 v167, v153
	s_andn2_saveexec_b64 s[30:31], s[30:31]
	v_ashrrev_i32_e32 v167, 31, v166
	v_lshlrev_b64 v[164:165], 12, v[166:167]
	v_lshl_add_u64 v[168:169], s[48:49], 0, v[164:165]
	s_or_b64 exec, exec, s[30:31]
	v_lshlrev_b64 v[164:165], 2, v[162:163]
	v_lshl_add_u64 v[168:169], v[168:169], 0, v[164:165]
	global_load_dwordx4 v[178:181], v[168:169], off
	global_load_dwordx4 v[182:185], v[168:169], off offset:16
	v_lshlrev_b64 v[186:187], 12, v[166:167]
	v_lshlrev_b64 v[188:189], 11, v[166:167]
	v_lshl_add_u64 v[186:187], s[84:85], 0, v[186:187]
	v_lshl_add_u64 v[188:189], s[10:11], 0, v[188:189]
	v_lshl_add_u64 v[190:191], v[186:187], 0, v[164:165]
	v_lshl_add_u64 v[192:193], v[162:163], 1, v[188:189]
	s_lshl_b32 s30, s14, 2
	s_ashr_i32 s31, s30, 31
	s_waitcnt vmcnt(0)
	v_pk_add_f32 v[142:143], v[142:143], v[180:181]
	v_pk_add_f32 v[140:141], v[140:141], v[178:179]
	v_pk_add_f32 v[180:181], v[138:139], v[184:185]
	v_pk_add_f32 v[178:179], v[136:137], v[182:183]
	v_pk_mul_f32 v[138:139], v[78:79], v[142:143]
	v_pk_mul_f32 v[136:137], v[76:77], v[140:141]
	global_store_dwordx4 v[190:191], v[140:143], off nt
	global_store_dwordx4 v[190:191], v[178:181], off offset:16 nt
	v_pk_mul_f32 v[182:183], v[74:75], v[180:181]
	v_pk_mul_f32 v[184:185], v[72:73], v[178:179]
	v_cvt_pk_bf16_f32 v136, v136, v137
	v_cvt_pk_bf16_f32 v137, v138, v139
	s_nop 0
	v_cvt_pk_bf16_f32 v138, v184, v185
	v_cvt_pk_bf16_f32 v139, v182, v183
	global_store_dwordx4 v[192:193], v[136:139], off nt
	global_load_dwordx4 v[182:185], v[168:169], off offset:512
	global_load_dwordx4 v[186:189], v[168:169], off offset:528
	v_and_b32_e32 v137, 64, v176
	v_xor_b32_e32 v136, 16, v176
	v_add_u32_e32 v137, 64, v137
	v_xor_b32_e32 v138, 32, v176
	v_cmp_lt_i32_e32 vcc, v136, v137
	v_mul_f32_e32 v139, v143, v143
	v_mul_f32_e32 v143, v181, v181
	v_cndmask_b32_e32 v136, v176, v136, vcc
	v_cmp_lt_i32_e32 vcc, v138, v137
	v_fmac_f32_e32 v139, v142, v142
	v_fmac_f32_e32 v143, v180, v180
	v_cndmask_b32_e32 v137, v176, v138, vcc
	v_mul_f32_e32 v138, v141, v141
	v_mul_f32_e32 v141, v179, v179
	v_fmac_f32_e32 v138, v140, v140
	v_fmac_f32_e32 v141, v178, v178
	v_add_f32_e32 v138, v138, v139
	v_add_f32_e32 v139, v141, v143
	v_add_f32_e32 v138, v138, v139
	v_lshlrev_b32_e32 v136, 2, v136
	s_waitcnt vmcnt(1)
	v_pk_add_f32 v[134:135], v[134:135], v[184:185]
	v_pk_add_f32 v[132:133], v[132:133], v[182:183]
	s_waitcnt vmcnt(0)
	v_pk_add_f32 v[130:131], v[130:131], v[188:189]
	v_pk_add_f32 v[128:129], v[128:129], v[186:187]
	v_mul_f32_e32 v139, v133, v133
	v_mul_f32_e32 v142, v135, v135
	v_mul_f32_e32 v143, v129, v129
	v_mul_f32_e32 v152, v131, v131
	v_fmac_f32_e32 v139, v132, v132
	v_fmac_f32_e32 v142, v134, v134
	v_fmac_f32_e32 v143, v128, v128
	v_fmac_f32_e32 v152, v130, v130
	global_store_dwordx4 v[190:191], v[132:135], off offset:512 nt
	global_store_dwordx4 v[190:191], v[128:131], off offset:528 nt
	v_pk_mul_f32 v[140:141], v[62:63], v[134:135]
	v_add_f32_e32 v134, v139, v142
	v_add_f32_e32 v135, v143, v152
	v_add_f32_e32 v134, v134, v135
	v_add_f32_e32 v139, v138, v134
	ds_bpermute_b32 v142, v136, v139
	v_pk_mul_f32 v[132:133], v[60:61], v[132:133]
	v_pk_mul_f32 v[134:135], v[56:57], v[128:129]
	v_cvt_pk_bf16_f32 v138, v132, v133
	v_lshlrev_b32_e32 v132, 2, v137
	s_waitcnt lgkmcnt(0)
	v_add_f32_e32 v128, v139, v142
	ds_bpermute_b32 v129, v132, v128
	v_pk_mul_f32 v[130:131], v[58:59], v[130:131]
	v_cvt_pk_bf16_f32 v139, v140, v141
	v_cvt_pk_bf16_f32 v140, v134, v135
	s_nop 0
	v_cvt_pk_bf16_f32 v141, v130, v131
	global_store_dwordx4 v[192:193], v[138:141], off offset:256 nt
	s_and_saveexec_b64 s[34:35], s[4:5]
	s_cbranch_execz .LBB0_1432
	v_lshlrev_b64 v[130:131], 6, v[166:167]
	v_lshl_add_u64 v[130:131], s[12:13], 0, v[130:131]
	v_lshl_add_u64 v[130:131], s[30:31], 2, v[130:131]
	s_lshl_b32 s14, s52, 2
	v_lshl_add_u64 v[130:131], v[130:131], 0, s[14:15]
	s_waitcnt lgkmcnt(0)
	v_add_f32_e32 v128, v128, v129
	global_store_dword v[130:131], v128, off nt
; __device__ __forceinline__ u32x4 pack8(const f32x4 a, const f32x4 b) { u32x4 w; w.x = cvt_pk_bf16(a[0], a[1]); w.y = cvt_pk_bf16(a[2], a[3]); w.z = cvt_pk_bf16(b[0], b[1]); w.w = cvt_pk_bf16(b[2], b[3]); return w; }
; __device__ __forceinline__ float dot4(const f32x4 a, const f32x4 b) { return (a[0] * b[0] + a[1] * b[1]) + (a[2] * b[2] + a[3] * b[3]); }
;     __device__ __forceinline__ void operator()(const f32x4 (&acc)[2][2][4][2], const Unit& u, int wr, int wc, int fr, int fq) const {
;         const int rbase = u.pm * 256 + wr * 64 + fr, cb = u.pn * 256 + wc * 32 + fq * 8;
;         f32x4 w[2][2];
; #pragma unroll
;         for (int bj = 0; bj < 2; ++bj) { w[bj][0] = *(const f32x4*)(ln2 + cb + bj * 128); w[bj][1] = *(const f32x4*)(ln2 + cb + bj * 128 + 4); }
; #pragma unroll
;         for (int ai = 0; ai < 2; ++ai)
; #pragma unroll
;             for (int m = 0; m < 4; ++m) { const int row = rbase + ai * 128 + m * 16; const float* xr = (row < MP ? xp + (size_t)row * 1024 : xs + (size_t)(row - MP) * 1024) + cb;
;                 float ss = 0.f;
; #pragma unroll
;                 for (int bj = 0; bj < 2; ++bj) { const f32x4 h0 = *(const f32x4*)(xr + bj * 128) + acc[ai][bj][m][0], h1 = *(const f32x4*)(xr + bj * 128 + 4) + acc[ai][bj][m][1];
;                     float* yp = y + (size_t)row * 1024 + cb + bj * 128; *(f32x4*)yp = h0; *(f32x4*)(yp + 4) = h1;
;                     ss += dot4(h0, h0) + dot4(h1, h1);
;                     *(u32x4*)(HN + (size_t)row * 1024 + cb + bj * 128) = pack8(h0 * w[bj][0], h1 * w[bj][1]); }
;                 ss += __shfl_xor(ss, 16); ss += __shfl_xor(ss, 32);
;                 if (fq == 0) SSP[(size_t)row * 16 + u.pn * 4 + wc] = ss;
;                 asm volatile("" ::: "memory"); }
.LBB0_1432:
	s_or_b64 exec, exec, s[34:35]
	s_waitcnt lgkmcnt(0)
	v_or_b32_e32 v128, 16, v166
	v_cmp_lt_i32_e32 vcc, s66, v128
	s_and_saveexec_b64 s[34:35], vcc
	s_xor_b64 s[34:35], exec, s[34:35]
	v_add_u32_e32 v152, 0xffff0010, v166
	v_lshlrev_b64 v[130:131], 12, v[152:153]
	v_lshl_add_u64 v[130:131], s[50:51], 0, v[130:131]
	v_mov_b32_e32 v129, v153
	s_andn2_saveexec_b64 s[34:35], s[34:35]
	v_ashrrev_i32_e32 v129, 31, v128
	v_lshlrev_b64 v[130:131], 12, v[128:129]
	v_lshl_add_u64 v[130:131], s[48:49], 0, v[130:131]
	s_or_b64 exec, exec, s[34:35]
	v_lshl_add_u64 v[130:131], v[130:131], 0, v[164:165]
	global_load_dwordx4 v[138:141], v[130:131], off
	global_load_dwordx4 v[178:181], v[130:131], off offset:16
	v_lshlrev_b64 v[134:135], 12, v[128:129]
	v_lshlrev_b64 v[142:143], 11, v[128:129]
	v_lshl_add_u64 v[134:135], s[84:85], 0, v[134:135]
	v_lshl_add_u64 v[142:143], s[10:11], 0, v[142:143]
	v_lshl_add_u64 v[134:135], v[134:135], 0, v[164:165]
	v_lshl_add_u64 v[142:143], v[162:163], 1, v[142:143]
	s_waitcnt vmcnt(1)
	v_pk_add_f32 v[126:127], v[126:127], v[140:141]
	v_pk_add_f32 v[124:125], v[124:125], v[138:139]
	s_waitcnt vmcnt(0)
	v_pk_add_f32 v[122:123], v[122:123], v[180:181]
	v_pk_add_f32 v[120:121], v[120:121], v[178:179]
	v_pk_mul_f32 v[140:141], v[78:79], v[126:127]
	v_pk_mul_f32 v[138:139], v[76:77], v[124:125]
	global_store_dwordx4 v[134:135], v[124:127], off nt
	global_store_dwordx4 v[134:135], v[120:123], off offset:16 nt
	v_pk_mul_f32 v[168:169], v[74:75], v[122:123]
	v_pk_mul_f32 v[178:179], v[72:73], v[120:121]
	v_cvt_pk_bf16_f32 v138, v138, v139
	v_cvt_pk_bf16_f32 v139, v140, v141
	v_mul_f32_e32 v125, v125, v125
	v_cvt_pk_bf16_f32 v140, v178, v179
	v_cvt_pk_bf16_f32 v141, v168, v169
	global_store_dwordx4 v[142:143], v[138:141], off nt
	global_load_dwordx4 v[138:141], v[130:131], off offset:512
	s_nop 0
	global_load_dwordx4 v[178:181], v[130:131], off offset:528
	v_mul_f32_e32 v127, v127, v127
	v_mul_f32_e32 v121, v121, v121
	v_mul_f32_e32 v123, v123, v123
	v_fmac_f32_e32 v125, v124, v124
	v_fmac_f32_e32 v127, v126, v126
	v_fmac_f32_e32 v121, v120, v120
	v_fmac_f32_e32 v123, v122, v122
	v_add_f32_e32 v120, v125, v127
	v_add_f32_e32 v121, v121, v123
	v_add_f32_e32 v120, v120, v121
	s_waitcnt vmcnt(1)
	v_pk_add_f32 v[118:119], v[118:119], v[140:141]
	v_pk_add_f32 v[116:117], v[116:117], v[138:139]
	s_waitcnt vmcnt(0)
	v_pk_add_f32 v[114:115], v[114:115], v[180:181]
	v_pk_add_f32 v[112:113], v[112:113], v[178:179]
	v_mul_f32_e32 v121, v117, v117
	v_mul_f32_e32 v122, v119, v119
	v_mul_f32_e32 v123, v113, v113
	v_mul_f32_e32 v124, v115, v115
	v_fmac_f32_e32 v121, v116, v116
	v_fmac_f32_e32 v122, v118, v118
	v_fmac_f32_e32 v123, v112, v112
	v_fmac_f32_e32 v124, v114, v114
	v_add_f32_e32 v121, v121, v122
	v_add_f32_e32 v122, v123, v124
	v_add_f32_e32 v121, v121, v122
	v_add_f32_e32 v124, v120, v121
	ds_bpermute_b32 v125, v136, v124
	global_store_dwordx4 v[134:135], v[116:119], off offset:512 nt
	global_store_dwordx4 v[134:135], v[112:115], off offset:528 nt
	v_pk_mul_f32 v[122:123], v[56:57], v[112:113]
	v_pk_mul_f32 v[116:117], v[60:61], v[116:117]
	v_pk_mul_f32 v[118:119], v[62:63], v[118:119]
	s_waitcnt lgkmcnt(0)
	v_add_f32_e32 v112, v124, v125
	ds_bpermute_b32 v113, v132, v112
	v_pk_mul_f32 v[120:121], v[58:59], v[114:115]
	v_cvt_pk_bf16_f32 v114, v116, v117
	v_cvt_pk_bf16_f32 v115, v118, v119
	v_cvt_pk_bf16_f32 v116, v122, v123
	s_nop 0
	v_cvt_pk_bf16_f32 v117, v120, v121
	global_store_dwordx4 v[142:143], v[114:117], off offset:256 nt
	s_and_saveexec_b64 s[34:35], s[4:5]
	s_cbranch_execz .LBB0_1438
	v_lshlrev_b64 v[114:115], 6, v[128:129]
	v_lshl_add_u64 v[114:115], s[12:13], 0, v[114:115]
	v_lshl_add_u64 v[114:115], s[30:31], 2, v[114:115]
	s_lshl_b32 s14, s52, 2
	v_lshl_add_u64 v[114:115], v[114:115], 0, s[14:15]
	s_waitcnt lgkmcnt(0)
	v_add_f32_e32 v112, v112, v113
	global_store_dword v[114:115], v112, off nt
.LBB0_1438:
	s_or_b64 exec, exec, s[34:35]
	s_waitcnt lgkmcnt(0)
	v_or_b32_e32 v112, 32, v166
	v_cmp_lt_i32_e32 vcc, s66, v112
	s_and_saveexec_b64 s[34:35], vcc
	s_xor_b64 s[34:35], exec, s[34:35]
	v_add_u32_e32 v152, 0xffff0020, v166
	v_lshlrev_b64 v[114:115], 12, v[152:153]
	v_lshl_add_u64 v[114:115], s[50:51], 0, v[114:115]
	v_mov_b32_e32 v113, v153
	s_andn2_saveexec_b64 s[34:35], s[34:35]
	v_ashrrev_i32_e32 v113, 31, v112
	v_lshlrev_b64 v[114:115], 12, v[112:113]
	v_lshl_add_u64 v[114:115], s[48:49], 0, v[114:115]
	s_or_b64 exec, exec, s[34:35]
	v_lshl_add_u64 v[122:123], v[114:115], 0, v[164:165]
	global_load_dwordx4 v[114:117], v[122:123], off
	global_load_dwordx4 v[118:121], v[122:123], off offset:16
	v_lshlrev_b64 v[124:125], 12, v[112:113]
	v_lshlrev_b64 v[126:127], 11, v[112:113]
	v_lshl_add_u64 v[124:125], s[84:85], 0, v[124:125]
	v_lshl_add_u64 v[126:127], s[10:11], 0, v[126:127]
	v_lshl_add_u64 v[124:125], v[124:125], 0, v[164:165]
	v_lshl_add_u64 v[126:127], v[162:163], 1, v[126:127]
	s_waitcnt vmcnt(1)
	v_pk_add_f32 v[110:111], v[110:111], v[116:117]
	v_pk_add_f32 v[108:109], v[108:109], v[114:115]
	s_waitcnt vmcnt(0)
	v_pk_add_f32 v[106:107], v[106:107], v[120:121]
	v_pk_add_f32 v[104:105], v[104:105], v[118:119]
	v_pk_mul_f32 v[116:117], v[78:79], v[110:111]
	v_pk_mul_f32 v[114:115], v[76:77], v[108:109]
	global_store_dwordx4 v[124:125], v[108:111], off nt
	global_store_dwordx4 v[124:125], v[104:107], off offset:16 nt
	v_pk_mul_f32 v[118:119], v[74:75], v[106:107]
	v_pk_mul_f32 v[120:121], v[72:73], v[104:105]
	v_cvt_pk_bf16_f32 v114, v114, v115
	v_cvt_pk_bf16_f32 v115, v116, v117
	v_mul_f32_e32 v109, v109, v109
	v_cvt_pk_bf16_f32 v116, v120, v121
	v_cvt_pk_bf16_f32 v117, v118, v119
	global_store_dwordx4 v[126:127], v[114:117], off nt
	global_load_dwordx4 v[114:117], v[122:123], off offset:512
	s_nop 0
	global_load_dwordx4 v[118:121], v[122:123], off offset:528
	v_mul_f32_e32 v111, v111, v111
	v_mul_f32_e32 v105, v105, v105
	v_mul_f32_e32 v107, v107, v107
	v_fmac_f32_e32 v109, v108, v108
	v_fmac_f32_e32 v111, v110, v110
	v_fmac_f32_e32 v105, v104, v104
	v_fmac_f32_e32 v107, v106, v106
	v_add_f32_e32 v104, v109, v111
	v_add_f32_e32 v105, v105, v107
	v_add_f32_e32 v104, v104, v105
	s_waitcnt vmcnt(1)
; __device__ __forceinline__ u32x4 pack8(const f32x4 a, const f32x4 b) { u32x4 w; w.x = cvt_pk_bf16(a[0], a[1]); w.y = cvt_pk_bf16(a[2], a[3]); w.z = cvt_pk_bf16(b[0], b[1]); w.w = cvt_pk_bf16(b[2], b[3]); return w; }
; __device__ __forceinline__ float dot4(const f32x4 a, const f32x4 b) { return (a[0] * b[0] + a[1] * b[1]) + (a[2] * b[2] + a[3] * b[3]); }
;     __device__ __forceinline__ void operator()(const f32x4 (&acc)[2][2][4][2], const Unit& u, int wr, int wc, int fr, int fq) const {
;         const int rbase = u.pm * 256 + wr * 64 + fr, cb = u.pn * 256 + wc * 32 + fq * 8;
;         f32x4 w[2][2];
; #pragma unroll
;         for (int bj = 0; bj < 2; ++bj) { w[bj][0] = *(const f32x4*)(ln2 + cb + bj * 128); w[bj][1] = *(const f32x4*)(ln2 + cb + bj * 128 + 4); }
; #pragma unroll
;         for (int ai = 0; ai < 2; ++ai)
; #pragma unroll
;             for (int m = 0; m < 4; ++m) { const int row = rbase + ai * 128 + m * 16; const float* xr = (row < MP ? xp + (size_t)row * 1024 : xs + (size_t)(row - MP) * 1024) + cb;
;                 float ss = 0.f;
; #pragma unroll
;                 for (int bj = 0; bj < 2; ++bj) { const f32x4 h0 = *(const f32x4*)(xr + bj * 128) + acc[ai][bj][m][0], h1 = *(const f32x4*)(xr + bj * 128 + 4) + acc[ai][bj][m][1];
;                     float* yp = y + (size_t)row * 1024 + cb + bj * 128; *(f32x4*)yp = h0; *(f32x4*)(yp + 4) = h1;
;                     ss += dot4(h0, h0) + dot4(h1, h1);
;                     *(u32x4*)(HN + (size_t)row * 1024 + cb + bj * 128) = pack8(h0 * w[bj][0], h1 * w[bj][1]); }
;                 ss += __shfl_xor(ss, 16); ss += __shfl_xor(ss, 32);
;                 if (fq == 0) SSP[(size_t)row * 16 + u.pn * 4 + wc] = ss;
;                 asm volatile("" ::: "memory"); }
	v_pk_add_f32 v[102:103], v[102:103], v[116:117]
	v_pk_add_f32 v[100:101], v[100:101], v[114:115]
	s_waitcnt vmcnt(0)
	v_pk_add_f32 v[98:99], v[98:99], v[120:121]
	v_pk_add_f32 v[96:97], v[96:97], v[118:119]
	v_mul_f32_e32 v105, v101, v101
	v_mul_f32_e32 v106, v103, v103
	v_mul_f32_e32 v107, v97, v97
	v_mul_f32_e32 v108, v99, v99
	v_fmac_f32_e32 v105, v100, v100
	v_fmac_f32_e32 v106, v102, v102
	v_fmac_f32_e32 v107, v96, v96
	v_fmac_f32_e32 v108, v98, v98
	v_add_f32_e32 v105, v105, v106
	v_add_f32_e32 v106, v107, v108
	v_add_f32_e32 v105, v105, v106
	v_add_f32_e32 v108, v104, v105
	ds_bpermute_b32 v109, v136, v108
	global_store_dwordx4 v[124:125], v[100:103], off offset:512 nt
	global_store_dwordx4 v[124:125], v[96:99], off offset:528 nt
	v_pk_mul_f32 v[106:107], v[56:57], v[96:97]
	v_pk_mul_f32 v[100:101], v[60:61], v[100:101]
	v_pk_mul_f32 v[102:103], v[62:63], v[102:103]
	s_waitcnt lgkmcnt(0)
	v_add_f32_e32 v96, v108, v109
	ds_bpermute_b32 v97, v132, v96
	v_pk_mul_f32 v[104:105], v[58:59], v[98:99]
	v_cvt_pk_bf16_f32 v98, v100, v101
	v_cvt_pk_bf16_f32 v99, v102, v103
	v_cvt_pk_bf16_f32 v100, v106, v107
	s_nop 0
	v_cvt_pk_bf16_f32 v101, v104, v105
	global_store_dwordx4 v[126:127], v[98:101], off offset:256 nt
	s_and_saveexec_b64 s[34:35], s[4:5]
	s_cbranch_execz .LBB0_1444
	v_lshlrev_b64 v[98:99], 6, v[112:113]
	v_lshl_add_u64 v[98:99], s[12:13], 0, v[98:99]
	v_lshl_add_u64 v[98:99], s[30:31], 2, v[98:99]
	s_lshl_b32 s14, s52, 2
	v_lshl_add_u64 v[98:99], v[98:99], 0, s[14:15]
	s_waitcnt lgkmcnt(0)
	v_add_f32_e32 v96, v96, v97
	global_store_dword v[98:99], v96, off nt
.LBB0_1444:
	s_or_b64 exec, exec, s[34:35]
	s_waitcnt lgkmcnt(0)
	v_or_b32_e32 v96, 48, v166
	v_cmp_lt_i32_e32 vcc, s66, v96
	s_and_saveexec_b64 s[34:35], vcc
	s_xor_b64 s[34:35], exec, s[34:35]
	v_add_u32_e32 v152, 0xffff0030, v166
	v_lshlrev_b64 v[98:99], 12, v[152:153]
	v_lshl_add_u64 v[98:99], s[50:51], 0, v[98:99]
	v_mov_b32_e32 v97, v153
	s_andn2_saveexec_b64 s[34:35], s[34:35]
	v_ashrrev_i32_e32 v97, 31, v96
	v_lshlrev_b64 v[98:99], 12, v[96:97]
	v_lshl_add_u64 v[98:99], s[48:49], 0, v[98:99]
	s_or_b64 exec, exec, s[34:35]
	v_lshl_add_u64 v[106:107], v[98:99], 0, v[164:165]
	global_load_dwordx4 v[98:101], v[106:107], off
	global_load_dwordx4 v[102:105], v[106:107], off offset:16
	v_lshlrev_b64 v[108:109], 12, v[96:97]
	v_lshlrev_b64 v[110:111], 11, v[96:97]
	v_lshl_add_u64 v[108:109], s[84:85], 0, v[108:109]
	v_lshl_add_u64 v[110:111], s[10:11], 0, v[110:111]
	v_lshl_add_u64 v[108:109], v[108:109], 0, v[164:165]
	v_lshl_add_u64 v[110:111], v[162:163], 1, v[110:111]
	s_waitcnt vmcnt(1)
	v_pk_add_f32 v[94:95], v[94:95], v[100:101]
	v_pk_add_f32 v[92:93], v[92:93], v[98:99]
	s_waitcnt vmcnt(0)
	v_pk_add_f32 v[90:91], v[90:91], v[104:105]
	v_pk_add_f32 v[88:89], v[88:89], v[102:103]
	v_pk_mul_f32 v[100:101], v[78:79], v[94:95]
	v_pk_mul_f32 v[98:99], v[76:77], v[92:93]
	global_store_dwordx4 v[108:109], v[92:95], off nt
	global_store_dwordx4 v[108:109], v[88:91], off offset:16 nt
	v_pk_mul_f32 v[102:103], v[74:75], v[90:91]
	v_pk_mul_f32 v[104:105], v[72:73], v[88:89]
	v_cvt_pk_bf16_f32 v98, v98, v99
	v_cvt_pk_bf16_f32 v99, v100, v101
	v_mul_f32_e32 v93, v93, v93
	v_cvt_pk_bf16_f32 v100, v104, v105
	v_cvt_pk_bf16_f32 v101, v102, v103
	global_store_dwordx4 v[110:111], v[98:101], off nt
	global_load_dwordx4 v[98:101], v[106:107], off offset:512
	s_nop 0
	global_load_dwordx4 v[102:105], v[106:107], off offset:528
	v_mul_f32_e32 v95, v95, v95
	v_mul_f32_e32 v89, v89, v89
	v_mul_f32_e32 v91, v91, v91
	v_fmac_f32_e32 v93, v92, v92
	v_fmac_f32_e32 v95, v94, v94
	v_fmac_f32_e32 v89, v88, v88
	v_fmac_f32_e32 v91, v90, v90
	v_add_f32_e32 v88, v93, v95
	v_add_f32_e32 v89, v89, v91
	v_add_f32_e32 v88, v88, v89
	s_waitcnt vmcnt(1)
	v_pk_add_f32 v[86:87], v[86:87], v[100:101]
	v_pk_add_f32 v[84:85], v[84:85], v[98:99]
	s_waitcnt vmcnt(0)
	v_pk_add_f32 v[82:83], v[82:83], v[104:105]
	v_pk_add_f32 v[80:81], v[80:81], v[102:103]
	v_mul_f32_e32 v89, v85, v85
	v_mul_f32_e32 v90, v87, v87
	v_mul_f32_e32 v91, v81, v81
	v_mul_f32_e32 v92, v83, v83
	v_fmac_f32_e32 v89, v84, v84
	v_fmac_f32_e32 v90, v86, v86
	v_fmac_f32_e32 v91, v80, v80
	v_fmac_f32_e32 v92, v82, v82
	v_add_f32_e32 v89, v89, v90
	v_add_f32_e32 v90, v91, v92
	v_add_f32_e32 v89, v89, v90
	v_add_f32_e32 v92, v88, v89
	ds_bpermute_b32 v93, v136, v92
	global_store_dwordx4 v[108:109], v[84:87], off offset:512 nt
	global_store_dwordx4 v[108:109], v[80:83], off offset:528 nt
	v_pk_mul_f32 v[90:91], v[56:57], v[80:81]
	v_pk_mul_f32 v[84:85], v[60:61], v[84:85]
	v_pk_mul_f32 v[86:87], v[62:63], v[86:87]
	s_waitcnt lgkmcnt(0)
	v_add_f32_e32 v80, v92, v93
	ds_bpermute_b32 v81, v132, v80
	v_pk_mul_f32 v[88:89], v[58:59], v[82:83]
	v_cvt_pk_bf16_f32 v82, v84, v85
	v_cvt_pk_bf16_f32 v83, v86, v87
	v_cvt_pk_bf16_f32 v84, v90, v91
	s_nop 0
	v_cvt_pk_bf16_f32 v85, v88, v89
	global_store_dwordx4 v[110:111], v[82:85], off offset:256 nt
	s_and_saveexec_b64 s[34:35], s[4:5]
	s_cbranch_execz .LBB0_1450
	v_lshlrev_b64 v[82:83], 6, v[96:97]
	v_lshl_add_u64 v[82:83], s[12:13], 0, v[82:83]
	v_lshl_add_u64 v[82:83], s[30:31], 2, v[82:83]
	s_lshl_b32 s14, s52, 2
	v_lshl_add_u64 v[82:83], v[82:83], 0, s[14:15]
	s_waitcnt lgkmcnt(0)
	v_add_f32_e32 v80, v80, v81
	global_store_dword v[82:83], v80, off nt
; __device__ __forceinline__ u32x4 pack8(const f32x4 a, const f32x4 b) { u32x4 w; w.x = cvt_pk_bf16(a[0], a[1]); w.y = cvt_pk_bf16(a[2], a[3]); w.z = cvt_pk_bf16(b[0], b[1]); w.w = cvt_pk_bf16(b[2], b[3]); return w; }
; __device__ __forceinline__ float dot4(const f32x4 a, const f32x4 b) { return (a[0] * b[0] + a[1] * b[1]) + (a[2] * b[2] + a[3] * b[3]); }
;     __device__ __forceinline__ void operator()(const f32x4 (&acc)[2][2][4][2], const Unit& u, int wr, int wc, int fr, int fq) const {
;         const int rbase = u.pm * 256 + wr * 64 + fr, cb = u.pn * 256 + wc * 32 + fq * 8;
;         f32x4 w[2][2];
; #pragma unroll
;         for (int bj = 0; bj < 2; ++bj) { w[bj][0] = *(const f32x4*)(ln2 + cb + bj * 128); w[bj][1] = *(const f32x4*)(ln2 + cb + bj * 128 + 4); }
; #pragma unroll
;         for (int ai = 0; ai < 2; ++ai)
; #pragma unroll
;             for (int m = 0; m < 4; ++m) { const int row = rbase + ai * 128 + m * 16; const float* xr = (row < MP ? xp + (size_t)row * 1024 : xs + (size_t)(row - MP) * 1024) + cb;
;                 float ss = 0.f;
; #pragma unroll
;                 for (int bj = 0; bj < 2; ++bj) { const f32x4 h0 = *(const f32x4*)(xr + bj * 128) + acc[ai][bj][m][0], h1 = *(const f32x4*)(xr + bj * 128 + 4) + acc[ai][bj][m][1];
;                     float* yp = y + (size_t)row * 1024 + cb + bj * 128; *(f32x4*)yp = h0; *(f32x4*)(yp + 4) = h1;
;                     ss += dot4(h0, h0) + dot4(h1, h1);
;                     *(u32x4*)(HN + (size_t)row * 1024 + cb + bj * 128) = pack8(h0 * w[bj][0], h1 * w[bj][1]); }
;                 ss += __shfl_xor(ss, 16); ss += __shfl_xor(ss, 32);
;                 if (fq == 0) SSP[(size_t)row * 16 + u.pn * 4 + wc] = ss;
;                 asm volatile("" ::: "memory"); }
.LBB0_1450:
	s_or_b64 exec, exec, s[34:35]
	s_waitcnt lgkmcnt(0)
	v_add_u32_e32 v80, 0x80, v166
	v_cmp_lt_i32_e32 vcc, s67, v166
	s_and_saveexec_b64 s[34:35], vcc
	s_xor_b64 s[34:35], exec, s[34:35]
	v_add_u32_e32 v152, 0xffff0080, v166
	v_lshlrev_b64 v[82:83], 12, v[152:153]
	v_lshl_add_u64 v[82:83], s[50:51], 0, v[82:83]
	v_mov_b32_e32 v81, v153
	s_andn2_saveexec_b64 s[34:35], s[34:35]
	v_ashrrev_i32_e32 v81, 31, v80
	v_lshlrev_b64 v[82:83], 12, v[80:81]
	v_lshl_add_u64 v[82:83], s[48:49], 0, v[82:83]
	s_or_b64 exec, exec, s[34:35]
	v_lshl_add_u64 v[90:91], v[82:83], 0, v[164:165]
	global_load_dwordx4 v[82:85], v[90:91], off
	global_load_dwordx4 v[86:89], v[90:91], off offset:16
	v_lshlrev_b64 v[92:93], 12, v[80:81]
	v_lshlrev_b64 v[94:95], 11, v[80:81]
	v_lshl_add_u64 v[92:93], s[84:85], 0, v[92:93]
	v_lshl_add_u64 v[94:95], s[10:11], 0, v[94:95]
	v_lshl_add_u64 v[92:93], v[92:93], 0, v[164:165]
	v_lshl_add_u64 v[94:95], v[162:163], 1, v[94:95]
	s_waitcnt vmcnt(1)
	v_pk_add_f32 v[70:71], v[70:71], v[84:85]
	v_pk_add_f32 v[68:69], v[68:69], v[82:83]
	s_waitcnt vmcnt(0)
	v_pk_add_f32 v[66:67], v[66:67], v[88:89]
	v_pk_add_f32 v[64:65], v[64:65], v[86:87]
	v_pk_mul_f32 v[84:85], v[78:79], v[70:71]
	v_pk_mul_f32 v[82:83], v[76:77], v[68:69]
	global_store_dwordx4 v[92:93], v[68:71], off nt
	global_store_dwordx4 v[92:93], v[64:67], off offset:16 nt
	v_pk_mul_f32 v[86:87], v[74:75], v[66:67]
	v_pk_mul_f32 v[88:89], v[72:73], v[64:65]
	v_cvt_pk_bf16_f32 v82, v82, v83
	v_cvt_pk_bf16_f32 v83, v84, v85
	v_mul_f32_e32 v69, v69, v69
	v_cvt_pk_bf16_f32 v84, v88, v89
	v_cvt_pk_bf16_f32 v85, v86, v87
	global_store_dwordx4 v[94:95], v[82:85], off nt
	global_load_dwordx4 v[82:85], v[90:91], off offset:512
	s_nop 0
	global_load_dwordx4 v[86:89], v[90:91], off offset:528
	v_mul_f32_e32 v71, v71, v71
	v_mul_f32_e32 v65, v65, v65
	v_mul_f32_e32 v67, v67, v67
	v_fmac_f32_e32 v69, v68, v68
	v_fmac_f32_e32 v71, v70, v70
	v_fmac_f32_e32 v65, v64, v64
	v_fmac_f32_e32 v67, v66, v66
	v_add_f32_e32 v64, v69, v71
	v_add_f32_e32 v65, v65, v67
	v_add_f32_e32 v64, v64, v65
	s_waitcnt vmcnt(1)
	v_pk_add_f32 v[54:55], v[54:55], v[84:85]
	v_pk_add_f32 v[52:53], v[52:53], v[82:83]
	s_waitcnt vmcnt(0)
	v_pk_add_f32 v[50:51], v[50:51], v[88:89]
	v_pk_add_f32 v[48:49], v[48:49], v[86:87]
	v_mul_f32_e32 v65, v53, v53
	v_mul_f32_e32 v66, v55, v55
	v_mul_f32_e32 v67, v49, v49
	v_mul_f32_e32 v68, v51, v51
	v_fmac_f32_e32 v65, v52, v52
	v_fmac_f32_e32 v66, v54, v54
	v_fmac_f32_e32 v67, v48, v48
	v_fmac_f32_e32 v68, v50, v50
	v_add_f32_e32 v65, v65, v66
	v_add_f32_e32 v66, v67, v68
	v_add_f32_e32 v65, v65, v66
	v_add_f32_e32 v68, v64, v65
	ds_bpermute_b32 v69, v136, v68
	global_store_dwordx4 v[92:93], v[52:55], off offset:512 nt
	global_store_dwordx4 v[92:93], v[48:51], off offset:528 nt
	v_pk_mul_f32 v[66:67], v[56:57], v[48:49]
	v_pk_mul_f32 v[52:53], v[60:61], v[52:53]
	v_pk_mul_f32 v[54:55], v[62:63], v[54:55]
	s_waitcnt lgkmcnt(0)
	v_add_f32_e32 v48, v68, v69
	ds_bpermute_b32 v49, v132, v48
	v_pk_mul_f32 v[64:65], v[58:59], v[50:51]
	v_cvt_pk_bf16_f32 v50, v52, v53
	v_cvt_pk_bf16_f32 v51, v54, v55
	v_cvt_pk_bf16_f32 v52, v66, v67
	s_nop 0
	v_cvt_pk_bf16_f32 v53, v64, v65
	global_store_dwordx4 v[94:95], v[50:53], off offset:256 nt
	s_and_saveexec_b64 s[34:35], s[4:5]
	s_cbranch_execz .LBB0_1456
	v_lshlrev_b64 v[50:51], 6, v[80:81]
	v_lshl_add_u64 v[50:51], s[12:13], 0, v[50:51]
	v_lshl_add_u64 v[50:51], s[30:31], 2, v[50:51]
	s_lshl_b32 s14, s52, 2
	v_lshl_add_u64 v[50:51], v[50:51], 0, s[14:15]
	s_waitcnt lgkmcnt(0)
	v_add_f32_e32 v48, v48, v49
	global_store_dword v[50:51], v48, off nt
.LBB0_1456:
	s_or_b64 exec, exec, s[34:35]
	s_waitcnt lgkmcnt(0)
	v_add_u32_e32 v48, 0x90, v166
	v_cmp_lt_i32_e32 vcc, s68, v166
	s_and_saveexec_b64 s[34:35], vcc
	s_xor_b64 s[34:35], exec, s[34:35]
	v_add_u32_e32 v152, 0xffff0090, v166
	v_lshlrev_b64 v[50:51], 12, v[152:153]
	v_lshl_add_u64 v[50:51], s[50:51], 0, v[50:51]
	v_mov_b32_e32 v49, v153
	s_andn2_saveexec_b64 s[34:35], s[34:35]
	v_ashrrev_i32_e32 v49, 31, v48
	v_lshlrev_b64 v[50:51], 12, v[48:49]
	v_lshl_add_u64 v[50:51], s[48:49], 0, v[50:51]
	s_or_b64 exec, exec, s[34:35]
	v_lshl_add_u64 v[54:55], v[50:51], 0, v[164:165]
	global_load_dwordx4 v[50:53], v[54:55], off
	global_load_dwordx4 v[64:67], v[54:55], off offset:16
	v_lshlrev_b64 v[68:69], 12, v[48:49]
	v_lshlrev_b64 v[70:71], 11, v[48:49]
	v_lshl_add_u64 v[68:69], s[84:85], 0, v[68:69]
	v_lshl_add_u64 v[70:71], s[10:11], 0, v[70:71]
	v_lshl_add_u64 v[68:69], v[68:69], 0, v[164:165]
	v_lshl_add_u64 v[70:71], v[162:163], 1, v[70:71]
	s_waitcnt vmcnt(1)
	v_pk_add_f32 v[46:47], v[46:47], v[52:53]
	v_pk_add_f32 v[44:45], v[44:45], v[50:51]
	s_waitcnt vmcnt(0)
	v_pk_add_f32 v[42:43], v[42:43], v[66:67]
	v_pk_add_f32 v[40:41], v[40:41], v[64:65]
	v_pk_mul_f32 v[52:53], v[78:79], v[46:47]
	v_pk_mul_f32 v[50:51], v[76:77], v[44:45]
	global_store_dwordx4 v[68:69], v[44:47], off nt
	global_store_dwordx4 v[68:69], v[40:43], off offset:16 nt
	v_pk_mul_f32 v[64:65], v[74:75], v[42:43]
	v_pk_mul_f32 v[66:67], v[72:73], v[40:41]
	v_cvt_pk_bf16_f32 v50, v50, v51
	v_cvt_pk_bf16_f32 v51, v52, v53
	v_mul_f32_e32 v45, v45, v45
	v_cvt_pk_bf16_f32 v52, v66, v67
	v_cvt_pk_bf16_f32 v53, v64, v65
	global_store_dwordx4 v[70:71], v[50:53], off nt
	global_load_dwordx4 v[50:53], v[54:55], off offset:512
	s_nop 0
	global_load_dwordx4 v[64:67], v[54:55], off offset:528
	v_mul_f32_e32 v47, v47, v47
	v_mul_f32_e32 v41, v41, v41
	v_mul_f32_e32 v43, v43, v43
	v_fmac_f32_e32 v45, v44, v44
	v_fmac_f32_e32 v47, v46, v46
	v_fmac_f32_e32 v41, v40, v40
	v_fmac_f32_e32 v43, v42, v42
	v_add_f32_e32 v40, v45, v47
	v_add_f32_e32 v41, v41, v43
	v_add_f32_e32 v40, v40, v41
	s_waitcnt vmcnt(1)
	v_pk_add_f32 v[38:39], v[38:39], v[52:53]
	v_pk_add_f32 v[36:37], v[36:37], v[50:51]
	s_waitcnt vmcnt(0)
	v_pk_add_f32 v[34:35], v[34:35], v[66:67]
	v_pk_add_f32 v[32:33], v[32:33], v[64:65]
	v_mul_f32_e32 v41, v37, v37
	v_mul_f32_e32 v42, v39, v39
	v_mul_f32_e32 v43, v33, v33
	v_mul_f32_e32 v44, v35, v35
	v_fmac_f32_e32 v41, v36, v36
	v_fmac_f32_e32 v42, v38, v38
	v_fmac_f32_e32 v43, v32, v32
	v_fmac_f32_e32 v44, v34, v34
	v_add_f32_e32 v41, v41, v42
	v_add_f32_e32 v42, v43, v44
	v_add_f32_e32 v41, v41, v42
	v_add_f32_e32 v44, v40, v41
	ds_bpermute_b32 v45, v136, v44
	global_store_dwordx4 v[68:69], v[36:39], off offset:512 nt
	global_store_dwordx4 v[68:69], v[32:35], off offset:528 nt
	v_pk_mul_f32 v[42:43], v[56:57], v[32:33]
	v_pk_mul_f32 v[36:37], v[60:61], v[36:37]
	v_pk_mul_f32 v[38:39], v[62:63], v[38:39]
	s_waitcnt lgkmcnt(0)
	v_add_f32_e32 v32, v44, v45
	ds_bpermute_b32 v33, v132, v32
	v_pk_mul_f32 v[40:41], v[58:59], v[34:35]
	v_cvt_pk_bf16_f32 v34, v36, v37
	v_cvt_pk_bf16_f32 v35, v38, v39
	v_cvt_pk_bf16_f32 v36, v42, v43
	s_nop 0
	v_cvt_pk_bf16_f32 v37, v40, v41
	global_store_dwordx4 v[70:71], v[34:37], off offset:256 nt
	s_and_saveexec_b64 s[34:35], s[4:5]
	s_cbranch_execz .LBB0_1462
; __device__ __forceinline__ u32x4 pack8(const f32x4 a, const f32x4 b) { u32x4 w; w.x = cvt_pk_bf16(a[0], a[1]); w.y = cvt_pk_bf16(a[2], a[3]); w.z = cvt_pk_bf16(b[0], b[1]); w.w = cvt_pk_bf16(b[2], b[3]); return w; }
; __device__ __forceinline__ float dot4(const f32x4 a, const f32x4 b) { return (a[0] * b[0] + a[1] * b[1]) + (a[2] * b[2] + a[3] * b[3]); }
;     __device__ __forceinline__ void operator()(const f32x4 (&acc)[2][2][4][2], const Unit& u, int wr, int wc, int fr, int fq) const {
;         const int rbase = u.pm * 256 + wr * 64 + fr, cb = u.pn * 256 + wc * 32 + fq * 8;
;         f32x4 w[2][2];
; #pragma unroll
;         for (int bj = 0; bj < 2; ++bj) { w[bj][0] = *(const f32x4*)(ln2 + cb + bj * 128); w[bj][1] = *(const f32x4*)(ln2 + cb + bj * 128 + 4); }
; #pragma unroll
;         for (int ai = 0; ai < 2; ++ai)
; #pragma unroll
;             for (int m = 0; m < 4; ++m) { const int row = rbase + ai * 128 + m * 16; const float* xr = (row < MP ? xp + (size_t)row * 1024 : xs + (size_t)(row - MP) * 1024) + cb;
;                 float ss = 0.f;
; #pragma unroll
;                 for (int bj = 0; bj < 2; ++bj) { const f32x4 h0 = *(const f32x4*)(xr + bj * 128) + acc[ai][bj][m][0], h1 = *(const f32x4*)(xr + bj * 128 + 4) + acc[ai][bj][m][1];
;                     float* yp = y + (size_t)row * 1024 + cb + bj * 128; *(f32x4*)yp = h0; *(f32x4*)(yp + 4) = h1;
;                     ss += dot4(h0, h0) + dot4(h1, h1);
;                     *(u32x4*)(HN + (size_t)row * 1024 + cb + bj * 128) = pack8(h0 * w[bj][0], h1 * w[bj][1]); }
;                 ss += __shfl_xor(ss, 16); ss += __shfl_xor(ss, 32);
;                 if (fq == 0) SSP[(size_t)row * 16 + u.pn * 4 + wc] = ss;
;                 asm volatile("" ::: "memory"); }
	v_lshlrev_b64 v[34:35], 6, v[48:49]
	v_lshl_add_u64 v[34:35], s[12:13], 0, v[34:35]
	v_lshl_add_u64 v[34:35], s[30:31], 2, v[34:35]
	s_lshl_b32 s14, s52, 2
	v_lshl_add_u64 v[34:35], v[34:35], 0, s[14:15]
	s_waitcnt lgkmcnt(0)
	v_add_f32_e32 v32, v32, v33
	global_store_dword v[34:35], v32, off nt
.LBB0_1462:
	s_or_b64 exec, exec, s[34:35]
	s_waitcnt lgkmcnt(0)
	v_add_u32_e32 v32, 0xa0, v166
	v_cmp_lt_i32_e32 vcc, s69, v166
	s_and_saveexec_b64 s[34:35], vcc
	s_xor_b64 s[34:35], exec, s[34:35]
	v_add_u32_e32 v152, 0xffff00a0, v166
	v_lshlrev_b64 v[34:35], 12, v[152:153]
	v_lshl_add_u64 v[34:35], s[50:51], 0, v[34:35]
	v_mov_b32_e32 v33, v153
	s_andn2_saveexec_b64 s[34:35], s[34:35]
	v_ashrrev_i32_e32 v33, 31, v32
	v_lshlrev_b64 v[34:35], 12, v[32:33]
	v_lshl_add_u64 v[34:35], s[48:49], 0, v[34:35]
	s_or_b64 exec, exec, s[34:35]
	v_lshl_add_u64 v[42:43], v[34:35], 0, v[164:165]
	global_load_dwordx4 v[34:37], v[42:43], off
	global_load_dwordx4 v[38:41], v[42:43], off offset:16
	v_lshlrev_b64 v[44:45], 12, v[32:33]
	v_lshlrev_b64 v[46:47], 11, v[32:33]
	v_lshl_add_u64 v[44:45], s[84:85], 0, v[44:45]
	v_lshl_add_u64 v[46:47], s[10:11], 0, v[46:47]
	v_lshl_add_u64 v[44:45], v[44:45], 0, v[164:165]
	v_lshl_add_u64 v[46:47], v[162:163], 1, v[46:47]
	s_waitcnt vmcnt(1)
	v_pk_add_f32 v[30:31], v[30:31], v[36:37]
	v_pk_add_f32 v[28:29], v[28:29], v[34:35]
	s_waitcnt vmcnt(0)
	v_pk_add_f32 v[26:27], v[26:27], v[40:41]
	v_pk_add_f32 v[24:25], v[24:25], v[38:39]
	v_pk_mul_f32 v[36:37], v[78:79], v[30:31]
	v_pk_mul_f32 v[34:35], v[76:77], v[28:29]
	global_store_dwordx4 v[44:45], v[28:31], off nt
	global_store_dwordx4 v[44:45], v[24:27], off offset:16 nt
	v_pk_mul_f32 v[38:39], v[74:75], v[26:27]
	v_pk_mul_f32 v[40:41], v[72:73], v[24:25]
	v_cvt_pk_bf16_f32 v34, v34, v35
	v_cvt_pk_bf16_f32 v35, v36, v37
	v_mul_f32_e32 v29, v29, v29
	v_cvt_pk_bf16_f32 v36, v40, v41
	v_cvt_pk_bf16_f32 v37, v38, v39
	global_store_dwordx4 v[46:47], v[34:37], off nt
	global_load_dwordx4 v[34:37], v[42:43], off offset:512
	s_nop 0
	global_load_dwordx4 v[38:41], v[42:43], off offset:528
	v_mul_f32_e32 v31, v31, v31
	v_mul_f32_e32 v25, v25, v25
	v_mul_f32_e32 v27, v27, v27
	v_fmac_f32_e32 v29, v28, v28
	v_fmac_f32_e32 v31, v30, v30
	v_fmac_f32_e32 v25, v24, v24
	v_fmac_f32_e32 v27, v26, v26
	v_add_f32_e32 v24, v29, v31
	v_add_f32_e32 v25, v25, v27
	v_add_f32_e32 v24, v24, v25
	s_waitcnt vmcnt(1)
	v_pk_add_f32 v[22:23], v[22:23], v[36:37]
	v_pk_add_f32 v[20:21], v[20:21], v[34:35]
	s_waitcnt vmcnt(0)
	v_pk_add_f32 v[18:19], v[18:19], v[40:41]
	v_pk_add_f32 v[16:17], v[16:17], v[38:39]
	v_mul_f32_e32 v25, v21, v21
	v_mul_f32_e32 v26, v23, v23
	v_mul_f32_e32 v27, v17, v17
	v_mul_f32_e32 v28, v19, v19
	v_fmac_f32_e32 v25, v20, v20
	v_fmac_f32_e32 v26, v22, v22
	v_fmac_f32_e32 v27, v16, v16
	v_fmac_f32_e32 v28, v18, v18
	v_add_f32_e32 v25, v25, v26
	v_add_f32_e32 v26, v27, v28
	v_add_f32_e32 v25, v25, v26
	v_add_f32_e32 v28, v24, v25
	ds_bpermute_b32 v29, v136, v28
	global_store_dwordx4 v[44:45], v[20:23], off offset:512 nt
	global_store_dwordx4 v[44:45], v[16:19], off offset:528 nt
	v_pk_mul_f32 v[26:27], v[56:57], v[16:17]
	v_pk_mul_f32 v[20:21], v[60:61], v[20:21]
	v_pk_mul_f32 v[22:23], v[62:63], v[22:23]
	s_waitcnt lgkmcnt(0)
	v_add_f32_e32 v16, v28, v29
	ds_bpermute_b32 v17, v132, v16
	v_pk_mul_f32 v[24:25], v[58:59], v[18:19]
	v_cvt_pk_bf16_f32 v18, v20, v21
	v_cvt_pk_bf16_f32 v19, v22, v23
	v_cvt_pk_bf16_f32 v20, v26, v27
	s_nop 0
	v_cvt_pk_bf16_f32 v21, v24, v25
	global_store_dwordx4 v[46:47], v[18:21], off offset:256 nt
	s_and_saveexec_b64 s[34:35], s[4:5]
	s_cbranch_execz .LBB0_1468
	v_lshlrev_b64 v[18:19], 6, v[32:33]
	v_lshl_add_u64 v[18:19], s[12:13], 0, v[18:19]
	v_lshl_add_u64 v[18:19], s[30:31], 2, v[18:19]
	s_lshl_b32 s14, s52, 2
	v_lshl_add_u64 v[18:19], v[18:19], 0, s[14:15]
	s_waitcnt lgkmcnt(0)
	v_add_f32_e32 v16, v16, v17
	global_store_dword v[18:19], v16, off nt
; __device__ __forceinline__ u32x4 pack8(const f32x4 a, const f32x4 b) { u32x4 w; w.x = cvt_pk_bf16(a[0], a[1]); w.y = cvt_pk_bf16(a[2], a[3]); w.z = cvt_pk_bf16(b[0], b[1]); w.w = cvt_pk_bf16(b[2], b[3]); return w; }
; __device__ __forceinline__ float dot4(const f32x4 a, const f32x4 b) { return (a[0] * b[0] + a[1] * b[1]) + (a[2] * b[2] + a[3] * b[3]); }
;     __device__ __forceinline__ void operator()(const f32x4 (&acc)[2][2][4][2], const Unit& u, int wr, int wc, int fr, int fq) const {
;         const int rbase = u.pm * 256 + wr * 64 + fr, cb = u.pn * 256 + wc * 32 + fq * 8;
;         f32x4 w[2][2];
; #pragma unroll
;         for (int bj = 0; bj < 2; ++bj) { w[bj][0] = *(const f32x4*)(ln2 + cb + bj * 128); w[bj][1] = *(const f32x4*)(ln2 + cb + bj * 128 + 4); }
; #pragma unroll
;         for (int ai = 0; ai < 2; ++ai)
; #pragma unroll
;             for (int m = 0; m < 4; ++m) { const int row = rbase + ai * 128 + m * 16; const float* xr = (row < MP ? xp + (size_t)row * 1024 : xs + (size_t)(row - MP) * 1024) + cb;
;                 float ss = 0.f;
; #pragma unroll
;                 for (int bj = 0; bj < 2; ++bj) { const f32x4 h0 = *(const f32x4*)(xr + bj * 128) + acc[ai][bj][m][0], h1 = *(const f32x4*)(xr + bj * 128 + 4) + acc[ai][bj][m][1];
;                     float* yp = y + (size_t)row * 1024 + cb + bj * 128; *(f32x4*)yp = h0; *(f32x4*)(yp + 4) = h1;
;                     ss += dot4(h0, h0) + dot4(h1, h1);
;                     *(u32x4*)(HN + (size_t)row * 1024 + cb + bj * 128) = pack8(h0 * w[bj][0], h1 * w[bj][1]); }
;                 ss += __shfl_xor(ss, 16); ss += __shfl_xor(ss, 32);
;                 if (fq == 0) SSP[(size_t)row * 16 + u.pn * 4 + wc] = ss;
;                 asm volatile("" ::: "memory"); }
.LBB0_1468:
	s_or_b64 exec, exec, s[34:35]
	s_waitcnt lgkmcnt(0)
	v_add_u32_e32 v16, 0xb0, v166
	v_cmp_lt_i32_e32 vcc, s70, v166
	s_and_saveexec_b64 s[34:35], vcc
	s_xor_b64 s[34:35], exec, s[34:35]
	v_add_u32_e32 v152, 0xffff00b0, v166
	v_lshlrev_b64 v[18:19], 12, v[152:153]
	v_lshl_add_u64 v[18:19], s[50:51], 0, v[18:19]
	v_mov_b32_e32 v17, v153
	s_andn2_saveexec_b64 s[34:35], s[34:35]
	v_ashrrev_i32_e32 v17, 31, v16
	v_lshlrev_b64 v[18:19], 12, v[16:17]
	v_lshl_add_u64 v[18:19], s[48:49], 0, v[18:19]
	s_or_b64 exec, exec, s[34:35]
	v_lshl_add_u64 v[26:27], v[18:19], 0, v[164:165]
	global_load_dwordx4 v[18:21], v[26:27], off
	global_load_dwordx4 v[22:25], v[26:27], off offset:16
	v_lshlrev_b64 v[28:29], 12, v[16:17]
	v_lshlrev_b64 v[30:31], 11, v[16:17]
	v_lshl_add_u64 v[28:29], s[84:85], 0, v[28:29]
	v_lshl_add_u64 v[30:31], s[10:11], 0, v[30:31]
	v_lshl_add_u64 v[28:29], v[28:29], 0, v[164:165]
	v_lshl_add_u64 v[30:31], v[162:163], 1, v[30:31]
	s_waitcnt vmcnt(1)
	v_pk_add_f32 v[14:15], v[14:15], v[20:21]
	v_pk_add_f32 v[12:13], v[12:13], v[18:19]
	s_waitcnt vmcnt(0)
	v_pk_add_f32 v[10:11], v[10:11], v[24:25]
	v_pk_add_f32 v[8:9], v[8:9], v[22:23]
	v_pk_mul_f32 v[20:21], v[78:79], v[14:15]
	v_pk_mul_f32 v[18:19], v[76:77], v[12:13]
	global_store_dwordx4 v[28:29], v[12:15], off nt
	global_store_dwordx4 v[28:29], v[8:11], off offset:16 nt
	v_pk_mul_f32 v[22:23], v[74:75], v[10:11]
	v_pk_mul_f32 v[24:25], v[72:73], v[8:9]
	v_cvt_pk_bf16_f32 v18, v18, v19
	v_cvt_pk_bf16_f32 v19, v20, v21
	v_mul_f32_e32 v13, v13, v13
	v_cvt_pk_bf16_f32 v20, v24, v25
	v_cvt_pk_bf16_f32 v21, v22, v23
	global_store_dwordx4 v[30:31], v[18:21], off nt
	global_load_dwordx4 v[18:21], v[26:27], off offset:512
	s_nop 0
	global_load_dwordx4 v[22:25], v[26:27], off offset:528
	v_mul_f32_e32 v15, v15, v15
	v_mul_f32_e32 v9, v9, v9
	v_mul_f32_e32 v11, v11, v11
	v_fmac_f32_e32 v13, v12, v12
	v_fmac_f32_e32 v15, v14, v14
	v_fmac_f32_e32 v9, v8, v8
	v_fmac_f32_e32 v11, v10, v10
	v_add_f32_e32 v8, v13, v15
	v_add_f32_e32 v9, v9, v11
	v_add_f32_e32 v8, v8, v9
	s_waitcnt vmcnt(1)
	v_pk_add_f32 v[6:7], v[6:7], v[20:21]
	v_pk_add_f32 v[4:5], v[4:5], v[18:19]
	s_waitcnt vmcnt(0)
	v_pk_add_f32 v[2:3], v[2:3], v[24:25]
	v_pk_add_f32 v[0:1], v[0:1], v[22:23]
	v_mul_f32_e32 v9, v5, v5
	v_mul_f32_e32 v10, v7, v7
	v_mul_f32_e32 v11, v1, v1
	v_mul_f32_e32 v12, v3, v3
	v_fmac_f32_e32 v9, v4, v4
	v_fmac_f32_e32 v10, v6, v6
	v_fmac_f32_e32 v11, v0, v0
	v_fmac_f32_e32 v12, v2, v2
	v_add_f32_e32 v9, v9, v10
	v_add_f32_e32 v10, v11, v12
	v_add_f32_e32 v9, v9, v10
	v_add_f32_e32 v12, v8, v9
	ds_bpermute_b32 v13, v136, v12
	global_store_dwordx4 v[28:29], v[4:7], off offset:512 nt
	global_store_dwordx4 v[28:29], v[0:3], off offset:528 nt
	v_pk_mul_f32 v[10:11], v[56:57], v[0:1]
	v_pk_mul_f32 v[4:5], v[60:61], v[4:5]
	v_pk_mul_f32 v[6:7], v[62:63], v[6:7]
	s_waitcnt lgkmcnt(0)
	v_add_f32_e32 v0, v12, v13
	ds_bpermute_b32 v1, v132, v0
	v_pk_mul_f32 v[8:9], v[58:59], v[2:3]
	v_cvt_pk_bf16_f32 v2, v4, v5
	v_cvt_pk_bf16_f32 v3, v6, v7
	v_cvt_pk_bf16_f32 v4, v10, v11
	s_nop 0
	v_cvt_pk_bf16_f32 v5, v8, v9
	global_store_dwordx4 v[30:31], v[2:5], off offset:256 nt
	s_and_saveexec_b64 s[34:35], s[4:5]
	s_cbranch_execz .LBB0_1474
	v_lshlrev_b64 v[2:3], 6, v[16:17]
	v_lshl_add_u64 v[2:3], s[12:13], 0, v[2:3]
	v_lshl_add_u64 v[2:3], s[30:31], 2, v[2:3]
	s_lshl_b32 s14, s52, 2
	v_lshl_add_u64 v[2:3], v[2:3], 0, s[14:15]
	s_waitcnt lgkmcnt(0)
	v_add_f32_e32 v0, v0, v1
	global_store_dword v[2:3], v0, off nt

; __device__ __forceinline__ u32x4 pack8(const f32x4 a, const f32x4 b) { u32x4 w; w.x = cvt_pk_bf16(a[0], a[1]); w.y = cvt_pk_bf16(a[2], a[3]); w.z = cvt_pk_bf16(b[0], b[1]); w.w = cvt_pk_bf16(b[2], b[3]); return w; }
;     __device__ __forceinline__ void operator()(const f32x4 (&acc)[2][2][4][2], const Unit& u, int wr, int wc, int fr, int fq) const {
;         const int rbase = u.pm * 256 + wr * 64 + fr, cb = u.pn * 256 + wc * 32 + fq * 8;
; #pragma unroll
;         for (int ai = 0; ai < 2; ++ai)
; #pragma unroll
;             for (int m = 0; m < 4; ++m) { const int row = rbase + ai * 128 + m * 16; const f32x4* sp = (const f32x4*)(SSP + (size_t)row * 16);
;                 const f32x4 s4 = (sp[0] + sp[1]) + (sp[2] + sp[3]); const float rstd = __builtin_amdgcn_rsqf(((s4[0] + s4[1]) + (s4[2] + s4[3])) * (1.0f / 1024.0f) + EPS);
; #pragma unroll
;                 for (int bj = 0; bj < 2; ++bj) { f32x4 v0 = acc[ai][bj][m][0] * rstd, v1 = acc[ai][bj][m][1] * rstd;
; #pragma unroll
;                     for (int i = 0; i < 4; ++i) { const float a = fmaxf(v0[i], 0.f), b = fmaxf(v1[i], 0.f); v0[i] = a * a; v1[i] = b * b; }
;                     *(u32x4*)(Z + (size_t)row * FF + cb + bj * 128) = pack8(v0, v1); }
;                 asm volatile("" ::: "memory"); }
.LBB0_1543:
	v_lshlrev_b64 v[220:221], 13, v[146:147]
	v_lshl_or_b32 v222, s60, 8, v150
	v_ashrrev_i32_e32 v223, 31, v222
	v_lshlrev_b64 v[222:223], 1, v[222:223]
	v_lshl_add_u64 v[220:221], s[8:9], 0, v[220:221]
	v_lshl_add_u64 v[220:221], v[220:221], 0, v[222:223]
	v_mov_b64_e32 v[224:225], v[220:221]
	s_mov_b64 s[98:99], 0x2000
	s_mov_b64 s[100:101], 0xa0000
	v_lshl_add_u64 v[222:223], v[144:145], 0, s[98:99]
	s_mov_b64 s[98:99], 0x20000
	s_waitcnt vmcnt(12)
	v_pk_add_f32 v[156:157], v[156:157], v[160:161]
	v_pk_add_f32 v[158:159], v[158:159], v[162:163]
	v_pk_add_f32 v[164:165], v[164:165], v[168:169]
	v_pk_add_f32 v[166:167], v[166:167], v[170:171]
	v_pk_add_f32 v[156:157], v[156:157], v[164:165]
	v_pk_add_f32 v[158:159], v[158:159], v[166:167]
	v_add_f32_e32 v156, v156, v157
	v_add_f32_e32 v158, v158, v159
	v_add_f32_e32 v156, v156, v158
	v_fmamk_f32 v156, v156, 0x3a800000, v154
	v_rsq_f32_e32 v144, v156
	s_waitcnt vmcnt(8)
	v_pk_add_f32 v[172:173], v[172:173], v[176:177]
	v_pk_add_f32 v[174:175], v[174:175], v[178:179]
	v_pk_add_f32 v[180:181], v[180:181], v[184:185]
	v_pk_add_f32 v[182:183], v[182:183], v[186:187]
	v_pk_add_f32 v[172:173], v[172:173], v[180:181]
	v_pk_add_f32 v[174:175], v[174:175], v[182:183]
	v_add_f32_e32 v172, v172, v173
	v_add_f32_e32 v174, v174, v175
	v_add_f32_e32 v172, v172, v174
	v_fmamk_f32 v172, v172, 0x3a800000, v154
	v_rsq_f32_e32 v145, v172
	s_waitcnt vmcnt(4)
	v_pk_add_f32 v[188:189], v[188:189], v[192:193]
	v_pk_add_f32 v[190:191], v[190:191], v[194:195]
	v_pk_add_f32 v[196:197], v[196:197], v[200:201]
	v_pk_add_f32 v[198:199], v[198:199], v[202:203]
	v_pk_add_f32 v[188:189], v[188:189], v[196:197]
	v_pk_add_f32 v[190:191], v[190:191], v[198:199]
	v_add_f32_e32 v188, v188, v189
	v_add_f32_e32 v190, v190, v191
	v_add_f32_e32 v188, v188, v190
	v_fmamk_f32 v188, v188, 0x3a800000, v154
	v_rsq_f32_e32 v146, v188
	s_waitcnt vmcnt(0)
	v_pk_add_f32 v[204:205], v[204:205], v[208:209]
	v_pk_add_f32 v[206:207], v[206:207], v[210:211]
	v_pk_add_f32 v[212:213], v[212:213], v[216:217]
	v_pk_add_f32 v[214:215], v[214:215], v[218:219]
	v_pk_add_f32 v[204:205], v[204:205], v[212:213]
	v_pk_add_f32 v[206:207], v[206:207], v[214:215]
	v_add_f32_e32 v204, v204, v205
	v_add_f32_e32 v206, v206, v207
	v_add_f32_e32 v204, v204, v206
	v_fmamk_f32 v204, v204, 0x3a800000, v154
	v_rsq_f32_e32 v147, v204
	global_load_dwordx4 v[156:159], v[222:223], off
	global_load_dwordx4 v[160:163], v[222:223], off offset:16
	global_load_dwordx4 v[164:167], v[222:223], off offset:32
	global_load_dwordx4 v[168:171], v[222:223], off offset:48
	global_load_dwordx4 v[172:175], v[222:223], off offset:1024
	global_load_dwordx4 v[176:179], v[222:223], off offset:1040
	global_load_dwordx4 v[180:183], v[222:223], off offset:1056
	global_load_dwordx4 v[184:187], v[222:223], off offset:1072
	global_load_dwordx4 v[188:191], v[222:223], off offset:2048
	global_load_dwordx4 v[192:195], v[222:223], off offset:2064
	global_load_dwordx4 v[196:199], v[222:223], off offset:2080
	global_load_dwordx4 v[200:203], v[222:223], off offset:2096
	global_load_dwordx4 v[204:207], v[222:223], off offset:3072
	global_load_dwordx4 v[208:211], v[222:223], off offset:3088
	global_load_dwordx4 v[212:215], v[222:223], off offset:3104
	global_load_dwordx4 v[216:219], v[222:223], off offset:3120
	v_mul_f32_e32 v112, v144, v112
	v_mul_f32_e32 v113, v144, v113
	v_mul_f32_e32 v114, v144, v114
	v_mul_f32_e32 v115, v144, v115
	v_mul_f32_e32 v116, v144, v116
	v_mul_f32_e32 v117, v144, v117
	v_mul_f32_e32 v118, v144, v118
	v_mul_f32_e32 v119, v144, v119
	v_mul_f32_e32 v120, v144, v120
	v_mul_f32_e32 v121, v144, v121
	v_mul_f32_e32 v122, v144, v122
	v_mul_f32_e32 v123, v144, v123
	v_mul_f32_e32 v124, v144, v124
	v_mul_f32_e32 v125, v144, v125
	v_mul_f32_e32 v126, v144, v126
	v_mul_f32_e32 v127, v144, v127
	v_max_f32_e32 v112, 0, v112
	v_max_f32_e32 v113, 0, v113
	v_max_f32_e32 v114, 0, v114
	v_max_f32_e32 v115, 0, v115
	v_max_f32_e32 v116, 0, v116
	v_max_f32_e32 v117, 0, v117
	v_max_f32_e32 v118, 0, v118
	v_max_f32_e32 v119, 0, v119
	v_max_f32_e32 v120, 0, v120
	v_max_f32_e32 v121, 0, v121
	v_max_f32_e32 v122, 0, v122
	v_max_f32_e32 v123, 0, v123
	v_max_f32_e32 v124, 0, v124
	v_max_f32_e32 v125, 0, v125
	v_max_f32_e32 v126, 0, v126
	v_max_f32_e32 v127, 0, v127
	v_mul_f32_e32 v112, v112, v112
	v_mul_f32_e32 v113, v113, v113
	v_mul_f32_e32 v114, v114, v114
	v_mul_f32_e32 v115, v115, v115
	v_mul_f32_e32 v116, v116, v116
	v_mul_f32_e32 v117, v117, v117
	v_mul_f32_e32 v118, v118, v118
	v_mul_f32_e32 v119, v119, v119
	v_mul_f32_e32 v120, v120, v120
	v_mul_f32_e32 v121, v121, v121
	v_mul_f32_e32 v122, v122, v122
	v_mul_f32_e32 v123, v123, v123
	v_mul_f32_e32 v124, v124, v124
	v_mul_f32_e32 v125, v125, v125
	v_mul_f32_e32 v126, v126, v126
	v_mul_f32_e32 v127, v127, v127
	v_cvt_pk_bf16_f32 v124, v124, v125
	v_cvt_pk_bf16_f32 v125, v126, v127
	v_cvt_pk_bf16_f32 v126, v120, v121
	v_cvt_pk_bf16_f32 v127, v122, v123
	v_cvt_pk_bf16_f32 v116, v116, v117
	v_cvt_pk_bf16_f32 v117, v118, v119
	v_cvt_pk_bf16_f32 v118, v112, v113
	v_cvt_pk_bf16_f32 v119, v114, v115
	global_store_dwordx4 v[220:221], v[124:127], off nt
	global_store_dwordx4 v[220:221], v[116:119], off offset:256 nt
	v_lshl_add_u64 v[220:221], v[220:221], 0, s[98:99]
	v_mul_f32_e32 v96, v145, v96
	v_mul_f32_e32 v97, v145, v97
	v_mul_f32_e32 v98, v145, v98
	v_mul_f32_e32 v99, v145, v99
	v_mul_f32_e32 v100, v145, v100
	v_mul_f32_e32 v101, v145, v101
	v_mul_f32_e32 v102, v145, v102
	v_mul_f32_e32 v103, v145, v103
	v_mul_f32_e32 v104, v145, v104
	v_mul_f32_e32 v105, v145, v105
	v_mul_f32_e32 v106, v145, v106
	v_mul_f32_e32 v107, v145, v107
; __device__ __forceinline__ u32x4 pack8(const f32x4 a, const f32x4 b) { u32x4 w; w.x = cvt_pk_bf16(a[0], a[1]); w.y = cvt_pk_bf16(a[2], a[3]); w.z = cvt_pk_bf16(b[0], b[1]); w.w = cvt_pk_bf16(b[2], b[3]); return w; }
;     __device__ __forceinline__ void operator()(const f32x4 (&acc)[2][2][4][2], const Unit& u, int wr, int wc, int fr, int fq) const {
;         const int rbase = u.pm * 256 + wr * 64 + fr, cb = u.pn * 256 + wc * 32 + fq * 8;
; #pragma unroll
;         for (int ai = 0; ai < 2; ++ai)
; #pragma unroll
;             for (int m = 0; m < 4; ++m) { const int row = rbase + ai * 128 + m * 16; const f32x4* sp = (const f32x4*)(SSP + (size_t)row * 16);
;                 const f32x4 s4 = (sp[0] + sp[1]) + (sp[2] + sp[3]); const float rstd = __builtin_amdgcn_rsqf(((s4[0] + s4[1]) + (s4[2] + s4[3])) * (1.0f / 1024.0f) + EPS);
; #pragma unroll
;                 for (int bj = 0; bj < 2; ++bj) { f32x4 v0 = acc[ai][bj][m][0] * rstd, v1 = acc[ai][bj][m][1] * rstd;
; #pragma unroll
;                     for (int i = 0; i < 4; ++i) { const float a = fmaxf(v0[i], 0.f), b = fmaxf(v1[i], 0.f); v0[i] = a * a; v1[i] = b * b; }
;                     *(u32x4*)(Z + (size_t)row * FF + cb + bj * 128) = pack8(v0, v1); }
;                 asm volatile("" ::: "memory"); }
	v_mul_f32_e32 v108, v145, v108
	v_mul_f32_e32 v109, v145, v109
	v_mul_f32_e32 v110, v145, v110
	v_mul_f32_e32 v111, v145, v111
	v_max_f32_e32 v96, 0, v96
	v_max_f32_e32 v97, 0, v97
	v_max_f32_e32 v98, 0, v98
	v_max_f32_e32 v99, 0, v99
	v_max_f32_e32 v100, 0, v100
	v_max_f32_e32 v101, 0, v101
	v_max_f32_e32 v102, 0, v102
	v_max_f32_e32 v103, 0, v103
	v_max_f32_e32 v104, 0, v104
	v_max_f32_e32 v105, 0, v105
	v_max_f32_e32 v106, 0, v106
	v_max_f32_e32 v107, 0, v107
	v_max_f32_e32 v108, 0, v108
	v_max_f32_e32 v109, 0, v109
	v_max_f32_e32 v110, 0, v110
	v_max_f32_e32 v111, 0, v111
	v_mul_f32_e32 v96, v96, v96
	v_mul_f32_e32 v97, v97, v97
	v_mul_f32_e32 v98, v98, v98
	v_mul_f32_e32 v99, v99, v99
	v_mul_f32_e32 v100, v100, v100
	v_mul_f32_e32 v101, v101, v101
	v_mul_f32_e32 v102, v102, v102
	v_mul_f32_e32 v103, v103, v103
	v_mul_f32_e32 v104, v104, v104
	v_mul_f32_e32 v105, v105, v105
	v_mul_f32_e32 v106, v106, v106
	v_mul_f32_e32 v107, v107, v107
	v_mul_f32_e32 v108, v108, v108
	v_mul_f32_e32 v109, v109, v109
	v_mul_f32_e32 v110, v110, v110
	v_mul_f32_e32 v111, v111, v111
	v_cvt_pk_bf16_f32 v108, v108, v109
	v_cvt_pk_bf16_f32 v109, v110, v111
	v_cvt_pk_bf16_f32 v110, v104, v105
	v_cvt_pk_bf16_f32 v111, v106, v107
	v_cvt_pk_bf16_f32 v100, v100, v101
	v_cvt_pk_bf16_f32 v101, v102, v103
	v_cvt_pk_bf16_f32 v102, v96, v97
	v_cvt_pk_bf16_f32 v103, v98, v99
	global_store_dwordx4 v[220:221], v[108:111], off nt
	global_store_dwordx4 v[220:221], v[100:103], off offset:256 nt
	v_lshl_add_u64 v[220:221], v[220:221], 0, s[98:99]
	v_mul_f32_e32 v80, v146, v80
	v_mul_f32_e32 v81, v146, v81
	v_mul_f32_e32 v82, v146, v82
	v_mul_f32_e32 v83, v146, v83
	v_mul_f32_e32 v84, v146, v84
	v_mul_f32_e32 v85, v146, v85
	v_mul_f32_e32 v86, v146, v86
	v_mul_f32_e32 v87, v146, v87
	v_mul_f32_e32 v88, v146, v88
	v_mul_f32_e32 v89, v146, v89
	v_mul_f32_e32 v90, v146, v90
	v_mul_f32_e32 v91, v146, v91
	v_mul_f32_e32 v92, v146, v92
	v_mul_f32_e32 v93, v146, v93
	v_mul_f32_e32 v94, v146, v94
	v_mul_f32_e32 v95, v146, v95
	v_max_f32_e32 v80, 0, v80
	v_max_f32_e32 v81, 0, v81
	v_max_f32_e32 v82, 0, v82
	v_max_f32_e32 v83, 0, v83
	v_max_f32_e32 v84, 0, v84
	v_max_f32_e32 v85, 0, v85
	v_max_f32_e32 v86, 0, v86
	v_max_f32_e32 v87, 0, v87
	v_max_f32_e32 v88, 0, v88
	v_max_f32_e32 v89, 0, v89
	v_max_f32_e32 v90, 0, v90
	v_max_f32_e32 v91, 0, v91
	v_max_f32_e32 v92, 0, v92
	v_max_f32_e32 v93, 0, v93
	v_max_f32_e32 v94, 0, v94
	v_max_f32_e32 v95, 0, v95
	v_mul_f32_e32 v80, v80, v80
	v_mul_f32_e32 v81, v81, v81
	v_mul_f32_e32 v82, v82, v82
	v_mul_f32_e32 v83, v83, v83
	v_mul_f32_e32 v84, v84, v84
	v_mul_f32_e32 v85, v85, v85
	v_mul_f32_e32 v86, v86, v86
	v_mul_f32_e32 v87, v87, v87
	v_mul_f32_e32 v88, v88, v88
	v_mul_f32_e32 v89, v89, v89
	v_mul_f32_e32 v90, v90, v90
	v_mul_f32_e32 v91, v91, v91
	v_mul_f32_e32 v92, v92, v92
	v_mul_f32_e32 v93, v93, v93
	v_mul_f32_e32 v94, v94, v94
	v_mul_f32_e32 v95, v95, v95
	v_cvt_pk_bf16_f32 v92, v92, v93
	v_cvt_pk_bf16_f32 v93, v94, v95
	v_cvt_pk_bf16_f32 v94, v88, v89
	v_cvt_pk_bf16_f32 v95, v90, v91
	v_cvt_pk_bf16_f32 v84, v84, v85
	v_cvt_pk_bf16_f32 v85, v86, v87
	v_cvt_pk_bf16_f32 v86, v80, v81
	v_cvt_pk_bf16_f32 v87, v82, v83
	global_store_dwordx4 v[220:221], v[92:95], off nt
	global_store_dwordx4 v[220:221], v[84:87], off offset:256 nt
	v_lshl_add_u64 v[220:221], v[220:221], 0, s[98:99]
	v_mul_f32_e32 v64, v147, v64
	v_mul_f32_e32 v65, v147, v65
	v_mul_f32_e32 v66, v147, v66
	v_mul_f32_e32 v67, v147, v67
	v_mul_f32_e32 v68, v147, v68
	v_mul_f32_e32 v69, v147, v69
	v_mul_f32_e32 v70, v147, v70
	v_mul_f32_e32 v71, v147, v71
	v_mul_f32_e32 v72, v147, v72
	v_mul_f32_e32 v73, v147, v73
	v_mul_f32_e32 v74, v147, v74
	v_mul_f32_e32 v75, v147, v75
	v_mul_f32_e32 v76, v147, v76
	v_mul_f32_e32 v77, v147, v77
	v_mul_f32_e32 v78, v147, v78
	v_mul_f32_e32 v79, v147, v79
	v_max_f32_e32 v64, 0, v64
	v_max_f32_e32 v65, 0, v65
	v_max_f32_e32 v66, 0, v66
	v_max_f32_e32 v67, 0, v67
	v_max_f32_e32 v68, 0, v68
	v_max_f32_e32 v69, 0, v69
	v_max_f32_e32 v70, 0, v70
	v_max_f32_e32 v71, 0, v71
	v_max_f32_e32 v72, 0, v72
	v_max_f32_e32 v73, 0, v73
	v_max_f32_e32 v74, 0, v74
	v_max_f32_e32 v75, 0, v75
	v_max_f32_e32 v76, 0, v76
	v_max_f32_e32 v77, 0, v77
	v_max_f32_e32 v78, 0, v78
	v_max_f32_e32 v79, 0, v79
	v_mul_f32_e32 v64, v64, v64
	v_mul_f32_e32 v65, v65, v65
	v_mul_f32_e32 v66, v66, v66
	v_mul_f32_e32 v67, v67, v67
	v_mul_f32_e32 v68, v68, v68
	v_mul_f32_e32 v69, v69, v69
	v_mul_f32_e32 v70, v70, v70
	v_mul_f32_e32 v71, v71, v71
	v_mul_f32_e32 v72, v72, v72
	v_mul_f32_e32 v73, v73, v73
	v_mul_f32_e32 v74, v74, v74
	v_mul_f32_e32 v75, v75, v75
	v_mul_f32_e32 v76, v76, v76
	v_mul_f32_e32 v77, v77, v77
	v_mul_f32_e32 v78, v78, v78
	v_mul_f32_e32 v79, v79, v79
	v_cvt_pk_bf16_f32 v76, v76, v77
	v_cvt_pk_bf16_f32 v77, v78, v79
	v_cvt_pk_bf16_f32 v78, v72, v73
	v_cvt_pk_bf16_f32 v79, v74, v75
	v_cvt_pk_bf16_f32 v68, v68, v69
	v_cvt_pk_bf16_f32 v69, v70, v71
	v_cvt_pk_bf16_f32 v70, v64, v65
	v_cvt_pk_bf16_f32 v71, v66, v67
	global_store_dwordx4 v[220:221], v[76:79], off nt
	global_store_dwordx4 v[220:221], v[68:71], off offset:256 nt
	v_lshl_add_u64 v[220:221], v[220:221], 0, s[100:101]
	s_waitcnt vmcnt(20)
	v_pk_add_f32 v[156:157], v[156:157], v[160:161]
	v_pk_add_f32 v[158:159], v[158:159], v[162:163]
	v_pk_add_f32 v[164:165], v[164:165], v[168:169]
	v_pk_add_f32 v[166:167], v[166:167], v[170:171]
	v_pk_add_f32 v[156:157], v[156:157], v[164:165]
	v_pk_add_f32 v[158:159], v[158:159], v[166:167]
	v_add_f32_e32 v156, v156, v157
	v_add_f32_e32 v158, v158, v159
	v_add_f32_e32 v156, v156, v158
	v_fmamk_f32 v156, v156, 0x3a800000, v154
	v_rsq_f32_e32 v144, v156
	s_waitcnt vmcnt(16)
; __device__ __forceinline__ u32x4 pack8(const f32x4 a, const f32x4 b) { u32x4 w; w.x = cvt_pk_bf16(a[0], a[1]); w.y = cvt_pk_bf16(a[2], a[3]); w.z = cvt_pk_bf16(b[0], b[1]); w.w = cvt_pk_bf16(b[2], b[3]); return w; }
;     __device__ __forceinline__ void operator()(const f32x4 (&acc)[2][2][4][2], const Unit& u, int wr, int wc, int fr, int fq) const {
;         const int rbase = u.pm * 256 + wr * 64 + fr, cb = u.pn * 256 + wc * 32 + fq * 8;
; #pragma unroll
;         for (int ai = 0; ai < 2; ++ai)
; #pragma unroll
;             for (int m = 0; m < 4; ++m) { const int row = rbase + ai * 128 + m * 16; const f32x4* sp = (const f32x4*)(SSP + (size_t)row * 16);
;                 const f32x4 s4 = (sp[0] + sp[1]) + (sp[2] + sp[3]); const float rstd = __builtin_amdgcn_rsqf(((s4[0] + s4[1]) + (s4[2] + s4[3])) * (1.0f / 1024.0f) + EPS);
; #pragma unroll
;                 for (int bj = 0; bj < 2; ++bj) { f32x4 v0 = acc[ai][bj][m][0] * rstd, v1 = acc[ai][bj][m][1] * rstd;
; #pragma unroll
;                     for (int i = 0; i < 4; ++i) { const float a = fmaxf(v0[i], 0.f), b = fmaxf(v1[i], 0.f); v0[i] = a * a; v1[i] = b * b; }
;                     *(u32x4*)(Z + (size_t)row * FF + cb + bj * 128) = pack8(v0, v1); }
;                 asm volatile("" ::: "memory"); }
	v_pk_add_f32 v[172:173], v[172:173], v[176:177]
	v_pk_add_f32 v[174:175], v[174:175], v[178:179]
	v_pk_add_f32 v[180:181], v[180:181], v[184:185]
	v_pk_add_f32 v[182:183], v[182:183], v[186:187]
	v_pk_add_f32 v[172:173], v[172:173], v[180:181]
	v_pk_add_f32 v[174:175], v[174:175], v[182:183]
	v_add_f32_e32 v172, v172, v173
	v_add_f32_e32 v174, v174, v175
	v_add_f32_e32 v172, v172, v174
	v_fmamk_f32 v172, v172, 0x3a800000, v154
	v_rsq_f32_e32 v145, v172
	s_waitcnt vmcnt(12)
	v_pk_add_f32 v[188:189], v[188:189], v[192:193]
	v_pk_add_f32 v[190:191], v[190:191], v[194:195]
	v_pk_add_f32 v[196:197], v[196:197], v[200:201]
	v_pk_add_f32 v[198:199], v[198:199], v[202:203]
	v_pk_add_f32 v[188:189], v[188:189], v[196:197]
	v_pk_add_f32 v[190:191], v[190:191], v[198:199]
	v_add_f32_e32 v188, v188, v189
	v_add_f32_e32 v190, v190, v191
	v_add_f32_e32 v188, v188, v190
	v_fmamk_f32 v188, v188, 0x3a800000, v154
	v_rsq_f32_e32 v146, v188
	s_waitcnt vmcnt(8)
	v_pk_add_f32 v[204:205], v[204:205], v[208:209]
	v_pk_add_f32 v[206:207], v[206:207], v[210:211]
	v_pk_add_f32 v[212:213], v[212:213], v[216:217]
	v_pk_add_f32 v[214:215], v[214:215], v[218:219]
	v_pk_add_f32 v[204:205], v[204:205], v[212:213]
	v_pk_add_f32 v[206:207], v[206:207], v[214:215]
	v_add_f32_e32 v204, v204, v205
	v_add_f32_e32 v206, v206, v207
	v_add_f32_e32 v204, v204, v206
	v_fmamk_f32 v204, v204, 0x3a800000, v154
	v_rsq_f32_e32 v147, v204
	v_mul_f32_e32 v48, v144, v48
	v_mul_f32_e32 v49, v144, v49
	v_mul_f32_e32 v50, v144, v50
	v_mul_f32_e32 v51, v144, v51
	v_mul_f32_e32 v52, v144, v52
	v_mul_f32_e32 v53, v144, v53
	v_mul_f32_e32 v54, v144, v54
	v_mul_f32_e32 v55, v144, v55
	v_mul_f32_e32 v56, v144, v56
	v_mul_f32_e32 v57, v144, v57
	v_mul_f32_e32 v58, v144, v58
	v_mul_f32_e32 v59, v144, v59
	v_mul_f32_e32 v60, v144, v60
	v_mul_f32_e32 v61, v144, v61
	v_mul_f32_e32 v62, v144, v62
	v_mul_f32_e32 v63, v144, v63
	v_max_f32_e32 v48, 0, v48
	v_max_f32_e32 v49, 0, v49
	v_max_f32_e32 v50, 0, v50
	v_max_f32_e32 v51, 0, v51
	v_max_f32_e32 v52, 0, v52
	v_max_f32_e32 v53, 0, v53
	v_max_f32_e32 v54, 0, v54
	v_max_f32_e32 v55, 0, v55
	v_max_f32_e32 v56, 0, v56
	v_max_f32_e32 v57, 0, v57
	v_max_f32_e32 v58, 0, v58
	v_max_f32_e32 v59, 0, v59
	v_max_f32_e32 v60, 0, v60
	v_max_f32_e32 v61, 0, v61
	v_max_f32_e32 v62, 0, v62
	v_max_f32_e32 v63, 0, v63
	v_mul_f32_e32 v48, v48, v48
	v_mul_f32_e32 v49, v49, v49
	v_mul_f32_e32 v50, v50, v50
	v_mul_f32_e32 v51, v51, v51
	v_mul_f32_e32 v52, v52, v52
	v_mul_f32_e32 v53, v53, v53
	v_mul_f32_e32 v54, v54, v54
	v_mul_f32_e32 v55, v55, v55
	v_mul_f32_e32 v56, v56, v56
	v_mul_f32_e32 v57, v57, v57
	v_mul_f32_e32 v58, v58, v58
	v_mul_f32_e32 v59, v59, v59
	v_mul_f32_e32 v60, v60, v60
	v_mul_f32_e32 v61, v61, v61
	v_mul_f32_e32 v62, v62, v62
	v_mul_f32_e32 v63, v63, v63
	v_cvt_pk_bf16_f32 v60, v60, v61
	v_cvt_pk_bf16_f32 v61, v62, v63
	v_cvt_pk_bf16_f32 v62, v56, v57
	v_cvt_pk_bf16_f32 v63, v58, v59
	v_cvt_pk_bf16_f32 v52, v52, v53
	v_cvt_pk_bf16_f32 v53, v54, v55
	v_cvt_pk_bf16_f32 v54, v48, v49
	v_cvt_pk_bf16_f32 v55, v50, v51
	global_store_dwordx4 v[220:221], v[60:63], off nt
	global_store_dwordx4 v[220:221], v[52:55], off offset:256 nt
	v_lshl_add_u64 v[220:221], v[220:221], 0, s[98:99]
	v_mul_f32_e32 v32, v145, v32
	v_mul_f32_e32 v33, v145, v33
	v_mul_f32_e32 v34, v145, v34
	v_mul_f32_e32 v35, v145, v35
	v_mul_f32_e32 v36, v145, v36
	v_mul_f32_e32 v37, v145, v37
	v_mul_f32_e32 v38, v145, v38
	v_mul_f32_e32 v39, v145, v39
	v_mul_f32_e32 v40, v145, v40
	v_mul_f32_e32 v41, v145, v41
	v_mul_f32_e32 v42, v145, v42
	v_mul_f32_e32 v43, v145, v43
	v_mul_f32_e32 v44, v145, v44
	v_mul_f32_e32 v45, v145, v45
	v_mul_f32_e32 v46, v145, v46
	v_mul_f32_e32 v47, v145, v47
	v_max_f32_e32 v32, 0, v32
	v_max_f32_e32 v33, 0, v33
	v_max_f32_e32 v34, 0, v34
	v_max_f32_e32 v35, 0, v35
	v_max_f32_e32 v36, 0, v36
	v_max_f32_e32 v37, 0, v37
	v_max_f32_e32 v38, 0, v38
	v_max_f32_e32 v39, 0, v39
	v_max_f32_e32 v40, 0, v40
	v_max_f32_e32 v41, 0, v41
	v_max_f32_e32 v42, 0, v42
	v_max_f32_e32 v43, 0, v43
	v_max_f32_e32 v44, 0, v44
	v_max_f32_e32 v45, 0, v45
	v_max_f32_e32 v46, 0, v46
	v_max_f32_e32 v47, 0, v47
	v_mul_f32_e32 v32, v32, v32
	v_mul_f32_e32 v33, v33, v33
	v_mul_f32_e32 v34, v34, v34
	v_mul_f32_e32 v35, v35, v35
	v_mul_f32_e32 v36, v36, v36
	v_mul_f32_e32 v37, v37, v37
	v_mul_f32_e32 v38, v38, v38
; #define PG8_BAR __builtin_amdgcn_s_barrier()
; __device__ __forceinline__ u32x4 pack8(const f32x4 a, const f32x4 b) { u32x4 w; w.x = cvt_pk_bf16(a[0], a[1]); w.y = cvt_pk_bf16(a[2], a[3]); w.z = cvt_pk_bf16(b[0], b[1]); w.w = cvt_pk_bf16(b[2], b[3]); return w; }
; template <class Epi, class Sched, bool ALIGN_EPI = false, bool SP2 = false>
; __device__ __forceinline__ void gemm_phase(PG8_LAS unsigned char* lds, const Gemm g, const Sched& S, const Epi& E) {
;     ...
;         if constexpr (ALIGN_EPI) { if (wr == 0) PG8_BAR; }
;         if constexpr (!Epi::AFTER_DRAIN) { E(acc, cur, wr, wc, fr, fq); S.done(cur); }
;         if (!has_next) break;
; #pragma unroll
;         for (int a = 0; a < 2; ++a)
; #pragma unroll
;             for (int b = 0; b < 2; ++b)
; #pragma unroll
;                 for (int m = 0; m < 4; ++m)
; #pragma unroll
;                     for (int n = 0; n < 2; ++n) acc[a][b][m][n] = (f32x4){0.f, 0.f, 0.f, 0.f};
;         cur = nxt; cA = nA; cB = nB; ++ui;
;         if constexpr (ALIGN_EPI) { if (wr == 1) PG8_BAR; }
;     }
;     __device__ __forceinline__ void operator()(const f32x4 (&acc)[2][2][4][2], const Unit& u, int wr, int wc, int fr, int fq) const {
;         const int rbase = u.pm * 256 + wr * 64 + fr, cb = u.pn * 256 + wc * 32 + fq * 8;
; #pragma unroll
;         for (int ai = 0; ai < 2; ++ai)
; #pragma unroll
;             for (int m = 0; m < 4; ++m) { const int row = rbase + ai * 128 + m * 16; const f32x4* sp = (const f32x4*)(SSP + (size_t)row * 16);
;                 const f32x4 s4 = (sp[0] + sp[1]) + (sp[2] + sp[3]); const float rstd = __builtin_amdgcn_rsqf(((s4[0] + s4[1]) + (s4[2] + s4[3])) * (1.0f / 1024.0f) + EPS);
; #pragma unroll
;                 for (int bj = 0; bj < 2; ++bj) { f32x4 v0 = acc[ai][bj][m][0] * rstd, v1 = acc[ai][bj][m][1] * rstd;
; #pragma unroll
;                     for (int i = 0; i < 4; ++i) { const float a = fmaxf(v0[i], 0.f), b = fmaxf(v1[i], 0.f); v0[i] = a * a; v1[i] = b * b; }
;                     *(u32x4*)(Z + (size_t)row * FF + cb + bj * 128) = pack8(v0, v1); }
;                 asm volatile("" ::: "memory"); }
	v_mul_f32_e32 v39, v39, v39
	v_mul_f32_e32 v40, v40, v40
	v_mul_f32_e32 v41, v41, v41
	v_mul_f32_e32 v42, v42, v42
	v_mul_f32_e32 v43, v43, v43
	v_mul_f32_e32 v44, v44, v44
	v_mul_f32_e32 v45, v45, v45
	v_mul_f32_e32 v46, v46, v46
	v_mul_f32_e32 v47, v47, v47
	v_cvt_pk_bf16_f32 v44, v44, v45
	v_cvt_pk_bf16_f32 v45, v46, v47
	v_cvt_pk_bf16_f32 v46, v40, v41
	v_cvt_pk_bf16_f32 v47, v42, v43
	v_cvt_pk_bf16_f32 v36, v36, v37
	v_cvt_pk_bf16_f32 v37, v38, v39
	v_cvt_pk_bf16_f32 v38, v32, v33
	v_cvt_pk_bf16_f32 v39, v34, v35
	global_store_dwordx4 v[220:221], v[44:47], off nt
	global_store_dwordx4 v[220:221], v[36:39], off offset:256 nt
	v_lshl_add_u64 v[220:221], v[220:221], 0, s[98:99]
	v_mul_f32_e32 v16, v146, v16
	v_mul_f32_e32 v17, v146, v17
	v_mul_f32_e32 v18, v146, v18
	v_mul_f32_e32 v19, v146, v19
	v_mul_f32_e32 v20, v146, v20
	v_mul_f32_e32 v21, v146, v21
	v_mul_f32_e32 v22, v146, v22
	v_mul_f32_e32 v23, v146, v23
	v_mul_f32_e32 v24, v146, v24
	v_mul_f32_e32 v25, v146, v25
	v_mul_f32_e32 v26, v146, v26
	v_mul_f32_e32 v27, v146, v27
	v_mul_f32_e32 v28, v146, v28
	v_mul_f32_e32 v29, v146, v29
	v_mul_f32_e32 v30, v146, v30
	v_mul_f32_e32 v31, v146, v31
	v_max_f32_e32 v16, 0, v16
	v_max_f32_e32 v17, 0, v17
	v_max_f32_e32 v18, 0, v18
	v_max_f32_e32 v19, 0, v19
	v_max_f32_e32 v20, 0, v20
	v_max_f32_e32 v21, 0, v21
	v_max_f32_e32 v22, 0, v22
	v_max_f32_e32 v23, 0, v23
	v_max_f32_e32 v24, 0, v24
	v_max_f32_e32 v25, 0, v25
	v_max_f32_e32 v26, 0, v26
	v_max_f32_e32 v27, 0, v27
	v_max_f32_e32 v28, 0, v28
	v_max_f32_e32 v29, 0, v29
	v_max_f32_e32 v30, 0, v30
	v_max_f32_e32 v31, 0, v31
	v_mul_f32_e32 v16, v16, v16
	v_mul_f32_e32 v17, v17, v17
	v_mul_f32_e32 v18, v18, v18
	v_mul_f32_e32 v19, v19, v19
	v_mul_f32_e32 v20, v20, v20
	v_mul_f32_e32 v21, v21, v21
	v_mul_f32_e32 v22, v22, v22
	v_mul_f32_e32 v23, v23, v23
	v_mul_f32_e32 v24, v24, v24
	v_mul_f32_e32 v25, v25, v25
	v_mul_f32_e32 v26, v26, v26
	v_mul_f32_e32 v27, v27, v27
	v_mul_f32_e32 v28, v28, v28
	v_mul_f32_e32 v29, v29, v29
	v_mul_f32_e32 v30, v30, v30
	v_mul_f32_e32 v31, v31, v31
	v_cvt_pk_bf16_f32 v28, v28, v29
	v_cvt_pk_bf16_f32 v29, v30, v31
	v_cvt_pk_bf16_f32 v30, v24, v25
	v_cvt_pk_bf16_f32 v31, v26, v27
	v_cvt_pk_bf16_f32 v20, v20, v21
	v_cvt_pk_bf16_f32 v21, v22, v23
	v_cvt_pk_bf16_f32 v22, v16, v17
	v_cvt_pk_bf16_f32 v23, v18, v19
	global_store_dwordx4 v[220:221], v[28:31], off nt
	global_store_dwordx4 v[220:221], v[20:23], off offset:256 nt
	v_lshl_add_u64 v[220:221], v[220:221], 0, s[98:99]
	v_mul_f32_e32 v0, v147, v0
	v_mul_f32_e32 v1, v147, v1
	v_mul_f32_e32 v2, v147, v2
	v_mul_f32_e32 v3, v147, v3
	v_mul_f32_e32 v4, v147, v4
	v_mul_f32_e32 v5, v147, v5
	v_mul_f32_e32 v6, v147, v6
	v_mul_f32_e32 v7, v147, v7
	v_mul_f32_e32 v8, v147, v8
	v_mul_f32_e32 v9, v147, v9
	v_mul_f32_e32 v10, v147, v10
	v_mul_f32_e32 v11, v147, v11
	v_mul_f32_e32 v12, v147, v12
	v_mul_f32_e32 v13, v147, v13
	v_mul_f32_e32 v14, v147, v14
	v_mul_f32_e32 v15, v147, v15
	v_max_f32_e32 v0, 0, v0
	v_max_f32_e32 v1, 0, v1
	v_max_f32_e32 v2, 0, v2
	v_max_f32_e32 v3, 0, v3
	v_max_f32_e32 v4, 0, v4
	v_max_f32_e32 v5, 0, v5
	v_max_f32_e32 v6, 0, v6
	v_max_f32_e32 v7, 0, v7
	v_max_f32_e32 v8, 0, v8
	v_max_f32_e32 v9, 0, v9
	v_max_f32_e32 v10, 0, v10
	v_max_f32_e32 v11, 0, v11
	v_max_f32_e32 v12, 0, v12
	v_max_f32_e32 v13, 0, v13
	v_max_f32_e32 v14, 0, v14
	v_max_f32_e32 v15, 0, v15
	v_mul_f32_e32 v0, v0, v0
	v_mul_f32_e32 v1, v1, v1
	v_mul_f32_e32 v2, v2, v2
	v_mul_f32_e32 v3, v3, v3
	v_mul_f32_e32 v4, v4, v4
	v_mul_f32_e32 v5, v5, v5
	v_mul_f32_e32 v6, v6, v6
	v_mul_f32_e32 v7, v7, v7
	v_mul_f32_e32 v8, v8, v8
	v_mul_f32_e32 v9, v9, v9
	v_mul_f32_e32 v10, v10, v10
	v_mul_f32_e32 v11, v11, v11
	v_mul_f32_e32 v12, v12, v12
	v_mul_f32_e32 v13, v13, v13
	v_mul_f32_e32 v14, v14, v14
	v_mul_f32_e32 v15, v15, v15
	v_cvt_pk_bf16_f32 v12, v12, v13
	v_cvt_pk_bf16_f32 v13, v14, v15
	v_cvt_pk_bf16_f32 v14, v8, v9
	v_cvt_pk_bf16_f32 v15, v10, v11
	v_cvt_pk_bf16_f32 v4, v4, v5
	v_cvt_pk_bf16_f32 v5, v6, v7
	v_cvt_pk_bf16_f32 v6, v0, v1
	v_cvt_pk_bf16_f32 v7, v2, v3
	global_store_dwordx4 v[220:221], v[12:15], off nt
	global_store_dwordx4 v[220:221], v[4:7], off offset:256 nt
	s_andn2_b64 vcc, exec, s[4:5]
	s_mov_b64 s[4:5], -1
	s_cbranch_vccnz .LBB0_1536
	s_andn2_b64 vcc, exec, s[6:7]
	s_cbranch_vccnz .LBB0_1535
	s_barrier
	s_branch .LBB0_1535

;     __device__ __forceinline__ void operator()(const f32x4 (&acc)[2][2][4][2], const Unit& u, int wr, int wc, int fr, int fq) const {
;         const int rbase = u.pm * 256 + wr * 64 + fr, cb = u.pn * 256 + wc * 32 + fq * 8;
; #pragma unroll
;         for (int ai = 0; ai < 2; ++ai)
; #pragma unroll
;             for (int m = 0; m < 4; ++m) { float* yr = y + (size_t)(rbase + ai * 128 + m * 16) * 1024 + cb;
; #pragma unroll
;                 for (int bj = 0; bj < 2; ++bj) { float* yp = yr + bj * 128; const f32x4 a = *(const f32x4*)yp + acc[ai][bj][m][0], b = *(const f32x4*)(yp + 4) + acc[ai][bj][m][1]; *(f32x4*)yp = a; *(f32x4*)(yp + 4) = b; }
;                 asm volatile("" ::: "memory"); }
;     }
.LBB0_2139:
	v_and_b32_e32 v244, 8, v146
	v_cmp_eq_u32_e32 vcc, 0, v244
	s_nop 1
	v_mov_b32_dpp v244, v124 row_ror:8 row_mask:0xf bank_mask:0xf
	v_mov_b32_dpp v245, v125 row_ror:8 row_mask:0xf bank_mask:0xf
	v_mov_b32_dpp v246, v126 row_ror:8 row_mask:0xf bank_mask:0xf
	v_mov_b32_dpp v247, v127 row_ror:8 row_mask:0xf bank_mask:0xf
	v_mov_b32_dpp v248, v120 row_ror:8 row_mask:0xf bank_mask:0xf
	v_mov_b32_dpp v249, v121 row_ror:8 row_mask:0xf bank_mask:0xf
	v_mov_b32_dpp v250, v122 row_ror:8 row_mask:0xf bank_mask:0xf
	v_mov_b32_dpp v251, v123 row_ror:8 row_mask:0xf bank_mask:0xf
	s_nop 0
	v_cndmask_b32_e32 v124, v248, v124, vcc
	v_cndmask_b32_e32 v125, v249, v125, vcc
	v_cndmask_b32_e32 v126, v250, v126, vcc
	v_cndmask_b32_e32 v127, v251, v127, vcc
	v_cndmask_b32_e32 v120, v120, v244, vcc
	v_cndmask_b32_e32 v121, v121, v245, vcc
	v_cndmask_b32_e32 v122, v122, v246, vcc
	v_cndmask_b32_e32 v123, v123, v247, vcc
	v_mov_b32_dpp v244, v116 row_ror:8 row_mask:0xf bank_mask:0xf
	v_mov_b32_dpp v245, v117 row_ror:8 row_mask:0xf bank_mask:0xf
	v_mov_b32_dpp v246, v118 row_ror:8 row_mask:0xf bank_mask:0xf
	v_mov_b32_dpp v247, v119 row_ror:8 row_mask:0xf bank_mask:0xf
	v_mov_b32_dpp v248, v112 row_ror:8 row_mask:0xf bank_mask:0xf
	v_mov_b32_dpp v249, v113 row_ror:8 row_mask:0xf bank_mask:0xf
	v_mov_b32_dpp v250, v114 row_ror:8 row_mask:0xf bank_mask:0xf
	v_mov_b32_dpp v251, v115 row_ror:8 row_mask:0xf bank_mask:0xf
	s_nop 0
	v_cndmask_b32_e32 v116, v248, v116, vcc
	v_cndmask_b32_e32 v117, v249, v117, vcc
	v_cndmask_b32_e32 v118, v250, v118, vcc
	v_cndmask_b32_e32 v119, v251, v119, vcc
	v_cndmask_b32_e32 v112, v112, v244, vcc
	v_cndmask_b32_e32 v113, v113, v245, vcc
	v_cndmask_b32_e32 v114, v114, v246, vcc
	v_cndmask_b32_e32 v115, v115, v247, vcc
	s_waitcnt vmcnt(16)
	v_pk_add_f32 v[124:125], v[124:125], v[152:153]
	v_pk_add_f32 v[126:127], v[126:127], v[154:155]
	v_pk_add_f32 v[120:121], v[120:121], v[156:157]
	v_pk_add_f32 v[122:123], v[122:123], v[158:159]
	v_pk_add_f32 v[116:117], v[116:117], v[160:161]
	v_pk_add_f32 v[118:119], v[118:119], v[162:163]
	v_pk_add_f32 v[112:113], v[112:113], v[164:165]
	v_pk_add_f32 v[114:115], v[114:115], v[166:167]
	global_store_dwordx4 v[220:221], v[124:127], off nt
	global_store_dwordx4 v[222:223], v[120:123], off nt
	global_store_dwordx4 v[220:221], v[116:119], off offset:512 nt
	global_store_dwordx4 v[222:223], v[112:115], off offset:512 nt
	v_lshl_add_u64 v[220:221], v[220:221], 0, s[98:99]
	v_lshl_add_u64 v[222:223], v[222:223], 0, s[98:99]
	global_load_dwordx4 v[152:155], v[216:217], off
	global_load_dwordx4 v[156:159], v[218:219], off
	global_load_dwordx4 v[160:163], v[216:217], off offset:512
	global_load_dwordx4 v[164:167], v[218:219], off offset:512
	v_lshl_add_u64 v[216:217], v[216:217], 0, s[98:99]
	v_lshl_add_u64 v[218:219], v[218:219], 0, s[98:99]
	v_mov_b32_dpp v244, v108 row_ror:8 row_mask:0xf bank_mask:0xf
	v_mov_b32_dpp v245, v109 row_ror:8 row_mask:0xf bank_mask:0xf
	v_mov_b32_dpp v246, v110 row_ror:8 row_mask:0xf bank_mask:0xf
	v_mov_b32_dpp v247, v111 row_ror:8 row_mask:0xf bank_mask:0xf
	v_mov_b32_dpp v248, v104 row_ror:8 row_mask:0xf bank_mask:0xf
	v_mov_b32_dpp v249, v105 row_ror:8 row_mask:0xf bank_mask:0xf
	v_mov_b32_dpp v250, v106 row_ror:8 row_mask:0xf bank_mask:0xf
	v_mov_b32_dpp v251, v107 row_ror:8 row_mask:0xf bank_mask:0xf
	s_nop 0
	v_cndmask_b32_e32 v108, v248, v108, vcc
	v_cndmask_b32_e32 v109, v249, v109, vcc
	v_cndmask_b32_e32 v110, v250, v110, vcc
	v_cndmask_b32_e32 v111, v251, v111, vcc
	v_cndmask_b32_e32 v104, v104, v244, vcc
	v_cndmask_b32_e32 v105, v105, v245, vcc
	v_cndmask_b32_e32 v106, v106, v246, vcc
	v_cndmask_b32_e32 v107, v107, v247, vcc
	v_mov_b32_dpp v244, v100 row_ror:8 row_mask:0xf bank_mask:0xf
	v_mov_b32_dpp v245, v101 row_ror:8 row_mask:0xf bank_mask:0xf
	v_mov_b32_dpp v246, v102 row_ror:8 row_mask:0xf bank_mask:0xf
	v_mov_b32_dpp v247, v103 row_ror:8 row_mask:0xf bank_mask:0xf
	v_mov_b32_dpp v248, v96 row_ror:8 row_mask:0xf bank_mask:0xf
	v_mov_b32_dpp v249, v97 row_ror:8 row_mask:0xf bank_mask:0xf
	v_mov_b32_dpp v250, v98 row_ror:8 row_mask:0xf bank_mask:0xf
	v_mov_b32_dpp v251, v99 row_ror:8 row_mask:0xf bank_mask:0xf
	s_nop 0
	v_cndmask_b32_e32 v100, v248, v100, vcc
	v_cndmask_b32_e32 v101, v249, v101, vcc
	v_cndmask_b32_e32 v102, v250, v102, vcc
	v_cndmask_b32_e32 v103, v251, v103, vcc
	v_cndmask_b32_e32 v96, v96, v244, vcc
	v_cndmask_b32_e32 v97, v97, v245, vcc
	v_cndmask_b32_e32 v98, v98, v246, vcc
	v_cndmask_b32_e32 v99, v99, v247, vcc
	s_waitcnt vmcnt(20)
;     __device__ __forceinline__ void operator()(const f32x4 (&acc)[2][2][4][2], const Unit& u, int wr, int wc, int fr, int fq) const {
;         const int rbase = u.pm * 256 + wr * 64 + fr, cb = u.pn * 256 + wc * 32 + fq * 8;
; #pragma unroll
;         for (int ai = 0; ai < 2; ++ai)
; #pragma unroll
;             for (int m = 0; m < 4; ++m) { float* yr = y + (size_t)(rbase + ai * 128 + m * 16) * 1024 + cb;
; #pragma unroll
;                 for (int bj = 0; bj < 2; ++bj) { float* yp = yr + bj * 128; const f32x4 a = *(const f32x4*)yp + acc[ai][bj][m][0], b = *(const f32x4*)(yp + 4) + acc[ai][bj][m][1]; *(f32x4*)yp = a; *(f32x4*)(yp + 4) = b; }
;                 asm volatile("" ::: "memory"); }
;     }
	v_pk_add_f32 v[108:109], v[108:109], v[168:169]
	v_pk_add_f32 v[110:111], v[110:111], v[170:171]
	v_pk_add_f32 v[104:105], v[104:105], v[172:173]
	v_pk_add_f32 v[106:107], v[106:107], v[174:175]
	v_pk_add_f32 v[100:101], v[100:101], v[176:177]
	v_pk_add_f32 v[102:103], v[102:103], v[178:179]
	v_pk_add_f32 v[96:97], v[96:97], v[180:181]
	v_pk_add_f32 v[98:99], v[98:99], v[182:183]
	global_store_dwordx4 v[220:221], v[108:111], off nt
	global_store_dwordx4 v[222:223], v[104:107], off nt
	global_store_dwordx4 v[220:221], v[100:103], off offset:512 nt
	global_store_dwordx4 v[222:223], v[96:99], off offset:512 nt
	v_lshl_add_u64 v[220:221], v[220:221], 0, s[98:99]
	v_lshl_add_u64 v[222:223], v[222:223], 0, s[98:99]
	global_load_dwordx4 v[168:171], v[216:217], off
	global_load_dwordx4 v[172:175], v[218:219], off
	global_load_dwordx4 v[176:179], v[216:217], off offset:512
	global_load_dwordx4 v[180:183], v[218:219], off offset:512
	v_lshl_add_u64 v[216:217], v[216:217], 0, s[98:99]
	v_lshl_add_u64 v[218:219], v[218:219], 0, s[98:99]
	v_mov_b32_dpp v244, v92 row_ror:8 row_mask:0xf bank_mask:0xf
	v_mov_b32_dpp v245, v93 row_ror:8 row_mask:0xf bank_mask:0xf
	v_mov_b32_dpp v246, v94 row_ror:8 row_mask:0xf bank_mask:0xf
	v_mov_b32_dpp v247, v95 row_ror:8 row_mask:0xf bank_mask:0xf
	v_mov_b32_dpp v248, v88 row_ror:8 row_mask:0xf bank_mask:0xf
	v_mov_b32_dpp v249, v89 row_ror:8 row_mask:0xf bank_mask:0xf
	v_mov_b32_dpp v250, v90 row_ror:8 row_mask:0xf bank_mask:0xf
	v_mov_b32_dpp v251, v91 row_ror:8 row_mask:0xf bank_mask:0xf
	s_nop 0
	v_cndmask_b32_e32 v92, v248, v92, vcc
	v_cndmask_b32_e32 v93, v249, v93, vcc
	v_cndmask_b32_e32 v94, v250, v94, vcc
	v_cndmask_b32_e32 v95, v251, v95, vcc
	v_cndmask_b32_e32 v88, v88, v244, vcc
	v_cndmask_b32_e32 v89, v89, v245, vcc
	v_cndmask_b32_e32 v90, v90, v246, vcc
	v_cndmask_b32_e32 v91, v91, v247, vcc
	v_mov_b32_dpp v244, v84 row_ror:8 row_mask:0xf bank_mask:0xf
	v_mov_b32_dpp v245, v85 row_ror:8 row_mask:0xf bank_mask:0xf
	v_mov_b32_dpp v246, v86 row_ror:8 row_mask:0xf bank_mask:0xf
	v_mov_b32_dpp v247, v87 row_ror:8 row_mask:0xf bank_mask:0xf
	v_mov_b32_dpp v248, v80 row_ror:8 row_mask:0xf bank_mask:0xf
	v_mov_b32_dpp v249, v81 row_ror:8 row_mask:0xf bank_mask:0xf
	v_mov_b32_dpp v250, v82 row_ror:8 row_mask:0xf bank_mask:0xf
	v_mov_b32_dpp v251, v83 row_ror:8 row_mask:0xf bank_mask:0xf
	s_nop 0
	v_cndmask_b32_e32 v84, v248, v84, vcc
	v_cndmask_b32_e32 v85, v249, v85, vcc
	v_cndmask_b32_e32 v86, v250, v86, vcc
	v_cndmask_b32_e32 v87, v251, v87, vcc
	v_cndmask_b32_e32 v80, v80, v244, vcc
	v_cndmask_b32_e32 v81, v81, v245, vcc
	v_cndmask_b32_e32 v82, v82, v246, vcc
	v_cndmask_b32_e32 v83, v83, v247, vcc
	s_waitcnt vmcnt(24)
	v_pk_add_f32 v[92:93], v[92:93], v[184:185]
	v_pk_add_f32 v[94:95], v[94:95], v[186:187]
	v_pk_add_f32 v[88:89], v[88:89], v[188:189]
	v_pk_add_f32 v[90:91], v[90:91], v[190:191]
	v_pk_add_f32 v[84:85], v[84:85], v[192:193]
	v_pk_add_f32 v[86:87], v[86:87], v[194:195]
	v_pk_add_f32 v[80:81], v[80:81], v[196:197]
	v_pk_add_f32 v[82:83], v[82:83], v[198:199]
	global_store_dwordx4 v[220:221], v[92:95], off nt
	global_store_dwordx4 v[222:223], v[88:91], off nt
	global_store_dwordx4 v[220:221], v[84:87], off offset:512 nt
	global_store_dwordx4 v[222:223], v[80:83], off offset:512 nt
	v_lshl_add_u64 v[220:221], v[220:221], 0, s[98:99]
	v_lshl_add_u64 v[222:223], v[222:223], 0, s[98:99]
	global_load_dwordx4 v[184:187], v[216:217], off
	global_load_dwordx4 v[188:191], v[218:219], off
	global_load_dwordx4 v[192:195], v[216:217], off offset:512
	global_load_dwordx4 v[196:199], v[218:219], off offset:512
	v_mov_b32_dpp v244, v76 row_ror:8 row_mask:0xf bank_mask:0xf
	v_mov_b32_dpp v245, v77 row_ror:8 row_mask:0xf bank_mask:0xf
	v_mov_b32_dpp v246, v78 row_ror:8 row_mask:0xf bank_mask:0xf
	v_mov_b32_dpp v247, v79 row_ror:8 row_mask:0xf bank_mask:0xf
	v_mov_b32_dpp v248, v72 row_ror:8 row_mask:0xf bank_mask:0xf
	v_mov_b32_dpp v249, v73 row_ror:8 row_mask:0xf bank_mask:0xf
	v_mov_b32_dpp v250, v74 row_ror:8 row_mask:0xf bank_mask:0xf
	v_mov_b32_dpp v251, v75 row_ror:8 row_mask:0xf bank_mask:0xf
	s_nop 0
	v_cndmask_b32_e32 v76, v248, v76, vcc
	v_cndmask_b32_e32 v77, v249, v77, vcc
	v_cndmask_b32_e32 v78, v250, v78, vcc
	v_cndmask_b32_e32 v79, v251, v79, vcc
	v_cndmask_b32_e32 v72, v72, v244, vcc
	v_cndmask_b32_e32 v73, v73, v245, vcc
	v_cndmask_b32_e32 v74, v74, v246, vcc
	v_cndmask_b32_e32 v75, v75, v247, vcc
	v_mov_b32_dpp v244, v68 row_ror:8 row_mask:0xf bank_mask:0xf
	v_mov_b32_dpp v245, v69 row_ror:8 row_mask:0xf bank_mask:0xf
	v_mov_b32_dpp v246, v70 row_ror:8 row_mask:0xf bank_mask:0xf
	v_mov_b32_dpp v247, v71 row_ror:8 row_mask:0xf bank_mask:0xf
	v_mov_b32_dpp v248, v64 row_ror:8 row_mask:0xf bank_mask:0xf
	v_mov_b32_dpp v249, v65 row_ror:8 row_mask:0xf bank_mask:0xf
	v_mov_b32_dpp v250, v66 row_ror:8 row_mask:0xf bank_mask:0xf
	v_mov_b32_dpp v251, v67 row_ror:8 row_mask:0xf bank_mask:0xf
	s_nop 0
	v_cndmask_b32_e32 v68, v248, v68, vcc
	v_cndmask_b32_e32 v69, v249, v69, vcc
	v_cndmask_b32_e32 v70, v250, v70, vcc
	v_cndmask_b32_e32 v71, v251, v71, vcc
	v_cndmask_b32_e32 v64, v64, v244, vcc
	v_cndmask_b32_e32 v65, v65, v245, vcc
	v_cndmask_b32_e32 v66, v66, v246, vcc
	v_cndmask_b32_e32 v67, v67, v247, vcc
	s_waitcnt vmcnt(28)
;     __device__ __forceinline__ void operator()(const f32x4 (&acc)[2][2][4][2], const Unit& u, int wr, int wc, int fr, int fq) const {
;         const int rbase = u.pm * 256 + wr * 64 + fr, cb = u.pn * 256 + wc * 32 + fq * 8;
; #pragma unroll
;         for (int ai = 0; ai < 2; ++ai)
; #pragma unroll
;             for (int m = 0; m < 4; ++m) { float* yr = y + (size_t)(rbase + ai * 128 + m * 16) * 1024 + cb;
; #pragma unroll
;                 for (int bj = 0; bj < 2; ++bj) { float* yp = yr + bj * 128; const f32x4 a = *(const f32x4*)yp + acc[ai][bj][m][0], b = *(const f32x4*)(yp + 4) + acc[ai][bj][m][1]; *(f32x4*)yp = a; *(f32x4*)(yp + 4) = b; }
;                 asm volatile("" ::: "memory"); }
;     }
	v_pk_add_f32 v[76:77], v[76:77], v[200:201]
	v_pk_add_f32 v[78:79], v[78:79], v[202:203]
	v_pk_add_f32 v[72:73], v[72:73], v[204:205]
	v_pk_add_f32 v[74:75], v[74:75], v[206:207]
	v_pk_add_f32 v[68:69], v[68:69], v[208:209]
	v_pk_add_f32 v[70:71], v[70:71], v[210:211]
	v_pk_add_f32 v[64:65], v[64:65], v[212:213]
	v_pk_add_f32 v[66:67], v[66:67], v[214:215]
	global_store_dwordx4 v[220:221], v[76:79], off nt
	global_store_dwordx4 v[222:223], v[72:75], off nt
	global_store_dwordx4 v[220:221], v[68:71], off offset:512 nt
	global_store_dwordx4 v[222:223], v[64:67], off offset:512 nt
	v_lshl_add_u64 v[220:221], v[220:221], 0, s[100:101]
	v_lshl_add_u64 v[222:223], v[222:223], 0, s[100:101]
	v_mov_b32_dpp v244, v60 row_ror:8 row_mask:0xf bank_mask:0xf
	v_mov_b32_dpp v245, v61 row_ror:8 row_mask:0xf bank_mask:0xf
	v_mov_b32_dpp v246, v62 row_ror:8 row_mask:0xf bank_mask:0xf
	v_mov_b32_dpp v247, v63 row_ror:8 row_mask:0xf bank_mask:0xf
	v_mov_b32_dpp v248, v56 row_ror:8 row_mask:0xf bank_mask:0xf
	v_mov_b32_dpp v249, v57 row_ror:8 row_mask:0xf bank_mask:0xf
	v_mov_b32_dpp v250, v58 row_ror:8 row_mask:0xf bank_mask:0xf
	v_mov_b32_dpp v251, v59 row_ror:8 row_mask:0xf bank_mask:0xf
	s_nop 0
	v_cndmask_b32_e32 v60, v248, v60, vcc
	v_cndmask_b32_e32 v61, v249, v61, vcc
	v_cndmask_b32_e32 v62, v250, v62, vcc
	v_cndmask_b32_e32 v63, v251, v63, vcc
	v_cndmask_b32_e32 v56, v56, v244, vcc
	v_cndmask_b32_e32 v57, v57, v245, vcc
	v_cndmask_b32_e32 v58, v58, v246, vcc
	v_cndmask_b32_e32 v59, v59, v247, vcc
	v_mov_b32_dpp v244, v52 row_ror:8 row_mask:0xf bank_mask:0xf
	v_mov_b32_dpp v245, v53 row_ror:8 row_mask:0xf bank_mask:0xf
	v_mov_b32_dpp v246, v54 row_ror:8 row_mask:0xf bank_mask:0xf
	v_mov_b32_dpp v247, v55 row_ror:8 row_mask:0xf bank_mask:0xf
	v_mov_b32_dpp v248, v48 row_ror:8 row_mask:0xf bank_mask:0xf
	v_mov_b32_dpp v249, v49 row_ror:8 row_mask:0xf bank_mask:0xf
	v_mov_b32_dpp v250, v50 row_ror:8 row_mask:0xf bank_mask:0xf
	v_mov_b32_dpp v251, v51 row_ror:8 row_mask:0xf bank_mask:0xf
	s_nop 0
	v_cndmask_b32_e32 v52, v248, v52, vcc
	v_cndmask_b32_e32 v53, v249, v53, vcc
	v_cndmask_b32_e32 v54, v250, v54, vcc
	v_cndmask_b32_e32 v55, v251, v55, vcc
	v_cndmask_b32_e32 v48, v48, v244, vcc
	v_cndmask_b32_e32 v49, v49, v245, vcc
	v_cndmask_b32_e32 v50, v50, v246, vcc
	v_cndmask_b32_e32 v51, v51, v247, vcc
	s_waitcnt vmcnt(28)
	v_pk_add_f32 v[60:61], v[60:61], v[228:229]
	v_pk_add_f32 v[62:63], v[62:63], v[230:231]
	v_pk_add_f32 v[56:57], v[56:57], v[232:233]
	v_pk_add_f32 v[58:59], v[58:59], v[234:235]
	v_pk_add_f32 v[52:53], v[52:53], v[236:237]
	v_pk_add_f32 v[54:55], v[54:55], v[238:239]
	v_pk_add_f32 v[48:49], v[48:49], v[240:241]
	v_pk_add_f32 v[50:51], v[50:51], v[242:243]
	global_store_dwordx4 v[220:221], v[60:63], off nt
	global_store_dwordx4 v[222:223], v[56:59], off nt
	global_store_dwordx4 v[220:221], v[52:55], off offset:512 nt
	global_store_dwordx4 v[222:223], v[48:51], off offset:512 nt
	v_lshl_add_u64 v[220:221], v[220:221], 0, s[98:99]
	v_lshl_add_u64 v[222:223], v[222:223], 0, s[98:99]
	v_mov_b32_dpp v244, v44 row_ror:8 row_mask:0xf bank_mask:0xf
	v_mov_b32_dpp v245, v45 row_ror:8 row_mask:0xf bank_mask:0xf
	v_mov_b32_dpp v246, v46 row_ror:8 row_mask:0xf bank_mask:0xf
	v_mov_b32_dpp v247, v47 row_ror:8 row_mask:0xf bank_mask:0xf
	v_mov_b32_dpp v248, v40 row_ror:8 row_mask:0xf bank_mask:0xf
	v_mov_b32_dpp v249, v41 row_ror:8 row_mask:0xf bank_mask:0xf
	v_mov_b32_dpp v250, v42 row_ror:8 row_mask:0xf bank_mask:0xf
	v_mov_b32_dpp v251, v43 row_ror:8 row_mask:0xf bank_mask:0xf
	s_nop 0
	v_cndmask_b32_e32 v44, v248, v44, vcc
	v_cndmask_b32_e32 v45, v249, v45, vcc
	v_cndmask_b32_e32 v46, v250, v46, vcc
	v_cndmask_b32_e32 v47, v251, v47, vcc
	v_cndmask_b32_e32 v40, v40, v244, vcc
	v_cndmask_b32_e32 v41, v41, v245, vcc
	v_cndmask_b32_e32 v42, v42, v246, vcc
	v_cndmask_b32_e32 v43, v43, v247, vcc
	v_mov_b32_dpp v244, v36 row_ror:8 row_mask:0xf bank_mask:0xf
	v_mov_b32_dpp v245, v37 row_ror:8 row_mask:0xf bank_mask:0xf
	v_mov_b32_dpp v246, v38 row_ror:8 row_mask:0xf bank_mask:0xf
	v_mov_b32_dpp v247, v39 row_ror:8 row_mask:0xf bank_mask:0xf
	v_mov_b32_dpp v248, v32 row_ror:8 row_mask:0xf bank_mask:0xf
	v_mov_b32_dpp v249, v33 row_ror:8 row_mask:0xf bank_mask:0xf
	v_mov_b32_dpp v250, v34 row_ror:8 row_mask:0xf bank_mask:0xf
	v_mov_b32_dpp v251, v35 row_ror:8 row_mask:0xf bank_mask:0xf
	s_nop 0
	v_cndmask_b32_e32 v36, v248, v36, vcc
	v_cndmask_b32_e32 v37, v249, v37, vcc
	v_cndmask_b32_e32 v38, v250, v38, vcc
	v_cndmask_b32_e32 v39, v251, v39, vcc
	v_cndmask_b32_e32 v32, v32, v244, vcc
	v_cndmask_b32_e32 v33, v33, v245, vcc
	v_cndmask_b32_e32 v34, v34, v246, vcc
	v_cndmask_b32_e32 v35, v35, v247, vcc
	s_waitcnt vmcnt(24)
; #define PG8_BAR __builtin_amdgcn_s_barrier()
; template <class Epi, class Sched, bool ALIGN_EPI = false, bool SP2 = false>
; __device__ __forceinline__ void gemm_phase(PG8_LAS unsigned char* lds, const Gemm g, const Sched& S, const Epi& E) {
;     ...
;         if constexpr (ALIGN_EPI) { if (wr == 0) PG8_BAR; }
;         if constexpr (!Epi::AFTER_DRAIN) { E(acc, cur, wr, wc, fr, fq); S.done(cur); }
;         if (!has_next) break;
; #pragma unroll
;         for (int a = 0; a < 2; ++a)
; #pragma unroll
;             for (int b = 0; b < 2; ++b)
; #pragma unroll
;                 for (int m = 0; m < 4; ++m)
; #pragma unroll
;                     for (int n = 0; n < 2; ++n) acc[a][b][m][n] = (f32x4){0.f, 0.f, 0.f, 0.f};
;         cur = nxt; cA = nA; cB = nB; ++ui;
;         if constexpr (ALIGN_EPI) { if (wr == 1) PG8_BAR; }
;     }
;     __device__ __forceinline__ void operator()(const f32x4 (&acc)[2][2][4][2], const Unit& u, int wr, int wc, int fr, int fq) const {
;         const int rbase = u.pm * 256 + wr * 64 + fr, cb = u.pn * 256 + wc * 32 + fq * 8;
; #pragma unroll
;         for (int ai = 0; ai < 2; ++ai)
; #pragma unroll
;             for (int m = 0; m < 4; ++m) { float* yr = y + (size_t)(rbase + ai * 128 + m * 16) * 1024 + cb;
; #pragma unroll
;                 for (int bj = 0; bj < 2; ++bj) { float* yp = yr + bj * 128; const f32x4 a = *(const f32x4*)yp + acc[ai][bj][m][0], b = *(const f32x4*)(yp + 4) + acc[ai][bj][m][1]; *(f32x4*)yp = a; *(f32x4*)(yp + 4) = b; }
;                 asm volatile("" ::: "memory"); }
;     }
	v_pk_add_f32 v[44:45], v[44:45], v[152:153]
	v_pk_add_f32 v[46:47], v[46:47], v[154:155]
	v_pk_add_f32 v[40:41], v[40:41], v[156:157]
	v_pk_add_f32 v[42:43], v[42:43], v[158:159]
	v_pk_add_f32 v[36:37], v[36:37], v[160:161]
	v_pk_add_f32 v[38:39], v[38:39], v[162:163]
	v_pk_add_f32 v[32:33], v[32:33], v[164:165]
	v_pk_add_f32 v[34:35], v[34:35], v[166:167]
	global_store_dwordx4 v[220:221], v[44:47], off nt
	global_store_dwordx4 v[222:223], v[40:43], off nt
	global_store_dwordx4 v[220:221], v[36:39], off offset:512 nt
	global_store_dwordx4 v[222:223], v[32:35], off offset:512 nt
	v_lshl_add_u64 v[220:221], v[220:221], 0, s[98:99]
	v_lshl_add_u64 v[222:223], v[222:223], 0, s[98:99]
	v_mov_b32_dpp v244, v28 row_ror:8 row_mask:0xf bank_mask:0xf
	v_mov_b32_dpp v245, v29 row_ror:8 row_mask:0xf bank_mask:0xf
	v_mov_b32_dpp v246, v30 row_ror:8 row_mask:0xf bank_mask:0xf
	v_mov_b32_dpp v247, v31 row_ror:8 row_mask:0xf bank_mask:0xf
	v_mov_b32_dpp v248, v24 row_ror:8 row_mask:0xf bank_mask:0xf
	v_mov_b32_dpp v249, v25 row_ror:8 row_mask:0xf bank_mask:0xf
	v_mov_b32_dpp v250, v26 row_ror:8 row_mask:0xf bank_mask:0xf
	v_mov_b32_dpp v251, v27 row_ror:8 row_mask:0xf bank_mask:0xf
	s_nop 0
	v_cndmask_b32_e32 v28, v248, v28, vcc
	v_cndmask_b32_e32 v29, v249, v29, vcc
	v_cndmask_b32_e32 v30, v250, v30, vcc
	v_cndmask_b32_e32 v31, v251, v31, vcc
	v_cndmask_b32_e32 v24, v24, v244, vcc
	v_cndmask_b32_e32 v25, v25, v245, vcc
	v_cndmask_b32_e32 v26, v26, v246, vcc
	v_cndmask_b32_e32 v27, v27, v247, vcc
	v_mov_b32_dpp v244, v20 row_ror:8 row_mask:0xf bank_mask:0xf
	v_mov_b32_dpp v245, v21 row_ror:8 row_mask:0xf bank_mask:0xf
	v_mov_b32_dpp v246, v22 row_ror:8 row_mask:0xf bank_mask:0xf
	v_mov_b32_dpp v247, v23 row_ror:8 row_mask:0xf bank_mask:0xf
	v_mov_b32_dpp v248, v16 row_ror:8 row_mask:0xf bank_mask:0xf
	v_mov_b32_dpp v249, v17 row_ror:8 row_mask:0xf bank_mask:0xf
	v_mov_b32_dpp v250, v18 row_ror:8 row_mask:0xf bank_mask:0xf
	v_mov_b32_dpp v251, v19 row_ror:8 row_mask:0xf bank_mask:0xf
	s_nop 0
	v_cndmask_b32_e32 v20, v248, v20, vcc
	v_cndmask_b32_e32 v21, v249, v21, vcc
	v_cndmask_b32_e32 v22, v250, v22, vcc
	v_cndmask_b32_e32 v23, v251, v23, vcc
	v_cndmask_b32_e32 v16, v16, v244, vcc
	v_cndmask_b32_e32 v17, v17, v245, vcc
	v_cndmask_b32_e32 v18, v18, v246, vcc
	v_cndmask_b32_e32 v19, v19, v247, vcc
	s_waitcnt vmcnt(20)
	v_pk_add_f32 v[28:29], v[28:29], v[168:169]
	v_pk_add_f32 v[30:31], v[30:31], v[170:171]
	v_pk_add_f32 v[24:25], v[24:25], v[172:173]
	v_pk_add_f32 v[26:27], v[26:27], v[174:175]
	v_pk_add_f32 v[20:21], v[20:21], v[176:177]
	v_pk_add_f32 v[22:23], v[22:23], v[178:179]
	v_pk_add_f32 v[16:17], v[16:17], v[180:181]
	v_pk_add_f32 v[18:19], v[18:19], v[182:183]
	global_store_dwordx4 v[220:221], v[28:31], off nt
	global_store_dwordx4 v[222:223], v[24:27], off nt
	global_store_dwordx4 v[220:221], v[20:23], off offset:512 nt
	global_store_dwordx4 v[222:223], v[16:19], off offset:512 nt
	v_lshl_add_u64 v[220:221], v[220:221], 0, s[98:99]
	v_lshl_add_u64 v[222:223], v[222:223], 0, s[98:99]
	v_mov_b32_dpp v244, v12 row_ror:8 row_mask:0xf bank_mask:0xf
	v_mov_b32_dpp v245, v13 row_ror:8 row_mask:0xf bank_mask:0xf
	v_mov_b32_dpp v246, v14 row_ror:8 row_mask:0xf bank_mask:0xf
	v_mov_b32_dpp v247, v15 row_ror:8 row_mask:0xf bank_mask:0xf
	v_mov_b32_dpp v248, v8 row_ror:8 row_mask:0xf bank_mask:0xf
	v_mov_b32_dpp v249, v9 row_ror:8 row_mask:0xf bank_mask:0xf
	v_mov_b32_dpp v250, v10 row_ror:8 row_mask:0xf bank_mask:0xf
	v_mov_b32_dpp v251, v11 row_ror:8 row_mask:0xf bank_mask:0xf
	s_nop 0
	v_cndmask_b32_e32 v12, v248, v12, vcc
	v_cndmask_b32_e32 v13, v249, v13, vcc
	v_cndmask_b32_e32 v14, v250, v14, vcc
	v_cndmask_b32_e32 v15, v251, v15, vcc
	v_cndmask_b32_e32 v8, v8, v244, vcc
	v_cndmask_b32_e32 v9, v9, v245, vcc
	v_cndmask_b32_e32 v10, v10, v246, vcc
	v_cndmask_b32_e32 v11, v11, v247, vcc
	v_mov_b32_dpp v244, v4 row_ror:8 row_mask:0xf bank_mask:0xf
	v_mov_b32_dpp v245, v5 row_ror:8 row_mask:0xf bank_mask:0xf
	v_mov_b32_dpp v246, v6 row_ror:8 row_mask:0xf bank_mask:0xf
	v_mov_b32_dpp v247, v7 row_ror:8 row_mask:0xf bank_mask:0xf
	v_mov_b32_dpp v248, v0 row_ror:8 row_mask:0xf bank_mask:0xf
	v_mov_b32_dpp v249, v1 row_ror:8 row_mask:0xf bank_mask:0xf
	v_mov_b32_dpp v250, v2 row_ror:8 row_mask:0xf bank_mask:0xf
	v_mov_b32_dpp v251, v3 row_ror:8 row_mask:0xf bank_mask:0xf
	s_nop 0
	v_cndmask_b32_e32 v4, v248, v4, vcc
	v_cndmask_b32_e32 v5, v249, v5, vcc
	v_cndmask_b32_e32 v6, v250, v6, vcc
	v_cndmask_b32_e32 v7, v251, v7, vcc
	v_cndmask_b32_e32 v0, v0, v244, vcc
	v_cndmask_b32_e32 v1, v1, v245, vcc
	v_cndmask_b32_e32 v2, v2, v246, vcc
	v_cndmask_b32_e32 v3, v3, v247, vcc
	s_waitcnt vmcnt(16)
	v_pk_add_f32 v[12:13], v[12:13], v[184:185]
	v_pk_add_f32 v[14:15], v[14:15], v[186:187]
	v_pk_add_f32 v[8:9], v[8:9], v[188:189]
	v_pk_add_f32 v[10:11], v[10:11], v[190:191]
	v_pk_add_f32 v[4:5], v[4:5], v[192:193]
	v_pk_add_f32 v[6:7], v[6:7], v[194:195]
	v_pk_add_f32 v[0:1], v[0:1], v[196:197]
	v_pk_add_f32 v[2:3], v[2:3], v[198:199]
	global_store_dwordx4 v[220:221], v[12:15], off nt
	global_store_dwordx4 v[222:223], v[8:11], off nt
	global_store_dwordx4 v[220:221], v[4:7], off offset:512 nt
	global_store_dwordx4 v[222:223], v[0:3], off offset:512 nt
	s_andn2_b64 vcc, exec, s[0:1]
	s_mov_b64 s[0:1], -1
	s_cbranch_vccnz .LBB0_2132
	s_andn2_b64 vcc, exec, s[4:5]
	s_cbranch_vccnz .LBB0_2131
	s_barrier
	s_branch .LBB0_2131
